# LDS-DMA 2-stage K-loop in 8 GEMM instances + per-block K rotation + batched residual loads in f32 epilogues
# speedup vs baseline: 1.0383x; 1.0383x over previous
.LBB0_298:
	v_mbcnt_hi_u32_b32 v188, -1, v210
	s_load_dwordx2 s[2:3], s[0:1], 0x158
	s_load_dwordx2 s[4:5], s[0:1], 0xc0
	s_ashr_i32 s7, s6, 31
	v_mov_b32_e32 v1, v188
	s_and_b32 s7, s7, s42
	s_add_i32 s68, s7, s6
	v_add_u32_e32 v0, s70, v1
	v_ashrrev_i32_e32 v189, 3, v0
	v_readfirstlane_b32 s8, v0
	v_lshlrev_b32_e32 v0, 3, v1
	v_and_b32_e32 v0, 56, v0
	s_cmpk_lt_i32 s68, 0x300
	s_cselect_b64 s[6:7], -1, 0
	s_cmpk_gt_i32 s68, 0x2ff
	v_lshlrev_b32_e32 v160, 1, v0
	v_add_u32_e32 v190, 64, v189
	s_cbranch_scc1 .LBB0_300
	s_mul_hi_i32 s9, s68, 0x2aaaaaab
	s_lshr_b32 s10, s9, 31
	s_add_i32 s9, s9, s10
	s_mul_i32 s10, s9, -6
	s_lshl_b32 s9, s9, 8
	v_add_u32_e32 v2, s9, v189
	v_min_i32_e32 v2, 0x7fff, v2
	v_ashrrev_i32_e32 v3, 31, v2
	v_lshlrev_b64 v[2:3], 11, v[2:3]
	s_add_i32 s10, s10, s68
	s_waitcnt lgkmcnt(0)
	v_lshl_add_u64 v[2:3], s[2:3], 0, v[2:3]
	v_mov_b32_e32 v161, 0
	s_lshl_b32 s10, s10, 8
	v_lshl_add_u64 v[2:3], v[2:3], 0, v[160:161]
	v_mbcnt_hi_u32_b32 v158, -1, v210
	s_and_b32 s90, s70, 0x40
	v_and_b32_e32 v159, 48, v158
	v_or_b32_e32 v159, s90, v159
	s_lshl_b32 s88, s70, 4
	s_lshl_b32 s92, s22, 4
	s_and_b32 s92, s92, 0x780
	s_mov_b32 s93, 0
	s_add_u32 m0, s88, 0
	v_lshl_add_u64 v[2:3], v[2:3], 0, s[92:93]
	v_xor_b32_e32 v2, v159, v2
	global_load_lds_dwordx4 v[2:3], off
	v_add_u32_e32 v2, s10, v189
	v_ashrrev_i32_e32 v3, 31, v2
	v_lshlrev_b64 v[2:3], 11, v[2:3]
	v_lshl_add_u64 v[2:3], s[4:5], 0, v[2:3]
	v_lshl_add_u64 v[2:3], v[2:3], 0, v[160:161]
	s_add_u32 m0, s88, 32768
	v_lshl_add_u64 v[2:3], v[2:3], 0, s[92:93]
	v_xor_b32_e32 v2, v159, v2
	global_load_lds_dwordx4 v[2:3], off
	v_add_u32_e32 v2, s9, v190
	v_min_i32_e32 v2, 0x7fff, v2
	v_ashrrev_i32_e32 v3, 31, v2
	v_lshlrev_b64 v[2:3], 11, v[2:3]
	v_lshl_add_u64 v[2:3], s[2:3], 0, v[2:3]
	v_lshl_add_u64 v[2:3], v[2:3], 0, v[160:161]
	s_add_u32 m0, s88, 8192
	v_lshl_add_u64 v[2:3], v[2:3], 0, s[92:93]
	v_xor_b32_e32 v2, v159, v2
	global_load_lds_dwordx4 v[2:3], off
	v_add_u32_e32 v2, s10, v190
	v_ashrrev_i32_e32 v3, 31, v2
	v_lshlrev_b64 v[2:3], 11, v[2:3]
	v_lshl_add_u64 v[2:3], s[4:5], 0, v[2:3]
	v_lshl_add_u64 v[2:3], v[2:3], 0, v[160:161]
	v_add_u32_e32 v4, 0x80, v189
	s_add_u32 m0, s88, 40960
	v_lshl_add_u64 v[2:3], v[2:3], 0, s[92:93]
	v_xor_b32_e32 v2, v159, v2
	global_load_lds_dwordx4 v[2:3], off
	v_add_u32_e32 v2, s9, v4
	v_min_i32_e32 v2, 0x7fff, v2
	v_ashrrev_i32_e32 v3, 31, v2
	v_lshlrev_b64 v[2:3], 11, v[2:3]
	v_lshl_add_u64 v[2:3], s[2:3], 0, v[2:3]
	v_lshl_add_u64 v[2:3], v[2:3], 0, v[160:161]
	s_add_u32 m0, s88, 16384
	v_lshl_add_u64 v[2:3], v[2:3], 0, s[92:93]
	v_xor_b32_e32 v2, v159, v2
	global_load_lds_dwordx4 v[2:3], off
	v_add_u32_e32 v2, s10, v4
	v_ashrrev_i32_e32 v3, 31, v2
	v_lshlrev_b64 v[2:3], 11, v[2:3]
	v_lshl_add_u64 v[2:3], s[4:5], 0, v[2:3]
	v_lshl_add_u64 v[2:3], v[2:3], 0, v[160:161]
	v_add_u32_e32 v4, 0xc0, v189
	s_add_u32 m0, s88, 49152
	v_lshl_add_u64 v[2:3], v[2:3], 0, s[92:93]
	v_xor_b32_e32 v2, v159, v2
	global_load_lds_dwordx4 v[2:3], off
	v_add_u32_e32 v2, s9, v4
	v_min_i32_e32 v2, 0x7fff, v2
	v_ashrrev_i32_e32 v3, 31, v2
	v_lshlrev_b64 v[2:3], 11, v[2:3]
	v_lshl_add_u64 v[2:3], s[2:3], 0, v[2:3]
	v_lshl_add_u64 v[2:3], v[2:3], 0, v[160:161]
	s_add_u32 m0, s88, 24576
	v_lshl_add_u64 v[2:3], v[2:3], 0, s[92:93]
	v_xor_b32_e32 v2, v159, v2
	global_load_lds_dwordx4 v[2:3], off
	v_add_u32_e32 v2, s10, v4
	v_ashrrev_i32_e32 v3, 31, v2
	v_lshlrev_b64 v[2:3], 11, v[2:3]
	v_lshl_add_u64 v[2:3], s[4:5], 0, v[2:3]
	v_lshl_add_u64 v[2:3], v[2:3], 0, v[160:161]
	s_add_u32 m0, s88, 57344
	v_lshl_add_u64 v[2:3], v[2:3], 0, s[92:93]
	v_xor_b32_e32 v2, v159, v2
	global_load_lds_dwordx4 v[2:3], off

.LBB0_303:
	s_mul_hi_i32 s5, s68, 0x2aaaaaab
	s_lshr_b32 s2, s5, 31
	s_add_i32 s5, s5, s2
	s_lshl_b32 s69, s5, 8
	s_waitcnt lgkmcnt(0)
	v_add_u32_e32 v0, s69, v189
	v_min_i32_e32 v0, 0x7fff, v0
	v_ashrrev_i32_e32 v1, 31, v0
	v_lshlrev_b64 v[0:1], 11, v[0:1]
	s_mul_i32 s2, s5, 0x600
	v_lshl_add_u64 v[172:173], v[168:169], 0, v[0:1]
	v_subrev_u32_e32 v0, s2, v200
	v_ashrrev_i32_e32 v1, 31, v0
	v_lshlrev_b64 v[0:1], 11, v[0:1]
	v_lshl_add_u64 v[180:181], v[170:171], 0, v[0:1]
	v_subrev_u32_e32 v0, s2, v201
	v_ashrrev_i32_e32 v1, 31, v0
	v_lshlrev_b64 v[0:1], 11, v[0:1]
	v_lshl_add_u64 v[182:183], v[170:171], 0, v[0:1]
	v_subrev_u32_e32 v0, s2, v202
	v_ashrrev_i32_e32 v1, 31, v0
	v_add_u32_e32 v2, s69, v190
	v_add_u32_e32 v4, s69, v163
	v_add_u32_e32 v6, s69, v192
	v_lshlrev_b64 v[0:1], 11, v[0:1]
	v_min_i32_e32 v2, 0x7fff, v2
	v_min_i32_e32 v4, 0x7fff, v4
	v_min_i32_e32 v6, 0x7fff, v6
	v_lshl_add_u64 v[184:185], v[170:171], 0, v[0:1]
	v_subrev_u32_e32 v0, s2, v203
	v_ashrrev_i32_e32 v3, 31, v2
	v_ashrrev_i32_e32 v5, 31, v4
	v_ashrrev_i32_e32 v7, 31, v6
	v_ashrrev_i32_e32 v1, 31, v0
	v_lshlrev_b64 v[2:3], 11, v[2:3]
	v_lshlrev_b64 v[4:5], 11, v[4:5]
	v_lshlrev_b64 v[6:7], 11, v[6:7]
	v_lshlrev_b64 v[0:1], 11, v[0:1]
	s_mov_b32 s4, s68
	v_lshl_add_u64 v[174:175], v[168:169], 0, v[2:3]
	v_lshl_add_u64 v[176:177], v[168:169], 0, v[4:5]
	v_lshl_add_u64 v[178:179], v[168:169], 0, v[6:7]
	v_lshl_add_u64 v[186:187], v[170:171], 0, v[0:1]
	s_mov_b64 s[2:3], 0
	s_mov_b32 s6, s25
	v_mov_b32_e32 v0, v161
	v_mov_b32_e32 v1, v161
	v_mov_b32_e32 v2, v161
	v_mov_b32_e32 v3, v161
	v_mov_b32_e32 v4, v161
	v_mov_b32_e32 v5, v161
	v_mov_b32_e32 v6, v161
	v_mov_b32_e32 v7, v161
	v_mov_b32_e32 v8, v161
	v_mov_b32_e32 v9, v161
	v_mov_b32_e32 v10, v161
	v_mov_b32_e32 v11, v161
	v_mov_b32_e32 v12, v161
	v_mov_b32_e32 v13, v161
	v_mov_b32_e32 v14, v161
	v_mov_b32_e32 v15, v161
	v_mov_b32_e32 v16, v161
	v_mov_b32_e32 v17, v161
	v_mov_b32_e32 v18, v161
	v_mov_b32_e32 v19, v161
	v_mov_b32_e32 v20, v161
	v_mov_b32_e32 v21, v161
	v_mov_b32_e32 v22, v161
	v_mov_b32_e32 v23, v161
	v_mov_b32_e32 v24, v161
	v_mov_b32_e32 v25, v161
	v_mov_b32_e32 v26, v161
	v_mov_b32_e32 v27, v161
	v_mov_b32_e32 v28, v161
	v_mov_b32_e32 v29, v161
	v_mov_b32_e32 v30, v161
	v_mov_b32_e32 v31, v161
	v_mov_b32_e32 v32, v161
	v_mov_b32_e32 v33, v161
	v_mov_b32_e32 v34, v161
	v_mov_b32_e32 v35, v161
	v_mov_b32_e32 v36, v161
	v_mov_b32_e32 v37, v161
	v_mov_b32_e32 v38, v161
	v_mov_b32_e32 v39, v161
	v_mov_b32_e32 v40, v161
	v_mov_b32_e32 v41, v161
	v_mov_b32_e32 v42, v161
	v_mov_b32_e32 v43, v161
	v_mov_b32_e32 v44, v161
	v_mov_b32_e32 v45, v161
	v_mov_b32_e32 v46, v161
	v_mov_b32_e32 v47, v161
	v_mov_b32_e32 v48, v161
	v_mov_b32_e32 v49, v161
	v_mov_b32_e32 v50, v161
	v_mov_b32_e32 v51, v161
	v_mov_b32_e32 v52, v161
	v_mov_b32_e32 v53, v161
	v_mov_b32_e32 v54, v161
	v_mov_b32_e32 v55, v161
	v_mov_b32_e32 v56, v161
	v_mov_b32_e32 v57, v161
	v_mov_b32_e32 v58, v161
	v_mov_b32_e32 v59, v161
	v_mov_b32_e32 v60, v161
	v_mov_b32_e32 v61, v161
	v_mov_b32_e32 v62, v161
	v_mov_b32_e32 v63, v161
	v_mov_b32_e32 v64, v161
	v_mov_b32_e32 v65, v161
	v_mov_b32_e32 v66, v161
	v_mov_b32_e32 v67, v161
	v_mov_b32_e32 v68, v161
	v_mov_b32_e32 v69, v161
	v_mov_b32_e32 v70, v161
	v_mov_b32_e32 v71, v161
	v_mov_b32_e32 v72, v161
	v_mov_b32_e32 v73, v161
	v_mov_b32_e32 v74, v161
	v_mov_b32_e32 v75, v161
	v_mov_b32_e32 v76, v161
	v_mov_b32_e32 v77, v161
	v_mov_b32_e32 v78, v161
	v_mov_b32_e32 v79, v161
	v_mov_b32_e32 v80, v161
	v_mov_b32_e32 v81, v161
	v_mov_b32_e32 v82, v161
	v_mov_b32_e32 v83, v161
	v_mov_b32_e32 v84, v161
	v_mov_b32_e32 v85, v161
	v_mov_b32_e32 v86, v161
	v_mov_b32_e32 v87, v161
	v_mov_b32_e32 v88, v161
	v_mov_b32_e32 v89, v161
	v_mov_b32_e32 v90, v161
	v_mov_b32_e32 v91, v161
	v_mov_b32_e32 v92, v161
	v_mov_b32_e32 v93, v161
	v_mov_b32_e32 v94, v161
	v_mov_b32_e32 v95, v161
	v_mov_b32_e32 v96, v161
	v_mov_b32_e32 v97, v161
	v_mov_b32_e32 v98, v161
	v_mov_b32_e32 v99, v161
	v_mov_b32_e32 v100, v161
	v_mov_b32_e32 v101, v161
	v_mov_b32_e32 v102, v161
	v_mov_b32_e32 v103, v161
	v_mov_b32_e32 v104, v161
	v_mov_b32_e32 v105, v161
	v_mov_b32_e32 v106, v161
	v_mov_b32_e32 v107, v161
	v_mov_b32_e32 v108, v161
	v_mov_b32_e32 v109, v161
	v_mov_b32_e32 v110, v161
	v_mov_b32_e32 v111, v161
	v_mov_b32_e32 v112, v161
	v_mov_b32_e32 v113, v161
	v_mov_b32_e32 v114, v161
	v_mov_b32_e32 v115, v161
	v_mov_b32_e32 v116, v161
	v_mov_b32_e32 v117, v161
	v_mov_b32_e32 v118, v161
	v_mov_b32_e32 v119, v161
	v_mov_b32_e32 v120, v161
	v_mov_b32_e32 v121, v161
	v_mov_b32_e32 v122, v161
	v_mov_b32_e32 v123, v161
	v_mov_b32_e32 v124, v161
	v_mov_b32_e32 v125, v161
	v_mov_b32_e32 v126, v161
	v_mov_b32_e32 v127, v161
	v_mbcnt_hi_u32_b32 v128, -1, v210
	s_and_b32 s90, s70, 0x40
	v_and_b32_e32 v159, 48, v128
	v_or_b32_e32 v159, s90, v159
	v_and_b32_e32 v129, 31, v128
	v_lshrrev_b32_e32 v130, 5, v128
	v_bfe_u32 v131, v128, 1, 3
	v_lshlrev_b32_e32 v132, 7, v129
	s_lshr_b32 s91, s70, 7
	s_lshl_b32 s91, s91, 13
	s_lshl_b32 s90, s90, 8
	s_add_u32 s90, s90, 0x8000
	s_lshl_b32 s88, s70, 4
	s_mov_b32 s89, 0x10000
	s_lshl_b32 s92, s22, 4
	s_and_b32 s92, s92, 0x780
	s_mov_b32 s93, 0
	v_xor_b32_e32 v133, v130, v131
	v_lshl_add_u32 v133, v133, 4, v132
	v_add_u32_e32 v232, s91, v133
	v_add_u32_e32 v236, s90, v133
	v_or_b32_e32 v133, 2, v130
	v_xor_b32_e32 v133, v133, v131
	v_lshl_add_u32 v133, v133, 4, v132
	v_add_u32_e32 v233, s91, v133
	v_add_u32_e32 v237, s90, v133
	v_or_b32_e32 v133, 4, v130
	v_xor_b32_e32 v133, v133, v131
	v_lshl_add_u32 v133, v133, 4, v132
	v_add_u32_e32 v234, s91, v133
	v_add_u32_e32 v238, s90, v133
	v_or_b32_e32 v133, 6, v130
	v_xor_b32_e32 v133, v133, v131
	v_lshl_add_u32 v133, v133, 4, v132
	v_add_u32_e32 v235, s91, v133
	v_add_u32_e32 v239, s90, v133
	s_waitcnt vmcnt(0)
	s_barrier
	ds_read_b128 v[206:209], v232
	ds_read_b128 v[216:219], v236
	ds_read_b128 v[212:215], v232 offset:4096
	ds_read_b128 v[220:223], v236 offset:4096
	ds_read_b128 v[224:227], v236 offset:8192
	ds_read_b128 v[228:231], v236 offset:12288
	s_add_u32 s94, s2, s92
	s_add_u32 s94, s94, 0x80
	s_and_b32 s94, s94, 0x780
	s_sub_u32 s94, s94, 0x80
	s_subb_u32 s95, 0, 0
	s_add_u32 s90, s88, s89
	s_add_u32 m0, s90, 0
	v_lshl_add_u64 v[152:153], v[172:173], 0, s[94:95]
	v_xor_b32_e32 v152, v159, v152
	global_load_lds_dwordx4 v[152:153], off
	s_add_u32 m0, s90, 32768
	v_lshl_add_u64 v[154:155], v[180:181], 0, s[94:95]
	v_xor_b32_e32 v154, v159, v154
	global_load_lds_dwordx4 v[154:155], off
	s_add_u32 m0, s90, 8192
	v_lshl_add_u64 v[156:157], v[174:175], 0, s[94:95]
	v_xor_b32_e32 v156, v159, v156
	global_load_lds_dwordx4 v[156:157], off
	s_add_u32 m0, s90, 40960
	v_lshl_add_u64 v[152:153], v[182:183], 0, s[94:95]
	v_xor_b32_e32 v152, v159, v152
	global_load_lds_dwordx4 v[152:153], off
	s_add_u32 m0, s90, 16384
	v_lshl_add_u64 v[154:155], v[176:177], 0, s[94:95]
	v_xor_b32_e32 v154, v159, v154
	global_load_lds_dwordx4 v[154:155], off
	s_add_u32 m0, s90, 49152
	v_lshl_add_u64 v[156:157], v[184:185], 0, s[94:95]
	v_xor_b32_e32 v156, v159, v156
	global_load_lds_dwordx4 v[156:157], off
	s_add_u32 m0, s90, 24576
	v_lshl_add_u64 v[152:153], v[178:179], 0, s[94:95]
	v_xor_b32_e32 v152, v159, v152
	global_load_lds_dwordx4 v[152:153], off
	s_add_u32 m0, s90, 57344
	v_lshl_add_u64 v[154:155], v[186:187], 0, s[94:95]
	v_xor_b32_e32 v154, v159, v154
	global_load_lds_dwordx4 v[154:155], off
	s_xor_b32 s89, s89, 0x10000
.Lgk0_loop:
	ds_read_b128 v[128:131], v233
	ds_read_b128 v[136:139], v237
	ds_read_b128 v[132:135], v233 offset:4096
	ds_read_b128 v[140:143], v237 offset:4096
	ds_read_b128 v[144:147], v237 offset:8192
	ds_read_b128 v[148:151], v237 offset:12288
	s_waitcnt lgkmcnt(6)
	v_mfma_f32_32x32x16_bf16 v[112:127], v[206:209], v[216:219], v[112:127]
	v_mfma_f32_32x32x16_bf16 v[48:63], v[212:215], v[216:219], v[48:63]
	v_mfma_f32_32x32x16_bf16 v[96:111], v[206:209], v[220:223], v[96:111]
	v_mfma_f32_32x32x16_bf16 v[32:47], v[212:215], v[220:223], v[32:47]
	v_mfma_f32_32x32x16_bf16 v[80:95], v[206:209], v[224:227], v[80:95]
	v_mfma_f32_32x32x16_bf16 v[16:31], v[212:215], v[224:227], v[16:31]
	v_mfma_f32_32x32x16_bf16 v[64:79], v[206:209], v[228:231], v[64:79]
	v_mfma_f32_32x32x16_bf16 v[0:15], v[212:215], v[228:231], v[0:15]
	ds_read_b128 v[206:209], v234
	ds_read_b128 v[216:219], v238
	ds_read_b128 v[212:215], v234 offset:4096
	ds_read_b128 v[220:223], v238 offset:4096
	ds_read_b128 v[224:227], v238 offset:8192
	ds_read_b128 v[228:231], v238 offset:12288
	s_waitcnt lgkmcnt(6)
	v_mfma_f32_32x32x16_bf16 v[112:127], v[128:131], v[136:139], v[112:127]
	v_mfma_f32_32x32x16_bf16 v[48:63], v[132:135], v[136:139], v[48:63]
	v_mfma_f32_32x32x16_bf16 v[96:111], v[128:131], v[140:143], v[96:111]
	v_mfma_f32_32x32x16_bf16 v[32:47], v[132:135], v[140:143], v[32:47]
	v_mfma_f32_32x32x16_bf16 v[80:95], v[128:131], v[144:147], v[80:95]
	v_mfma_f32_32x32x16_bf16 v[16:31], v[132:135], v[144:147], v[16:31]
	v_mfma_f32_32x32x16_bf16 v[64:79], v[128:131], v[148:151], v[64:79]
	v_mfma_f32_32x32x16_bf16 v[0:15], v[132:135], v[148:151], v[0:15]
	ds_read_b128 v[128:131], v235
	ds_read_b128 v[136:139], v239
	ds_read_b128 v[132:135], v235 offset:4096
	ds_read_b128 v[140:143], v239 offset:4096
	ds_read_b128 v[144:147], v239 offset:8192
	ds_read_b128 v[148:151], v239 offset:12288
	s_waitcnt lgkmcnt(6)
	v_mfma_f32_32x32x16_bf16 v[112:127], v[206:209], v[216:219], v[112:127]
	v_mfma_f32_32x32x16_bf16 v[48:63], v[212:215], v[216:219], v[48:63]
	v_mfma_f32_32x32x16_bf16 v[96:111], v[206:209], v[220:223], v[96:111]
	v_mfma_f32_32x32x16_bf16 v[32:47], v[212:215], v[220:223], v[32:47]
	v_mfma_f32_32x32x16_bf16 v[80:95], v[206:209], v[224:227], v[80:95]
	v_mfma_f32_32x32x16_bf16 v[16:31], v[212:215], v[224:227], v[16:31]
	v_mfma_f32_32x32x16_bf16 v[64:79], v[206:209], v[228:231], v[64:79]
	v_mfma_f32_32x32x16_bf16 v[0:15], v[212:215], v[228:231], v[0:15]
	s_waitcnt vmcnt(0) lgkmcnt(0)
	s_barrier
	v_xor_b32_e32 v232, 0x10000, v232
	v_xor_b32_e32 v236, 0x10000, v236
	ds_read_b128 v[206:209], v232
	ds_read_b128 v[216:219], v236
	ds_read_b128 v[212:215], v232 offset:4096
	ds_read_b128 v[220:223], v236 offset:4096
	ds_read_b128 v[224:227], v236 offset:8192
	ds_read_b128 v[228:231], v236 offset:12288
	s_cmpk_eq_i32 s2, 0x700
	s_cbranch_scc1 .Lgk0_nodma
	s_add_u32 s94, s2, s92
	s_add_u32 s94, s94, 0x100
	s_and_b32 s94, s94, 0x780
	s_sub_u32 s94, s94, 0x80
	s_subb_u32 s95, 0, 0
	s_add_u32 s90, s88, s89
	v_mfma_f32_32x32x16_bf16 v[112:127], v[128:131], v[136:139], v[112:127]
	v_xor_b32_e32 v233, 0x10000, v233
	v_xor_b32_e32 v237, 0x10000, v237
	s_add_u32 m0, s90, 0
	v_lshl_add_u64 v[152:153], v[172:173], 0, s[94:95]
	v_xor_b32_e32 v152, v159, v152
	global_load_lds_dwordx4 v[152:153], off
	v_mfma_f32_32x32x16_bf16 v[48:63], v[132:135], v[136:139], v[48:63]
	v_xor_b32_e32 v234, 0x10000, v234
	v_xor_b32_e32 v238, 0x10000, v238
	s_add_u32 m0, s90, 32768
	v_lshl_add_u64 v[154:155], v[180:181], 0, s[94:95]
	v_xor_b32_e32 v154, v159, v154
	global_load_lds_dwordx4 v[154:155], off
	v_mfma_f32_32x32x16_bf16 v[96:111], v[128:131], v[140:143], v[96:111]
	v_xor_b32_e32 v235, 0x10000, v235
	v_xor_b32_e32 v239, 0x10000, v239
	s_add_u32 m0, s90, 8192
	v_lshl_add_u64 v[156:157], v[174:175], 0, s[94:95]
	v_xor_b32_e32 v156, v159, v156
	global_load_lds_dwordx4 v[156:157], off
	v_mfma_f32_32x32x16_bf16 v[32:47], v[132:135], v[140:143], v[32:47]
	s_add_u32 m0, s90, 40960
	v_lshl_add_u64 v[152:153], v[182:183], 0, s[94:95]
	v_xor_b32_e32 v152, v159, v152
	global_load_lds_dwordx4 v[152:153], off
	v_mfma_f32_32x32x16_bf16 v[80:95], v[128:131], v[144:147], v[80:95]
	s_add_u32 m0, s90, 16384
	v_lshl_add_u64 v[154:155], v[176:177], 0, s[94:95]
	v_xor_b32_e32 v154, v159, v154
	global_load_lds_dwordx4 v[154:155], off
	v_mfma_f32_32x32x16_bf16 v[16:31], v[132:135], v[144:147], v[16:31]
	s_add_u32 m0, s90, 49152
	v_lshl_add_u64 v[156:157], v[184:185], 0, s[94:95]
	v_xor_b32_e32 v156, v159, v156
	global_load_lds_dwordx4 v[156:157], off
	v_mfma_f32_32x32x16_bf16 v[64:79], v[128:131], v[148:151], v[64:79]
	s_add_u32 m0, s90, 24576
	v_lshl_add_u64 v[152:153], v[178:179], 0, s[94:95]
	v_xor_b32_e32 v152, v159, v152
	global_load_lds_dwordx4 v[152:153], off
	v_mfma_f32_32x32x16_bf16 v[0:15], v[132:135], v[148:151], v[0:15]
	s_add_u32 m0, s90, 57344
	v_lshl_add_u64 v[154:155], v[186:187], 0, s[94:95]
	v_xor_b32_e32 v154, v159, v154
	global_load_lds_dwordx4 v[154:155], off
	s_branch .Lgk0_join
.Lgk0_nodma:
	v_mfma_f32_32x32x16_bf16 v[112:127], v[128:131], v[136:139], v[112:127]
	v_xor_b32_e32 v233, 0x10000, v233
	v_xor_b32_e32 v237, 0x10000, v237
	v_mfma_f32_32x32x16_bf16 v[48:63], v[132:135], v[136:139], v[48:63]
	v_xor_b32_e32 v234, 0x10000, v234
	v_xor_b32_e32 v238, 0x10000, v238
	v_mfma_f32_32x32x16_bf16 v[96:111], v[128:131], v[140:143], v[96:111]
	v_xor_b32_e32 v235, 0x10000, v235
	v_xor_b32_e32 v239, 0x10000, v239
	v_mfma_f32_32x32x16_bf16 v[32:47], v[132:135], v[140:143], v[32:47]
	v_mfma_f32_32x32x16_bf16 v[80:95], v[128:131], v[144:147], v[80:95]
	v_mfma_f32_32x32x16_bf16 v[16:31], v[132:135], v[144:147], v[16:31]
	v_mfma_f32_32x32x16_bf16 v[64:79], v[128:131], v[148:151], v[64:79]
	v_mfma_f32_32x32x16_bf16 v[0:15], v[132:135], v[148:151], v[0:15]
.Lgk0_join:
	s_xor_b32 s89, s89, 0x10000
	s_add_i32 s6, s6, 1
	s_add_u32 s2, s2, 0x80
	s_addc_u32 s3, s3, 0
	s_cmpk_eq_i32 s2, 0x780
	s_cbranch_scc0 .Lgk0_loop
	s_add_i32 s68, s4, s42
	s_cmpk_gt_i32 s68, 0x2ff
	s_cselect_b64 s[28:29], -1, 0
	s_and_b64 vcc, exec, s[28:29]
	s_cbranch_vccnz .LBB0_307
	s_mul_hi_i32 s2, s68, 0x2aaaaaab
	s_lshr_b32 s3, s2, 31
	s_add_i32 s2, s2, s3
	s_mul_i32 s3, s2, -6
	s_lshl_b32 s2, s2, 8
	v_add_u32_e32 v129, s2, v190
	s_add_i32 s3, s3, s68
	v_min_i32_e32 v132, 0x7fff, v129
	v_add_u32_e32 v129, s2, v163
	s_lshl_b32 s3, s3, 8
	v_add_u32_e32 v128, s2, v189
	v_min_i32_e32 v136, 0x7fff, v129
	v_add_u32_e32 v129, s2, v192
	v_min_i32_e32 v128, 0x7fff, v128
	v_add_u32_e32 v130, s3, v189
	v_add_u32_e32 v134, s3, v190
	v_add_u32_e32 v138, s3, v163
	v_min_i32_e32 v140, 0x7fff, v129
	v_add_u32_e32 v142, s3, v192
	v_ashrrev_i32_e32 v143, 31, v142
	v_ashrrev_i32_e32 v141, 31, v140
	v_ashrrev_i32_e32 v139, 31, v138
	v_ashrrev_i32_e32 v137, 31, v136
	v_ashrrev_i32_e32 v135, 31, v134
	v_ashrrev_i32_e32 v133, 31, v132
	v_ashrrev_i32_e32 v131, 31, v130
	v_ashrrev_i32_e32 v129, 31, v128
	v_lshlrev_b64 v[142:143], 11, v[142:143]
	v_lshlrev_b64 v[140:141], 11, v[140:141]
	v_lshlrev_b64 v[138:139], 11, v[138:139]
	v_lshlrev_b64 v[136:137], 11, v[136:137]
	v_lshlrev_b64 v[134:135], 11, v[134:135]
	v_lshlrev_b64 v[132:133], 11, v[132:133]
	v_lshlrev_b64 v[130:131], 11, v[130:131]
	v_lshlrev_b64 v[128:129], 11, v[128:129]
	v_lshl_add_u64 v[156:157], v[164:165], 0, v[142:143]
	v_lshl_add_u64 v[152:153], v[166:167], 0, v[140:141]
	v_lshl_add_u64 v[148:149], v[164:165], 0, v[138:139]
	v_lshl_add_u64 v[144:145], v[166:167], 0, v[136:137]
	v_lshl_add_u64 v[140:141], v[164:165], 0, v[134:135]
	v_lshl_add_u64 v[136:137], v[166:167], 0, v[132:133]
	v_lshl_add_u64 v[132:133], v[164:165], 0, v[130:131]
	v_lshl_add_u64 v[128:129], v[166:167], 0, v[128:129]
	s_add_u32 m0, s88, 0
	v_lshl_add_u64 v[128:129], v[128:129], 0, s[92:93]
	v_xor_b32_e32 v128, v159, v128
	global_load_lds_dwordx4 v[128:129], off
	s_add_u32 m0, s88, 32768
	v_lshl_add_u64 v[132:133], v[132:133], 0, s[92:93]
	v_xor_b32_e32 v132, v159, v132
	global_load_lds_dwordx4 v[132:133], off
	s_add_u32 m0, s88, 8192
	v_lshl_add_u64 v[136:137], v[136:137], 0, s[92:93]
	v_xor_b32_e32 v136, v159, v136
	global_load_lds_dwordx4 v[136:137], off
	s_add_u32 m0, s88, 40960
	v_lshl_add_u64 v[140:141], v[140:141], 0, s[92:93]
	v_xor_b32_e32 v140, v159, v140
	global_load_lds_dwordx4 v[140:141], off
	s_add_u32 m0, s88, 16384
	v_lshl_add_u64 v[144:145], v[144:145], 0, s[92:93]
	v_xor_b32_e32 v144, v159, v144
	global_load_lds_dwordx4 v[144:145], off
	s_add_u32 m0, s88, 49152
	v_lshl_add_u64 v[148:149], v[148:149], 0, s[92:93]
	v_xor_b32_e32 v148, v159, v148
	global_load_lds_dwordx4 v[148:149], off
	s_add_u32 m0, s88, 24576
	v_lshl_add_u64 v[152:153], v[152:153], 0, s[92:93]
	v_xor_b32_e32 v152, v159, v152
	global_load_lds_dwordx4 v[152:153], off
	s_add_u32 m0, s88, 57344
	v_lshl_add_u64 v[156:157], v[156:157], 0, s[92:93]
	v_xor_b32_e32 v156, v159, v156
	global_load_lds_dwordx4 v[156:157], off
.LBB0_307:
	ds_read_b128 v[128:131], v233
	ds_read_b128 v[136:139], v237
	ds_read_b128 v[132:135], v233 offset:4096
	ds_read_b128 v[140:143], v237 offset:4096
	ds_read_b128 v[144:147], v237 offset:8192
	ds_read_b128 v[148:151], v237 offset:12288
	s_waitcnt lgkmcnt(6)
	v_mfma_f32_32x32x16_bf16 v[112:127], v[206:209], v[216:219], v[112:127]
	v_mfma_f32_32x32x16_bf16 v[48:63], v[212:215], v[216:219], v[48:63]
	v_mfma_f32_32x32x16_bf16 v[96:111], v[206:209], v[220:223], v[96:111]
	v_mfma_f32_32x32x16_bf16 v[32:47], v[212:215], v[220:223], v[32:47]
	v_mfma_f32_32x32x16_bf16 v[80:95], v[206:209], v[224:227], v[80:95]
	v_mfma_f32_32x32x16_bf16 v[16:31], v[212:215], v[224:227], v[16:31]
	v_mfma_f32_32x32x16_bf16 v[64:79], v[206:209], v[228:231], v[64:79]
	v_mfma_f32_32x32x16_bf16 v[0:15], v[212:215], v[228:231], v[0:15]
	ds_read_b128 v[206:209], v234
	ds_read_b128 v[216:219], v238
	ds_read_b128 v[212:215], v234 offset:4096
	ds_read_b128 v[220:223], v238 offset:4096
	ds_read_b128 v[224:227], v238 offset:8192
	ds_read_b128 v[228:231], v238 offset:12288
	s_waitcnt lgkmcnt(6)
	v_mfma_f32_32x32x16_bf16 v[112:127], v[128:131], v[136:139], v[112:127]
	v_mfma_f32_32x32x16_bf16 v[48:63], v[132:135], v[136:139], v[48:63]
	v_mfma_f32_32x32x16_bf16 v[96:111], v[128:131], v[140:143], v[96:111]
	v_mfma_f32_32x32x16_bf16 v[32:47], v[132:135], v[140:143], v[32:47]
	v_mfma_f32_32x32x16_bf16 v[80:95], v[128:131], v[144:147], v[80:95]
	v_mfma_f32_32x32x16_bf16 v[16:31], v[132:135], v[144:147], v[16:31]
	v_mfma_f32_32x32x16_bf16 v[64:79], v[128:131], v[148:151], v[64:79]
	v_mfma_f32_32x32x16_bf16 v[0:15], v[132:135], v[148:151], v[0:15]
	ds_read_b128 v[128:131], v235
	ds_read_b128 v[136:139], v239
	ds_read_b128 v[132:135], v235 offset:4096
	ds_read_b128 v[140:143], v239 offset:4096
	ds_read_b128 v[144:147], v239 offset:8192
	ds_read_b128 v[148:151], v239 offset:12288
	s_waitcnt lgkmcnt(6)
	v_mfma_f32_32x32x16_bf16 v[112:127], v[206:209], v[216:219], v[112:127]
	v_mfma_f32_32x32x16_bf16 v[48:63], v[212:215], v[216:219], v[48:63]
	v_mfma_f32_32x32x16_bf16 v[96:111], v[206:209], v[220:223], v[96:111]
	v_mfma_f32_32x32x16_bf16 v[32:47], v[212:215], v[220:223], v[32:47]
	v_mfma_f32_32x32x16_bf16 v[80:95], v[206:209], v[224:227], v[80:95]
	v_mfma_f32_32x32x16_bf16 v[16:31], v[212:215], v[224:227], v[16:31]
	v_mfma_f32_32x32x16_bf16 v[64:79], v[206:209], v[228:231], v[64:79]
	v_mfma_f32_32x32x16_bf16 v[0:15], v[212:215], v[228:231], v[0:15]
	s_waitcnt lgkmcnt(0)
	s_barrier
	v_xor_b32_e32 v232, 0x10000, v232
	v_xor_b32_e32 v236, 0x10000, v236
	v_mfma_f32_32x32x16_bf16 v[112:127], v[128:131], v[136:139], v[112:127]
	v_xor_b32_e32 v233, 0x10000, v233
	v_xor_b32_e32 v237, 0x10000, v237
	v_mfma_f32_32x32x16_bf16 v[48:63], v[132:135], v[136:139], v[48:63]
	v_xor_b32_e32 v234, 0x10000, v234
	v_xor_b32_e32 v238, 0x10000, v238
	v_mfma_f32_32x32x16_bf16 v[96:111], v[128:131], v[140:143], v[96:111]
	v_xor_b32_e32 v235, 0x10000, v235
	v_xor_b32_e32 v239, 0x10000, v239
	v_mfma_f32_32x32x16_bf16 v[32:47], v[132:135], v[140:143], v[32:47]
	v_mfma_f32_32x32x16_bf16 v[80:95], v[128:131], v[144:147], v[80:95]
	v_mfma_f32_32x32x16_bf16 v[16:31], v[132:135], v[144:147], v[16:31]
	v_mfma_f32_32x32x16_bf16 v[64:79], v[128:131], v[148:151], v[64:79]
	v_mfma_f32_32x32x16_bf16 v[0:15], v[132:135], v[148:151], v[0:15]
	s_mul_i32 s2, s5, -6
	s_add_i32 s2, s2, s4
	s_lshl_b32 s2, s2, 8
	s_or_b32 s24, s2, s56
	s_cmpk_lg_i32 s24, 0x180
	s_cselect_b64 s[8:9], -1, 0
	s_cmpk_gt_i32 s24, 0x180
	s_cselect_b64 s[4:5], -1, 0
	v_cndmask_b32_e64 v160, 0, 1, s[4:5]
	s_mov_b64 s[2:3], -1
	s_and_b64 vcc, exec, s[8:9]
	v_cmp_ne_u32_e64 s[6:7], 1, v160
	s_nop 3
	v_mov_b32_e32 v177, v191
	s_cbranch_vccz .LBB0_311
	s_and_b64 vcc, exec, s[6:7]
	s_nop 4
	v_mov_b32_e32 v175, v96
	v_mov_b32_e32 v174, v112
	s_cbranch_vccnz .LBB0_310
	v_mul_f32_e32 v160, 0xbfb8aa3b, v112
	v_mul_f32_e32 v172, 0xbfb8aa3b, v96
	v_exp_f32_e32 v160, v160
	v_exp_f32_e32 v172, v172
	v_mov_b32_e32 v174, v112
	v_mov_b32_e32 v175, v96
	v_add_f32_e32 v160, 1.0, v160
	v_add_f32_e32 v173, 1.0, v172
	v_rcp_f32_e32 v172, v160
	v_rcp_f32_e32 v173, v173
	s_nop 0
	v_pk_mul_f32 v[174:175], v[174:175], v[172:173]

.LBB0_1270:
	v_mbcnt_hi_u32_b32 v211, -1, v210
	s_load_dwordx2 s[2:3], s[0:1], 0xf0
	s_load_dwordx2 s[4:5], s[0:1], 0x158
	s_ashr_i32 s7, s6, 31
	v_mov_b32_e32 v1, v211
	s_and_b32 s7, s7, s42
	s_add_i32 s54, s7, s6
	v_add_u32_e32 v0, s70, v1
	v_ashrrev_i32_e32 v212, 3, v0
	v_readfirstlane_b32 s8, v0
	v_lshlrev_b32_e32 v0, 3, v1
	v_and_b32_e32 v0, 56, v0
	s_cmpk_lt_i32 s54, 0x200
	s_cselect_b64 s[6:7], -1, 0
	s_cmpk_gt_i32 s54, 0x1ff
	v_lshlrev_b32_e32 v168, 1, v0
	v_add_u32_e32 v213, 64, v212
	s_cbranch_scc1 .LBB0_1272
	s_ashr_i32 s9, s54, 31
	s_lshr_b32 s9, s9, 30
	s_add_i32 s9, s54, s9
	s_ashr_i32 s9, s9, 2
	s_lshl_b32 s10, s9, 8
	v_add_u32_e32 v2, s10, v212
	v_min_i32_e32 v2, 0x7fff, v2
	v_ashrrev_i32_e32 v3, 31, v2
	v_lshlrev_b64 v[2:3], 11, v[2:3]
	s_lshl_b32 s9, s9, 10
	s_lshl_b32 s11, s54, 8
	s_waitcnt lgkmcnt(0)
	v_lshl_add_u64 v[2:3], s[4:5], 0, v[2:3]
	v_mov_b32_e32 v169, 0
	s_sub_i32 s9, s11, s9
	v_lshl_add_u64 v[2:3], v[2:3], 0, v[168:169]
	v_mbcnt_hi_u32_b32 v158, -1, v210
	s_and_b32 s90, s70, 0x40
	v_and_b32_e32 v159, 48, v158
	v_or_b32_e32 v159, s90, v159
	s_lshl_b32 s88, s70, 4
	s_lshl_b32 s92, s22, 4
	s_and_b32 s92, s92, 0x780
	s_mov_b32 s93, 0
	s_add_u32 m0, s88, 0
	v_lshl_add_u64 v[2:3], v[2:3], 0, s[92:93]
	v_xor_b32_e32 v2, v159, v2
	global_load_lds_dwordx4 v[2:3], off
	v_add_u32_e32 v2, s9, v212
	v_ashrrev_i32_e32 v3, 31, v2
	v_lshlrev_b64 v[2:3], 11, v[2:3]
	v_lshl_add_u64 v[2:3], s[2:3], 0, v[2:3]
	v_lshl_add_u64 v[2:3], v[2:3], 0, v[168:169]
	s_add_u32 m0, s88, 32768
	v_lshl_add_u64 v[2:3], v[2:3], 0, s[92:93]
	v_xor_b32_e32 v2, v159, v2
	global_load_lds_dwordx4 v[2:3], off
	v_add_u32_e32 v2, s10, v213
	v_min_i32_e32 v2, 0x7fff, v2
	v_ashrrev_i32_e32 v3, 31, v2
	v_lshlrev_b64 v[2:3], 11, v[2:3]
	v_lshl_add_u64 v[2:3], s[4:5], 0, v[2:3]
	v_lshl_add_u64 v[2:3], v[2:3], 0, v[168:169]
	s_add_u32 m0, s88, 8192
	v_lshl_add_u64 v[2:3], v[2:3], 0, s[92:93]
	v_xor_b32_e32 v2, v159, v2
	global_load_lds_dwordx4 v[2:3], off
	v_add_u32_e32 v2, s9, v213
	v_ashrrev_i32_e32 v3, 31, v2
	v_lshlrev_b64 v[2:3], 11, v[2:3]
	v_lshl_add_u64 v[2:3], s[2:3], 0, v[2:3]
	v_lshl_add_u64 v[2:3], v[2:3], 0, v[168:169]
	v_add_u32_e32 v4, 0x80, v212
	s_add_u32 m0, s88, 40960
	v_lshl_add_u64 v[2:3], v[2:3], 0, s[92:93]
	v_xor_b32_e32 v2, v159, v2
	global_load_lds_dwordx4 v[2:3], off
	v_add_u32_e32 v2, s10, v4
	v_min_i32_e32 v2, 0x7fff, v2
	v_ashrrev_i32_e32 v3, 31, v2
	v_lshlrev_b64 v[2:3], 11, v[2:3]
	v_lshl_add_u64 v[2:3], s[4:5], 0, v[2:3]
	v_lshl_add_u64 v[2:3], v[2:3], 0, v[168:169]
	s_add_u32 m0, s88, 16384
	v_lshl_add_u64 v[2:3], v[2:3], 0, s[92:93]
	v_xor_b32_e32 v2, v159, v2
	global_load_lds_dwordx4 v[2:3], off
	v_add_u32_e32 v2, s9, v4
	v_ashrrev_i32_e32 v3, 31, v2
	v_lshlrev_b64 v[2:3], 11, v[2:3]
	v_lshl_add_u64 v[2:3], s[2:3], 0, v[2:3]
	v_lshl_add_u64 v[2:3], v[2:3], 0, v[168:169]
	v_add_u32_e32 v4, 0xc0, v212
	s_add_u32 m0, s88, 49152
	v_lshl_add_u64 v[2:3], v[2:3], 0, s[92:93]
	v_xor_b32_e32 v2, v159, v2
	global_load_lds_dwordx4 v[2:3], off
	v_add_u32_e32 v2, s10, v4
	v_min_i32_e32 v2, 0x7fff, v2
	v_ashrrev_i32_e32 v3, 31, v2
	v_lshlrev_b64 v[2:3], 11, v[2:3]
	v_lshl_add_u64 v[2:3], s[4:5], 0, v[2:3]
	v_lshl_add_u64 v[2:3], v[2:3], 0, v[168:169]
	s_add_u32 m0, s88, 24576
	v_lshl_add_u64 v[2:3], v[2:3], 0, s[92:93]
	v_xor_b32_e32 v2, v159, v2
	global_load_lds_dwordx4 v[2:3], off
	v_add_u32_e32 v2, s9, v4
	v_ashrrev_i32_e32 v3, 31, v2
	v_lshlrev_b64 v[2:3], 11, v[2:3]
	v_lshl_add_u64 v[2:3], s[2:3], 0, v[2:3]
	v_lshl_add_u64 v[2:3], v[2:3], 0, v[168:169]
	s_add_u32 m0, s88, 57344
	v_lshl_add_u64 v[2:3], v[2:3], 0, s[92:93]
	v_xor_b32_e32 v2, v159, v2
	global_load_lds_dwordx4 v[2:3], off

.LBB0_1275:
	s_ashr_i32 s2, s54, 31
	s_lshr_b32 s2, s2, 30
	s_add_i32 s2, s54, s2
	s_ashr_i32 s2, s2, 2
	s_lshl_b32 s4, s2, 8
	v_add_u32_e32 v0, s4, v212
	v_min_i32_e32 v0, 0x7fff, v0
	v_ashrrev_i32_e32 v1, 31, v0
	s_lshl_b32 s6, s2, 10
	v_lshlrev_b64 v[0:1], 11, v[0:1]
	v_lshl_add_u64 v[160:161], v[176:177], 0, v[0:1]
	v_subrev_u32_e32 v0, s6, v220
	v_ashrrev_i32_e32 v1, 31, v0
	v_lshlrev_b64 v[0:1], 11, v[0:1]
	v_lshl_add_u64 v[180:181], v[178:179], 0, v[0:1]
	v_subrev_u32_e32 v0, s6, v221
	v_ashrrev_i32_e32 v1, 31, v0
	v_lshlrev_b64 v[0:1], 11, v[0:1]
	v_lshl_add_u64 v[182:183], v[178:179], 0, v[0:1]
	v_subrev_u32_e32 v0, s6, v222
	v_ashrrev_i32_e32 v1, 31, v0
	v_add_u32_e32 v2, s4, v213
	v_add_u32_e32 v4, s4, v171
	v_add_u32_e32 v6, s4, v215
	v_lshlrev_b64 v[0:1], 11, v[0:1]
	v_min_i32_e32 v2, 0x7fff, v2
	v_min_i32_e32 v4, 0x7fff, v4
	v_min_i32_e32 v6, 0x7fff, v6
	v_lshl_add_u64 v[184:185], v[178:179], 0, v[0:1]
	v_subrev_u32_e32 v0, s6, v223
	v_ashrrev_i32_e32 v3, 31, v2
	v_ashrrev_i32_e32 v5, 31, v4
	v_ashrrev_i32_e32 v7, 31, v6
	v_ashrrev_i32_e32 v1, 31, v0
	v_lshlrev_b64 v[2:3], 11, v[2:3]
	v_lshlrev_b64 v[4:5], 11, v[4:5]
	v_lshlrev_b64 v[6:7], 11, v[6:7]
	v_lshlrev_b64 v[0:1], 11, v[0:1]
	s_mov_b32 s5, s54
	v_lshl_add_u64 v[162:163], v[176:177], 0, v[2:3]
	v_lshl_add_u64 v[164:165], v[176:177], 0, v[4:5]
	v_lshl_add_u64 v[166:167], v[176:177], 0, v[6:7]
	v_lshl_add_u64 v[186:187], v[178:179], 0, v[0:1]
	s_mov_b64 s[2:3], 0
	s_mov_b32 s7, 0
	v_mov_b32_e32 v0, 0
	v_mov_b32_e32 v1, v169
	v_mov_b32_e32 v2, v169
	v_mov_b32_e32 v3, v169
	v_mov_b32_e32 v4, v169
	v_mov_b32_e32 v5, v169
	v_mov_b32_e32 v6, v169
	v_mov_b32_e32 v7, v169
	v_mov_b32_e32 v8, v169
	v_mov_b32_e32 v9, v169
	v_mov_b32_e32 v10, v169
	v_mov_b32_e32 v11, v169
	v_mov_b32_e32 v12, v169
	v_mov_b32_e32 v13, v169
	v_mov_b32_e32 v14, v169
	v_mov_b32_e32 v15, v169
	v_mov_b32_e32 v16, 0
	v_mov_b32_e32 v17, v169
	v_mov_b32_e32 v18, v169
	v_mov_b32_e32 v19, v169
	v_mov_b32_e32 v20, v169
	v_mov_b32_e32 v21, v169
	v_mov_b32_e32 v22, v169
	v_mov_b32_e32 v23, v169
	v_mov_b32_e32 v24, v169
	v_mov_b32_e32 v25, v169
	v_mov_b32_e32 v26, v169
	v_mov_b32_e32 v27, v169
	v_mov_b32_e32 v28, v169
	v_mov_b32_e32 v29, v169
	v_mov_b32_e32 v30, v169
	v_mov_b32_e32 v31, v169
	v_mov_b32_e32 v32, 0
	v_mov_b32_e32 v33, v169
	v_mov_b32_e32 v34, v169
	v_mov_b32_e32 v35, v169
	v_mov_b32_e32 v36, v169
	v_mov_b32_e32 v37, v169
	v_mov_b32_e32 v38, v169
	v_mov_b32_e32 v39, v169
	v_mov_b32_e32 v40, v169
	v_mov_b32_e32 v41, v169
	v_mov_b32_e32 v42, v169
	v_mov_b32_e32 v43, v169
	v_mov_b32_e32 v44, v169
	v_mov_b32_e32 v45, v169
	v_mov_b32_e32 v46, v169
	v_mov_b32_e32 v47, v169
	v_mov_b32_e32 v48, 0
	v_mov_b32_e32 v49, v169
	v_mov_b32_e32 v50, v169
	v_mov_b32_e32 v51, v169
	v_mov_b32_e32 v52, v169
	v_mov_b32_e32 v53, v169
	v_mov_b32_e32 v54, v169
	v_mov_b32_e32 v55, v169
	v_mov_b32_e32 v56, v169
	v_mov_b32_e32 v57, v169
	v_mov_b32_e32 v58, v169
	v_mov_b32_e32 v59, v169
	v_mov_b32_e32 v60, v169
	v_mov_b32_e32 v61, v169
	v_mov_b32_e32 v62, v169
	v_mov_b32_e32 v63, v169
	v_mov_b32_e32 v64, 0
	v_mov_b32_e32 v65, v169
	v_mov_b32_e32 v66, v169
	v_mov_b32_e32 v67, v169
	v_mov_b32_e32 v68, v169
	v_mov_b32_e32 v69, v169
	v_mov_b32_e32 v70, v169
	v_mov_b32_e32 v71, v169
	v_mov_b32_e32 v72, v169
	v_mov_b32_e32 v73, v169
	v_mov_b32_e32 v74, v169
	v_mov_b32_e32 v75, v169
	v_mov_b32_e32 v76, v169
	v_mov_b32_e32 v77, v169
	v_mov_b32_e32 v78, v169
	v_mov_b32_e32 v79, v169
	v_mov_b32_e32 v80, 0
	v_mov_b32_e32 v81, v169
	v_mov_b32_e32 v82, v169
	v_mov_b32_e32 v83, v169
	v_mov_b32_e32 v84, v169
	v_mov_b32_e32 v85, v169
	v_mov_b32_e32 v86, v169
	v_mov_b32_e32 v87, v169
	v_mov_b32_e32 v88, v169
	v_mov_b32_e32 v89, v169
	v_mov_b32_e32 v90, v169
	v_mov_b32_e32 v91, v169
	v_mov_b32_e32 v92, v169
	v_mov_b32_e32 v93, v169
	v_mov_b32_e32 v94, v169
	v_mov_b32_e32 v95, v169
	v_mov_b32_e32 v96, 0
	v_mov_b32_e32 v97, v169
	v_mov_b32_e32 v98, v169
	v_mov_b32_e32 v99, v169
	v_mov_b32_e32 v100, v169
	v_mov_b32_e32 v101, v169
	v_mov_b32_e32 v102, v169
	v_mov_b32_e32 v103, v169
	v_mov_b32_e32 v104, v169
	v_mov_b32_e32 v105, v169
	v_mov_b32_e32 v106, v169
	v_mov_b32_e32 v107, v169
	v_mov_b32_e32 v108, v169
	v_mov_b32_e32 v109, v169
	v_mov_b32_e32 v110, v169
	v_mov_b32_e32 v111, v169
	v_mov_b32_e32 v112, 0
	v_mov_b32_e32 v113, v169
	v_mov_b32_e32 v114, v169
	v_mov_b32_e32 v115, v169
	v_mov_b32_e32 v116, v169
	v_mov_b32_e32 v117, v169
	v_mov_b32_e32 v118, v169
	v_mov_b32_e32 v119, v169
	v_mov_b32_e32 v120, v169
	v_mov_b32_e32 v121, v169
	v_mov_b32_e32 v122, v169
	v_mov_b32_e32 v123, v169
	v_mov_b32_e32 v124, v169
	v_mov_b32_e32 v125, v169
	v_mov_b32_e32 v126, v169
	v_mov_b32_e32 v127, v169
	v_mbcnt_hi_u32_b32 v128, -1, v210
	s_and_b32 s90, s70, 0x40
	v_and_b32_e32 v159, 48, v128
	v_or_b32_e32 v159, s90, v159
	v_and_b32_e32 v129, 31, v128
	v_lshrrev_b32_e32 v130, 5, v128
	v_bfe_u32 v131, v128, 1, 3
	v_lshlrev_b32_e32 v132, 7, v129
	s_lshr_b32 s91, s70, 7
	s_lshl_b32 s91, s91, 13
	s_lshl_b32 s90, s90, 8
	s_add_u32 s90, s90, 0x8000
	s_lshl_b32 s88, s70, 4
	s_mov_b32 s89, 0x10000
	s_lshl_b32 s92, s22, 4
	s_and_b32 s92, s92, 0x780
	s_mov_b32 s93, 0
	v_xor_b32_e32 v133, v130, v131
	v_lshl_add_u32 v133, v133, 4, v132
	v_add_u32_e32 v230, s91, v133
	v_add_u32_e32 v234, s90, v133
	v_or_b32_e32 v133, 2, v130
	v_xor_b32_e32 v133, v133, v131
	v_lshl_add_u32 v133, v133, 4, v132
	v_add_u32_e32 v231, s91, v133
	v_add_u32_e32 v235, s90, v133
	v_or_b32_e32 v133, 4, v130
	v_xor_b32_e32 v133, v133, v131
	v_lshl_add_u32 v133, v133, 4, v132
	v_add_u32_e32 v232, s91, v133
	v_add_u32_e32 v236, s90, v133
	v_or_b32_e32 v133, 6, v130
	v_xor_b32_e32 v133, v133, v131
	v_lshl_add_u32 v133, v133, 4, v132
	v_add_u32_e32 v233, s91, v133
	v_add_u32_e32 v237, s90, v133
	s_waitcnt vmcnt(0)
	s_barrier
	ds_read_b128 v[188:191], v230
	ds_read_b128 v[196:199], v234
	ds_read_b128 v[192:195], v230 offset:4096
	ds_read_b128 v[200:203], v234 offset:4096
	ds_read_b128 v[204:207], v234 offset:8192
	ds_read_b128 v[226:229], v234 offset:12288
	s_add_u32 s94, s2, s92
	s_add_u32 s94, s94, 0x80
	s_and_b32 s94, s94, 0x780
	s_sub_u32 s94, s94, 0x80
	s_subb_u32 s95, 0, 0
	s_add_u32 s90, s88, s89
	s_add_u32 m0, s90, 0
	v_lshl_add_u64 v[152:153], v[160:161], 0, s[94:95]
	v_xor_b32_e32 v152, v159, v152
	global_load_lds_dwordx4 v[152:153], off
	s_add_u32 m0, s90, 32768
	v_lshl_add_u64 v[154:155], v[180:181], 0, s[94:95]
	v_xor_b32_e32 v154, v159, v154
	global_load_lds_dwordx4 v[154:155], off
	s_add_u32 m0, s90, 8192
	v_lshl_add_u64 v[156:157], v[162:163], 0, s[94:95]
	v_xor_b32_e32 v156, v159, v156
	global_load_lds_dwordx4 v[156:157], off
	s_add_u32 m0, s90, 40960
	v_lshl_add_u64 v[152:153], v[182:183], 0, s[94:95]
	v_xor_b32_e32 v152, v159, v152
	global_load_lds_dwordx4 v[152:153], off
	s_add_u32 m0, s90, 16384
	v_lshl_add_u64 v[154:155], v[164:165], 0, s[94:95]
	v_xor_b32_e32 v154, v159, v154
	global_load_lds_dwordx4 v[154:155], off
	s_add_u32 m0, s90, 49152
	v_lshl_add_u64 v[156:157], v[184:185], 0, s[94:95]
	v_xor_b32_e32 v156, v159, v156
	global_load_lds_dwordx4 v[156:157], off
	s_add_u32 m0, s90, 24576
	v_lshl_add_u64 v[152:153], v[166:167], 0, s[94:95]
	v_xor_b32_e32 v152, v159, v152
	global_load_lds_dwordx4 v[152:153], off
	s_add_u32 m0, s90, 57344
	v_lshl_add_u64 v[154:155], v[186:187], 0, s[94:95]
	v_xor_b32_e32 v154, v159, v154
	global_load_lds_dwordx4 v[154:155], off
	s_xor_b32 s89, s89, 0x10000
.Lgk1_loop:
	ds_read_b128 v[128:131], v231
	ds_read_b128 v[136:139], v235
	ds_read_b128 v[132:135], v231 offset:4096
	ds_read_b128 v[140:143], v235 offset:4096
	ds_read_b128 v[144:147], v235 offset:8192
	ds_read_b128 v[148:151], v235 offset:12288
	s_waitcnt lgkmcnt(6)
	v_mfma_f32_32x32x16_bf16 v[112:127], v[188:191], v[196:199], v[112:127]
	v_mfma_f32_32x32x16_bf16 v[48:63], v[192:195], v[196:199], v[48:63]
	v_mfma_f32_32x32x16_bf16 v[96:111], v[188:191], v[200:203], v[96:111]
	v_mfma_f32_32x32x16_bf16 v[32:47], v[192:195], v[200:203], v[32:47]
	v_mfma_f32_32x32x16_bf16 v[80:95], v[188:191], v[204:207], v[80:95]
	v_mfma_f32_32x32x16_bf16 v[16:31], v[192:195], v[204:207], v[16:31]
	v_mfma_f32_32x32x16_bf16 v[64:79], v[188:191], v[226:229], v[64:79]
	v_mfma_f32_32x32x16_bf16 v[0:15], v[192:195], v[226:229], v[0:15]
	ds_read_b128 v[188:191], v232
	ds_read_b128 v[196:199], v236
	ds_read_b128 v[192:195], v232 offset:4096
	ds_read_b128 v[200:203], v236 offset:4096
	ds_read_b128 v[204:207], v236 offset:8192
	ds_read_b128 v[226:229], v236 offset:12288
	s_waitcnt lgkmcnt(6)
	v_mfma_f32_32x32x16_bf16 v[112:127], v[128:131], v[136:139], v[112:127]
	v_mfma_f32_32x32x16_bf16 v[48:63], v[132:135], v[136:139], v[48:63]
	v_mfma_f32_32x32x16_bf16 v[96:111], v[128:131], v[140:143], v[96:111]
	v_mfma_f32_32x32x16_bf16 v[32:47], v[132:135], v[140:143], v[32:47]
	v_mfma_f32_32x32x16_bf16 v[80:95], v[128:131], v[144:147], v[80:95]
	v_mfma_f32_32x32x16_bf16 v[16:31], v[132:135], v[144:147], v[16:31]
	v_mfma_f32_32x32x16_bf16 v[64:79], v[128:131], v[148:151], v[64:79]
	v_mfma_f32_32x32x16_bf16 v[0:15], v[132:135], v[148:151], v[0:15]
	ds_read_b128 v[128:131], v233
	ds_read_b128 v[136:139], v237
	ds_read_b128 v[132:135], v233 offset:4096
	ds_read_b128 v[140:143], v237 offset:4096
	ds_read_b128 v[144:147], v237 offset:8192
	ds_read_b128 v[148:151], v237 offset:12288
	s_waitcnt lgkmcnt(6)
	v_mfma_f32_32x32x16_bf16 v[112:127], v[188:191], v[196:199], v[112:127]
	v_mfma_f32_32x32x16_bf16 v[48:63], v[192:195], v[196:199], v[48:63]
	v_mfma_f32_32x32x16_bf16 v[96:111], v[188:191], v[200:203], v[96:111]
	v_mfma_f32_32x32x16_bf16 v[32:47], v[192:195], v[200:203], v[32:47]
	v_mfma_f32_32x32x16_bf16 v[80:95], v[188:191], v[204:207], v[80:95]
	v_mfma_f32_32x32x16_bf16 v[16:31], v[192:195], v[204:207], v[16:31]
	v_mfma_f32_32x32x16_bf16 v[64:79], v[188:191], v[226:229], v[64:79]
	v_mfma_f32_32x32x16_bf16 v[0:15], v[192:195], v[226:229], v[0:15]
	s_waitcnt vmcnt(0) lgkmcnt(0)
	s_barrier
	v_xor_b32_e32 v230, 0x10000, v230
	v_xor_b32_e32 v234, 0x10000, v234
	ds_read_b128 v[188:191], v230
	ds_read_b128 v[196:199], v234
	ds_read_b128 v[192:195], v230 offset:4096
	ds_read_b128 v[200:203], v234 offset:4096
	ds_read_b128 v[204:207], v234 offset:8192
	ds_read_b128 v[226:229], v234 offset:12288
	s_cmpk_eq_i32 s2, 0x700
	s_cbranch_scc1 .Lgk1_nodma
	s_add_u32 s94, s2, s92
	s_add_u32 s94, s94, 0x100
	s_and_b32 s94, s94, 0x780
	s_sub_u32 s94, s94, 0x80
	s_subb_u32 s95, 0, 0
	s_add_u32 s90, s88, s89
	v_mfma_f32_32x32x16_bf16 v[112:127], v[128:131], v[136:139], v[112:127]
	v_xor_b32_e32 v231, 0x10000, v231
	v_xor_b32_e32 v235, 0x10000, v235
	s_add_u32 m0, s90, 0
	v_lshl_add_u64 v[152:153], v[160:161], 0, s[94:95]
	v_xor_b32_e32 v152, v159, v152
	global_load_lds_dwordx4 v[152:153], off
	v_mfma_f32_32x32x16_bf16 v[48:63], v[132:135], v[136:139], v[48:63]
	v_xor_b32_e32 v232, 0x10000, v232
	v_xor_b32_e32 v236, 0x10000, v236
	s_add_u32 m0, s90, 32768
	v_lshl_add_u64 v[154:155], v[180:181], 0, s[94:95]
	v_xor_b32_e32 v154, v159, v154
	global_load_lds_dwordx4 v[154:155], off
	v_mfma_f32_32x32x16_bf16 v[96:111], v[128:131], v[140:143], v[96:111]
	v_xor_b32_e32 v233, 0x10000, v233
	v_xor_b32_e32 v237, 0x10000, v237
	s_add_u32 m0, s90, 8192
	v_lshl_add_u64 v[156:157], v[162:163], 0, s[94:95]
	v_xor_b32_e32 v156, v159, v156
	global_load_lds_dwordx4 v[156:157], off
	v_mfma_f32_32x32x16_bf16 v[32:47], v[132:135], v[140:143], v[32:47]
	s_add_u32 m0, s90, 40960
	v_lshl_add_u64 v[152:153], v[182:183], 0, s[94:95]
	v_xor_b32_e32 v152, v159, v152
	global_load_lds_dwordx4 v[152:153], off
	v_mfma_f32_32x32x16_bf16 v[80:95], v[128:131], v[144:147], v[80:95]
	s_add_u32 m0, s90, 16384
	v_lshl_add_u64 v[154:155], v[164:165], 0, s[94:95]
	v_xor_b32_e32 v154, v159, v154
	global_load_lds_dwordx4 v[154:155], off
	v_mfma_f32_32x32x16_bf16 v[16:31], v[132:135], v[144:147], v[16:31]
	s_add_u32 m0, s90, 49152
	v_lshl_add_u64 v[156:157], v[184:185], 0, s[94:95]
	v_xor_b32_e32 v156, v159, v156
	global_load_lds_dwordx4 v[156:157], off
	v_mfma_f32_32x32x16_bf16 v[64:79], v[128:131], v[148:151], v[64:79]
	s_add_u32 m0, s90, 24576
	v_lshl_add_u64 v[152:153], v[166:167], 0, s[94:95]
	v_xor_b32_e32 v152, v159, v152
	global_load_lds_dwordx4 v[152:153], off
	v_mfma_f32_32x32x16_bf16 v[0:15], v[132:135], v[148:151], v[0:15]
	s_add_u32 m0, s90, 57344
	v_lshl_add_u64 v[154:155], v[186:187], 0, s[94:95]
	v_xor_b32_e32 v154, v159, v154
	global_load_lds_dwordx4 v[154:155], off
	s_branch .Lgk1_join
.Lgk1_nodma:
	v_mfma_f32_32x32x16_bf16 v[112:127], v[128:131], v[136:139], v[112:127]
	v_xor_b32_e32 v231, 0x10000, v231
	v_xor_b32_e32 v235, 0x10000, v235
	v_mfma_f32_32x32x16_bf16 v[48:63], v[132:135], v[136:139], v[48:63]
	v_xor_b32_e32 v232, 0x10000, v232
	v_xor_b32_e32 v236, 0x10000, v236
	v_mfma_f32_32x32x16_bf16 v[96:111], v[128:131], v[140:143], v[96:111]
	v_xor_b32_e32 v233, 0x10000, v233
	v_xor_b32_e32 v237, 0x10000, v237
	v_mfma_f32_32x32x16_bf16 v[32:47], v[132:135], v[140:143], v[32:47]
	v_mfma_f32_32x32x16_bf16 v[80:95], v[128:131], v[144:147], v[80:95]
	v_mfma_f32_32x32x16_bf16 v[16:31], v[132:135], v[144:147], v[16:31]
	v_mfma_f32_32x32x16_bf16 v[64:79], v[128:131], v[148:151], v[64:79]
	v_mfma_f32_32x32x16_bf16 v[0:15], v[132:135], v[148:151], v[0:15]
.Lgk1_join:
	s_xor_b32 s89, s89, 0x10000
	s_add_i32 s7, s7, 1
	s_add_u32 s2, s2, 0x80
	s_addc_u32 s3, s3, 0
	s_cmpk_eq_i32 s2, 0x780
	s_cbranch_scc0 .Lgk1_loop
	s_add_i32 s54, s5, s42
	s_cmpk_gt_i32 s54, 0x1ff
	s_cselect_b64 s[20:21], -1, 0
	s_and_b64 vcc, exec, s[20:21]
	s_cbranch_vccnz .LBB0_1279
	s_ashr_i32 s2, s54, 31
	s_lshr_b32 s2, s2, 30
	s_add_i32 s2, s54, s2
	s_ashr_i32 s2, s2, 2
	s_lshl_b32 s3, s2, 8
	v_add_u32_e32 v129, s3, v213
	s_lshl_b32 s2, s2, 10
	s_lshl_b32 s7, s54, 8
	v_min_i32_e32 v132, 0x7fff, v129
	v_add_u32_e32 v129, s3, v171
	s_sub_i32 s2, s7, s2
	v_add_u32_e32 v128, s3, v212
	v_min_i32_e32 v136, 0x7fff, v129
	v_add_u32_e32 v129, s3, v215
	v_min_i32_e32 v128, 0x7fff, v128
	v_add_u32_e32 v130, s2, v212
	v_add_u32_e32 v134, s2, v213
	v_add_u32_e32 v138, s2, v171
	v_min_i32_e32 v140, 0x7fff, v129
	v_add_u32_e32 v142, s2, v215
	v_ashrrev_i32_e32 v143, 31, v142
	v_ashrrev_i32_e32 v141, 31, v140
	v_ashrrev_i32_e32 v139, 31, v138
	v_ashrrev_i32_e32 v137, 31, v136
	v_ashrrev_i32_e32 v135, 31, v134
	v_ashrrev_i32_e32 v133, 31, v132
	v_ashrrev_i32_e32 v131, 31, v130
	v_ashrrev_i32_e32 v129, 31, v128
	v_lshlrev_b64 v[142:143], 11, v[142:143]
	v_lshlrev_b64 v[140:141], 11, v[140:141]
	v_lshlrev_b64 v[138:139], 11, v[138:139]
	v_lshlrev_b64 v[136:137], 11, v[136:137]
	v_lshlrev_b64 v[134:135], 11, v[134:135]
	v_lshlrev_b64 v[132:133], 11, v[132:133]
	v_lshlrev_b64 v[130:131], 11, v[130:131]
	v_lshlrev_b64 v[128:129], 11, v[128:129]
	v_lshl_add_u64 v[156:157], v[172:173], 0, v[142:143]
	v_lshl_add_u64 v[152:153], v[174:175], 0, v[140:141]
	v_lshl_add_u64 v[148:149], v[172:173], 0, v[138:139]
	v_lshl_add_u64 v[144:145], v[174:175], 0, v[136:137]
	v_lshl_add_u64 v[140:141], v[172:173], 0, v[134:135]
	v_lshl_add_u64 v[136:137], v[174:175], 0, v[132:133]
	v_lshl_add_u64 v[132:133], v[172:173], 0, v[130:131]
	v_lshl_add_u64 v[128:129], v[174:175], 0, v[128:129]
	s_add_u32 m0, s88, 0
	v_lshl_add_u64 v[128:129], v[128:129], 0, s[92:93]
	v_xor_b32_e32 v128, v159, v128
	global_load_lds_dwordx4 v[128:129], off
	s_add_u32 m0, s88, 32768
	v_lshl_add_u64 v[132:133], v[132:133], 0, s[92:93]
	v_xor_b32_e32 v132, v159, v132
	global_load_lds_dwordx4 v[132:133], off
	s_add_u32 m0, s88, 8192
	v_lshl_add_u64 v[136:137], v[136:137], 0, s[92:93]
	v_xor_b32_e32 v136, v159, v136
	global_load_lds_dwordx4 v[136:137], off
	s_add_u32 m0, s88, 40960
	v_lshl_add_u64 v[140:141], v[140:141], 0, s[92:93]
	v_xor_b32_e32 v140, v159, v140
	global_load_lds_dwordx4 v[140:141], off
	s_add_u32 m0, s88, 16384
	v_lshl_add_u64 v[144:145], v[144:145], 0, s[92:93]
	v_xor_b32_e32 v144, v159, v144
	global_load_lds_dwordx4 v[144:145], off
	s_add_u32 m0, s88, 49152
	v_lshl_add_u64 v[148:149], v[148:149], 0, s[92:93]
	v_xor_b32_e32 v148, v159, v148
	global_load_lds_dwordx4 v[148:149], off
	s_add_u32 m0, s88, 24576
	v_lshl_add_u64 v[152:153], v[152:153], 0, s[92:93]
	v_xor_b32_e32 v152, v159, v152
	global_load_lds_dwordx4 v[152:153], off
	s_add_u32 m0, s88, 57344
	v_lshl_add_u64 v[156:157], v[156:157], 0, s[92:93]
	v_xor_b32_e32 v156, v159, v156
	global_load_lds_dwordx4 v[156:157], off
.LBB0_1279:
	ds_read_b128 v[128:131], v231
	ds_read_b128 v[136:139], v235
	ds_read_b128 v[132:135], v231 offset:4096
	ds_read_b128 v[140:143], v235 offset:4096
	ds_read_b128 v[144:147], v235 offset:8192
	ds_read_b128 v[148:151], v235 offset:12288
	s_waitcnt lgkmcnt(6)
	v_mfma_f32_32x32x16_bf16 v[112:127], v[188:191], v[196:199], v[112:127]
	v_mfma_f32_32x32x16_bf16 v[48:63], v[192:195], v[196:199], v[48:63]
	v_mfma_f32_32x32x16_bf16 v[96:111], v[188:191], v[200:203], v[96:111]
	v_mfma_f32_32x32x16_bf16 v[32:47], v[192:195], v[200:203], v[32:47]
	v_mfma_f32_32x32x16_bf16 v[80:95], v[188:191], v[204:207], v[80:95]
	v_mfma_f32_32x32x16_bf16 v[16:31], v[192:195], v[204:207], v[16:31]
	v_mfma_f32_32x32x16_bf16 v[64:79], v[188:191], v[226:229], v[64:79]
	v_mfma_f32_32x32x16_bf16 v[0:15], v[192:195], v[226:229], v[0:15]
	ds_read_b128 v[188:191], v232
	ds_read_b128 v[196:199], v236
	ds_read_b128 v[192:195], v232 offset:4096
	ds_read_b128 v[200:203], v236 offset:4096
	ds_read_b128 v[204:207], v236 offset:8192
	ds_read_b128 v[226:229], v236 offset:12288
	s_waitcnt lgkmcnt(6)
	v_mfma_f32_32x32x16_bf16 v[112:127], v[128:131], v[136:139], v[112:127]
	v_mfma_f32_32x32x16_bf16 v[48:63], v[132:135], v[136:139], v[48:63]
	v_mfma_f32_32x32x16_bf16 v[96:111], v[128:131], v[140:143], v[96:111]
	v_mfma_f32_32x32x16_bf16 v[32:47], v[132:135], v[140:143], v[32:47]
	v_mfma_f32_32x32x16_bf16 v[80:95], v[128:131], v[144:147], v[80:95]
	v_mfma_f32_32x32x16_bf16 v[16:31], v[132:135], v[144:147], v[16:31]
	v_mfma_f32_32x32x16_bf16 v[64:79], v[128:131], v[148:151], v[64:79]
	v_mfma_f32_32x32x16_bf16 v[0:15], v[132:135], v[148:151], v[0:15]
	ds_read_b128 v[128:131], v233
	ds_read_b128 v[136:139], v237
	ds_read_b128 v[132:135], v233 offset:4096
	ds_read_b128 v[140:143], v237 offset:4096
	ds_read_b128 v[144:147], v237 offset:8192
	ds_read_b128 v[148:151], v237 offset:12288
	s_waitcnt lgkmcnt(6)
	v_mfma_f32_32x32x16_bf16 v[112:127], v[188:191], v[196:199], v[112:127]
	v_mfma_f32_32x32x16_bf16 v[48:63], v[192:195], v[196:199], v[48:63]
	v_mfma_f32_32x32x16_bf16 v[96:111], v[188:191], v[200:203], v[96:111]
	v_mfma_f32_32x32x16_bf16 v[32:47], v[192:195], v[200:203], v[32:47]
	v_mfma_f32_32x32x16_bf16 v[80:95], v[188:191], v[204:207], v[80:95]
	v_mfma_f32_32x32x16_bf16 v[16:31], v[192:195], v[204:207], v[16:31]
	v_mfma_f32_32x32x16_bf16 v[64:79], v[188:191], v[226:229], v[64:79]
	v_mfma_f32_32x32x16_bf16 v[0:15], v[192:195], v[226:229], v[0:15]
	s_waitcnt lgkmcnt(0)
	s_barrier
	v_xor_b32_e32 v230, 0x10000, v230
	v_xor_b32_e32 v234, 0x10000, v234
	v_mfma_f32_32x32x16_bf16 v[112:127], v[128:131], v[136:139], v[112:127]
	v_xor_b32_e32 v231, 0x10000, v231
	v_xor_b32_e32 v235, 0x10000, v235
	v_mfma_f32_32x32x16_bf16 v[48:63], v[132:135], v[136:139], v[48:63]
	v_xor_b32_e32 v232, 0x10000, v232
	v_xor_b32_e32 v236, 0x10000, v236
	v_mfma_f32_32x32x16_bf16 v[96:111], v[128:131], v[140:143], v[96:111]
	v_xor_b32_e32 v233, 0x10000, v233
	v_xor_b32_e32 v237, 0x10000, v237
	v_mfma_f32_32x32x16_bf16 v[32:47], v[132:135], v[140:143], v[32:47]
	v_mfma_f32_32x32x16_bf16 v[80:95], v[128:131], v[144:147], v[80:95]
	v_mfma_f32_32x32x16_bf16 v[16:31], v[132:135], v[144:147], v[16:31]
	v_mfma_f32_32x32x16_bf16 v[64:79], v[128:131], v[148:151], v[64:79]
	v_mfma_f32_32x32x16_bf16 v[0:15], v[132:135], v[148:151], v[0:15]
	s_lshl_b32 s2, s5, 8
	s_sub_i32 s2, s2, s6
	v_mov_b32_e32 v168, v214
	s_add_i32 s55, s4, s30
	s_or_b32 s26, s2, s31
	s_ashr_i32 s27, s26, 31
	s_load_dwordx2 s[24:25], s[0:1], 0x140
	v_ashrrev_i32_e32 v180, 3, v168
	v_and_b32_e32 v183, -4, v180
	v_add_u32_e32 v225, s55, v183
	v_add_u32_e32 v190, 8, v225
	v_min_i32_e32 v190, 0x7fff, v190
	v_ashrrev_i32_e32 v190, 12, v190
	v_min_i32_e32 v184, 0x7fff, v225
	v_and_b32_e32 v182, 31, v168
	v_ashrrev_i32_e32 v184, 12, v184
	v_or_b32_e32 v180, s26, v182
	v_mul_hi_i32_i24_e32 v185, 0x3000, v184
	v_mul_i32_i24_e32 v184, 0x3000, v184
	v_ashrrev_i32_e32 v181, 31, v180
	s_waitcnt lgkmcnt(0)
	v_lshl_add_u64 v[184:185], s[24:25], 0, v[184:185]
	v_add_u32_e32 v188, 9, v225
	v_mul_hi_i32_i24_e32 v187, 0x3000, v190
	v_mul_i32_i24_e32 v186, 0x3000, v190
	v_min_i32_e32 v188, 0x7fff, v188
	v_add_u32_e32 v190, 10, v225
	v_ashrrev_i32_e32 v188, 12, v188
	v_min_i32_e32 v190, 0x7fff, v190
	v_mul_hi_i32_i24_e32 v189, 0x3000, v188
	v_mul_i32_i24_e32 v188, 0x3000, v188
	v_ashrrev_i32_e32 v190, 12, v190
	v_lshl_add_u64 v[188:189], s[24:25], 0, v[188:189]
	v_mul_hi_i32_i24_e32 v191, 0x3000, v190
	v_mul_i32_i24_e32 v190, 0x3000, v190
	v_lshl_add_u64 v[184:185], v[184:185], 0, s[18:19]
	v_lshlrev_b64 v[180:181], 2, v[180:181]
	v_lshl_add_u64 v[186:187], s[24:25], 0, v[186:187]
	v_lshl_add_u64 v[188:189], v[188:189], 0, s[18:19]
	v_lshl_add_u64 v[190:191], s[24:25], 0, v[190:191]
	v_lshl_add_u64 v[208:209], v[184:185], 0, v[180:181]
	v_lshl_add_u64 v[186:187], v[186:187], 0, s[18:19]
	v_lshl_add_u64 v[190:191], v[190:191], 0, s[18:19]
	v_lshl_add_u64 v[230:231], v[186:187], 0, v[180:181]
	v_lshl_add_u64 v[196:197], v[188:189], 0, v[180:181]
	v_lshl_add_u64 v[198:199], v[190:191], 0, v[180:181]
	global_load_dword v232, v[208:209], off
	global_load_dword v233, v[208:209], off offset:128
	global_load_dword v238, v[230:231], off
	global_load_dword v239, v[230:231], off offset:128
	global_load_dword v240, v[196:197], off
	global_load_dword v241, v[196:197], off offset:128
	global_load_dword v242, v[198:199], off
	global_load_dword v243, v[198:199], off offset:128
	v_add_u32_e32 v196, 17, v225
	v_min_i32_e32 v196, 0x7fff, v196
	v_add_u32_e32 v198, 18, v225
	v_ashrrev_i32_e32 v196, 12, v196
	v_min_i32_e32 v198, 0x7fff, v198
	v_mul_hi_i32_i24_e32 v197, 0x3000, v196
	v_mul_i32_i24_e32 v196, 0x3000, v196
	v_ashrrev_i32_e32 v198, 12, v198
	v_lshl_add_u64 v[196:197], s[24:25], 0, v[196:197]
	v_mul_hi_i32_i24_e32 v199, 0x3000, v198
	v_mul_i32_i24_e32 v198, 0x3000, v198
	v_add_u32_e32 v192, 11, v225
	v_add_u32_e32 v194, 16, v225
	v_min_i32_e32 v192, 0x7fff, v192
	v_min_i32_e32 v194, 0x7fff, v194
	v_ashrrev_i32_e32 v192, 12, v192
	v_ashrrev_i32_e32 v194, 12, v194
	v_mul_hi_i32_i24_e32 v193, 0x3000, v192
	v_mul_i32_i24_e32 v192, 0x3000, v192
	v_mul_hi_i32_i24_e32 v195, 0x3000, v194
	v_mul_i32_i24_e32 v194, 0x3000, v194
	v_lshl_add_u64 v[192:193], s[24:25], 0, v[192:193]
	v_lshl_add_u64 v[194:195], s[24:25], 0, v[194:195]
	v_lshl_add_u64 v[192:193], v[192:193], 0, s[18:19]
	v_lshl_add_u64 v[194:195], v[194:195], 0, s[18:19]
	v_lshl_add_u64 v[196:197], v[196:197], 0, s[18:19]
	v_lshl_add_u64 v[198:199], s[24:25], 0, v[198:199]
	v_lshl_add_u64 v[208:209], v[192:193], 0, v[180:181]
	v_lshl_add_u64 v[198:199], v[198:199], 0, s[18:19]
	v_lshl_add_u64 v[226:227], v[198:199], 0, v[180:181]
	s_waitcnt vmcnt(7)
	v_mul_f32_e32 v112, v112, v232
	v_lshl_add_u64 v[204:205], v[194:195], 0, v[180:181]
	v_lshl_add_u64 v[206:207], v[196:197], 0, v[180:181]
	s_waitcnt vmcnt(6)
	s_nop 2
	v_mul_f32_e32 v96, v96, v233
	v_mul_f32_e32 v97, v97, v233
	global_load_dword v234, v[208:209], off
	global_load_dword v235, v[208:209], off offset:128
	global_load_dword v236, v[204:205], off
	global_load_dword v237, v[204:205], off offset:128
	global_load_dword v244, v[206:207], off
	global_load_dword v245, v[206:207], off offset:128
	global_load_dword v246, v[226:227], off
	global_load_dword v247, v[226:227], off offset:128
	v_add_u32_e32 v204, 25, v225
	v_add_u32_e32 v206, 26, v225
	v_min_i32_e32 v204, 0x7fff, v204
	v_min_i32_e32 v206, 0x7fff, v206
	v_ashrrev_i32_e32 v204, 12, v204
	v_ashrrev_i32_e32 v206, 12, v206
	v_add_u32_e32 v200, 19, v225
	v_min_i32_e32 v200, 0x7fff, v200
	v_add_u32_e32 v202, 24, v225
	v_ashrrev_i32_e32 v200, 12, v200
	v_min_i32_e32 v202, 0x7fff, v202
	v_mul_hi_i32_i24_e32 v201, 0x3000, v200
	v_mul_i32_i24_e32 v200, 0x3000, v200
	v_ashrrev_i32_e32 v202, 12, v202
	v_mul_hi_i32_i24_e32 v205, 0x3000, v204
	v_mul_i32_i24_e32 v204, 0x3000, v204
	v_mul_hi_i32_i24_e32 v207, 0x3000, v206
	v_mul_i32_i24_e32 v206, 0x3000, v206
	v_lshl_add_u64 v[200:201], s[24:25], 0, v[200:201]
	v_mul_hi_i32_i24_e32 v203, 0x3000, v202
	v_mul_i32_i24_e32 v202, 0x3000, v202
	v_lshl_add_u64 v[204:205], s[24:25], 0, v[204:205]
	v_lshl_add_u64 v[206:207], s[24:25], 0, v[206:207]
	v_lshl_add_u64 v[200:201], v[200:201], 0, s[18:19]
	v_lshl_add_u64 v[202:203], s[24:25], 0, v[202:203]
	v_lshl_add_u64 v[204:205], v[204:205], 0, s[18:19]
	v_lshl_add_u64 v[206:207], v[206:207], 0, s[18:19]
	v_lshl_add_u64 v[208:209], v[200:201], 0, v[180:181]
	v_lshl_add_u64 v[202:203], v[202:203], 0, s[18:19]
	v_lshl_add_u64 v[228:229], v[204:205], 0, v[180:181]
	v_lshl_add_u64 v[230:231], v[206:207], 0, v[180:181]
	v_lshl_add_u64 v[226:227], v[202:203], 0, v[180:181]
	global_load_dword v248, v[208:209], off
	global_load_dword v249, v[208:209], off offset:128
	global_load_dword v250, v[226:227], off
	global_load_dword v251, v[226:227], off offset:128
	global_load_dword v252, v[228:229], off
	s_nop 0
	global_load_dword v228, v[228:229], off offset:128
	s_nop 0
	global_load_dword v229, v[230:231], off
	s_nop 0
	global_load_dword v230, v[230:231], off offset:128
	v_add_u32_e32 v208, 27, v225
	v_min_i32_e32 v208, 0x7fff, v208
	v_ashrrev_i32_e32 v208, 12, v208
	v_mul_hi_i32_i24_e32 v209, 0x3000, v208
	v_mul_i32_i24_e32 v208, 0x3000, v208
	v_lshl_add_u64 v[208:209], s[24:25], 0, v[208:209]
	v_lshl_add_u64 v[208:209], v[208:209], 0, s[18:19]
	v_lshl_add_u64 v[226:227], v[208:209], 0, v[180:181]
	global_load_dword v225, v[226:227], off
	s_nop 0
	global_load_dword v226, v[226:227], off offset:128
	v_mad_u64_u32 v[160:161], s[2:3], v183, s36, v[182:183]
	v_lshl_add_u32 v162, v160, 2, s34
	ds_write2_b32 v162, v112, v96 offset1:32
	v_mul_f32_e32 v96, v113, v232
	ds_write2_b32 v162, v96, v97 offset0:68 offset1:100
	v_mul_f32_e32 v96, v114, v232
	v_mul_f32_e32 v97, v98, v233
	ds_write2_b32 v162, v96, v97 offset0:136 offset1:168
	v_mul_f32_e32 v96, v115, v232
	v_mul_f32_e32 v97, v99, v233
	ds_write2_b32 v162, v96, v97 offset0:204 offset1:236
	s_waitcnt vmcnt(23)
	v_mul_f32_e32 v96, v116, v238
	s_waitcnt vmcnt(22)
	v_mul_f32_e32 v97, v100, v239
	v_add_u32_e32 v115, 0x800, v162
	ds_write2_b32 v115, v96, v97 offset0:32 offset1:64
	s_waitcnt vmcnt(21)
	v_mul_f32_e32 v96, v117, v240
	s_waitcnt vmcnt(20)
	v_mul_f32_e32 v97, v101, v241
	ds_write2_b32 v115, v96, v97 offset0:100 offset1:132
	s_waitcnt vmcnt(19)
	v_mul_f32_e32 v96, v118, v242
	s_waitcnt vmcnt(18)
	v_mul_f32_e32 v97, v102, v243
	ds_write2_b32 v115, v96, v97 offset0:168 offset1:200
	v_add_u32_e32 v116, 0xa00, v162
	v_add_u32_e32 v117, 0x1000, v162
	v_add_u32_e32 v118, 0x1400, v162
	v_ashrrev_i32_e32 v163, 4, v168
	v_and_b32_e32 v160, 15, v168
	v_mul_lo_u32 v161, v163, s37
	s_waitcnt vmcnt(17)
	v_mul_f32_e32 v96, v119, v234
	s_waitcnt vmcnt(16)
	v_mul_f32_e32 v97, v103, v235
	ds_write2_b32 v116, v96, v97 offset0:108 offset1:140
	s_waitcnt vmcnt(15)
	v_mul_f32_e32 v96, v120, v236
	s_waitcnt vmcnt(14)
	v_mul_f32_e32 v97, v104, v237
	ds_write2_b32 v117, v96, v97 offset0:64 offset1:96
	s_waitcnt vmcnt(13)
	v_mul_f32_e32 v96, v121, v244
	s_waitcnt vmcnt(12)
	v_mul_f32_e32 v97, v105, v245
	ds_write2_b32 v117, v96, v97 offset0:132 offset1:164
	s_waitcnt vmcnt(11)
	v_mul_f32_e32 v96, v122, v246
	s_waitcnt vmcnt(10)
	v_mul_f32_e32 v97, v106, v247
	ds_write2_b32 v117, v96, v97 offset0:200 offset1:232
	v_add_u32_e32 v119, 0x1800, v162
	v_add_u32_e32 v120, 0x1a00, v162
	v_lshl_add_u32 v164, v160, 4, s34
	v_lshlrev_b32_e32 v168, 2, v160
	v_add_u32_e32 v160, s55, v163
	v_add_u32_e32 v121, 0x1c00, v162
	v_cmp_gt_i32_e32 vcc, s38, v160
	v_add_u32_e32 v114, v164, v161
	v_ashrrev_i32_e32 v161, 31, v160
	s_waitcnt vmcnt(9)
	v_mul_f32_e32 v96, v123, v248
	s_waitcnt vmcnt(8)
	v_mul_f32_e32 v97, v107, v249
	ds_write2_b32 v118, v96, v97 offset0:12 offset1:44
	s_waitcnt vmcnt(7)
	v_mul_f32_e32 v96, v124, v250
	s_waitcnt vmcnt(6)
	v_mul_f32_e32 v97, v108, v251
	ds_write2_b32 v119, v96, v97 offset0:96 offset1:128
	s_waitcnt vmcnt(5)
	v_mul_f32_e32 v96, v125, v252
	s_waitcnt vmcnt(4)
	v_mul_f32_e32 v97, v109, v228
	ds_write2_b32 v119, v96, v97 offset0:164 offset1:196
	s_waitcnt vmcnt(3)
	v_mul_f32_e32 v96, v126, v229
	s_waitcnt vmcnt(2)
	v_mul_f32_e32 v97, v110, v230
	ds_write2_b32 v120, v96, v97 offset0:104 offset1:136
	s_waitcnt vmcnt(1)
	v_mul_f32_e32 v96, v127, v225
	s_waitcnt vmcnt(0)
	v_mul_f32_e32 v97, v111, v226
	ds_write2_b32 v121, v96, v97 offset0:44 offset1:76
	v_or_b32_e32 v96, s26, v168
	v_mov_b32_e32 v97, s27
	v_add_u32_e32 v128, 0, v160
	v_ashrrev_i32_e32 v129, 31, v128
	v_lshlrev_b64 v[128:129], 10, v[128:129]
	v_lshl_add_u64 v[128:129], v[128:129], 0, v[96:97]
	v_lshlrev_b64 v[128:129], 2, v[128:129]
	v_lshl_add_u64 v[128:129], s[16:17], 0, v[128:129]
	global_load_dwordx4 v[128:131], v[128:129], off
	v_add_u32_e32 v132, 4, v160
	v_ashrrev_i32_e32 v133, 31, v132
	v_lshlrev_b64 v[132:133], 10, v[132:133]
	v_lshl_add_u64 v[132:133], v[132:133], 0, v[96:97]
	v_lshlrev_b64 v[132:133], 2, v[132:133]
	v_lshl_add_u64 v[132:133], s[16:17], 0, v[132:133]
	global_load_dwordx4 v[132:135], v[132:133], off
	v_add_u32_e32 v136, 8, v160
	v_ashrrev_i32_e32 v137, 31, v136
	v_lshlrev_b64 v[136:137], 10, v[136:137]
	v_lshl_add_u64 v[136:137], v[136:137], 0, v[96:97]
	v_lshlrev_b64 v[136:137], 2, v[136:137]
	v_lshl_add_u64 v[136:137], s[16:17], 0, v[136:137]
	global_load_dwordx4 v[136:139], v[136:137], off
	v_add_u32_e32 v140, 12, v160
	v_ashrrev_i32_e32 v141, 31, v140
	v_lshlrev_b64 v[140:141], 10, v[140:141]
	v_lshl_add_u64 v[140:141], v[140:141], 0, v[96:97]
	v_lshlrev_b64 v[140:141], 2, v[140:141]
	v_lshl_add_u64 v[140:141], s[16:17], 0, v[140:141]
	global_load_dwordx4 v[140:143], v[140:141], off
	v_add_u32_e32 v144, 16, v160
	v_ashrrev_i32_e32 v145, 31, v144
	v_lshlrev_b64 v[144:145], 10, v[144:145]
	v_lshl_add_u64 v[144:145], v[144:145], 0, v[96:97]
	v_lshlrev_b64 v[144:145], 2, v[144:145]
	v_lshl_add_u64 v[144:145], s[16:17], 0, v[144:145]
	global_load_dwordx4 v[144:147], v[144:145], off
	v_add_u32_e32 v148, 20, v160
	v_ashrrev_i32_e32 v149, 31, v148
	v_lshlrev_b64 v[148:149], 10, v[148:149]
	v_lshl_add_u64 v[148:149], v[148:149], 0, v[96:97]
	v_lshlrev_b64 v[148:149], 2, v[148:149]
	v_lshl_add_u64 v[148:149], s[16:17], 0, v[148:149]
	global_load_dwordx4 v[148:151], v[148:149], off
	v_add_u32_e32 v152, 24, v160
	v_ashrrev_i32_e32 v153, 31, v152
	v_lshlrev_b64 v[152:153], 10, v[152:153]
	v_lshl_add_u64 v[152:153], v[152:153], 0, v[96:97]
	v_lshlrev_b64 v[152:153], 2, v[152:153]
	v_lshl_add_u64 v[152:153], s[16:17], 0, v[152:153]
	global_load_dwordx4 v[152:155], v[152:153], off
	v_add_u32_e32 v156, 28, v160
	v_ashrrev_i32_e32 v157, 31, v156
	v_lshlrev_b64 v[156:157], 10, v[156:157]
	v_lshl_add_u64 v[156:157], v[156:157], 0, v[96:97]
	v_lshlrev_b64 v[156:157], 2, v[156:157]
	v_lshl_add_u64 v[156:157], s[16:17], 0, v[156:157]
	global_load_dwordx4 v[156:159], v[156:157], off
	s_and_saveexec_b64 s[2:3], vcc
	s_cbranch_execz .LBB0_1281
	v_lshlrev_b64 v[98:99], 10, v[160:161]
	v_lshl_add_u64 v[98:99], v[98:99], 0, v[96:97]
	v_lshlrev_b64 v[106:107], 2, v[98:99]
	v_lshl_add_u64 v[98:99], s[16:17], 0, v[106:107]
	ds_read_b128 v[102:105], v114
	s_load_dwordx2 s[4:5], s[0:1], 0xb8
	s_waitcnt vmcnt(7) lgkmcnt(0)
	v_pk_add_f32 v[100:101], v[104:105], v[130:131]
	v_pk_add_f32 v[98:99], v[102:103], v[128:129]
	v_lshl_add_u64 v[102:103], s[4:5], 0, v[106:107]
	global_store_dwordx4 v[102:103], v[98:101], off
.LBB0_1281:
	s_or_b64 exec, exec, s[2:3]
	s_nop 0
	v_add_u32_e32 v100, 4, v160
	v_cmp_gt_i32_e64 s[2:3], s39, v160
	v_ashrrev_i32_e32 v101, 31, v100
	s_and_saveexec_b64 s[4:5], s[2:3]
	s_cbranch_execz .LBB0_1283
	v_lshlrev_b64 v[98:99], 10, v[100:101]
	v_lshl_add_u64 v[98:99], v[98:99], 0, v[96:97]
	v_lshlrev_b64 v[98:99], 2, v[98:99]
	v_lshl_add_u64 v[102:103], s[16:17], 0, v[98:99]
	ds_read_b128 v[106:109], v114 offset:1088
	s_load_dwordx2 s[6:7], s[0:1], 0xb8
	s_waitcnt lgkmcnt(0)
	v_lshl_add_u64 v[98:99], s[6:7], 0, v[98:99]
	s_waitcnt vmcnt(7)
	v_pk_add_f32 v[104:105], v[108:109], v[134:135]
	v_pk_add_f32 v[102:103], v[106:107], v[132:133]
	global_store_dwordx4 v[98:99], v[102:105], off
.LBB0_1283:
	s_or_b64 exec, exec, s[4:5]
	s_nop 0
	v_add_u32_e32 v102, 8, v160
	v_cmp_gt_i32_e64 s[4:5], s48, v160
	v_ashrrev_i32_e32 v103, 31, v102
	s_and_saveexec_b64 s[6:7], s[4:5]
	s_cbranch_execz .LBB0_1285
	v_lshlrev_b64 v[98:99], 10, v[102:103]
	v_lshl_add_u64 v[98:99], v[98:99], 0, v[96:97]
	v_lshlrev_b64 v[98:99], 2, v[98:99]
	v_lshl_add_u64 v[104:105], s[16:17], 0, v[98:99]
	ds_read_b128 v[108:111], v114 offset:2176
	s_load_dwordx2 s[8:9], s[0:1], 0xb8
	s_waitcnt lgkmcnt(0)
	v_lshl_add_u64 v[98:99], s[8:9], 0, v[98:99]
	s_waitcnt vmcnt(7)
	v_pk_add_f32 v[106:107], v[110:111], v[138:139]
	v_pk_add_f32 v[104:105], v[108:109], v[136:137]
	global_store_dwordx4 v[98:99], v[104:107], off
.LBB0_1285:
	s_or_b64 exec, exec, s[6:7]
	s_nop 0
	v_add_u32_e32 v104, 12, v160
	v_cmp_gt_i32_e64 s[6:7], s49, v160
	v_ashrrev_i32_e32 v105, 31, v104
	s_and_saveexec_b64 s[8:9], s[6:7]
	s_cbranch_execz .LBB0_1287
	v_lshlrev_b64 v[98:99], 10, v[104:105]
	v_lshl_add_u64 v[98:99], v[98:99], 0, v[96:97]
	v_lshlrev_b64 v[98:99], 2, v[98:99]
	v_lshl_add_u64 v[106:107], s[16:17], 0, v[98:99]
	ds_read_b128 v[110:113], v114 offset:3264
	s_load_dwordx2 s[10:11], s[0:1], 0xb8
	s_waitcnt lgkmcnt(0)
	v_lshl_add_u64 v[98:99], s[10:11], 0, v[98:99]
	s_waitcnt vmcnt(7)
	v_pk_add_f32 v[108:109], v[112:113], v[142:143]
	v_pk_add_f32 v[106:107], v[110:111], v[140:141]
	global_store_dwordx4 v[98:99], v[106:109], off
.LBB0_1287:
	s_or_b64 exec, exec, s[8:9]
	s_nop 0
	v_add_u32_e32 v106, 16, v160
	v_cmp_gt_i32_e64 s[8:9], s50, v160
	v_ashrrev_i32_e32 v107, 31, v106
	s_and_saveexec_b64 s[10:11], s[8:9]
	s_cbranch_execz .LBB0_1289
	v_lshlrev_b64 v[98:99], 10, v[106:107]
	v_lshl_add_u64 v[98:99], v[98:99], 0, v[96:97]
	v_lshlrev_b64 v[98:99], 2, v[98:99]
	v_lshl_add_u64 v[108:109], s[16:17], 0, v[98:99]
	ds_read_b128 v[122:125], v114 offset:4352
	s_load_dwordx2 s[12:13], s[0:1], 0xb8
	s_waitcnt lgkmcnt(0)
	v_lshl_add_u64 v[98:99], s[12:13], 0, v[98:99]
	s_waitcnt vmcnt(7)
	v_pk_add_f32 v[110:111], v[124:125], v[146:147]
	v_pk_add_f32 v[108:109], v[122:123], v[144:145]
	global_store_dwordx4 v[98:99], v[108:111], off
.LBB0_1289:
	s_or_b64 exec, exec, s[10:11]
	s_nop 0
	v_add_u32_e32 v108, 20, v160
	v_cmp_gt_i32_e64 s[10:11], s51, v160
	v_ashrrev_i32_e32 v109, 31, v108
	s_and_saveexec_b64 s[12:13], s[10:11]
	s_cbranch_execz .LBB0_1291
	v_lshlrev_b64 v[98:99], 10, v[108:109]
	v_lshl_add_u64 v[98:99], v[98:99], 0, v[96:97]
	v_lshlrev_b64 v[98:99], 2, v[98:99]
	v_lshl_add_u64 v[110:111], s[16:17], 0, v[98:99]
	ds_read_b128 v[122:125], v114 offset:5440
	s_load_dwordx2 s[14:15], s[0:1], 0xb8
	s_waitcnt lgkmcnt(0)
	v_lshl_add_u64 v[98:99], s[14:15], 0, v[98:99]
	s_waitcnt vmcnt(7)
	v_pk_add_f32 v[112:113], v[124:125], v[150:151]
	v_pk_add_f32 v[110:111], v[122:123], v[148:149]
	global_store_dwordx4 v[98:99], v[110:113], off
.LBB0_1291:
	s_or_b64 exec, exec, s[12:13]
	s_nop 0
	v_add_u32_e32 v110, 24, v160
	v_cmp_gt_i32_e64 s[12:13], s52, v160
	v_ashrrev_i32_e32 v111, 31, v110
	s_and_saveexec_b64 s[14:15], s[12:13]
	s_cbranch_execz .LBB0_1293
	v_lshlrev_b64 v[98:99], 10, v[110:111]
	v_lshl_add_u64 v[98:99], v[98:99], 0, v[96:97]
	v_lshlrev_b64 v[98:99], 2, v[98:99]
	v_lshl_add_u64 v[112:113], s[16:17], 0, v[98:99]
	ds_read_b128 v[164:167], v114 offset:6528
	s_load_dwordx2 s[28:29], s[0:1], 0xb8
	s_waitcnt lgkmcnt(0)
	v_lshl_add_u64 v[98:99], s[28:29], 0, v[98:99]
	s_waitcnt vmcnt(7)
	v_pk_add_f32 v[124:125], v[166:167], v[154:155]
	v_pk_add_f32 v[122:123], v[164:165], v[152:153]
	global_store_dwordx4 v[98:99], v[122:125], off
.LBB0_1293:
	s_or_b64 exec, exec, s[14:15]
	v_add_u32_e32 v112, 28, v160
	v_cmp_gt_i32_e64 s[14:15], s53, v160
	v_ashrrev_i32_e32 v113, 31, v112
	s_and_saveexec_b64 s[28:29], s[14:15]
	s_cbranch_execz .LBB0_1295
	v_lshlrev_b64 v[98:99], 10, v[112:113]
	v_lshl_add_u64 v[98:99], v[98:99], 0, v[96:97]
	v_lshlrev_b64 v[98:99], 2, v[98:99]
	v_lshl_add_u64 v[122:123], s[16:17], 0, v[98:99]
	ds_read_b128 v[164:167], v114 offset:7616
	s_load_dwordx2 s[56:57], s[0:1], 0xb8
	s_waitcnt lgkmcnt(0)
	v_lshl_add_u64 v[98:99], s[56:57], 0, v[98:99]
	s_waitcnt vmcnt(7)
	v_pk_add_f32 v[124:125], v[166:167], v[158:159]
	v_pk_add_f32 v[122:123], v[164:165], v[156:157]
	global_store_dwordx4 v[98:99], v[122:125], off
.LBB0_1295:
	s_or_b64 exec, exec, s[28:29]
	v_add3_u32 v98, v182, s26, 64
	v_ashrrev_i32_e32 v99, 31, v98
	v_lshlrev_b64 v[98:99], 2, v[98:99]
	v_lshl_add_u64 v[122:123], v[184:185], 0, v[98:99]
	v_lshl_add_u64 v[124:125], v[186:187], 0, v[98:99]
	v_lshl_add_u64 v[126:127], v[188:189], 0, v[98:99]
	v_lshl_add_u64 v[164:165], v[190:191], 0, v[98:99]
	global_load_dword v166, v[122:123], off
	global_load_dword v167, v[122:123], off offset:128
	global_load_dword v182, v[124:125], off
	global_load_dword v184, v[124:125], off offset:128
	global_load_dword v185, v[126:127], off
	global_load_dword v186, v[126:127], off offset:128
	global_load_dword v187, v[164:165], off
	global_load_dword v188, v[164:165], off offset:128
	v_lshl_add_u64 v[122:123], v[192:193], 0, v[98:99]
	v_lshl_add_u64 v[124:125], v[194:195], 0, v[98:99]
	v_lshl_add_u64 v[126:127], v[196:197], 0, v[98:99]
	v_lshl_add_u64 v[164:165], v[198:199], 0, v[98:99]
	global_load_dword v189, v[122:123], off
	global_load_dword v190, v[122:123], off offset:128
	global_load_dword v191, v[124:125], off
	global_load_dword v192, v[124:125], off offset:128
	global_load_dword v193, v[126:127], off
	global_load_dword v194, v[126:127], off offset:128
	global_load_dword v195, v[164:165], off
	global_load_dword v196, v[164:165], off offset:128
	v_lshl_add_u64 v[122:123], v[200:201], 0, v[98:99]
	v_lshl_add_u64 v[124:125], v[202:203], 0, v[98:99]
	v_lshl_add_u64 v[126:127], v[204:205], 0, v[98:99]
	v_lshl_add_u64 v[164:165], v[206:207], 0, v[98:99]
	global_load_dword v197, v[122:123], off
	global_load_dword v198, v[122:123], off offset:128
	global_load_dword v199, v[124:125], off
	s_nop 0
	global_load_dword v124, v[124:125], off offset:128
	s_nop 0
	global_load_dword v125, v[126:127], off
	s_nop 0
	global_load_dword v126, v[126:127], off offset:128
	s_nop 0
	global_load_dword v127, v[164:165], off
	s_nop 0
	global_load_dword v164, v[164:165], off offset:128
	v_lshl_add_u64 v[122:123], v[208:209], 0, v[98:99]
	global_load_dword v165, v[122:123], off
	s_nop 0
	global_load_dword v122, v[122:123], off offset:128
	s_waitcnt vmcnt(25)
	v_mul_f32_e32 v80, v80, v166
	s_waitcnt vmcnt(24)
	v_mul_f32_e32 v64, v64, v167
	v_mul_f32_e32 v65, v65, v167
	v_mul_f32_e32 v81, v81, v166
	v_mul_f32_e32 v82, v82, v166
	v_mul_f32_e32 v66, v66, v167
	v_mul_f32_e32 v83, v83, v166
	v_mul_f32_e32 v67, v67, v167
	s_waitcnt vmcnt(23)
	v_mul_f32_e32 v84, v84, v182
	s_waitcnt vmcnt(22)
	v_mul_f32_e32 v68, v68, v184
	s_waitcnt vmcnt(21)
	v_mul_f32_e32 v85, v85, v185
	s_waitcnt vmcnt(20)
	v_mul_f32_e32 v69, v69, v186
	s_waitcnt vmcnt(19)
	v_mul_f32_e32 v86, v86, v187
	s_waitcnt vmcnt(18)
	v_mul_f32_e32 v70, v70, v188
	s_waitcnt vmcnt(17)
	v_mul_f32_e32 v87, v87, v189
	s_waitcnt vmcnt(16)
	v_mul_f32_e32 v71, v71, v190
	s_waitcnt vmcnt(15)
	v_mul_f32_e32 v88, v88, v191
	s_waitcnt vmcnt(14)
	v_mul_f32_e32 v72, v72, v192
	s_waitcnt vmcnt(13)
	v_mul_f32_e32 v89, v89, v193
	s_waitcnt vmcnt(12)
	v_mul_f32_e32 v73, v73, v194
	s_waitcnt vmcnt(11)
	v_mul_f32_e32 v90, v90, v195
	s_waitcnt vmcnt(10)
	v_mul_f32_e32 v74, v74, v196
	s_waitcnt vmcnt(9)
	v_mul_f32_e32 v91, v91, v197
	s_waitcnt vmcnt(8)
	v_mul_f32_e32 v75, v75, v198
	s_waitcnt vmcnt(7)
	v_mul_f32_e32 v92, v92, v199
	s_waitcnt vmcnt(6)
	v_mul_f32_e32 v76, v76, v124
	s_waitcnt vmcnt(5)
	v_mul_f32_e32 v93, v93, v125
	s_waitcnt vmcnt(4)
	v_mul_f32_e32 v77, v77, v126
	s_waitcnt vmcnt(3)
	v_mul_f32_e32 v94, v94, v127
	s_waitcnt vmcnt(2)
	v_mul_f32_e32 v78, v78, v164
	ds_write2_b32 v162, v80, v64 offset1:32
	ds_write2_b32 v162, v81, v65 offset0:68 offset1:100
	ds_write2_b32 v162, v82, v66 offset0:136 offset1:168
	ds_write2_b32 v162, v83, v67 offset0:204 offset1:236
	ds_write2_b32 v115, v84, v68 offset0:32 offset1:64
	ds_write2_b32 v115, v85, v69 offset0:100 offset1:132
	ds_write2_b32 v115, v86, v70 offset0:168 offset1:200
	ds_write2_b32 v116, v87, v71 offset0:108 offset1:140
	ds_write2_b32 v117, v88, v72 offset0:64 offset1:96
	ds_write2_b32 v117, v89, v73 offset0:132 offset1:164
	ds_write2_b32 v117, v90, v74 offset0:200 offset1:232
	ds_write2_b32 v118, v91, v75 offset0:12 offset1:44
	ds_write2_b32 v119, v92, v76 offset0:96 offset1:128
	ds_write2_b32 v119, v93, v77 offset0:164 offset1:196
	ds_write2_b32 v120, v94, v78 offset0:104 offset1:136
	s_waitcnt vmcnt(1)
	v_mul_f32_e32 v64, v95, v165
	s_waitcnt vmcnt(0)
	v_mul_f32_e32 v65, v79, v122
	ds_write2_b32 v121, v64, v65 offset0:44 offset1:76
	v_lshl_add_u64 v[64:65], v[168:169], 0, s[26:27]
	v_add_u32_e32 v128, 0, v160
	v_ashrrev_i32_e32 v129, 31, v128
	v_lshlrev_b64 v[128:129], 10, v[128:129]
	v_lshl_add_u64 v[128:129], v[128:129], 0, v[64:65]
	v_lshlrev_b64 v[128:129], 2, v[128:129]
	v_lshl_add_u64 v[128:129], s[16:17], 0, v[128:129]
	global_load_dwordx4 v[128:131], v[128:129], off offset:256
	v_add_u32_e32 v132, 4, v160
	v_ashrrev_i32_e32 v133, 31, v132
	v_lshlrev_b64 v[132:133], 10, v[132:133]
	v_lshl_add_u64 v[132:133], v[132:133], 0, v[64:65]
	v_lshlrev_b64 v[132:133], 2, v[132:133]
	v_lshl_add_u64 v[132:133], s[16:17], 0, v[132:133]
	global_load_dwordx4 v[132:135], v[132:133], off offset:256
	v_add_u32_e32 v136, 8, v160
	v_ashrrev_i32_e32 v137, 31, v136
	v_lshlrev_b64 v[136:137], 10, v[136:137]
	v_lshl_add_u64 v[136:137], v[136:137], 0, v[64:65]
	v_lshlrev_b64 v[136:137], 2, v[136:137]
	v_lshl_add_u64 v[136:137], s[16:17], 0, v[136:137]
	global_load_dwordx4 v[136:139], v[136:137], off offset:256
	v_add_u32_e32 v140, 12, v160
	v_ashrrev_i32_e32 v141, 31, v140
	v_lshlrev_b64 v[140:141], 10, v[140:141]
	v_lshl_add_u64 v[140:141], v[140:141], 0, v[64:65]
	v_lshlrev_b64 v[140:141], 2, v[140:141]
	v_lshl_add_u64 v[140:141], s[16:17], 0, v[140:141]
	global_load_dwordx4 v[140:143], v[140:141], off offset:256
	v_add_u32_e32 v144, 16, v160
	v_ashrrev_i32_e32 v145, 31, v144
	v_lshlrev_b64 v[144:145], 10, v[144:145]
	v_lshl_add_u64 v[144:145], v[144:145], 0, v[64:65]
	v_lshlrev_b64 v[144:145], 2, v[144:145]
	v_lshl_add_u64 v[144:145], s[16:17], 0, v[144:145]
	global_load_dwordx4 v[144:147], v[144:145], off offset:256
	v_add_u32_e32 v148, 20, v160
	v_ashrrev_i32_e32 v149, 31, v148
	v_lshlrev_b64 v[148:149], 10, v[148:149]
	v_lshl_add_u64 v[148:149], v[148:149], 0, v[64:65]
	v_lshlrev_b64 v[148:149], 2, v[148:149]
	v_lshl_add_u64 v[148:149], s[16:17], 0, v[148:149]
	global_load_dwordx4 v[148:151], v[148:149], off offset:256
	v_add_u32_e32 v152, 24, v160
	v_ashrrev_i32_e32 v153, 31, v152
	v_lshlrev_b64 v[152:153], 10, v[152:153]
	v_lshl_add_u64 v[152:153], v[152:153], 0, v[64:65]
	v_lshlrev_b64 v[152:153], 2, v[152:153]
	v_lshl_add_u64 v[152:153], s[16:17], 0, v[152:153]
	global_load_dwordx4 v[152:155], v[152:153], off offset:256
	v_add_u32_e32 v156, 28, v160
	v_ashrrev_i32_e32 v157, 31, v156
	v_lshlrev_b64 v[156:157], 10, v[156:157]
	v_lshl_add_u64 v[156:157], v[156:157], 0, v[64:65]
	v_lshlrev_b64 v[156:157], 2, v[156:157]
	v_lshl_add_u64 v[156:157], s[16:17], 0, v[156:157]
	global_load_dwordx4 v[156:159], v[156:157], off offset:256
	s_and_saveexec_b64 s[26:27], vcc
	s_cbranch_execz .LBB0_1303
	v_lshlrev_b64 v[66:67], 10, v[160:161]
	v_lshl_add_u64 v[66:67], v[66:67], 0, v[64:65]
	v_lshlrev_b64 v[74:75], 2, v[66:67]
	v_lshl_add_u64 v[66:67], s[16:17], 0, v[74:75]
	ds_read_b128 v[70:73], v114
	s_load_dwordx2 s[28:29], s[0:1], 0xb8
	s_waitcnt vmcnt(7) lgkmcnt(0)
	v_pk_add_f32 v[68:69], v[72:73], v[130:131]
	v_pk_add_f32 v[66:67], v[70:71], v[128:129]
	v_lshl_add_u64 v[70:71], s[28:29], 0, v[74:75]
	global_store_dwordx4 v[70:71], v[66:69], off offset:256
	s_or_b64 exec, exec, s[26:27]
	s_and_saveexec_b64 s[26:27], s[2:3]
	s_cbranch_execnz .LBB0_1304

.LBB0_1298:
	v_lshlrev_b64 v[66:67], 10, v[102:103]
	v_lshl_add_u64 v[66:67], v[66:67], 0, v[64:65]
	v_lshlrev_b64 v[74:75], 2, v[66:67]
	v_lshl_add_u64 v[66:67], s[16:17], 0, v[74:75]
	ds_read_b128 v[70:73], v114 offset:2176
	s_load_dwordx2 s[4:5], s[0:1], 0xb8
	s_waitcnt vmcnt(7) lgkmcnt(0)
	v_pk_add_f32 v[68:69], v[72:73], v[138:139]
	v_pk_add_f32 v[66:67], v[70:71], v[136:137]
	v_lshl_add_u64 v[70:71], s[4:5], 0, v[74:75]
	global_store_dwordx4 v[70:71], v[66:69], off offset:256
	s_or_b64 exec, exec, s[2:3]
	s_and_saveexec_b64 s[2:3], s[6:7]
	s_cbranch_execnz .LBB0_1306

.LBB0_1300:
	v_lshlrev_b64 v[66:67], 10, v[106:107]
	v_lshl_add_u64 v[66:67], v[66:67], 0, v[64:65]
	v_lshlrev_b64 v[74:75], 2, v[66:67]
	v_lshl_add_u64 v[66:67], s[16:17], 0, v[74:75]
	ds_read_b128 v[70:73], v114 offset:4352
	s_load_dwordx2 s[4:5], s[0:1], 0xb8
	s_waitcnt vmcnt(7) lgkmcnt(0)
	v_pk_add_f32 v[68:69], v[72:73], v[146:147]
	v_pk_add_f32 v[66:67], v[70:71], v[144:145]
	v_lshl_add_u64 v[70:71], s[4:5], 0, v[74:75]
	global_store_dwordx4 v[70:71], v[66:69], off offset:256
	s_or_b64 exec, exec, s[2:3]
	s_and_saveexec_b64 s[2:3], s[10:11]
	s_cbranch_execnz .LBB0_1308

.LBB0_1302:
	v_lshlrev_b64 v[66:67], 10, v[110:111]
	v_lshl_add_u64 v[66:67], v[66:67], 0, v[64:65]
	v_lshlrev_b64 v[74:75], 2, v[66:67]
	v_lshl_add_u64 v[66:67], s[16:17], 0, v[74:75]
	ds_read_b128 v[70:73], v114 offset:6528
	s_load_dwordx2 s[4:5], s[0:1], 0xb8
	s_waitcnt vmcnt(7) lgkmcnt(0)
	v_pk_add_f32 v[68:69], v[72:73], v[154:155]
	v_pk_add_f32 v[66:67], v[70:71], v[152:153]
	v_lshl_add_u64 v[70:71], s[4:5], 0, v[74:75]
	global_store_dwordx4 v[70:71], v[66:69], off offset:256
	s_or_b64 exec, exec, s[2:3]
	s_and_saveexec_b64 s[2:3], s[14:15]
	s_cbranch_execnz .LBB0_1310
	s_branch .LBB0_1311

.LBB0_1304:
	v_lshlrev_b64 v[66:67], 10, v[100:101]
	v_lshl_add_u64 v[66:67], v[66:67], 0, v[64:65]
	v_lshlrev_b64 v[74:75], 2, v[66:67]
	v_lshl_add_u64 v[66:67], s[16:17], 0, v[74:75]
	ds_read_b128 v[70:73], v114 offset:1088
	s_load_dwordx2 s[2:3], s[0:1], 0xb8
	s_waitcnt vmcnt(7) lgkmcnt(0)
	v_pk_add_f32 v[68:69], v[72:73], v[134:135]
	v_pk_add_f32 v[66:67], v[70:71], v[132:133]
	v_lshl_add_u64 v[70:71], s[2:3], 0, v[74:75]
	global_store_dwordx4 v[70:71], v[66:69], off offset:256
	s_or_b64 exec, exec, s[26:27]
	s_and_saveexec_b64 s[2:3], s[4:5]
	s_cbranch_execnz .LBB0_1298

.LBB0_1306:
	v_lshlrev_b64 v[66:67], 10, v[104:105]
	v_lshl_add_u64 v[66:67], v[66:67], 0, v[64:65]
	v_lshlrev_b64 v[74:75], 2, v[66:67]
	v_lshl_add_u64 v[66:67], s[16:17], 0, v[74:75]
	ds_read_b128 v[70:73], v114 offset:3264
	s_load_dwordx2 s[4:5], s[0:1], 0xb8
	s_waitcnt vmcnt(7) lgkmcnt(0)
	v_pk_add_f32 v[68:69], v[72:73], v[142:143]
	v_pk_add_f32 v[66:67], v[70:71], v[140:141]
	v_lshl_add_u64 v[70:71], s[4:5], 0, v[74:75]
	global_store_dwordx4 v[70:71], v[66:69], off offset:256
	s_or_b64 exec, exec, s[2:3]
	s_and_saveexec_b64 s[2:3], s[8:9]
	s_cbranch_execnz .LBB0_1300

.LBB0_1308:
	v_lshlrev_b64 v[66:67], 10, v[108:109]
	v_lshl_add_u64 v[66:67], v[66:67], 0, v[64:65]
	v_lshlrev_b64 v[74:75], 2, v[66:67]
	v_lshl_add_u64 v[66:67], s[16:17], 0, v[74:75]
	ds_read_b128 v[70:73], v114 offset:5440
	s_load_dwordx2 s[4:5], s[0:1], 0xb8
	s_waitcnt vmcnt(7) lgkmcnt(0)
	v_pk_add_f32 v[68:69], v[72:73], v[150:151]
	v_pk_add_f32 v[66:67], v[70:71], v[148:149]
	v_lshl_add_u64 v[70:71], s[4:5], 0, v[74:75]
	global_store_dwordx4 v[70:71], v[66:69], off offset:256
	s_or_b64 exec, exec, s[2:3]
	s_and_saveexec_b64 s[2:3], s[12:13]
	s_cbranch_execnz .LBB0_1302

.LBB0_1310:
	v_lshlrev_b64 v[66:67], 10, v[112:113]
	v_lshl_add_u64 v[66:67], v[66:67], 0, v[64:65]
	v_lshlrev_b64 v[74:75], 2, v[66:67]
	v_lshl_add_u64 v[66:67], s[16:17], 0, v[74:75]
	ds_read_b128 v[70:73], v114 offset:7616
	s_load_dwordx2 s[4:5], s[0:1], 0xb8
	s_waitcnt vmcnt(7) lgkmcnt(0)
	v_pk_add_f32 v[68:69], v[72:73], v[158:159]
	v_pk_add_f32 v[66:67], v[70:71], v[156:157]
	v_lshl_add_u64 v[70:71], s[4:5], 0, v[74:75]
	global_store_dwordx4 v[70:71], v[66:69], off offset:256
.LBB0_1311:
	s_or_b64 exec, exec, s[2:3]
	s_or_b32 s2, s55, 32
	v_add_u32_e32 v102, s2, v183
	v_min_i32_e32 v66, 0x7fff, v102
	v_add_u32_e32 v68, 8, v102
	v_add_u32_e32 v70, 9, v102
	v_add_u32_e32 v72, 10, v102
	v_ashrrev_i32_e32 v66, 12, v66
	v_min_i32_e32 v68, 0x7fff, v68
	v_min_i32_e32 v70, 0x7fff, v70
	v_min_i32_e32 v72, 0x7fff, v72
	v_mul_hi_i32_i24_e32 v67, 0x3000, v66
	v_mul_i32_i24_e32 v66, 0x3000, v66
	v_ashrrev_i32_e32 v68, 12, v68
	v_ashrrev_i32_e32 v70, 12, v70
	v_ashrrev_i32_e32 v72, 12, v72
	v_lshl_add_u64 v[66:67], s[24:25], 0, v[66:67]
	v_mul_hi_i32_i24_e32 v69, 0x3000, v68
	v_mul_i32_i24_e32 v68, 0x3000, v68
	v_mul_hi_i32_i24_e32 v71, 0x3000, v70
	v_mul_i32_i24_e32 v70, 0x3000, v70
	v_mul_hi_i32_i24_e32 v73, 0x3000, v72
	v_mul_i32_i24_e32 v72, 0x3000, v72
	v_lshl_add_u64 v[66:67], v[66:67], 0, s[18:19]
	v_lshl_add_u64 v[68:69], s[24:25], 0, v[68:69]
	v_lshl_add_u64 v[70:71], s[24:25], 0, v[70:71]
	v_lshl_add_u64 v[72:73], s[24:25], 0, v[72:73]
	v_lshl_add_u64 v[74:75], v[66:67], 0, v[180:181]
	v_lshl_add_u64 v[68:69], v[68:69], 0, s[18:19]
	v_lshl_add_u64 v[70:71], v[70:71], 0, s[18:19]
	v_lshl_add_u64 v[72:73], v[72:73], 0, s[18:19]
	v_lshl_add_u64 v[76:77], v[68:69], 0, v[180:181]
	v_lshl_add_u64 v[78:79], v[70:71], 0, v[180:181]
	v_lshl_add_u64 v[80:81], v[72:73], 0, v[180:181]
	global_load_dword v103, v[74:75], off
	global_load_dword v104, v[74:75], off offset:128
	global_load_dword v105, v[76:77], off
	global_load_dword v106, v[76:77], off offset:128
	global_load_dword v107, v[78:79], off
	global_load_dword v108, v[78:79], off offset:128
	global_load_dword v109, v[80:81], off
	global_load_dword v110, v[80:81], off offset:128
	v_add_u32_e32 v74, 11, v102
	v_add_u32_e32 v82, 18, v102
	v_min_i32_e32 v74, 0x7fff, v74
	v_add_u32_e32 v76, 16, v102
	v_add_u32_e32 v80, 17, v102
	v_min_i32_e32 v82, 0x7fff, v82
	v_ashrrev_i32_e32 v74, 12, v74
	v_min_i32_e32 v76, 0x7fff, v76
	v_min_i32_e32 v80, 0x7fff, v80
	v_ashrrev_i32_e32 v82, 12, v82
	v_mul_hi_i32_i24_e32 v75, 0x3000, v74
	v_mul_i32_i24_e32 v74, 0x3000, v74
	v_ashrrev_i32_e32 v76, 12, v76
	v_ashrrev_i32_e32 v80, 12, v80
	v_mul_hi_i32_i24_e32 v83, 0x3000, v82
	v_mul_i32_i24_e32 v82, 0x3000, v82
	v_lshl_add_u64 v[74:75], s[24:25], 0, v[74:75]
	v_mul_hi_i32_i24_e32 v77, 0x3000, v76
	v_mul_i32_i24_e32 v76, 0x3000, v76
	v_mul_hi_i32_i24_e32 v81, 0x3000, v80
	v_mul_i32_i24_e32 v80, 0x3000, v80
	v_lshl_add_u64 v[82:83], s[24:25], 0, v[82:83]
	v_lshl_add_u64 v[74:75], v[74:75], 0, s[18:19]
	v_lshl_add_u64 v[76:77], s[24:25], 0, v[76:77]
	v_lshl_add_u64 v[80:81], s[24:25], 0, v[80:81]
	v_lshl_add_u64 v[82:83], v[82:83], 0, s[18:19]
	v_lshl_add_u64 v[78:79], v[74:75], 0, v[180:181]
	v_lshl_add_u64 v[76:77], v[76:77], 0, s[18:19]
	v_lshl_add_u64 v[80:81], v[80:81], 0, s[18:19]
	v_lshl_add_u64 v[88:89], v[82:83], 0, v[180:181]
	v_lshl_add_u64 v[84:85], v[76:77], 0, v[180:181]
	v_lshl_add_u64 v[86:87], v[80:81], 0, v[180:181]
	global_load_dword v111, v[78:79], off
	global_load_dword v112, v[78:79], off offset:128
	global_load_dword v113, v[84:85], off
	global_load_dword v122, v[84:85], off offset:128
	global_load_dword v123, v[86:87], off
	global_load_dword v124, v[86:87], off offset:128
	global_load_dword v125, v[88:89], off
	global_load_dword v126, v[88:89], off offset:128
	v_add_u32_e32 v78, 19, v102
	v_add_u32_e32 v88, 25, v102
	v_add_u32_e32 v90, 26, v102
	v_min_i32_e32 v78, 0x7fff, v78
	v_add_u32_e32 v86, 24, v102
	v_min_i32_e32 v88, 0x7fff, v88
	v_min_i32_e32 v90, 0x7fff, v90
	v_ashrrev_i32_e32 v78, 12, v78
	v_min_i32_e32 v86, 0x7fff, v86
	v_ashrrev_i32_e32 v88, 12, v88
	v_ashrrev_i32_e32 v90, 12, v90
	v_mul_hi_i32_i24_e32 v79, 0x3000, v78
	v_mul_i32_i24_e32 v78, 0x3000, v78
	v_ashrrev_i32_e32 v86, 12, v86
	v_mul_hi_i32_i24_e32 v89, 0x3000, v88
	v_mul_i32_i24_e32 v88, 0x3000, v88
	v_mul_hi_i32_i24_e32 v91, 0x3000, v90
	v_mul_i32_i24_e32 v90, 0x3000, v90
	v_lshl_add_u64 v[78:79], s[24:25], 0, v[78:79]
	v_mul_hi_i32_i24_e32 v87, 0x3000, v86
	v_mul_i32_i24_e32 v86, 0x3000, v86
	v_lshl_add_u64 v[88:89], s[24:25], 0, v[88:89]
	v_lshl_add_u64 v[90:91], s[24:25], 0, v[90:91]
	v_lshl_add_u64 v[84:85], v[78:79], 0, s[18:19]
	v_lshl_add_u64 v[86:87], s[24:25], 0, v[86:87]
	v_lshl_add_u64 v[88:89], v[88:89], 0, s[18:19]
	v_lshl_add_u64 v[90:91], v[90:91], 0, s[18:19]
	v_lshl_add_u64 v[78:79], v[84:85], 0, v[180:181]
	v_lshl_add_u64 v[86:87], v[86:87], 0, s[18:19]
	v_lshl_add_u64 v[94:95], v[88:89], 0, v[180:181]
	v_lshl_add_u64 v[100:101], v[90:91], 0, v[180:181]
	v_lshl_add_u64 v[92:93], v[86:87], 0, v[180:181]
	global_load_dword v127, v[78:79], off
	global_load_dword v160, v[78:79], off offset:128
	global_load_dword v161, v[92:93], off
	global_load_dword v164, v[92:93], off offset:128
	global_load_dword v165, v[94:95], off
	s_nop 0
	global_load_dword v94, v[94:95], off offset:128
	s_nop 0
	global_load_dword v95, v[100:101], off
	s_nop 0
	global_load_dword v100, v[100:101], off offset:128
	v_add_u32_e32 v78, 27, v102
	v_min_i32_e32 v78, 0x7fff, v78
	v_ashrrev_i32_e32 v78, 12, v78
	v_mul_hi_i32_i24_e32 v79, 0x3000, v78
	v_mul_i32_i24_e32 v78, 0x3000, v78
	v_lshl_add_u64 v[78:79], s[24:25], 0, v[78:79]
	v_lshl_add_u64 v[92:93], v[78:79], 0, s[18:19]
	v_lshl_add_u64 v[78:79], v[92:93], 0, v[180:181]
	global_load_dword v101, v[78:79], off
	s_nop 0
	global_load_dword v79, v[78:79], off offset:128
	s_waitcnt vmcnt(25)
	v_mul_f32_e32 v48, v48, v103
	s_waitcnt vmcnt(24)
	v_mul_f32_e32 v32, v32, v104
	ds_write2_b32 v162, v48, v32 offset1:32
	v_mul_f32_e32 v32, v49, v103
	v_mul_f32_e32 v33, v33, v104
	ds_write2_b32 v162, v32, v33 offset0:68 offset1:100
	v_mul_f32_e32 v32, v50, v103
	v_mul_f32_e32 v33, v34, v104
	ds_write2_b32 v162, v32, v33 offset0:136 offset1:168
	v_mul_f32_e32 v32, v51, v103
	v_mul_f32_e32 v33, v35, v104
	ds_write2_b32 v162, v32, v33 offset0:204 offset1:236
	s_waitcnt vmcnt(23)
	v_mul_f32_e32 v32, v52, v105
	s_waitcnt vmcnt(22)
	v_mul_f32_e32 v33, v36, v106
	ds_write2_b32 v115, v32, v33 offset0:32 offset1:64
	s_waitcnt vmcnt(21)
	v_mul_f32_e32 v32, v53, v107
	s_waitcnt vmcnt(20)
	v_mul_f32_e32 v33, v37, v108
	ds_write2_b32 v115, v32, v33 offset0:100 offset1:132
	s_waitcnt vmcnt(19)
	v_mul_f32_e32 v32, v54, v109
	s_waitcnt vmcnt(18)
	v_mul_f32_e32 v33, v38, v110
	ds_write2_b32 v115, v32, v33 offset0:168 offset1:200
	v_add_u32_e32 v78, s2, v163
	v_cmp_gt_i32_e32 vcc, s38, v78
	s_waitcnt vmcnt(17)
	v_mul_f32_e32 v32, v55, v111
	s_waitcnt vmcnt(16)
	v_mul_f32_e32 v33, v39, v112
	ds_write2_b32 v116, v32, v33 offset0:108 offset1:140
	s_waitcnt vmcnt(15)
	v_mul_f32_e32 v32, v56, v113
	s_waitcnt vmcnt(14)
	v_mul_f32_e32 v33, v40, v122
	ds_write2_b32 v117, v32, v33 offset0:64 offset1:96
	s_waitcnt vmcnt(13)
	v_mul_f32_e32 v32, v57, v123
	s_waitcnt vmcnt(12)
	v_mul_f32_e32 v33, v41, v124
	ds_write2_b32 v117, v32, v33 offset0:132 offset1:164
	s_waitcnt vmcnt(11)
	v_mul_f32_e32 v32, v58, v125
	s_waitcnt vmcnt(10)
	v_mul_f32_e32 v33, v42, v126
	ds_write2_b32 v117, v32, v33 offset0:200 offset1:232
	s_waitcnt vmcnt(9)
	v_mul_f32_e32 v32, v59, v127
	s_waitcnt vmcnt(8)
	v_mul_f32_e32 v33, v43, v160
	ds_write2_b32 v118, v32, v33 offset0:12 offset1:44
	s_waitcnt vmcnt(7)
	v_mul_f32_e32 v32, v60, v161
	s_waitcnt vmcnt(6)
	v_mul_f32_e32 v33, v44, v164
	ds_write2_b32 v119, v32, v33 offset0:96 offset1:128
	s_waitcnt vmcnt(5)
	v_mul_f32_e32 v32, v61, v165
	s_waitcnt vmcnt(4)
	v_mul_f32_e32 v33, v45, v94
	ds_write2_b32 v119, v32, v33 offset0:164 offset1:196
	s_waitcnt vmcnt(3)
	v_mul_f32_e32 v32, v62, v95
	s_waitcnt vmcnt(2)
	v_mul_f32_e32 v33, v46, v100
	ds_write2_b32 v120, v32, v33 offset0:104 offset1:136
	s_waitcnt vmcnt(1)
	v_mul_f32_e32 v32, v63, v101
	s_waitcnt vmcnt(0)
	v_mul_f32_e32 v33, v47, v79
	v_ashrrev_i32_e32 v79, 31, v78
	ds_write2_b32 v121, v32, v33 offset0:44 offset1:76
	v_add_u32_e32 v128, 0, v78
	v_ashrrev_i32_e32 v129, 31, v128
	v_lshlrev_b64 v[128:129], 10, v[128:129]
	v_lshl_add_u64 v[128:129], v[128:129], 0, v[96:97]
	v_lshlrev_b64 v[128:129], 2, v[128:129]
	v_lshl_add_u64 v[128:129], s[16:17], 0, v[128:129]
	global_load_dwordx4 v[128:131], v[128:129], off
	v_add_u32_e32 v132, 4, v78
	v_ashrrev_i32_e32 v133, 31, v132
	v_lshlrev_b64 v[132:133], 10, v[132:133]
	v_lshl_add_u64 v[132:133], v[132:133], 0, v[96:97]
	v_lshlrev_b64 v[132:133], 2, v[132:133]
	v_lshl_add_u64 v[132:133], s[16:17], 0, v[132:133]
	global_load_dwordx4 v[132:135], v[132:133], off
	v_add_u32_e32 v136, 8, v78
	v_ashrrev_i32_e32 v137, 31, v136
	v_lshlrev_b64 v[136:137], 10, v[136:137]
	v_lshl_add_u64 v[136:137], v[136:137], 0, v[96:97]
	v_lshlrev_b64 v[136:137], 2, v[136:137]
	v_lshl_add_u64 v[136:137], s[16:17], 0, v[136:137]
	global_load_dwordx4 v[136:139], v[136:137], off
	v_add_u32_e32 v140, 12, v78
	v_ashrrev_i32_e32 v141, 31, v140
	v_lshlrev_b64 v[140:141], 10, v[140:141]
	v_lshl_add_u64 v[140:141], v[140:141], 0, v[96:97]
	v_lshlrev_b64 v[140:141], 2, v[140:141]
	v_lshl_add_u64 v[140:141], s[16:17], 0, v[140:141]
	global_load_dwordx4 v[140:143], v[140:141], off
	v_add_u32_e32 v144, 16, v78
	v_ashrrev_i32_e32 v145, 31, v144
	v_lshlrev_b64 v[144:145], 10, v[144:145]
	v_lshl_add_u64 v[144:145], v[144:145], 0, v[96:97]
	v_lshlrev_b64 v[144:145], 2, v[144:145]
	v_lshl_add_u64 v[144:145], s[16:17], 0, v[144:145]
	global_load_dwordx4 v[144:147], v[144:145], off
	v_add_u32_e32 v148, 20, v78
	v_ashrrev_i32_e32 v149, 31, v148
	v_lshlrev_b64 v[148:149], 10, v[148:149]
	v_lshl_add_u64 v[148:149], v[148:149], 0, v[96:97]
	v_lshlrev_b64 v[148:149], 2, v[148:149]
	v_lshl_add_u64 v[148:149], s[16:17], 0, v[148:149]
	global_load_dwordx4 v[148:151], v[148:149], off
	v_add_u32_e32 v152, 24, v78
	v_ashrrev_i32_e32 v153, 31, v152
	v_lshlrev_b64 v[152:153], 10, v[152:153]
	v_lshl_add_u64 v[152:153], v[152:153], 0, v[96:97]
	v_lshlrev_b64 v[152:153], 2, v[152:153]
	v_lshl_add_u64 v[152:153], s[16:17], 0, v[152:153]
	global_load_dwordx4 v[152:155], v[152:153], off
	v_add_u32_e32 v156, 28, v78
	v_ashrrev_i32_e32 v157, 31, v156
	v_lshlrev_b64 v[156:157], 10, v[156:157]
	v_lshl_add_u64 v[156:157], v[156:157], 0, v[96:97]
	v_lshlrev_b64 v[156:157], 2, v[156:157]
	v_lshl_add_u64 v[156:157], s[16:17], 0, v[156:157]
	global_load_dwordx4 v[156:159], v[156:157], off
	s_and_saveexec_b64 s[2:3], vcc
	s_cbranch_execz .LBB0_1313
	v_lshlrev_b64 v[32:33], 10, v[78:79]
	v_lshl_add_u64 v[32:33], v[32:33], 0, v[96:97]
	v_lshlrev_b64 v[40:41], 2, v[32:33]
	v_lshl_add_u64 v[32:33], s[16:17], 0, v[40:41]
	ds_read_b128 v[36:39], v114
	s_load_dwordx2 s[4:5], s[0:1], 0xb8
	s_waitcnt vmcnt(7) lgkmcnt(0)
	v_pk_add_f32 v[34:35], v[38:39], v[130:131]
	v_pk_add_f32 v[32:33], v[36:37], v[128:129]
	v_lshl_add_u64 v[36:37], s[4:5], 0, v[40:41]
	global_store_dwordx4 v[36:37], v[32:35], off
.LBB0_1313:
	s_or_b64 exec, exec, s[2:3]
	s_nop 0
	v_add_u32_e32 v32, 4, v78
	v_cmp_gt_i32_e64 s[2:3], s39, v78
	v_ashrrev_i32_e32 v33, 31, v32
	s_and_saveexec_b64 s[4:5], s[2:3]
	s_cbranch_execz .LBB0_1315
	v_lshlrev_b64 v[34:35], 10, v[32:33]
	v_lshl_add_u64 v[34:35], v[34:35], 0, v[96:97]
	v_lshlrev_b64 v[42:43], 2, v[34:35]
	v_lshl_add_u64 v[34:35], s[16:17], 0, v[42:43]
	ds_read_b128 v[38:41], v114 offset:1088
	s_load_dwordx2 s[6:7], s[0:1], 0xb8
	s_waitcnt vmcnt(7) lgkmcnt(0)
	v_pk_add_f32 v[36:37], v[40:41], v[134:135]
	v_pk_add_f32 v[34:35], v[38:39], v[132:133]
	v_lshl_add_u64 v[38:39], s[6:7], 0, v[42:43]
	global_store_dwordx4 v[38:39], v[34:37], off
.LBB0_1315:
	s_or_b64 exec, exec, s[4:5]
	s_nop 0
	v_add_u32_e32 v34, 8, v78
	v_cmp_gt_i32_e64 s[4:5], s48, v78
	v_ashrrev_i32_e32 v35, 31, v34
	s_and_saveexec_b64 s[6:7], s[4:5]
	s_cbranch_execz .LBB0_1317
	v_lshlrev_b64 v[36:37], 10, v[34:35]
	v_lshl_add_u64 v[36:37], v[36:37], 0, v[96:97]
	v_lshlrev_b64 v[44:45], 2, v[36:37]
	v_lshl_add_u64 v[36:37], s[16:17], 0, v[44:45]
	ds_read_b128 v[40:43], v114 offset:2176
	s_load_dwordx2 s[8:9], s[0:1], 0xb8
	s_waitcnt vmcnt(7) lgkmcnt(0)
	v_pk_add_f32 v[38:39], v[42:43], v[138:139]
	v_pk_add_f32 v[36:37], v[40:41], v[136:137]
	v_lshl_add_u64 v[40:41], s[8:9], 0, v[44:45]
	global_store_dwordx4 v[40:41], v[36:39], off
.LBB0_1317:
	s_or_b64 exec, exec, s[6:7]
	s_nop 0
	v_add_u32_e32 v36, 12, v78
	v_cmp_gt_i32_e64 s[6:7], s49, v78
	v_ashrrev_i32_e32 v37, 31, v36
	s_and_saveexec_b64 s[8:9], s[6:7]
	s_cbranch_execz .LBB0_1319
	v_lshlrev_b64 v[38:39], 10, v[36:37]
	v_lshl_add_u64 v[38:39], v[38:39], 0, v[96:97]
	v_lshlrev_b64 v[46:47], 2, v[38:39]
	v_lshl_add_u64 v[38:39], s[16:17], 0, v[46:47]
	ds_read_b128 v[42:45], v114 offset:3264
	s_load_dwordx2 s[10:11], s[0:1], 0xb8
	s_waitcnt vmcnt(7) lgkmcnt(0)
	v_pk_add_f32 v[40:41], v[44:45], v[142:143]
	v_pk_add_f32 v[38:39], v[42:43], v[140:141]
	v_lshl_add_u64 v[42:43], s[10:11], 0, v[46:47]
	global_store_dwordx4 v[42:43], v[38:41], off
.LBB0_1319:
	s_or_b64 exec, exec, s[8:9]
	s_nop 0
	v_add_u32_e32 v38, 16, v78
	v_cmp_gt_i32_e64 s[8:9], s50, v78
	v_ashrrev_i32_e32 v39, 31, v38
	s_and_saveexec_b64 s[10:11], s[8:9]
	s_cbranch_execz .LBB0_1321
	v_lshlrev_b64 v[40:41], 10, v[38:39]
	v_lshl_add_u64 v[40:41], v[40:41], 0, v[96:97]
	v_lshlrev_b64 v[48:49], 2, v[40:41]
	v_lshl_add_u64 v[40:41], s[16:17], 0, v[48:49]
	ds_read_b128 v[44:47], v114 offset:4352
	s_load_dwordx2 s[12:13], s[0:1], 0xb8
	s_waitcnt vmcnt(7) lgkmcnt(0)
	v_pk_add_f32 v[42:43], v[46:47], v[146:147]
	v_pk_add_f32 v[40:41], v[44:45], v[144:145]
	v_lshl_add_u64 v[44:45], s[12:13], 0, v[48:49]
	global_store_dwordx4 v[44:45], v[40:43], off
.LBB0_1321:
	s_or_b64 exec, exec, s[10:11]
	s_nop 0
	v_add_u32_e32 v40, 20, v78
	v_cmp_gt_i32_e64 s[10:11], s51, v78
	v_ashrrev_i32_e32 v41, 31, v40
	s_and_saveexec_b64 s[12:13], s[10:11]
	s_cbranch_execz .LBB0_1323
	v_lshlrev_b64 v[42:43], 10, v[40:41]
	v_lshl_add_u64 v[42:43], v[42:43], 0, v[96:97]
	v_lshlrev_b64 v[50:51], 2, v[42:43]
	v_lshl_add_u64 v[42:43], s[16:17], 0, v[50:51]
	ds_read_b128 v[46:49], v114 offset:5440
	s_load_dwordx2 s[14:15], s[0:1], 0xb8
	s_waitcnt vmcnt(7) lgkmcnt(0)
	v_pk_add_f32 v[44:45], v[48:49], v[150:151]
	v_pk_add_f32 v[42:43], v[46:47], v[148:149]
	v_lshl_add_u64 v[46:47], s[14:15], 0, v[50:51]
	global_store_dwordx4 v[46:47], v[42:45], off
.LBB0_1323:
	s_or_b64 exec, exec, s[12:13]
	s_nop 0
	v_add_u32_e32 v42, 24, v78
	v_cmp_gt_i32_e64 s[12:13], s52, v78
	v_ashrrev_i32_e32 v43, 31, v42
	s_and_saveexec_b64 s[14:15], s[12:13]
	s_cbranch_execz .LBB0_1325
	v_lshlrev_b64 v[44:45], 10, v[42:43]
	v_lshl_add_u64 v[44:45], v[44:45], 0, v[96:97]
	v_lshlrev_b64 v[52:53], 2, v[44:45]
	v_lshl_add_u64 v[44:45], s[16:17], 0, v[52:53]
	ds_read_b128 v[48:51], v114 offset:6528
	s_load_dwordx2 s[24:25], s[0:1], 0xb8
	s_waitcnt vmcnt(7) lgkmcnt(0)
	v_pk_add_f32 v[46:47], v[50:51], v[154:155]
	v_pk_add_f32 v[44:45], v[48:49], v[152:153]
	v_lshl_add_u64 v[48:49], s[24:25], 0, v[52:53]
	global_store_dwordx4 v[48:49], v[44:47], off
.LBB0_1325:
	s_or_b64 exec, exec, s[14:15]
	s_nop 0
	v_add_u32_e32 v44, 28, v78
	v_cmp_gt_i32_e64 s[14:15], s53, v78
	v_ashrrev_i32_e32 v45, 31, v44
	s_and_saveexec_b64 s[24:25], s[14:15]
	s_cbranch_execz .LBB0_1327
	v_lshlrev_b64 v[46:47], 10, v[44:45]
	v_lshl_add_u64 v[46:47], v[46:47], 0, v[96:97]
	v_lshlrev_b64 v[54:55], 2, v[46:47]
	v_lshl_add_u64 v[46:47], s[16:17], 0, v[54:55]
	ds_read_b128 v[50:53], v114 offset:7616
	s_load_dwordx2 s[26:27], s[0:1], 0xb8
	s_waitcnt vmcnt(7) lgkmcnt(0)
	v_pk_add_f32 v[48:49], v[52:53], v[158:159]
	v_pk_add_f32 v[46:47], v[50:51], v[156:157]
	v_lshl_add_u64 v[50:51], s[26:27], 0, v[54:55]
	global_store_dwordx4 v[50:51], v[46:49], off
.LBB0_1327:
	s_or_b64 exec, exec, s[24:25]
	s_nop 0
	v_lshl_add_u64 v[46:47], v[66:67], 0, v[98:99]
	v_lshl_add_u64 v[48:49], v[68:69], 0, v[98:99]
	v_lshl_add_u64 v[50:51], v[70:71], 0, v[98:99]
	v_lshl_add_u64 v[52:53], v[72:73], 0, v[98:99]
	global_load_dword v54, v[46:47], off
	global_load_dword v55, v[46:47], off offset:128
	global_load_dword v56, v[48:49], off
	global_load_dword v57, v[48:49], off offset:128
	global_load_dword v58, v[50:51], off
	global_load_dword v59, v[50:51], off offset:128
	global_load_dword v60, v[52:53], off
	global_load_dword v61, v[52:53], off offset:128
	v_lshl_add_u64 v[46:47], v[74:75], 0, v[98:99]
	v_lshl_add_u64 v[48:49], v[76:77], 0, v[98:99]
	v_lshl_add_u64 v[50:51], v[80:81], 0, v[98:99]
	v_lshl_add_u64 v[52:53], v[82:83], 0, v[98:99]
	global_load_dword v62, v[46:47], off
	global_load_dword v63, v[46:47], off offset:128
	global_load_dword v66, v[48:49], off
	global_load_dword v67, v[48:49], off offset:128
	global_load_dword v68, v[50:51], off
	global_load_dword v69, v[50:51], off offset:128
	global_load_dword v70, v[52:53], off
	global_load_dword v71, v[52:53], off offset:128
	v_lshl_add_u64 v[46:47], v[84:85], 0, v[98:99]
	v_lshl_add_u64 v[48:49], v[86:87], 0, v[98:99]
	v_lshl_add_u64 v[50:51], v[88:89], 0, v[98:99]
	v_lshl_add_u64 v[52:53], v[90:91], 0, v[98:99]
	global_load_dword v72, v[46:47], off
	global_load_dword v73, v[46:47], off offset:128
	global_load_dword v74, v[48:49], off
	s_nop 0
	global_load_dword v48, v[48:49], off offset:128
	s_nop 0
	global_load_dword v49, v[50:51], off
	s_nop 0
	global_load_dword v50, v[50:51], off offset:128
	s_nop 0
	global_load_dword v51, v[52:53], off
	s_nop 0
	global_load_dword v52, v[52:53], off offset:128
	v_lshl_add_u64 v[46:47], v[92:93], 0, v[98:99]
	global_load_dword v53, v[46:47], off
	s_nop 0
	global_load_dword v46, v[46:47], off offset:128
	s_waitcnt vmcnt(25)
	v_mul_f32_e32 v16, v16, v54
	s_waitcnt vmcnt(24)
	v_mul_f32_e32 v0, v0, v55
	v_mul_f32_e32 v1, v1, v55
	v_mul_f32_e32 v17, v17, v54
	v_mul_f32_e32 v18, v18, v54
	v_mul_f32_e32 v2, v2, v55
	v_mul_f32_e32 v19, v19, v54
	v_mul_f32_e32 v3, v3, v55
	s_waitcnt vmcnt(23)
	v_mul_f32_e32 v20, v20, v56
	s_waitcnt vmcnt(22)
	v_mul_f32_e32 v4, v4, v57
	s_waitcnt vmcnt(21)
	v_mul_f32_e32 v21, v21, v58
	s_waitcnt vmcnt(20)
	v_mul_f32_e32 v5, v5, v59
	s_waitcnt vmcnt(19)
	v_mul_f32_e32 v22, v22, v60
	s_waitcnt vmcnt(18)
	v_mul_f32_e32 v6, v6, v61
	s_waitcnt vmcnt(17)
	v_mul_f32_e32 v23, v23, v62
	s_waitcnt vmcnt(16)
	v_mul_f32_e32 v7, v7, v63
	s_waitcnt vmcnt(15)
	v_mul_f32_e32 v24, v24, v66
	s_waitcnt vmcnt(14)
	v_mul_f32_e32 v8, v8, v67
	s_waitcnt vmcnt(13)
	v_mul_f32_e32 v25, v25, v68
	s_waitcnt vmcnt(12)
	v_mul_f32_e32 v9, v9, v69
	s_waitcnt vmcnt(11)
	v_mul_f32_e32 v26, v26, v70
	s_waitcnt vmcnt(10)
	v_mul_f32_e32 v10, v10, v71
	s_waitcnt vmcnt(9)
	v_mul_f32_e32 v27, v27, v72
	s_waitcnt vmcnt(8)
	v_mul_f32_e32 v11, v11, v73
	s_waitcnt vmcnt(7)
	v_mul_f32_e32 v28, v28, v74
	s_waitcnt vmcnt(6)
	v_mul_f32_e32 v12, v12, v48
	s_waitcnt vmcnt(5)
	v_mul_f32_e32 v29, v29, v49
	s_waitcnt vmcnt(4)
	v_mul_f32_e32 v13, v13, v50
	s_waitcnt vmcnt(3)
	v_mul_f32_e32 v30, v30, v51
	s_waitcnt vmcnt(2)
	v_mul_f32_e32 v14, v14, v52
	ds_write2_b32 v162, v16, v0 offset1:32
	ds_write2_b32 v162, v17, v1 offset0:68 offset1:100
	ds_write2_b32 v162, v18, v2 offset0:136 offset1:168
	ds_write2_b32 v162, v19, v3 offset0:204 offset1:236
	ds_write2_b32 v115, v20, v4 offset0:32 offset1:64
	ds_write2_b32 v115, v21, v5 offset0:100 offset1:132
	ds_write2_b32 v115, v22, v6 offset0:168 offset1:200
	ds_write2_b32 v116, v23, v7 offset0:108 offset1:140
	ds_write2_b32 v117, v24, v8 offset0:64 offset1:96
	ds_write2_b32 v117, v25, v9 offset0:132 offset1:164
	ds_write2_b32 v117, v26, v10 offset0:200 offset1:232
	ds_write2_b32 v118, v27, v11 offset0:12 offset1:44
	ds_write2_b32 v119, v28, v12 offset0:96 offset1:128
	ds_write2_b32 v119, v29, v13 offset0:164 offset1:196
	ds_write2_b32 v120, v30, v14 offset0:104 offset1:136
	s_waitcnt vmcnt(1)
	v_mul_f32_e32 v0, v31, v53
	s_waitcnt vmcnt(0)
	v_mul_f32_e32 v1, v15, v46
	ds_write2_b32 v121, v0, v1 offset0:44 offset1:76
	v_add_u32_e32 v128, 0, v78
	v_ashrrev_i32_e32 v129, 31, v128
	v_lshlrev_b64 v[128:129], 10, v[128:129]
	v_lshl_add_u64 v[128:129], v[128:129], 0, v[64:65]
	v_lshlrev_b64 v[128:129], 2, v[128:129]
	v_lshl_add_u64 v[128:129], s[16:17], 0, v[128:129]
	global_load_dwordx4 v[128:131], v[128:129], off offset:256
	v_add_u32_e32 v132, 4, v78
	v_ashrrev_i32_e32 v133, 31, v132
	v_lshlrev_b64 v[132:133], 10, v[132:133]
	v_lshl_add_u64 v[132:133], v[132:133], 0, v[64:65]
	v_lshlrev_b64 v[132:133], 2, v[132:133]
	v_lshl_add_u64 v[132:133], s[16:17], 0, v[132:133]
	global_load_dwordx4 v[132:135], v[132:133], off offset:256
	v_add_u32_e32 v136, 8, v78
	v_ashrrev_i32_e32 v137, 31, v136
	v_lshlrev_b64 v[136:137], 10, v[136:137]
	v_lshl_add_u64 v[136:137], v[136:137], 0, v[64:65]
	v_lshlrev_b64 v[136:137], 2, v[136:137]
	v_lshl_add_u64 v[136:137], s[16:17], 0, v[136:137]
	global_load_dwordx4 v[136:139], v[136:137], off offset:256
	v_add_u32_e32 v140, 12, v78
	v_ashrrev_i32_e32 v141, 31, v140
	v_lshlrev_b64 v[140:141], 10, v[140:141]
	v_lshl_add_u64 v[140:141], v[140:141], 0, v[64:65]
	v_lshlrev_b64 v[140:141], 2, v[140:141]
	v_lshl_add_u64 v[140:141], s[16:17], 0, v[140:141]
	global_load_dwordx4 v[140:143], v[140:141], off offset:256
	v_add_u32_e32 v144, 16, v78
	v_ashrrev_i32_e32 v145, 31, v144
	v_lshlrev_b64 v[144:145], 10, v[144:145]
	v_lshl_add_u64 v[144:145], v[144:145], 0, v[64:65]
	v_lshlrev_b64 v[144:145], 2, v[144:145]
	v_lshl_add_u64 v[144:145], s[16:17], 0, v[144:145]
	global_load_dwordx4 v[144:147], v[144:145], off offset:256
	v_add_u32_e32 v148, 20, v78
	v_ashrrev_i32_e32 v149, 31, v148
	v_lshlrev_b64 v[148:149], 10, v[148:149]
	v_lshl_add_u64 v[148:149], v[148:149], 0, v[64:65]
	v_lshlrev_b64 v[148:149], 2, v[148:149]
	v_lshl_add_u64 v[148:149], s[16:17], 0, v[148:149]
	global_load_dwordx4 v[148:151], v[148:149], off offset:256
	v_add_u32_e32 v152, 24, v78
	v_ashrrev_i32_e32 v153, 31, v152
	v_lshlrev_b64 v[152:153], 10, v[152:153]
	v_lshl_add_u64 v[152:153], v[152:153], 0, v[64:65]
	v_lshlrev_b64 v[152:153], 2, v[152:153]
	v_lshl_add_u64 v[152:153], s[16:17], 0, v[152:153]
	global_load_dwordx4 v[152:155], v[152:153], off offset:256
	v_add_u32_e32 v156, 28, v78
	v_ashrrev_i32_e32 v157, 31, v156
	v_lshlrev_b64 v[156:157], 10, v[156:157]
	v_lshl_add_u64 v[156:157], v[156:157], 0, v[64:65]
	v_lshlrev_b64 v[156:157], 2, v[156:157]
	v_lshl_add_u64 v[156:157], s[16:17], 0, v[156:157]
	global_load_dwordx4 v[156:159], v[156:157], off offset:256
	s_and_saveexec_b64 s[24:25], vcc
	s_cbranch_execz .LBB0_1335
	v_lshlrev_b64 v[0:1], 10, v[78:79]
	v_lshl_add_u64 v[0:1], v[0:1], 0, v[64:65]
	v_lshlrev_b64 v[8:9], 2, v[0:1]
	v_lshl_add_u64 v[0:1], s[16:17], 0, v[8:9]
	ds_read_b128 v[4:7], v114
	s_load_dwordx2 s[26:27], s[0:1], 0xb8
	s_waitcnt vmcnt(7) lgkmcnt(0)
	v_pk_add_f32 v[2:3], v[6:7], v[130:131]
	v_pk_add_f32 v[0:1], v[4:5], v[128:129]
	v_lshl_add_u64 v[4:5], s[26:27], 0, v[8:9]
	global_store_dwordx4 v[4:5], v[0:3], off offset:256
	s_or_b64 exec, exec, s[24:25]
	s_and_saveexec_b64 s[24:25], s[2:3]
	s_cbranch_execnz .LBB0_1336

.LBB0_1330:
	v_lshlrev_b64 v[0:1], 10, v[34:35]
	v_lshl_add_u64 v[0:1], v[0:1], 0, v[64:65]
	v_lshlrev_b64 v[8:9], 2, v[0:1]
	v_lshl_add_u64 v[0:1], s[16:17], 0, v[8:9]
	ds_read_b128 v[4:7], v114 offset:2176
	s_load_dwordx2 s[4:5], s[0:1], 0xb8
	s_waitcnt vmcnt(7) lgkmcnt(0)
	v_pk_add_f32 v[2:3], v[6:7], v[138:139]
	v_pk_add_f32 v[0:1], v[4:5], v[136:137]
	v_lshl_add_u64 v[4:5], s[4:5], 0, v[8:9]
	global_store_dwordx4 v[4:5], v[0:3], off offset:256
	s_or_b64 exec, exec, s[2:3]
	s_and_saveexec_b64 s[2:3], s[6:7]
	s_cbranch_execnz .LBB0_1338

.LBB0_1332:
	v_lshlrev_b64 v[0:1], 10, v[38:39]
	v_lshl_add_u64 v[0:1], v[0:1], 0, v[64:65]
	v_lshlrev_b64 v[8:9], 2, v[0:1]
	v_lshl_add_u64 v[0:1], s[16:17], 0, v[8:9]
	ds_read_b128 v[4:7], v114 offset:4352
	s_load_dwordx2 s[4:5], s[0:1], 0xb8
	s_waitcnt vmcnt(7) lgkmcnt(0)
	v_pk_add_f32 v[2:3], v[6:7], v[146:147]
	v_pk_add_f32 v[0:1], v[4:5], v[144:145]
	v_lshl_add_u64 v[4:5], s[4:5], 0, v[8:9]
	global_store_dwordx4 v[4:5], v[0:3], off offset:256
	s_or_b64 exec, exec, s[2:3]
	s_and_saveexec_b64 s[2:3], s[10:11]
	s_cbranch_execnz .LBB0_1340

.LBB0_1334:
	v_lshlrev_b64 v[0:1], 10, v[42:43]
	v_lshl_add_u64 v[0:1], v[0:1], 0, v[64:65]
	v_lshlrev_b64 v[8:9], 2, v[0:1]
	v_lshl_add_u64 v[0:1], s[16:17], 0, v[8:9]
	ds_read_b128 v[4:7], v114 offset:6528
	s_load_dwordx2 s[4:5], s[0:1], 0xb8
	s_waitcnt vmcnt(7) lgkmcnt(0)
	v_pk_add_f32 v[2:3], v[6:7], v[154:155]
	v_pk_add_f32 v[0:1], v[4:5], v[152:153]
	v_lshl_add_u64 v[4:5], s[4:5], 0, v[8:9]
	global_store_dwordx4 v[4:5], v[0:3], off offset:256
	s_or_b64 exec, exec, s[2:3]
	s_and_saveexec_b64 s[2:3], s[14:15]
	s_cbranch_execz .LBB0_1274
	s_branch .LBB0_1342

.LBB0_1336:
	v_lshlrev_b64 v[0:1], 10, v[32:33]
	v_lshl_add_u64 v[0:1], v[0:1], 0, v[64:65]
	v_lshlrev_b64 v[8:9], 2, v[0:1]
	v_lshl_add_u64 v[0:1], s[16:17], 0, v[8:9]
	ds_read_b128 v[4:7], v114 offset:1088
	s_load_dwordx2 s[2:3], s[0:1], 0xb8
	s_waitcnt vmcnt(7) lgkmcnt(0)
	v_pk_add_f32 v[2:3], v[6:7], v[134:135]
	v_pk_add_f32 v[0:1], v[4:5], v[132:133]
	v_lshl_add_u64 v[4:5], s[2:3], 0, v[8:9]
	global_store_dwordx4 v[4:5], v[0:3], off offset:256
	s_or_b64 exec, exec, s[24:25]
	s_and_saveexec_b64 s[2:3], s[4:5]
	s_cbranch_execnz .LBB0_1330

.LBB0_1338:
	v_lshlrev_b64 v[0:1], 10, v[36:37]
	v_lshl_add_u64 v[0:1], v[0:1], 0, v[64:65]
	v_lshlrev_b64 v[8:9], 2, v[0:1]
	v_lshl_add_u64 v[0:1], s[16:17], 0, v[8:9]
	ds_read_b128 v[4:7], v114 offset:3264
	s_load_dwordx2 s[4:5], s[0:1], 0xb8
	s_waitcnt vmcnt(7) lgkmcnt(0)
	v_pk_add_f32 v[2:3], v[6:7], v[142:143]
	v_pk_add_f32 v[0:1], v[4:5], v[140:141]
	v_lshl_add_u64 v[4:5], s[4:5], 0, v[8:9]
	global_store_dwordx4 v[4:5], v[0:3], off offset:256
	s_or_b64 exec, exec, s[2:3]
	s_and_saveexec_b64 s[2:3], s[8:9]
	s_cbranch_execnz .LBB0_1332

.LBB0_1340:
	v_lshlrev_b64 v[0:1], 10, v[40:41]
	v_lshl_add_u64 v[0:1], v[0:1], 0, v[64:65]
	v_lshlrev_b64 v[8:9], 2, v[0:1]
	v_lshl_add_u64 v[0:1], s[16:17], 0, v[8:9]
	ds_read_b128 v[4:7], v114 offset:5440
	s_load_dwordx2 s[4:5], s[0:1], 0xb8
	s_waitcnt vmcnt(7) lgkmcnt(0)
	v_pk_add_f32 v[2:3], v[6:7], v[150:151]
	v_pk_add_f32 v[0:1], v[4:5], v[148:149]
	v_lshl_add_u64 v[4:5], s[4:5], 0, v[8:9]
	global_store_dwordx4 v[4:5], v[0:3], off offset:256
	s_or_b64 exec, exec, s[2:3]
	s_and_saveexec_b64 s[2:3], s[12:13]
	s_cbranch_execnz .LBB0_1334

.LBB0_1342:
	v_lshlrev_b64 v[0:1], 10, v[44:45]
	v_lshl_add_u64 v[0:1], v[0:1], 0, v[64:65]
	v_lshlrev_b64 v[8:9], 2, v[0:1]
	v_lshl_add_u64 v[0:1], s[16:17], 0, v[8:9]
	ds_read_b128 v[4:7], v114 offset:7616
	s_load_dwordx2 s[4:5], s[0:1], 0xb8
	s_waitcnt vmcnt(7) lgkmcnt(0)
	v_pk_add_f32 v[2:3], v[6:7], v[158:159]
	v_pk_add_f32 v[0:1], v[4:5], v[156:157]
	v_lshl_add_u64 v[4:5], s[4:5], 0, v[8:9]
	global_store_dwordx4 v[4:5], v[0:3], off offset:256
	s_branch .LBB0_1274

.LBB0_1460:
	v_mbcnt_hi_u32_b32 v192, -1, v210
	s_load_dwordx2 s[2:3], s[0:1], 0x158
	s_load_dwordx2 s[4:5], s[0:1], 0x100
	s_ashr_i32 s7, s6, 31
	v_mov_b32_e32 v1, v192
	s_and_b32 s7, s7, s42
	s_add_i32 s8, s7, s6
	v_add_u32_e32 v0, s70, v1
	v_ashrrev_i32_e32 v193, 3, v0
	v_readfirstlane_b32 s9, v0
	v_lshlrev_b32_e32 v0, 3, v1
	v_and_b32_e32 v0, 56, v0
	s_cmpk_lt_i32 s8, 0x480
	s_cselect_b64 s[6:7], -1, 0
	s_cmpk_gt_i32 s8, 0x47f
	v_lshlrev_b32_e32 v160, 1, v0
	v_add_u32_e32 v194, 64, v193
	s_cbranch_scc1 .LBB0_1462
	s_mul_hi_i32 s10, s8, 0x38e38e39
	s_lshr_b32 s11, s10, 31
	s_ashr_i32 s10, s10, 1
	s_add_i32 s10, s10, s11
	s_mul_i32 s11, s10, -9
	s_lshl_b32 s10, s10, 8
	v_add_u32_e32 v2, s10, v193
	v_min_i32_e32 v2, 0x7fff, v2
	v_ashrrev_i32_e32 v3, 31, v2
	v_lshlrev_b64 v[2:3], 11, v[2:3]
	s_add_i32 s11, s11, s8
	s_waitcnt lgkmcnt(0)
	v_lshl_add_u64 v[2:3], s[2:3], 0, v[2:3]
	v_mov_b32_e32 v161, 0
	s_lshl_b32 s11, s11, 8
	v_lshl_add_u64 v[2:3], v[2:3], 0, v[160:161]
	v_mbcnt_hi_u32_b32 v158, -1, v210
	s_and_b32 s90, s70, 0x40
	v_and_b32_e32 v159, 48, v158
	v_or_b32_e32 v159, s90, v159
	s_lshl_b32 s88, s70, 4
	s_lshl_b32 s92, s22, 4
	s_and_b32 s92, s92, 0x780
	s_mov_b32 s93, 0
	s_add_u32 m0, s88, 0
	v_lshl_add_u64 v[2:3], v[2:3], 0, s[92:93]
	v_xor_b32_e32 v2, v159, v2
	global_load_lds_dwordx4 v[2:3], off
	v_add_u32_e32 v2, s11, v193
	v_ashrrev_i32_e32 v3, 31, v2
	v_lshlrev_b64 v[2:3], 11, v[2:3]
	v_lshl_add_u64 v[2:3], s[4:5], 0, v[2:3]
	v_lshl_add_u64 v[2:3], v[2:3], 0, v[160:161]
	s_add_u32 m0, s88, 32768
	v_lshl_add_u64 v[2:3], v[2:3], 0, s[92:93]
	v_xor_b32_e32 v2, v159, v2
	global_load_lds_dwordx4 v[2:3], off
	v_add_u32_e32 v2, s10, v194
	v_min_i32_e32 v2, 0x7fff, v2
	v_ashrrev_i32_e32 v3, 31, v2
	v_lshlrev_b64 v[2:3], 11, v[2:3]
	v_lshl_add_u64 v[2:3], s[2:3], 0, v[2:3]
	v_lshl_add_u64 v[2:3], v[2:3], 0, v[160:161]
	s_add_u32 m0, s88, 8192
	v_lshl_add_u64 v[2:3], v[2:3], 0, s[92:93]
	v_xor_b32_e32 v2, v159, v2
	global_load_lds_dwordx4 v[2:3], off
	v_add_u32_e32 v2, s11, v194
	v_ashrrev_i32_e32 v3, 31, v2
	v_lshlrev_b64 v[2:3], 11, v[2:3]
	v_lshl_add_u64 v[2:3], s[4:5], 0, v[2:3]
	v_lshl_add_u64 v[2:3], v[2:3], 0, v[160:161]
	v_add_u32_e32 v4, 0x80, v193
	s_add_u32 m0, s88, 40960
	v_lshl_add_u64 v[2:3], v[2:3], 0, s[92:93]
	v_xor_b32_e32 v2, v159, v2
	global_load_lds_dwordx4 v[2:3], off
	v_add_u32_e32 v2, s10, v4
	v_min_i32_e32 v2, 0x7fff, v2
	v_ashrrev_i32_e32 v3, 31, v2
	v_lshlrev_b64 v[2:3], 11, v[2:3]
	v_lshl_add_u64 v[2:3], s[2:3], 0, v[2:3]
	v_lshl_add_u64 v[2:3], v[2:3], 0, v[160:161]
	s_add_u32 m0, s88, 16384
	v_lshl_add_u64 v[2:3], v[2:3], 0, s[92:93]
	v_xor_b32_e32 v2, v159, v2
	global_load_lds_dwordx4 v[2:3], off
	v_add_u32_e32 v2, s11, v4
	v_ashrrev_i32_e32 v3, 31, v2
	v_lshlrev_b64 v[2:3], 11, v[2:3]
	v_lshl_add_u64 v[2:3], s[4:5], 0, v[2:3]
	v_lshl_add_u64 v[2:3], v[2:3], 0, v[160:161]
	v_add_u32_e32 v4, 0xc0, v193
	s_add_u32 m0, s88, 49152
	v_lshl_add_u64 v[2:3], v[2:3], 0, s[92:93]
	v_xor_b32_e32 v2, v159, v2
	global_load_lds_dwordx4 v[2:3], off
	v_add_u32_e32 v2, s10, v4
	v_min_i32_e32 v2, 0x7fff, v2
	v_ashrrev_i32_e32 v3, 31, v2
	v_lshlrev_b64 v[2:3], 11, v[2:3]
	v_lshl_add_u64 v[2:3], s[2:3], 0, v[2:3]
	v_lshl_add_u64 v[2:3], v[2:3], 0, v[160:161]
	s_add_u32 m0, s88, 24576
	v_lshl_add_u64 v[2:3], v[2:3], 0, s[92:93]
	v_xor_b32_e32 v2, v159, v2
	global_load_lds_dwordx4 v[2:3], off
	v_add_u32_e32 v2, s11, v4
	v_ashrrev_i32_e32 v3, 31, v2
	v_lshlrev_b64 v[2:3], 11, v[2:3]
	v_lshl_add_u64 v[2:3], s[4:5], 0, v[2:3]
	v_lshl_add_u64 v[2:3], v[2:3], 0, v[160:161]
	s_add_u32 m0, s88, 57344
	v_lshl_add_u64 v[2:3], v[2:3], 0, s[92:93]
	v_xor_b32_e32 v2, v159, v2
	global_load_lds_dwordx4 v[2:3], off

.LBB0_1466:
	s_mul_hi_i32 s2, s8, 0x38e38e39
	s_lshr_b32 s3, s2, 31
	s_ashr_i32 s4, s2, 1
	s_add_i32 s4, s4, s3
	s_lshl_b32 s77, s4, 8
	v_add_u32_e32 v0, s77, v193
	v_min_i32_e32 v0, 0x7fff, v0
	v_ashrrev_i32_e32 v1, 31, v0
	v_lshlrev_b64 v[0:1], 11, v[0:1]
	s_mul_i32 s2, s4, 0x900
	v_lshl_add_u64 v[172:173], v[168:169], 0, v[0:1]
	v_subrev_u32_e32 v0, s2, v201
	v_ashrrev_i32_e32 v1, 31, v0
	v_lshlrev_b64 v[0:1], 11, v[0:1]
	v_lshl_add_u64 v[180:181], v[170:171], 0, v[0:1]
	v_subrev_u32_e32 v0, s2, v202
	v_ashrrev_i32_e32 v1, 31, v0
	v_lshlrev_b64 v[0:1], 11, v[0:1]
	v_lshl_add_u64 v[182:183], v[170:171], 0, v[0:1]
	v_subrev_u32_e32 v0, s2, v203
	v_ashrrev_i32_e32 v1, 31, v0
	v_add_u32_e32 v2, s77, v194
	v_add_u32_e32 v4, s77, v163
	v_add_u32_e32 v6, s77, v196
	v_lshlrev_b64 v[0:1], 11, v[0:1]
	v_min_i32_e32 v2, 0x7fff, v2
	v_min_i32_e32 v4, 0x7fff, v4
	v_min_i32_e32 v6, 0x7fff, v6
	v_lshl_add_u64 v[184:185], v[170:171], 0, v[0:1]
	v_subrev_u32_e32 v0, s2, v204
	v_ashrrev_i32_e32 v3, 31, v2
	v_ashrrev_i32_e32 v5, 31, v4
	v_ashrrev_i32_e32 v7, 31, v6
	v_ashrrev_i32_e32 v1, 31, v0
	v_lshlrev_b64 v[2:3], 11, v[2:3]
	v_lshlrev_b64 v[4:5], 11, v[4:5]
	v_lshlrev_b64 v[6:7], 11, v[6:7]
	v_lshlrev_b64 v[0:1], 11, v[0:1]
	v_lshl_add_u64 v[174:175], v[168:169], 0, v[2:3]
	v_lshl_add_u64 v[176:177], v[168:169], 0, v[4:5]
	v_lshl_add_u64 v[178:179], v[168:169], 0, v[6:7]
	v_lshl_add_u64 v[186:187], v[170:171], 0, v[0:1]
	s_mov_b64 s[2:3], 0
	s_mov_b32 s5, s25
	v_mov_b32_e32 v0, 0
	v_mov_b32_e32 v1, v161
	v_mov_b32_e32 v2, v161
	v_mov_b32_e32 v3, v161
	v_mov_b32_e32 v4, v161
	v_mov_b32_e32 v5, v161
	v_mov_b32_e32 v6, v161
	v_mov_b32_e32 v7, v161
	v_mov_b32_e32 v8, v161
	v_mov_b32_e32 v9, v161
	v_mov_b32_e32 v10, v161
	v_mov_b32_e32 v11, v161
	v_mov_b32_e32 v12, v161
	v_mov_b32_e32 v13, v161
	v_mov_b32_e32 v14, v161
	v_mov_b32_e32 v15, v161
	v_mov_b32_e32 v16, 0
	v_mov_b32_e32 v17, v161
	v_mov_b32_e32 v18, v161
	v_mov_b32_e32 v19, v161
	v_mov_b32_e32 v20, v161
	v_mov_b32_e32 v21, v161
	v_mov_b32_e32 v22, v161
	v_mov_b32_e32 v23, v161
	v_mov_b32_e32 v24, v161
	v_mov_b32_e32 v25, v161
	v_mov_b32_e32 v26, v161
	v_mov_b32_e32 v27, v161
	v_mov_b32_e32 v28, v161
	v_mov_b32_e32 v29, v161
	v_mov_b32_e32 v30, v161
	v_mov_b32_e32 v31, v161
	v_mov_b32_e32 v32, 0
	v_mov_b32_e32 v33, v161
	v_mov_b32_e32 v34, v161
	v_mov_b32_e32 v35, v161
	v_mov_b32_e32 v36, v161
	v_mov_b32_e32 v37, v161
	v_mov_b32_e32 v38, v161
	v_mov_b32_e32 v39, v161
	v_mov_b32_e32 v40, v161
	v_mov_b32_e32 v41, v161
	v_mov_b32_e32 v42, v161
	v_mov_b32_e32 v43, v161
	v_mov_b32_e32 v44, v161
	v_mov_b32_e32 v45, v161
	v_mov_b32_e32 v46, v161
	v_mov_b32_e32 v47, v161
	v_mov_b32_e32 v48, 0
	v_mov_b32_e32 v49, v161
	v_mov_b32_e32 v50, v161
	v_mov_b32_e32 v51, v161
	v_mov_b32_e32 v52, v161
	v_mov_b32_e32 v53, v161
	v_mov_b32_e32 v54, v161
	v_mov_b32_e32 v55, v161
	v_mov_b32_e32 v56, v161
	v_mov_b32_e32 v57, v161
	v_mov_b32_e32 v58, v161
	v_mov_b32_e32 v59, v161
	v_mov_b32_e32 v60, v161
	v_mov_b32_e32 v61, v161
	v_mov_b32_e32 v62, v161
	v_mov_b32_e32 v63, v161
	v_mov_b32_e32 v64, 0
	v_mov_b32_e32 v65, v161
	v_mov_b32_e32 v66, v161
	v_mov_b32_e32 v67, v161
	v_mov_b32_e32 v68, v161
	v_mov_b32_e32 v69, v161
	v_mov_b32_e32 v70, v161
	v_mov_b32_e32 v71, v161
	v_mov_b32_e32 v72, v161
	v_mov_b32_e32 v73, v161
	v_mov_b32_e32 v74, v161
	v_mov_b32_e32 v75, v161
	v_mov_b32_e32 v76, v161
	v_mov_b32_e32 v77, v161
	v_mov_b32_e32 v78, v161
	v_mov_b32_e32 v79, v161
	v_mov_b32_e32 v80, 0
	v_mov_b32_e32 v81, v161
	v_mov_b32_e32 v82, v161
	v_mov_b32_e32 v83, v161
	v_mov_b32_e32 v84, v161
	v_mov_b32_e32 v85, v161
	v_mov_b32_e32 v86, v161
	v_mov_b32_e32 v87, v161
	v_mov_b32_e32 v88, v161
	v_mov_b32_e32 v89, v161
	v_mov_b32_e32 v90, v161
	v_mov_b32_e32 v91, v161
	v_mov_b32_e32 v92, v161
	v_mov_b32_e32 v93, v161
	v_mov_b32_e32 v94, v161
	v_mov_b32_e32 v95, v161
	v_mov_b32_e32 v96, 0
	v_mov_b32_e32 v97, v161
	v_mov_b32_e32 v98, v161
	v_mov_b32_e32 v99, v161
	v_mov_b32_e32 v100, v161
	v_mov_b32_e32 v101, v161
	v_mov_b32_e32 v102, v161
	v_mov_b32_e32 v103, v161
	v_mov_b32_e32 v104, v161
	v_mov_b32_e32 v105, v161
	v_mov_b32_e32 v106, v161
	v_mov_b32_e32 v107, v161
	v_mov_b32_e32 v108, v161
	v_mov_b32_e32 v109, v161
	v_mov_b32_e32 v110, v161
	v_mov_b32_e32 v111, v161
	v_mov_b32_e32 v112, 0
	v_mov_b32_e32 v113, v161
	v_mov_b32_e32 v114, v161
	v_mov_b32_e32 v115, v161
	v_mov_b32_e32 v116, v161
	v_mov_b32_e32 v117, v161
	v_mov_b32_e32 v118, v161
	v_mov_b32_e32 v119, v161
	v_mov_b32_e32 v120, v161
	v_mov_b32_e32 v121, v161
	v_mov_b32_e32 v122, v161
	v_mov_b32_e32 v123, v161
	v_mov_b32_e32 v124, v161
	v_mov_b32_e32 v125, v161
	v_mov_b32_e32 v126, v161
	v_mov_b32_e32 v127, v161
	v_mbcnt_hi_u32_b32 v128, -1, v210
	s_and_b32 s90, s70, 0x40
	v_and_b32_e32 v159, 48, v128
	v_or_b32_e32 v159, s90, v159
	v_and_b32_e32 v129, 31, v128
	v_lshrrev_b32_e32 v130, 5, v128
	v_bfe_u32 v131, v128, 1, 3
	v_lshlrev_b32_e32 v132, 7, v129
	s_lshr_b32 s91, s70, 7
	s_lshl_b32 s91, s91, 13
	s_lshl_b32 s90, s90, 8
	s_add_u32 s90, s90, 0x8000
	s_lshl_b32 s88, s70, 4
	s_mov_b32 s89, 0x10000
	s_lshl_b32 s92, s22, 4
	s_and_b32 s92, s92, 0x780
	s_mov_b32 s93, 0
	v_xor_b32_e32 v133, v130, v131
	v_lshl_add_u32 v133, v133, 4, v132
	v_add_u32_e32 v232, s91, v133
	v_add_u32_e32 v236, s90, v133
	v_or_b32_e32 v133, 2, v130
	v_xor_b32_e32 v133, v133, v131
	v_lshl_add_u32 v133, v133, 4, v132
	v_add_u32_e32 v233, s91, v133
	v_add_u32_e32 v237, s90, v133
	v_or_b32_e32 v133, 4, v130
	v_xor_b32_e32 v133, v133, v131
	v_lshl_add_u32 v133, v133, 4, v132
	v_add_u32_e32 v234, s91, v133
	v_add_u32_e32 v238, s90, v133
	v_or_b32_e32 v133, 6, v130
	v_xor_b32_e32 v133, v133, v131
	v_lshl_add_u32 v133, v133, 4, v132
	v_add_u32_e32 v235, s91, v133
	v_add_u32_e32 v239, s90, v133
	s_waitcnt vmcnt(0)
	s_barrier
	ds_read_b128 v[188:191], v232
	ds_read_b128 v[216:219], v236
	ds_read_b128 v[212:215], v232 offset:4096
	ds_read_b128 v[220:223], v236 offset:4096
	ds_read_b128 v[224:227], v236 offset:8192
	ds_read_b128 v[228:231], v236 offset:12288
	s_add_u32 s94, s2, s92
	s_add_u32 s94, s94, 0x80
	s_and_b32 s94, s94, 0x780
	s_sub_u32 s94, s94, 0x80
	s_subb_u32 s95, 0, 0
	s_add_u32 s90, s88, s89
	s_add_u32 m0, s90, 0
	v_lshl_add_u64 v[152:153], v[172:173], 0, s[94:95]
	v_xor_b32_e32 v152, v159, v152
	global_load_lds_dwordx4 v[152:153], off
	s_add_u32 m0, s90, 32768
	v_lshl_add_u64 v[154:155], v[180:181], 0, s[94:95]
	v_xor_b32_e32 v154, v159, v154
	global_load_lds_dwordx4 v[154:155], off
	s_add_u32 m0, s90, 8192
	v_lshl_add_u64 v[156:157], v[174:175], 0, s[94:95]
	v_xor_b32_e32 v156, v159, v156
	global_load_lds_dwordx4 v[156:157], off
	s_add_u32 m0, s90, 40960
	v_lshl_add_u64 v[152:153], v[182:183], 0, s[94:95]
	v_xor_b32_e32 v152, v159, v152
	global_load_lds_dwordx4 v[152:153], off
	s_add_u32 m0, s90, 16384
	v_lshl_add_u64 v[154:155], v[176:177], 0, s[94:95]
	v_xor_b32_e32 v154, v159, v154
	global_load_lds_dwordx4 v[154:155], off
	s_add_u32 m0, s90, 49152
	v_lshl_add_u64 v[156:157], v[184:185], 0, s[94:95]
	v_xor_b32_e32 v156, v159, v156
	global_load_lds_dwordx4 v[156:157], off
	s_add_u32 m0, s90, 24576
	v_lshl_add_u64 v[152:153], v[178:179], 0, s[94:95]
	v_xor_b32_e32 v152, v159, v152
	global_load_lds_dwordx4 v[152:153], off
	s_add_u32 m0, s90, 57344
	v_lshl_add_u64 v[154:155], v[186:187], 0, s[94:95]
	v_xor_b32_e32 v154, v159, v154
	global_load_lds_dwordx4 v[154:155], off
	s_xor_b32 s89, s89, 0x10000
.Lgk2_loop:
	ds_read_b128 v[128:131], v233
	ds_read_b128 v[136:139], v237
	ds_read_b128 v[132:135], v233 offset:4096
	ds_read_b128 v[140:143], v237 offset:4096
	ds_read_b128 v[144:147], v237 offset:8192
	ds_read_b128 v[148:151], v237 offset:12288
	s_waitcnt lgkmcnt(6)
	v_mfma_f32_32x32x16_bf16 v[112:127], v[188:191], v[216:219], v[112:127]
	v_mfma_f32_32x32x16_bf16 v[48:63], v[212:215], v[216:219], v[48:63]
	v_mfma_f32_32x32x16_bf16 v[96:111], v[188:191], v[220:223], v[96:111]
	v_mfma_f32_32x32x16_bf16 v[32:47], v[212:215], v[220:223], v[32:47]
	v_mfma_f32_32x32x16_bf16 v[80:95], v[188:191], v[224:227], v[80:95]
	v_mfma_f32_32x32x16_bf16 v[16:31], v[212:215], v[224:227], v[16:31]
	v_mfma_f32_32x32x16_bf16 v[64:79], v[188:191], v[228:231], v[64:79]
	v_mfma_f32_32x32x16_bf16 v[0:15], v[212:215], v[228:231], v[0:15]
	ds_read_b128 v[188:191], v234
	ds_read_b128 v[216:219], v238
	ds_read_b128 v[212:215], v234 offset:4096
	ds_read_b128 v[220:223], v238 offset:4096
	ds_read_b128 v[224:227], v238 offset:8192
	ds_read_b128 v[228:231], v238 offset:12288
	s_waitcnt lgkmcnt(6)
	v_mfma_f32_32x32x16_bf16 v[112:127], v[128:131], v[136:139], v[112:127]
	v_mfma_f32_32x32x16_bf16 v[48:63], v[132:135], v[136:139], v[48:63]
	v_mfma_f32_32x32x16_bf16 v[96:111], v[128:131], v[140:143], v[96:111]
	v_mfma_f32_32x32x16_bf16 v[32:47], v[132:135], v[140:143], v[32:47]
	v_mfma_f32_32x32x16_bf16 v[80:95], v[128:131], v[144:147], v[80:95]
	v_mfma_f32_32x32x16_bf16 v[16:31], v[132:135], v[144:147], v[16:31]
	v_mfma_f32_32x32x16_bf16 v[64:79], v[128:131], v[148:151], v[64:79]
	v_mfma_f32_32x32x16_bf16 v[0:15], v[132:135], v[148:151], v[0:15]
	ds_read_b128 v[128:131], v235
	ds_read_b128 v[136:139], v239
	ds_read_b128 v[132:135], v235 offset:4096
	ds_read_b128 v[140:143], v239 offset:4096
	ds_read_b128 v[144:147], v239 offset:8192
	ds_read_b128 v[148:151], v239 offset:12288
	s_waitcnt lgkmcnt(6)
	v_mfma_f32_32x32x16_bf16 v[112:127], v[188:191], v[216:219], v[112:127]
	v_mfma_f32_32x32x16_bf16 v[48:63], v[212:215], v[216:219], v[48:63]
	v_mfma_f32_32x32x16_bf16 v[96:111], v[188:191], v[220:223], v[96:111]
	v_mfma_f32_32x32x16_bf16 v[32:47], v[212:215], v[220:223], v[32:47]
	v_mfma_f32_32x32x16_bf16 v[80:95], v[188:191], v[224:227], v[80:95]
	v_mfma_f32_32x32x16_bf16 v[16:31], v[212:215], v[224:227], v[16:31]
	v_mfma_f32_32x32x16_bf16 v[64:79], v[188:191], v[228:231], v[64:79]
	v_mfma_f32_32x32x16_bf16 v[0:15], v[212:215], v[228:231], v[0:15]
	s_waitcnt vmcnt(0) lgkmcnt(0)
	s_barrier
	v_xor_b32_e32 v232, 0x10000, v232
	v_xor_b32_e32 v236, 0x10000, v236
	ds_read_b128 v[188:191], v232
	ds_read_b128 v[216:219], v236
	ds_read_b128 v[212:215], v232 offset:4096
	ds_read_b128 v[220:223], v236 offset:4096
	ds_read_b128 v[224:227], v236 offset:8192
	ds_read_b128 v[228:231], v236 offset:12288
	s_cmpk_eq_i32 s2, 0x700
	s_cbranch_scc1 .Lgk2_nodma
	s_add_u32 s94, s2, s92
	s_add_u32 s94, s94, 0x100
	s_and_b32 s94, s94, 0x780
	s_sub_u32 s94, s94, 0x80
	s_subb_u32 s95, 0, 0
	s_add_u32 s90, s88, s89
	v_mfma_f32_32x32x16_bf16 v[112:127], v[128:131], v[136:139], v[112:127]
	v_xor_b32_e32 v233, 0x10000, v233
	v_xor_b32_e32 v237, 0x10000, v237
	s_add_u32 m0, s90, 0
	v_lshl_add_u64 v[152:153], v[172:173], 0, s[94:95]
	v_xor_b32_e32 v152, v159, v152
	global_load_lds_dwordx4 v[152:153], off
	v_mfma_f32_32x32x16_bf16 v[48:63], v[132:135], v[136:139], v[48:63]
	v_xor_b32_e32 v234, 0x10000, v234
	v_xor_b32_e32 v238, 0x10000, v238
	s_add_u32 m0, s90, 32768
	v_lshl_add_u64 v[154:155], v[180:181], 0, s[94:95]
	v_xor_b32_e32 v154, v159, v154
	global_load_lds_dwordx4 v[154:155], off
	v_mfma_f32_32x32x16_bf16 v[96:111], v[128:131], v[140:143], v[96:111]
	v_xor_b32_e32 v235, 0x10000, v235
	v_xor_b32_e32 v239, 0x10000, v239
	s_add_u32 m0, s90, 8192
	v_lshl_add_u64 v[156:157], v[174:175], 0, s[94:95]
	v_xor_b32_e32 v156, v159, v156
	global_load_lds_dwordx4 v[156:157], off
	v_mfma_f32_32x32x16_bf16 v[32:47], v[132:135], v[140:143], v[32:47]
	s_add_u32 m0, s90, 40960
	v_lshl_add_u64 v[152:153], v[182:183], 0, s[94:95]
	v_xor_b32_e32 v152, v159, v152
	global_load_lds_dwordx4 v[152:153], off
	v_mfma_f32_32x32x16_bf16 v[80:95], v[128:131], v[144:147], v[80:95]
	s_add_u32 m0, s90, 16384
	v_lshl_add_u64 v[154:155], v[176:177], 0, s[94:95]
	v_xor_b32_e32 v154, v159, v154
	global_load_lds_dwordx4 v[154:155], off
	v_mfma_f32_32x32x16_bf16 v[16:31], v[132:135], v[144:147], v[16:31]
	s_add_u32 m0, s90, 49152
	v_lshl_add_u64 v[156:157], v[184:185], 0, s[94:95]
	v_xor_b32_e32 v156, v159, v156
	global_load_lds_dwordx4 v[156:157], off
	v_mfma_f32_32x32x16_bf16 v[64:79], v[128:131], v[148:151], v[64:79]
	s_add_u32 m0, s90, 24576
	v_lshl_add_u64 v[152:153], v[178:179], 0, s[94:95]
	v_xor_b32_e32 v152, v159, v152
	global_load_lds_dwordx4 v[152:153], off
	v_mfma_f32_32x32x16_bf16 v[0:15], v[132:135], v[148:151], v[0:15]
	s_add_u32 m0, s90, 57344
	v_lshl_add_u64 v[154:155], v[186:187], 0, s[94:95]
	v_xor_b32_e32 v154, v159, v154
	global_load_lds_dwordx4 v[154:155], off
	s_branch .Lgk2_join

.Lgk2_join:
	s_xor_b32 s89, s89, 0x10000
	s_add_i32 s5, s5, 1
	s_add_u32 s2, s2, 0x80
	s_addc_u32 s3, s3, 0
	s_cmpk_eq_i32 s2, 0x780
	s_cbranch_scc0 .Lgk2_loop
	s_add_i32 s76, s8, s42
	s_cmpk_gt_i32 s76, 0x47f
	s_cselect_b64 s[50:51], -1, 0
	s_and_b64 vcc, exec, s[50:51]
	s_cbranch_vccnz .LBB0_1470
	s_mul_hi_i32 s2, s76, 0x38e38e39
	s_lshr_b32 s3, s2, 31
	s_ashr_i32 s2, s2, 1
	s_add_i32 s2, s2, s3
	s_mul_i32 s3, s2, -9
	s_lshl_b32 s2, s2, 8
	v_add_u32_e32 v129, s2, v194
	s_add_i32 s3, s3, s76
	v_min_i32_e32 v132, 0x7fff, v129
	v_add_u32_e32 v129, s2, v163
	s_lshl_b32 s3, s3, 8
	v_add_u32_e32 v128, s2, v193
	v_min_i32_e32 v136, 0x7fff, v129
	v_add_u32_e32 v129, s2, v196
	v_min_i32_e32 v128, 0x7fff, v128
	v_add_u32_e32 v130, s3, v193
	v_add_u32_e32 v134, s3, v194
	v_add_u32_e32 v138, s3, v163
	v_min_i32_e32 v140, 0x7fff, v129
	v_add_u32_e32 v142, s3, v196
	v_ashrrev_i32_e32 v143, 31, v142
	v_ashrrev_i32_e32 v141, 31, v140
	v_ashrrev_i32_e32 v139, 31, v138
	v_ashrrev_i32_e32 v137, 31, v136
	v_ashrrev_i32_e32 v135, 31, v134
	v_ashrrev_i32_e32 v133, 31, v132
	v_ashrrev_i32_e32 v131, 31, v130
	v_ashrrev_i32_e32 v129, 31, v128
	v_lshlrev_b64 v[142:143], 11, v[142:143]
	v_lshlrev_b64 v[140:141], 11, v[140:141]
	v_lshlrev_b64 v[138:139], 11, v[138:139]
	v_lshlrev_b64 v[136:137], 11, v[136:137]
	v_lshlrev_b64 v[134:135], 11, v[134:135]
	v_lshlrev_b64 v[132:133], 11, v[132:133]
	v_lshlrev_b64 v[130:131], 11, v[130:131]
	v_lshlrev_b64 v[128:129], 11, v[128:129]
	v_lshl_add_u64 v[156:157], v[164:165], 0, v[142:143]
	v_lshl_add_u64 v[152:153], v[166:167], 0, v[140:141]
	v_lshl_add_u64 v[148:149], v[164:165], 0, v[138:139]
	v_lshl_add_u64 v[144:145], v[166:167], 0, v[136:137]
	v_lshl_add_u64 v[140:141], v[164:165], 0, v[134:135]
	v_lshl_add_u64 v[136:137], v[166:167], 0, v[132:133]
	v_lshl_add_u64 v[132:133], v[164:165], 0, v[130:131]
	v_lshl_add_u64 v[128:129], v[166:167], 0, v[128:129]
	s_add_u32 m0, s88, 0
	v_lshl_add_u64 v[128:129], v[128:129], 0, s[92:93]
	v_xor_b32_e32 v128, v159, v128
	global_load_lds_dwordx4 v[128:129], off
	s_add_u32 m0, s88, 32768
	v_lshl_add_u64 v[132:133], v[132:133], 0, s[92:93]
	v_xor_b32_e32 v132, v159, v132
	global_load_lds_dwordx4 v[132:133], off
	s_add_u32 m0, s88, 8192
	v_lshl_add_u64 v[136:137], v[136:137], 0, s[92:93]
	v_xor_b32_e32 v136, v159, v136
	global_load_lds_dwordx4 v[136:137], off
	s_add_u32 m0, s88, 40960
	v_lshl_add_u64 v[140:141], v[140:141], 0, s[92:93]
	v_xor_b32_e32 v140, v159, v140
	global_load_lds_dwordx4 v[140:141], off
	s_add_u32 m0, s88, 16384
	v_lshl_add_u64 v[144:145], v[144:145], 0, s[92:93]
	v_xor_b32_e32 v144, v159, v144
	global_load_lds_dwordx4 v[144:145], off
	s_add_u32 m0, s88, 49152
	v_lshl_add_u64 v[148:149], v[148:149], 0, s[92:93]
	v_xor_b32_e32 v148, v159, v148
	global_load_lds_dwordx4 v[148:149], off
	s_add_u32 m0, s88, 24576
	v_lshl_add_u64 v[152:153], v[152:153], 0, s[92:93]
	v_xor_b32_e32 v152, v159, v152
	global_load_lds_dwordx4 v[152:153], off
	s_add_u32 m0, s88, 57344
	v_lshl_add_u64 v[156:157], v[156:157], 0, s[92:93]
	v_xor_b32_e32 v156, v159, v156
	global_load_lds_dwordx4 v[156:157], off
.LBB0_1470:
	ds_read_b128 v[128:131], v233
	ds_read_b128 v[136:139], v237
	ds_read_b128 v[132:135], v233 offset:4096
	ds_read_b128 v[140:143], v237 offset:4096
	ds_read_b128 v[144:147], v237 offset:8192
	ds_read_b128 v[148:151], v237 offset:12288
	s_waitcnt lgkmcnt(6)
	v_mfma_f32_32x32x16_bf16 v[112:127], v[188:191], v[216:219], v[112:127]
	v_mfma_f32_32x32x16_bf16 v[48:63], v[212:215], v[216:219], v[48:63]
	v_mfma_f32_32x32x16_bf16 v[96:111], v[188:191], v[220:223], v[96:111]
	v_mfma_f32_32x32x16_bf16 v[32:47], v[212:215], v[220:223], v[32:47]
	v_mfma_f32_32x32x16_bf16 v[80:95], v[188:191], v[224:227], v[80:95]
	v_mfma_f32_32x32x16_bf16 v[16:31], v[212:215], v[224:227], v[16:31]
	v_mfma_f32_32x32x16_bf16 v[64:79], v[188:191], v[228:231], v[64:79]
	v_mfma_f32_32x32x16_bf16 v[0:15], v[212:215], v[228:231], v[0:15]
	ds_read_b128 v[188:191], v234
	ds_read_b128 v[216:219], v238
	ds_read_b128 v[212:215], v234 offset:4096
	ds_read_b128 v[220:223], v238 offset:4096
	ds_read_b128 v[224:227], v238 offset:8192
	ds_read_b128 v[228:231], v238 offset:12288
	s_waitcnt lgkmcnt(6)
	v_mfma_f32_32x32x16_bf16 v[112:127], v[128:131], v[136:139], v[112:127]
	v_mfma_f32_32x32x16_bf16 v[48:63], v[132:135], v[136:139], v[48:63]
	v_mfma_f32_32x32x16_bf16 v[96:111], v[128:131], v[140:143], v[96:111]
	v_mfma_f32_32x32x16_bf16 v[32:47], v[132:135], v[140:143], v[32:47]
	v_mfma_f32_32x32x16_bf16 v[80:95], v[128:131], v[144:147], v[80:95]
	v_mfma_f32_32x32x16_bf16 v[16:31], v[132:135], v[144:147], v[16:31]
	v_mfma_f32_32x32x16_bf16 v[64:79], v[128:131], v[148:151], v[64:79]
	v_mfma_f32_32x32x16_bf16 v[0:15], v[132:135], v[148:151], v[0:15]
	ds_read_b128 v[128:131], v235
	ds_read_b128 v[136:139], v239
	ds_read_b128 v[132:135], v235 offset:4096
	ds_read_b128 v[140:143], v239 offset:4096
	ds_read_b128 v[144:147], v239 offset:8192
	ds_read_b128 v[148:151], v239 offset:12288
	s_waitcnt lgkmcnt(6)
	v_mfma_f32_32x32x16_bf16 v[112:127], v[188:191], v[216:219], v[112:127]
	v_mfma_f32_32x32x16_bf16 v[48:63], v[212:215], v[216:219], v[48:63]
	v_mfma_f32_32x32x16_bf16 v[96:111], v[188:191], v[220:223], v[96:111]
	v_mfma_f32_32x32x16_bf16 v[32:47], v[212:215], v[220:223], v[32:47]
	v_mfma_f32_32x32x16_bf16 v[80:95], v[188:191], v[224:227], v[80:95]
	v_mfma_f32_32x32x16_bf16 v[16:31], v[212:215], v[224:227], v[16:31]
	v_mfma_f32_32x32x16_bf16 v[64:79], v[188:191], v[228:231], v[64:79]
	v_mfma_f32_32x32x16_bf16 v[0:15], v[212:215], v[228:231], v[0:15]
	s_waitcnt lgkmcnt(0)
	s_barrier
	v_xor_b32_e32 v232, 0x10000, v232
	v_xor_b32_e32 v236, 0x10000, v236
	v_mfma_f32_32x32x16_bf16 v[112:127], v[128:131], v[136:139], v[112:127]
	v_xor_b32_e32 v233, 0x10000, v233
	v_xor_b32_e32 v237, 0x10000, v237
	v_mfma_f32_32x32x16_bf16 v[48:63], v[132:135], v[136:139], v[48:63]
	v_xor_b32_e32 v234, 0x10000, v234
	v_xor_b32_e32 v238, 0x10000, v238
	v_mfma_f32_32x32x16_bf16 v[96:111], v[128:131], v[140:143], v[96:111]
	v_xor_b32_e32 v235, 0x10000, v235
	v_xor_b32_e32 v239, 0x10000, v239
	v_mfma_f32_32x32x16_bf16 v[32:47], v[132:135], v[140:143], v[32:47]
	v_mfma_f32_32x32x16_bf16 v[80:95], v[128:131], v[144:147], v[80:95]
	v_mfma_f32_32x32x16_bf16 v[16:31], v[132:135], v[144:147], v[16:31]
	v_mfma_f32_32x32x16_bf16 v[64:79], v[128:131], v[148:151], v[64:79]
	v_mfma_f32_32x32x16_bf16 v[0:15], v[132:135], v[148:151], v[0:15]
	s_mul_i32 s2, s4, -9
	s_add_i32 s2, s2, s8
	s_lshl_b32 s2, s2, 8
	s_or_b32 s24, s2, s66
	s_ashr_i32 s58, s24, 6
	s_cmp_gt_i32 s58, 17
	s_cselect_b64 s[10:11], -1, 0
	s_cmp_gt_u32 s58, 19
	s_cselect_b64 s[2:3], -1, 0
	s_cmp_gt_i32 s58, 15
	s_cselect_b64 s[8:9], -1, 0
	s_cmp_lt_i32 s58, 16
	v_mov_b32_e32 v160, v195
	s_cselect_b64 s[4:5], -1, 0
	s_mov_b64 s[6:7], -1
	s_and_b64 vcc, exec, s[10:11]
	v_cndmask_b32_e64 v172, 0, 1, s[2:3]
	v_cmp_ne_u32_e64 s[2:3], 1, v172
	s_nop 3
	s_cbranch_vccz .LBB0_1474
	s_nop 3
	v_mov_b32_e32 v178, v112
	s_and_b64 vcc, exec, s[2:3]
	v_mov_b32_e32 v179, v96
	s_cbranch_vccnz .LBB0_1473
	v_mul_f32_e32 v172, 0xbfb8aa3b, v112
	v_mul_f32_e32 v173, 0xbfb8aa3b, v96
	v_exp_f32_e32 v172, v172
	v_exp_f32_e32 v173, v173
	v_add_f32_e32 v172, 1.0, v172
	v_add_f32_e32 v173, 1.0, v173
	v_rcp_f32_e32 v172, v172
	v_rcp_f32_e32 v173, v173
	s_nop 0
	v_pk_mul_f32 v[178:179], v[178:179], v[172:173]

.LBB0_2214:
	v_mbcnt_hi_u32_b32 v211, -1, v210
	s_load_dwordx2 s[2:3], s[0:1], 0x108
	s_load_dwordx2 s[4:5], s[0:1], 0x158
	s_ashr_i32 s7, s6, 31
	v_mov_b32_e32 v1, v211
	s_and_b32 s7, s7, s42
	s_add_i32 s54, s7, s6
	v_add_u32_e32 v0, s70, v1
	v_ashrrev_i32_e32 v212, 3, v0
	v_readfirstlane_b32 s8, v0
	v_lshlrev_b32_e32 v0, 3, v1
	v_and_b32_e32 v0, 56, v0
	s_cmpk_lt_i32 s54, 0x200
	s_cselect_b64 s[6:7], -1, 0
	s_cmpk_gt_i32 s54, 0x1ff
	v_lshlrev_b32_e32 v168, 1, v0
	v_add_u32_e32 v213, 64, v212
	s_cbranch_scc1 .LBB0_2216
	s_ashr_i32 s9, s54, 31
	s_lshr_b32 s9, s9, 30
	s_add_i32 s9, s54, s9
	s_ashr_i32 s9, s9, 2
	s_lshl_b32 s10, s9, 8
	v_add_u32_e32 v2, s10, v212
	v_min_i32_e32 v2, 0x7fff, v2
	v_ashrrev_i32_e32 v3, 31, v2
	v_lshlrev_b64 v[2:3], 11, v[2:3]
	s_lshl_b32 s9, s9, 10
	s_lshl_b32 s11, s54, 8
	s_waitcnt lgkmcnt(0)
	v_lshl_add_u64 v[2:3], s[4:5], 0, v[2:3]
	v_mov_b32_e32 v169, 0
	s_sub_i32 s9, s11, s9
	v_lshl_add_u64 v[2:3], v[2:3], 0, v[168:169]
	v_mbcnt_hi_u32_b32 v158, -1, v210
	s_and_b32 s90, s70, 0x40
	v_and_b32_e32 v159, 48, v158
	v_or_b32_e32 v159, s90, v159
	s_lshl_b32 s88, s70, 4
	s_lshl_b32 s92, s22, 4
	s_and_b32 s92, s92, 0x780
	s_mov_b32 s93, 0
	s_add_u32 m0, s88, 0
	v_lshl_add_u64 v[2:3], v[2:3], 0, s[92:93]
	v_xor_b32_e32 v2, v159, v2
	global_load_lds_dwordx4 v[2:3], off
	v_add_u32_e32 v2, s9, v212
	v_ashrrev_i32_e32 v3, 31, v2
	v_lshlrev_b64 v[2:3], 11, v[2:3]
	v_lshl_add_u64 v[2:3], s[2:3], 0, v[2:3]
	v_lshl_add_u64 v[2:3], v[2:3], 0, v[168:169]
	s_add_u32 m0, s88, 32768
	v_lshl_add_u64 v[2:3], v[2:3], 0, s[92:93]
	v_xor_b32_e32 v2, v159, v2
	global_load_lds_dwordx4 v[2:3], off
	v_add_u32_e32 v2, s10, v213
	v_min_i32_e32 v2, 0x7fff, v2
	v_ashrrev_i32_e32 v3, 31, v2
	v_lshlrev_b64 v[2:3], 11, v[2:3]
	v_lshl_add_u64 v[2:3], s[4:5], 0, v[2:3]
	v_lshl_add_u64 v[2:3], v[2:3], 0, v[168:169]
	s_add_u32 m0, s88, 8192
	v_lshl_add_u64 v[2:3], v[2:3], 0, s[92:93]
	v_xor_b32_e32 v2, v159, v2
	global_load_lds_dwordx4 v[2:3], off
	v_add_u32_e32 v2, s9, v213
	v_ashrrev_i32_e32 v3, 31, v2
	v_lshlrev_b64 v[2:3], 11, v[2:3]
	v_lshl_add_u64 v[2:3], s[2:3], 0, v[2:3]
	v_lshl_add_u64 v[2:3], v[2:3], 0, v[168:169]
	v_add_u32_e32 v4, 0x80, v212
	s_add_u32 m0, s88, 40960
	v_lshl_add_u64 v[2:3], v[2:3], 0, s[92:93]
	v_xor_b32_e32 v2, v159, v2
	global_load_lds_dwordx4 v[2:3], off
	v_add_u32_e32 v2, s10, v4
	v_min_i32_e32 v2, 0x7fff, v2
	v_ashrrev_i32_e32 v3, 31, v2
	v_lshlrev_b64 v[2:3], 11, v[2:3]
	v_lshl_add_u64 v[2:3], s[4:5], 0, v[2:3]
	v_lshl_add_u64 v[2:3], v[2:3], 0, v[168:169]
	s_add_u32 m0, s88, 16384
	v_lshl_add_u64 v[2:3], v[2:3], 0, s[92:93]
	v_xor_b32_e32 v2, v159, v2
	global_load_lds_dwordx4 v[2:3], off
	v_add_u32_e32 v2, s9, v4
	v_ashrrev_i32_e32 v3, 31, v2
	v_lshlrev_b64 v[2:3], 11, v[2:3]
	v_lshl_add_u64 v[2:3], s[2:3], 0, v[2:3]
	v_lshl_add_u64 v[2:3], v[2:3], 0, v[168:169]
	v_add_u32_e32 v4, 0xc0, v212
	s_add_u32 m0, s88, 49152
	v_lshl_add_u64 v[2:3], v[2:3], 0, s[92:93]
	v_xor_b32_e32 v2, v159, v2
	global_load_lds_dwordx4 v[2:3], off
	v_add_u32_e32 v2, s10, v4
	v_min_i32_e32 v2, 0x7fff, v2
	v_ashrrev_i32_e32 v3, 31, v2
	v_lshlrev_b64 v[2:3], 11, v[2:3]
	v_lshl_add_u64 v[2:3], s[4:5], 0, v[2:3]
	v_lshl_add_u64 v[2:3], v[2:3], 0, v[168:169]
	s_add_u32 m0, s88, 24576
	v_lshl_add_u64 v[2:3], v[2:3], 0, s[92:93]
	v_xor_b32_e32 v2, v159, v2
	global_load_lds_dwordx4 v[2:3], off
	v_add_u32_e32 v2, s9, v4
	v_ashrrev_i32_e32 v3, 31, v2
	v_lshlrev_b64 v[2:3], 11, v[2:3]
	v_lshl_add_u64 v[2:3], s[2:3], 0, v[2:3]
	v_lshl_add_u64 v[2:3], v[2:3], 0, v[168:169]
	s_add_u32 m0, s88, 57344
	v_lshl_add_u64 v[2:3], v[2:3], 0, s[92:93]
	v_xor_b32_e32 v2, v159, v2
	global_load_lds_dwordx4 v[2:3], off

.LBB0_2223:
	ds_read_b128 v[128:131], v231
	ds_read_b128 v[136:139], v235
	ds_read_b128 v[132:135], v231 offset:4096
	ds_read_b128 v[140:143], v235 offset:4096
	ds_read_b128 v[144:147], v235 offset:8192
	ds_read_b128 v[148:151], v235 offset:12288
	s_waitcnt lgkmcnt(6)
	v_mfma_f32_32x32x16_bf16 v[112:127], v[188:191], v[196:199], v[112:127]
	v_mfma_f32_32x32x16_bf16 v[48:63], v[192:195], v[196:199], v[48:63]
	v_mfma_f32_32x32x16_bf16 v[96:111], v[188:191], v[200:203], v[96:111]
	v_mfma_f32_32x32x16_bf16 v[32:47], v[192:195], v[200:203], v[32:47]
	v_mfma_f32_32x32x16_bf16 v[80:95], v[188:191], v[204:207], v[80:95]
	v_mfma_f32_32x32x16_bf16 v[16:31], v[192:195], v[204:207], v[16:31]
	v_mfma_f32_32x32x16_bf16 v[64:79], v[188:191], v[226:229], v[64:79]
	v_mfma_f32_32x32x16_bf16 v[0:15], v[192:195], v[226:229], v[0:15]
	ds_read_b128 v[188:191], v232
	ds_read_b128 v[196:199], v236
	ds_read_b128 v[192:195], v232 offset:4096
	ds_read_b128 v[200:203], v236 offset:4096
	ds_read_b128 v[204:207], v236 offset:8192
	ds_read_b128 v[226:229], v236 offset:12288
	s_waitcnt lgkmcnt(6)
	v_mfma_f32_32x32x16_bf16 v[112:127], v[128:131], v[136:139], v[112:127]
	v_mfma_f32_32x32x16_bf16 v[48:63], v[132:135], v[136:139], v[48:63]
	v_mfma_f32_32x32x16_bf16 v[96:111], v[128:131], v[140:143], v[96:111]
	v_mfma_f32_32x32x16_bf16 v[32:47], v[132:135], v[140:143], v[32:47]
	v_mfma_f32_32x32x16_bf16 v[80:95], v[128:131], v[144:147], v[80:95]
	v_mfma_f32_32x32x16_bf16 v[16:31], v[132:135], v[144:147], v[16:31]
	v_mfma_f32_32x32x16_bf16 v[64:79], v[128:131], v[148:151], v[64:79]
	v_mfma_f32_32x32x16_bf16 v[0:15], v[132:135], v[148:151], v[0:15]
	ds_read_b128 v[128:131], v233
	ds_read_b128 v[136:139], v237
	ds_read_b128 v[132:135], v233 offset:4096
	ds_read_b128 v[140:143], v237 offset:4096
	ds_read_b128 v[144:147], v237 offset:8192
	ds_read_b128 v[148:151], v237 offset:12288
	s_waitcnt lgkmcnt(6)
	v_mfma_f32_32x32x16_bf16 v[112:127], v[188:191], v[196:199], v[112:127]
	v_mfma_f32_32x32x16_bf16 v[48:63], v[192:195], v[196:199], v[48:63]
	v_mfma_f32_32x32x16_bf16 v[96:111], v[188:191], v[200:203], v[96:111]
	v_mfma_f32_32x32x16_bf16 v[32:47], v[192:195], v[200:203], v[32:47]
	v_mfma_f32_32x32x16_bf16 v[80:95], v[188:191], v[204:207], v[80:95]
	v_mfma_f32_32x32x16_bf16 v[16:31], v[192:195], v[204:207], v[16:31]
	v_mfma_f32_32x32x16_bf16 v[64:79], v[188:191], v[226:229], v[64:79]
	v_mfma_f32_32x32x16_bf16 v[0:15], v[192:195], v[226:229], v[0:15]
	s_waitcnt lgkmcnt(0)
	s_barrier
	v_xor_b32_e32 v230, 0x10000, v230
	v_xor_b32_e32 v234, 0x10000, v234
	v_mfma_f32_32x32x16_bf16 v[112:127], v[128:131], v[136:139], v[112:127]
	v_xor_b32_e32 v231, 0x10000, v231
	v_xor_b32_e32 v235, 0x10000, v235
	v_mfma_f32_32x32x16_bf16 v[48:63], v[132:135], v[136:139], v[48:63]
	v_xor_b32_e32 v232, 0x10000, v232
	v_xor_b32_e32 v236, 0x10000, v236
	v_mfma_f32_32x32x16_bf16 v[96:111], v[128:131], v[140:143], v[96:111]
	v_xor_b32_e32 v233, 0x10000, v233
	v_xor_b32_e32 v237, 0x10000, v237
	v_mfma_f32_32x32x16_bf16 v[32:47], v[132:135], v[140:143], v[32:47]
	v_mfma_f32_32x32x16_bf16 v[80:95], v[128:131], v[144:147], v[80:95]
	v_mfma_f32_32x32x16_bf16 v[16:31], v[132:135], v[144:147], v[16:31]
	v_mfma_f32_32x32x16_bf16 v[64:79], v[128:131], v[148:151], v[64:79]
	v_mfma_f32_32x32x16_bf16 v[0:15], v[132:135], v[148:151], v[0:15]
	s_lshl_b32 s2, s5, 8
	s_sub_i32 s2, s2, s6
	v_mov_b32_e32 v168, v214
	s_add_i32 s55, s4, s30
	s_or_b32 s26, s2, s31
	s_ashr_i32 s27, s26, 31
	s_load_dwordx2 s[24:25], s[0:1], 0x140
	v_ashrrev_i32_e32 v180, 3, v168
	v_and_b32_e32 v183, -4, v180
	v_add_u32_e32 v225, s55, v183
	v_add_u32_e32 v190, 8, v225
	v_min_i32_e32 v190, 0x7fff, v190
	v_ashrrev_i32_e32 v190, 12, v190
	v_add_u32_e32 v190, 8, v190
	v_mul_hi_i32_i24_e32 v191, 0x3000, v190
	v_mul_i32_i24_e32 v190, 0x3000, v190
	v_min_i32_e32 v184, 0x7fff, v225
	v_ashrrev_i32_e32 v184, 12, v184
	v_and_b32_e32 v182, 31, v168
	v_add_u32_e32 v184, 8, v184
	v_or_b32_e32 v180, s26, v182
	v_mul_hi_i32_i24_e32 v185, 0x3000, v184
	v_mul_i32_i24_e32 v184, 0x3000, v184
	v_ashrrev_i32_e32 v181, 31, v180
	s_waitcnt lgkmcnt(0)
	v_lshl_add_u64 v[184:185], s[24:25], 0, v[184:185]
	v_lshl_add_u64 v[184:185], v[184:185], 0, s[18:19]
	v_lshlrev_b64 v[180:181], 2, v[180:181]
	v_lshl_add_u64 v[196:197], v[184:185], 0, v[180:181]
	v_lshl_add_u64 v[186:187], s[24:25], 0, v[190:191]
	v_add_u32_e32 v188, 9, v225
	v_add_u32_e32 v190, 10, v225
	v_min_i32_e32 v188, 0x7fff, v188
	v_min_i32_e32 v190, 0x7fff, v190
	v_ashrrev_i32_e32 v188, 12, v188
	v_ashrrev_i32_e32 v190, 12, v190
	v_add_u32_e32 v188, 8, v188
	v_add_u32_e32 v190, 8, v190
	v_mul_hi_i32_i24_e32 v189, 0x3000, v188
	v_mul_i32_i24_e32 v188, 0x3000, v188
	v_mul_hi_i32_i24_e32 v191, 0x3000, v190
	v_mul_i32_i24_e32 v190, 0x3000, v190
	v_lshl_add_u64 v[188:189], s[24:25], 0, v[188:189]
	v_lshl_add_u64 v[190:191], s[24:25], 0, v[190:191]
	v_lshl_add_u64 v[186:187], v[186:187], 0, s[18:19]
	v_lshl_add_u64 v[188:189], v[188:189], 0, s[18:19]
	v_lshl_add_u64 v[190:191], v[190:191], 0, s[18:19]
	v_lshl_add_u64 v[206:207], v[186:187], 0, v[180:181]
	v_add_u32_e32 v208, 18, v225
	v_min_i32_e32 v208, 0x7fff, v208
	v_ashrrev_i32_e32 v208, 12, v208
	v_add_u32_e32 v208, 8, v208
	v_mul_hi_i32_i24_e32 v209, 0x3000, v208
	v_mul_i32_i24_e32 v208, 0x3000, v208
	v_lshl_add_u64 v[208:209], s[24:25], 0, v[208:209]
	v_lshl_add_u64 v[202:203], v[188:189], 0, v[180:181]
	v_lshl_add_u64 v[204:205], v[190:191], 0, v[180:181]
	global_load_dword v232, v[196:197], off
	global_load_dword v233, v[196:197], off offset:128
	global_load_dword v242, v[206:207], off
	global_load_dword v243, v[206:207], off offset:128
	global_load_dword v244, v[202:203], off
	global_load_dword v245, v[202:203], off offset:128
	global_load_dword v246, v[204:205], off
	global_load_dword v247, v[204:205], off offset:128
	v_add_u32_e32 v196, 17, v225
	v_min_i32_e32 v196, 0x7fff, v196
	v_ashrrev_i32_e32 v196, 12, v196
	v_add_u32_e32 v196, 8, v196
	v_mul_hi_i32_i24_e32 v197, 0x3000, v196
	v_mul_i32_i24_e32 v196, 0x3000, v196
	v_lshl_add_u64 v[196:197], s[24:25], 0, v[196:197]
	v_lshl_add_u64 v[196:197], v[196:197], 0, s[18:19]
	v_lshl_add_u64 v[206:207], v[196:197], 0, v[180:181]
	s_waitcnt vmcnt(7)
	s_nop 5
	v_mul_f32_e32 v112, v112, v232
	v_add_u32_e32 v192, 11, v225
	v_add_u32_e32 v194, 16, v225
	v_min_i32_e32 v192, 0x7fff, v192
	v_min_i32_e32 v194, 0x7fff, v194
	v_ashrrev_i32_e32 v192, 12, v192
	v_ashrrev_i32_e32 v194, 12, v194
	v_add_u32_e32 v192, 8, v192
	v_add_u32_e32 v194, 8, v194
	v_mul_hi_i32_i24_e32 v193, 0x3000, v192
	v_mul_i32_i24_e32 v192, 0x3000, v192
	v_mul_hi_i32_i24_e32 v195, 0x3000, v194
	v_mul_i32_i24_e32 v194, 0x3000, v194
	v_lshl_add_u64 v[192:193], s[24:25], 0, v[192:193]
	v_lshl_add_u64 v[194:195], s[24:25], 0, v[194:195]
	v_lshl_add_u64 v[192:193], v[192:193], 0, s[18:19]
	v_lshl_add_u64 v[194:195], v[194:195], 0, s[18:19]
	v_lshl_add_u64 v[202:203], v[192:193], 0, v[180:181]
	v_lshl_add_u64 v[204:205], v[194:195], 0, v[180:181]
	s_waitcnt vmcnt(6)
	s_nop 5
	v_mul_f32_e32 v96, v96, v233
	v_mul_f32_e32 v97, v97, v233
	v_lshl_add_u64 v[198:199], v[208:209], 0, s[18:19]
	v_lshl_add_u64 v[200:201], v[198:199], 0, v[180:181]
	global_load_dword v234, v[202:203], off
	global_load_dword v235, v[202:203], off offset:128
	global_load_dword v236, v[204:205], off
	global_load_dword v237, v[204:205], off offset:128
	global_load_dword v238, v[206:207], off
	global_load_dword v239, v[206:207], off offset:128
	global_load_dword v240, v[200:201], off
	global_load_dword v241, v[200:201], off offset:128
	v_add_u32_e32 v200, 19, v225
	v_add_u32_e32 v204, 25, v225
	v_add_u32_e32 v206, 26, v225
	v_min_i32_e32 v200, 0x7fff, v200
	v_add_u32_e32 v202, 24, v225
	v_min_i32_e32 v204, 0x7fff, v204
	v_min_i32_e32 v206, 0x7fff, v206
	v_ashrrev_i32_e32 v200, 12, v200
	v_min_i32_e32 v202, 0x7fff, v202
	v_ashrrev_i32_e32 v204, 12, v204
	v_ashrrev_i32_e32 v206, 12, v206
	v_add_u32_e32 v200, 8, v200
	v_ashrrev_i32_e32 v202, 12, v202
	v_add_u32_e32 v204, 8, v204
	v_add_u32_e32 v206, 8, v206
	v_mul_hi_i32_i24_e32 v201, 0x3000, v200
	v_mul_i32_i24_e32 v200, 0x3000, v200
	v_add_u32_e32 v202, 8, v202
	v_mul_hi_i32_i24_e32 v205, 0x3000, v204
	v_mul_i32_i24_e32 v204, 0x3000, v204
	v_mul_hi_i32_i24_e32 v207, 0x3000, v206
	v_mul_i32_i24_e32 v206, 0x3000, v206
	v_lshl_add_u64 v[200:201], s[24:25], 0, v[200:201]
	v_mul_hi_i32_i24_e32 v203, 0x3000, v202
	v_mul_i32_i24_e32 v202, 0x3000, v202
	v_lshl_add_u64 v[204:205], s[24:25], 0, v[204:205]
	v_lshl_add_u64 v[206:207], s[24:25], 0, v[206:207]
	v_lshl_add_u64 v[200:201], v[200:201], 0, s[18:19]
	v_lshl_add_u64 v[202:203], s[24:25], 0, v[202:203]
	v_lshl_add_u64 v[204:205], v[204:205], 0, s[18:19]
	v_lshl_add_u64 v[206:207], v[206:207], 0, s[18:19]
	v_lshl_add_u64 v[208:209], v[200:201], 0, v[180:181]
	v_lshl_add_u64 v[202:203], v[202:203], 0, s[18:19]
	v_lshl_add_u64 v[228:229], v[204:205], 0, v[180:181]
	v_lshl_add_u64 v[230:231], v[206:207], 0, v[180:181]
	v_lshl_add_u64 v[226:227], v[202:203], 0, v[180:181]
	global_load_dword v248, v[208:209], off
	global_load_dword v249, v[208:209], off offset:128
	global_load_dword v250, v[226:227], off
	global_load_dword v251, v[226:227], off offset:128
	global_load_dword v252, v[228:229], off
	s_nop 0
	global_load_dword v228, v[228:229], off offset:128
	s_nop 0
	global_load_dword v229, v[230:231], off
	s_nop 0
	global_load_dword v230, v[230:231], off offset:128
	v_add_u32_e32 v208, 27, v225
	v_min_i32_e32 v208, 0x7fff, v208
	v_ashrrev_i32_e32 v208, 12, v208
	v_add_u32_e32 v208, 8, v208
	v_mul_hi_i32_i24_e32 v209, 0x3000, v208
	v_mul_i32_i24_e32 v208, 0x3000, v208
	v_lshl_add_u64 v[208:209], s[24:25], 0, v[208:209]
	v_lshl_add_u64 v[208:209], v[208:209], 0, s[18:19]
	v_lshl_add_u64 v[226:227], v[208:209], 0, v[180:181]
	global_load_dword v225, v[226:227], off
	s_nop 0
	global_load_dword v226, v[226:227], off offset:128
	v_mad_u64_u32 v[160:161], s[2:3], v183, s36, v[182:183]
	v_lshl_add_u32 v162, v160, 2, s34
	ds_write2_b32 v162, v112, v96 offset1:32
	v_mul_f32_e32 v96, v113, v232
	ds_write2_b32 v162, v96, v97 offset0:68 offset1:100
	v_mul_f32_e32 v96, v114, v232
	v_mul_f32_e32 v97, v98, v233
	ds_write2_b32 v162, v96, v97 offset0:136 offset1:168
	v_mul_f32_e32 v96, v115, v232
	v_mul_f32_e32 v97, v99, v233
	ds_write2_b32 v162, v96, v97 offset0:204 offset1:236
	s_waitcnt vmcnt(23)
	v_mul_f32_e32 v96, v116, v242
	s_waitcnt vmcnt(22)
	v_mul_f32_e32 v97, v100, v243
	v_add_u32_e32 v115, 0x800, v162
	ds_write2_b32 v115, v96, v97 offset0:32 offset1:64
	s_waitcnt vmcnt(21)
	v_mul_f32_e32 v96, v117, v244
	s_waitcnt vmcnt(20)
	v_mul_f32_e32 v97, v101, v245
	ds_write2_b32 v115, v96, v97 offset0:100 offset1:132
	s_waitcnt vmcnt(19)
	v_mul_f32_e32 v96, v118, v246
	s_waitcnt vmcnt(18)
	v_mul_f32_e32 v97, v102, v247
	ds_write2_b32 v115, v96, v97 offset0:168 offset1:200
	v_add_u32_e32 v116, 0xa00, v162
	v_add_u32_e32 v117, 0x1000, v162
	s_waitcnt vmcnt(17)
	v_mul_f32_e32 v96, v119, v234
	s_waitcnt vmcnt(16)
	v_mul_f32_e32 v97, v103, v235
	ds_write2_b32 v116, v96, v97 offset0:108 offset1:140
	s_waitcnt vmcnt(15)
	v_mul_f32_e32 v96, v120, v236
	s_waitcnt vmcnt(14)
	v_mul_f32_e32 v97, v104, v237
	ds_write2_b32 v117, v96, v97 offset0:64 offset1:96
	s_waitcnt vmcnt(13)
	v_mul_f32_e32 v96, v121, v238
	s_waitcnt vmcnt(12)
	v_mul_f32_e32 v97, v105, v239
	ds_write2_b32 v117, v96, v97 offset0:132 offset1:164
	s_waitcnt vmcnt(11)
	v_mul_f32_e32 v96, v122, v240
	s_waitcnt vmcnt(10)
	v_mul_f32_e32 v97, v106, v241
	ds_write2_b32 v117, v96, v97 offset0:200 offset1:232
	v_add_u32_e32 v118, 0x1400, v162
	v_add_u32_e32 v119, 0x1800, v162
	v_ashrrev_i32_e32 v163, 4, v168
	v_and_b32_e32 v160, 15, v168
	v_add_u32_e32 v120, 0x1a00, v162
	v_mul_lo_u32 v164, v163, s37
	v_lshl_add_u32 v165, v160, 4, s34
	v_lshlrev_b32_e32 v168, 2, v160
	v_add_u32_e32 v160, s55, v163
	v_add_u32_e32 v121, 0x1c00, v162
	v_cmp_gt_i32_e32 vcc, s38, v160
	v_ashrrev_i32_e32 v161, 31, v160
	v_add_u32_e32 v114, v165, v164
	s_waitcnt vmcnt(9)
	v_mul_f32_e32 v96, v123, v248
	s_waitcnt vmcnt(8)
	v_mul_f32_e32 v97, v107, v249
	ds_write2_b32 v118, v96, v97 offset0:12 offset1:44
	s_waitcnt vmcnt(7)
	v_mul_f32_e32 v96, v124, v250
	s_waitcnt vmcnt(6)
	v_mul_f32_e32 v97, v108, v251
	ds_write2_b32 v119, v96, v97 offset0:96 offset1:128
	s_waitcnt vmcnt(5)
	v_mul_f32_e32 v96, v125, v252
	s_waitcnt vmcnt(4)
	v_mul_f32_e32 v97, v109, v228
	ds_write2_b32 v119, v96, v97 offset0:164 offset1:196
	s_waitcnt vmcnt(3)
	v_mul_f32_e32 v96, v126, v229
	s_waitcnt vmcnt(2)
	v_mul_f32_e32 v97, v110, v230
	ds_write2_b32 v120, v96, v97 offset0:104 offset1:136
	s_waitcnt vmcnt(1)
	v_mul_f32_e32 v96, v127, v225
	s_waitcnt vmcnt(0)
	v_mul_f32_e32 v97, v111, v226
	ds_write2_b32 v121, v96, v97 offset0:44 offset1:76
	v_or_b32_e32 v96, s26, v168
	v_mov_b32_e32 v97, s27
	v_add_u32_e32 v128, 0, v160
	v_ashrrev_i32_e32 v129, 31, v128
	v_lshlrev_b64 v[128:129], 12, v[128:129]
	v_lshl_add_u64 v[128:129], s[16:17], 0, v[128:129]
	v_lshl_add_u64 v[128:129], v[96:97], 2, v[128:129]
	global_load_dwordx4 v[128:131], v[128:129], off
	v_add_u32_e32 v132, 4, v160
	v_ashrrev_i32_e32 v133, 31, v132
	v_lshlrev_b64 v[132:133], 12, v[132:133]
	v_lshl_add_u64 v[132:133], s[16:17], 0, v[132:133]
	v_lshl_add_u64 v[132:133], v[96:97], 2, v[132:133]
	global_load_dwordx4 v[132:135], v[132:133], off
	v_add_u32_e32 v136, 8, v160
	v_ashrrev_i32_e32 v137, 31, v136
	v_lshlrev_b64 v[136:137], 12, v[136:137]
	v_lshl_add_u64 v[136:137], s[16:17], 0, v[136:137]
	v_lshl_add_u64 v[136:137], v[96:97], 2, v[136:137]
	global_load_dwordx4 v[136:139], v[136:137], off
	v_add_u32_e32 v140, 12, v160
	v_ashrrev_i32_e32 v141, 31, v140
	v_lshlrev_b64 v[140:141], 12, v[140:141]
	v_lshl_add_u64 v[140:141], s[16:17], 0, v[140:141]
	v_lshl_add_u64 v[140:141], v[96:97], 2, v[140:141]
	global_load_dwordx4 v[140:143], v[140:141], off
	v_add_u32_e32 v144, 16, v160
	v_ashrrev_i32_e32 v145, 31, v144
	v_lshlrev_b64 v[144:145], 12, v[144:145]
	v_lshl_add_u64 v[144:145], s[16:17], 0, v[144:145]
	v_lshl_add_u64 v[144:145], v[96:97], 2, v[144:145]
	global_load_dwordx4 v[144:147], v[144:145], off
	v_add_u32_e32 v148, 20, v160
	v_ashrrev_i32_e32 v149, 31, v148
	v_lshlrev_b64 v[148:149], 12, v[148:149]
	v_lshl_add_u64 v[148:149], s[16:17], 0, v[148:149]
	v_lshl_add_u64 v[148:149], v[96:97], 2, v[148:149]
	global_load_dwordx4 v[148:151], v[148:149], off
	v_add_u32_e32 v152, 24, v160
	v_ashrrev_i32_e32 v153, 31, v152
	v_lshlrev_b64 v[152:153], 12, v[152:153]
	v_lshl_add_u64 v[152:153], s[16:17], 0, v[152:153]
	v_lshl_add_u64 v[152:153], v[96:97], 2, v[152:153]
	global_load_dwordx4 v[152:155], v[152:153], off
	v_add_u32_e32 v156, 28, v160
	v_ashrrev_i32_e32 v157, 31, v156
	v_lshlrev_b64 v[156:157], 12, v[156:157]
	v_lshl_add_u64 v[156:157], s[16:17], 0, v[156:157]
	v_lshl_add_u64 v[156:157], v[96:97], 2, v[156:157]
	global_load_dwordx4 v[156:159], v[156:157], off
	s_and_saveexec_b64 s[2:3], vcc
	s_cbranch_execz .LBB0_2225
	v_lshlrev_b64 v[98:99], 12, v[160:161]
	v_lshl_add_u64 v[98:99], s[16:17], 0, v[98:99]
	v_lshl_add_u64 v[106:107], v[96:97], 2, v[98:99]
	ds_read_b128 v[102:105], v114
	s_waitcnt vmcnt(7) lgkmcnt(0)
	v_pk_add_f32 v[100:101], v[104:105], v[130:131]
	v_pk_add_f32 v[98:99], v[102:103], v[128:129]
	global_store_dwordx4 v[106:107], v[98:101], off
.LBB0_2225:
	s_or_b64 exec, exec, s[2:3]
	s_nop 0
	v_add_u32_e32 v100, 4, v160
	v_cmp_gt_i32_e64 s[2:3], s39, v160
	v_ashrrev_i32_e32 v101, 31, v100
	s_and_saveexec_b64 s[4:5], s[2:3]
	s_cbranch_execz .LBB0_2227
	v_lshlrev_b64 v[98:99], 12, v[100:101]
	v_lshl_add_u64 v[98:99], s[16:17], 0, v[98:99]
	v_lshl_add_u64 v[98:99], v[96:97], 2, v[98:99]
	ds_read_b128 v[106:109], v114 offset:1088
	s_waitcnt vmcnt(7) lgkmcnt(0)
	v_pk_add_f32 v[104:105], v[108:109], v[134:135]
	v_pk_add_f32 v[102:103], v[106:107], v[132:133]
	global_store_dwordx4 v[98:99], v[102:105], off
.LBB0_2227:
	s_or_b64 exec, exec, s[4:5]
	s_nop 0
	v_add_u32_e32 v102, 8, v160
	v_cmp_gt_i32_e64 s[4:5], s48, v160
	v_ashrrev_i32_e32 v103, 31, v102
	s_and_saveexec_b64 s[6:7], s[4:5]
	s_cbranch_execz .LBB0_2229
	v_lshlrev_b64 v[98:99], 12, v[102:103]
	v_lshl_add_u64 v[98:99], s[16:17], 0, v[98:99]
	v_lshl_add_u64 v[98:99], v[96:97], 2, v[98:99]
	ds_read_b128 v[108:111], v114 offset:2176
	s_waitcnt vmcnt(7) lgkmcnt(0)
	v_pk_add_f32 v[106:107], v[110:111], v[138:139]
	v_pk_add_f32 v[104:105], v[108:109], v[136:137]
	global_store_dwordx4 v[98:99], v[104:107], off
.LBB0_2229:
	s_or_b64 exec, exec, s[6:7]
	s_nop 0
	v_add_u32_e32 v104, 12, v160
	v_cmp_gt_i32_e64 s[6:7], s49, v160
	v_ashrrev_i32_e32 v105, 31, v104
	s_and_saveexec_b64 s[8:9], s[6:7]
	s_cbranch_execz .LBB0_2231
	v_lshlrev_b64 v[98:99], 12, v[104:105]
	v_lshl_add_u64 v[98:99], s[16:17], 0, v[98:99]
	v_lshl_add_u64 v[98:99], v[96:97], 2, v[98:99]
	ds_read_b128 v[110:113], v114 offset:3264
	s_waitcnt vmcnt(7) lgkmcnt(0)
	v_pk_add_f32 v[108:109], v[112:113], v[142:143]
	v_pk_add_f32 v[106:107], v[110:111], v[140:141]
	global_store_dwordx4 v[98:99], v[106:109], off
.LBB0_2231:
	s_or_b64 exec, exec, s[8:9]
	s_nop 0
	v_add_u32_e32 v106, 16, v160
	v_cmp_gt_i32_e64 s[8:9], s50, v160
	v_ashrrev_i32_e32 v107, 31, v106
	s_and_saveexec_b64 s[10:11], s[8:9]
	s_cbranch_execz .LBB0_2233
	v_lshlrev_b64 v[98:99], 12, v[106:107]
	v_lshl_add_u64 v[98:99], s[16:17], 0, v[98:99]
	v_lshl_add_u64 v[98:99], v[96:97], 2, v[98:99]
	ds_read_b128 v[122:125], v114 offset:4352
	s_waitcnt vmcnt(7) lgkmcnt(0)
	v_pk_add_f32 v[110:111], v[124:125], v[146:147]
	v_pk_add_f32 v[108:109], v[122:123], v[144:145]
	global_store_dwordx4 v[98:99], v[108:111], off
.LBB0_2233:
	s_or_b64 exec, exec, s[10:11]
	s_nop 0
	v_add_u32_e32 v108, 20, v160
	v_cmp_gt_i32_e64 s[10:11], s51, v160
	v_ashrrev_i32_e32 v109, 31, v108
	s_and_saveexec_b64 s[12:13], s[10:11]
	s_cbranch_execz .LBB0_2235
	v_lshlrev_b64 v[98:99], 12, v[108:109]
	v_lshl_add_u64 v[98:99], s[16:17], 0, v[98:99]
	v_lshl_add_u64 v[98:99], v[96:97], 2, v[98:99]
	ds_read_b128 v[122:125], v114 offset:5440
	s_waitcnt vmcnt(7) lgkmcnt(0)
	v_pk_add_f32 v[112:113], v[124:125], v[150:151]
	v_pk_add_f32 v[110:111], v[122:123], v[148:149]
	global_store_dwordx4 v[98:99], v[110:113], off
.LBB0_2235:
	s_or_b64 exec, exec, s[12:13]
	s_nop 0
	v_add_u32_e32 v110, 24, v160
	v_cmp_gt_i32_e64 s[12:13], s52, v160
	v_ashrrev_i32_e32 v111, 31, v110
	s_and_saveexec_b64 s[14:15], s[12:13]
	s_cbranch_execz .LBB0_2237
	v_lshlrev_b64 v[98:99], 12, v[110:111]
	v_lshl_add_u64 v[98:99], s[16:17], 0, v[98:99]
	v_lshl_add_u64 v[98:99], v[96:97], 2, v[98:99]
	ds_read_b128 v[164:167], v114 offset:6528
	s_waitcnt vmcnt(7) lgkmcnt(0)
	v_pk_add_f32 v[124:125], v[166:167], v[154:155]
	v_pk_add_f32 v[122:123], v[164:165], v[152:153]
	global_store_dwordx4 v[98:99], v[122:125], off
.LBB0_2237:
	s_or_b64 exec, exec, s[14:15]
	v_add_u32_e32 v112, 28, v160
	v_cmp_gt_i32_e64 s[14:15], s53, v160
	v_ashrrev_i32_e32 v113, 31, v112
	s_and_saveexec_b64 s[28:29], s[14:15]
	s_cbranch_execz .LBB0_2239
	v_lshlrev_b64 v[98:99], 12, v[112:113]
	v_lshl_add_u64 v[98:99], s[16:17], 0, v[98:99]
	v_lshl_add_u64 v[98:99], v[96:97], 2, v[98:99]
	ds_read_b128 v[164:167], v114 offset:7616
	s_waitcnt vmcnt(7) lgkmcnt(0)
	v_pk_add_f32 v[124:125], v[166:167], v[158:159]
	v_pk_add_f32 v[122:123], v[164:165], v[156:157]
	global_store_dwordx4 v[98:99], v[122:125], off
.LBB0_2239:
	s_or_b64 exec, exec, s[28:29]
	v_add3_u32 v98, v182, s26, 64
	v_ashrrev_i32_e32 v99, 31, v98
	v_lshlrev_b64 v[98:99], 2, v[98:99]
	v_lshl_add_u64 v[122:123], v[184:185], 0, v[98:99]
	v_lshl_add_u64 v[124:125], v[186:187], 0, v[98:99]
	v_lshl_add_u64 v[126:127], v[188:189], 0, v[98:99]
	v_lshl_add_u64 v[164:165], v[190:191], 0, v[98:99]
	global_load_dword v166, v[122:123], off
	global_load_dword v167, v[122:123], off offset:128
	global_load_dword v182, v[124:125], off
	global_load_dword v184, v[124:125], off offset:128
	global_load_dword v185, v[126:127], off
	global_load_dword v186, v[126:127], off offset:128
	global_load_dword v187, v[164:165], off
	global_load_dword v188, v[164:165], off offset:128
	v_lshl_add_u64 v[122:123], v[192:193], 0, v[98:99]
	v_lshl_add_u64 v[124:125], v[194:195], 0, v[98:99]
	v_lshl_add_u64 v[126:127], v[196:197], 0, v[98:99]
	v_lshl_add_u64 v[164:165], v[198:199], 0, v[98:99]
	global_load_dword v189, v[122:123], off
	global_load_dword v190, v[122:123], off offset:128
	global_load_dword v191, v[124:125], off
	global_load_dword v192, v[124:125], off offset:128
	global_load_dword v193, v[126:127], off
	global_load_dword v194, v[126:127], off offset:128
	global_load_dword v195, v[164:165], off
	global_load_dword v196, v[164:165], off offset:128
	v_lshl_add_u64 v[122:123], v[200:201], 0, v[98:99]
	v_lshl_add_u64 v[124:125], v[202:203], 0, v[98:99]
	v_lshl_add_u64 v[126:127], v[204:205], 0, v[98:99]
	v_lshl_add_u64 v[164:165], v[206:207], 0, v[98:99]
	global_load_dword v197, v[122:123], off
	global_load_dword v198, v[122:123], off offset:128
	global_load_dword v199, v[124:125], off
	s_nop 0
	global_load_dword v124, v[124:125], off offset:128
	s_nop 0
	global_load_dword v125, v[126:127], off
	s_nop 0
	global_load_dword v126, v[126:127], off offset:128
	s_nop 0
	global_load_dword v127, v[164:165], off
	s_nop 0
	global_load_dword v164, v[164:165], off offset:128
	v_lshl_add_u64 v[122:123], v[208:209], 0, v[98:99]
	global_load_dword v165, v[122:123], off
	s_nop 0
	global_load_dword v122, v[122:123], off offset:128
	s_waitcnt vmcnt(25)
	v_mul_f32_e32 v80, v80, v166
	s_waitcnt vmcnt(24)
	v_mul_f32_e32 v64, v64, v167
	v_mul_f32_e32 v65, v65, v167
	v_mul_f32_e32 v81, v81, v166
	v_mul_f32_e32 v82, v82, v166
	v_mul_f32_e32 v66, v66, v167
	v_mul_f32_e32 v83, v83, v166
	v_mul_f32_e32 v67, v67, v167
	s_waitcnt vmcnt(23)
	v_mul_f32_e32 v84, v84, v182
	s_waitcnt vmcnt(22)
	v_mul_f32_e32 v68, v68, v184
	s_waitcnt vmcnt(21)
	v_mul_f32_e32 v85, v85, v185
	s_waitcnt vmcnt(20)
	v_mul_f32_e32 v69, v69, v186
	s_waitcnt vmcnt(19)
	v_mul_f32_e32 v86, v86, v187
	s_waitcnt vmcnt(18)
	v_mul_f32_e32 v70, v70, v188
	s_waitcnt vmcnt(17)
	v_mul_f32_e32 v87, v87, v189
	s_waitcnt vmcnt(16)
	v_mul_f32_e32 v71, v71, v190
	s_waitcnt vmcnt(15)
	v_mul_f32_e32 v88, v88, v191
	s_waitcnt vmcnt(14)
	v_mul_f32_e32 v72, v72, v192
	s_waitcnt vmcnt(13)
	v_mul_f32_e32 v89, v89, v193
	s_waitcnt vmcnt(12)
	v_mul_f32_e32 v73, v73, v194
	s_waitcnt vmcnt(11)
	v_mul_f32_e32 v90, v90, v195
	s_waitcnt vmcnt(10)
	v_mul_f32_e32 v74, v74, v196
	s_waitcnt vmcnt(9)
	v_mul_f32_e32 v91, v91, v197
	s_waitcnt vmcnt(8)
	v_mul_f32_e32 v75, v75, v198
	s_waitcnt vmcnt(7)
	v_mul_f32_e32 v92, v92, v199
	s_waitcnt vmcnt(6)
	v_mul_f32_e32 v76, v76, v124
	s_waitcnt vmcnt(5)
	v_mul_f32_e32 v93, v93, v125
	s_waitcnt vmcnt(4)
	v_mul_f32_e32 v77, v77, v126
	s_waitcnt vmcnt(3)
	v_mul_f32_e32 v94, v94, v127
	s_waitcnt vmcnt(2)
	v_mul_f32_e32 v78, v78, v164
	ds_write2_b32 v162, v80, v64 offset1:32
	ds_write2_b32 v162, v81, v65 offset0:68 offset1:100
	ds_write2_b32 v162, v82, v66 offset0:136 offset1:168
	ds_write2_b32 v162, v83, v67 offset0:204 offset1:236
	ds_write2_b32 v115, v84, v68 offset0:32 offset1:64
	ds_write2_b32 v115, v85, v69 offset0:100 offset1:132
	ds_write2_b32 v115, v86, v70 offset0:168 offset1:200
	ds_write2_b32 v116, v87, v71 offset0:108 offset1:140
	ds_write2_b32 v117, v88, v72 offset0:64 offset1:96
	ds_write2_b32 v117, v89, v73 offset0:132 offset1:164
	ds_write2_b32 v117, v90, v74 offset0:200 offset1:232
	ds_write2_b32 v118, v91, v75 offset0:12 offset1:44
	ds_write2_b32 v119, v92, v76 offset0:96 offset1:128
	ds_write2_b32 v119, v93, v77 offset0:164 offset1:196
	ds_write2_b32 v120, v94, v78 offset0:104 offset1:136
	s_waitcnt vmcnt(1)
	v_mul_f32_e32 v64, v95, v165
	s_waitcnt vmcnt(0)
	v_mul_f32_e32 v65, v79, v122
	ds_write2_b32 v121, v64, v65 offset0:44 offset1:76
	v_lshl_add_u64 v[64:65], v[168:169], 0, s[26:27]
	v_add_u32_e32 v128, 0, v160
	v_ashrrev_i32_e32 v129, 31, v128
	v_lshlrev_b64 v[128:129], 12, v[128:129]
	v_lshl_add_u64 v[128:129], s[16:17], 0, v[128:129]
	v_lshl_add_u64 v[128:129], v[64:65], 2, v[128:129]
	global_load_dwordx4 v[128:131], v[128:129], off offset:256
	v_add_u32_e32 v132, 4, v160
	v_ashrrev_i32_e32 v133, 31, v132
	v_lshlrev_b64 v[132:133], 12, v[132:133]
	v_lshl_add_u64 v[132:133], s[16:17], 0, v[132:133]
	v_lshl_add_u64 v[132:133], v[64:65], 2, v[132:133]
	global_load_dwordx4 v[132:135], v[132:133], off offset:256
	v_add_u32_e32 v136, 8, v160
	v_ashrrev_i32_e32 v137, 31, v136
	v_lshlrev_b64 v[136:137], 12, v[136:137]
	v_lshl_add_u64 v[136:137], s[16:17], 0, v[136:137]
	v_lshl_add_u64 v[136:137], v[64:65], 2, v[136:137]
	global_load_dwordx4 v[136:139], v[136:137], off offset:256
	v_add_u32_e32 v140, 12, v160
	v_ashrrev_i32_e32 v141, 31, v140
	v_lshlrev_b64 v[140:141], 12, v[140:141]
	v_lshl_add_u64 v[140:141], s[16:17], 0, v[140:141]
	v_lshl_add_u64 v[140:141], v[64:65], 2, v[140:141]
	global_load_dwordx4 v[140:143], v[140:141], off offset:256
	v_add_u32_e32 v144, 16, v160
	v_ashrrev_i32_e32 v145, 31, v144
	v_lshlrev_b64 v[144:145], 12, v[144:145]
	v_lshl_add_u64 v[144:145], s[16:17], 0, v[144:145]
	v_lshl_add_u64 v[144:145], v[64:65], 2, v[144:145]
	global_load_dwordx4 v[144:147], v[144:145], off offset:256
	v_add_u32_e32 v148, 20, v160
	v_ashrrev_i32_e32 v149, 31, v148
	v_lshlrev_b64 v[148:149], 12, v[148:149]
	v_lshl_add_u64 v[148:149], s[16:17], 0, v[148:149]
	v_lshl_add_u64 v[148:149], v[64:65], 2, v[148:149]
	global_load_dwordx4 v[148:151], v[148:149], off offset:256
	v_add_u32_e32 v152, 24, v160
	v_ashrrev_i32_e32 v153, 31, v152
	v_lshlrev_b64 v[152:153], 12, v[152:153]
	v_lshl_add_u64 v[152:153], s[16:17], 0, v[152:153]
	v_lshl_add_u64 v[152:153], v[64:65], 2, v[152:153]
	global_load_dwordx4 v[152:155], v[152:153], off offset:256
	v_add_u32_e32 v156, 28, v160
	v_ashrrev_i32_e32 v157, 31, v156
	v_lshlrev_b64 v[156:157], 12, v[156:157]
	v_lshl_add_u64 v[156:157], s[16:17], 0, v[156:157]
	v_lshl_add_u64 v[156:157], v[64:65], 2, v[156:157]
	global_load_dwordx4 v[156:159], v[156:157], off offset:256
	s_and_saveexec_b64 s[26:27], vcc
	s_cbranch_execz .LBB0_2247
	v_lshlrev_b64 v[66:67], 12, v[160:161]
	v_lshl_add_u64 v[66:67], s[16:17], 0, v[66:67]
	v_lshl_add_u64 v[74:75], v[64:65], 2, v[66:67]
	ds_read_b128 v[70:73], v114
	s_waitcnt vmcnt(7) lgkmcnt(0)
	v_pk_add_f32 v[68:69], v[72:73], v[130:131]
	v_pk_add_f32 v[66:67], v[70:71], v[128:129]
	global_store_dwordx4 v[74:75], v[66:69], off offset:256
	s_or_b64 exec, exec, s[26:27]
	s_and_saveexec_b64 s[26:27], s[2:3]
	s_cbranch_execnz .LBB0_2248

.LBB0_2242:
	v_lshlrev_b64 v[66:67], 12, v[102:103]
	v_lshl_add_u64 v[66:67], s[16:17], 0, v[66:67]
	v_lshl_add_u64 v[74:75], v[64:65], 2, v[66:67]
	ds_read_b128 v[70:73], v114 offset:2176
	s_waitcnt vmcnt(7) lgkmcnt(0)
	v_pk_add_f32 v[68:69], v[72:73], v[138:139]
	v_pk_add_f32 v[66:67], v[70:71], v[136:137]
	global_store_dwordx4 v[74:75], v[66:69], off offset:256
	s_or_b64 exec, exec, s[2:3]
	s_and_saveexec_b64 s[2:3], s[6:7]
	s_cbranch_execnz .LBB0_2250

.LBB0_2244:
	v_lshlrev_b64 v[66:67], 12, v[106:107]
	v_lshl_add_u64 v[66:67], s[16:17], 0, v[66:67]
	v_lshl_add_u64 v[74:75], v[64:65], 2, v[66:67]
	ds_read_b128 v[70:73], v114 offset:4352
	s_waitcnt vmcnt(7) lgkmcnt(0)
	v_pk_add_f32 v[68:69], v[72:73], v[146:147]
	v_pk_add_f32 v[66:67], v[70:71], v[144:145]
	global_store_dwordx4 v[74:75], v[66:69], off offset:256
	s_or_b64 exec, exec, s[2:3]
	s_and_saveexec_b64 s[2:3], s[10:11]
	s_cbranch_execnz .LBB0_2252

.LBB0_2246:
	v_lshlrev_b64 v[66:67], 12, v[110:111]
	v_lshl_add_u64 v[66:67], s[16:17], 0, v[66:67]
	v_lshl_add_u64 v[74:75], v[64:65], 2, v[66:67]
	ds_read_b128 v[70:73], v114 offset:6528
	s_waitcnt vmcnt(7) lgkmcnt(0)
	v_pk_add_f32 v[68:69], v[72:73], v[154:155]
	v_pk_add_f32 v[66:67], v[70:71], v[152:153]
	global_store_dwordx4 v[74:75], v[66:69], off offset:256
	s_or_b64 exec, exec, s[2:3]
	s_and_saveexec_b64 s[2:3], s[14:15]
	s_cbranch_execnz .LBB0_2254
	s_branch .LBB0_2255

.LBB0_2248:
	v_lshlrev_b64 v[66:67], 12, v[100:101]
	v_lshl_add_u64 v[66:67], s[16:17], 0, v[66:67]
	v_lshl_add_u64 v[74:75], v[64:65], 2, v[66:67]
	ds_read_b128 v[70:73], v114 offset:1088
	s_waitcnt vmcnt(7) lgkmcnt(0)
	v_pk_add_f32 v[68:69], v[72:73], v[134:135]
	v_pk_add_f32 v[66:67], v[70:71], v[132:133]
	global_store_dwordx4 v[74:75], v[66:69], off offset:256
	s_or_b64 exec, exec, s[26:27]
	s_and_saveexec_b64 s[2:3], s[4:5]
	s_cbranch_execnz .LBB0_2242

.LBB0_2250:
	v_lshlrev_b64 v[66:67], 12, v[104:105]
	v_lshl_add_u64 v[66:67], s[16:17], 0, v[66:67]
	v_lshl_add_u64 v[74:75], v[64:65], 2, v[66:67]
	ds_read_b128 v[70:73], v114 offset:3264
	s_waitcnt vmcnt(7) lgkmcnt(0)
	v_pk_add_f32 v[68:69], v[72:73], v[142:143]
	v_pk_add_f32 v[66:67], v[70:71], v[140:141]
	global_store_dwordx4 v[74:75], v[66:69], off offset:256
	s_or_b64 exec, exec, s[2:3]
	s_and_saveexec_b64 s[2:3], s[8:9]
	s_cbranch_execnz .LBB0_2244

.LBB0_2252:
	v_lshlrev_b64 v[66:67], 12, v[108:109]
	v_lshl_add_u64 v[66:67], s[16:17], 0, v[66:67]
	v_lshl_add_u64 v[74:75], v[64:65], 2, v[66:67]
	ds_read_b128 v[70:73], v114 offset:5440
	s_waitcnt vmcnt(7) lgkmcnt(0)
	v_pk_add_f32 v[68:69], v[72:73], v[150:151]
	v_pk_add_f32 v[66:67], v[70:71], v[148:149]
	global_store_dwordx4 v[74:75], v[66:69], off offset:256
	s_or_b64 exec, exec, s[2:3]
	s_and_saveexec_b64 s[2:3], s[12:13]
	s_cbranch_execnz .LBB0_2246

.LBB0_2254:
	v_lshlrev_b64 v[66:67], 12, v[112:113]
	v_lshl_add_u64 v[66:67], s[16:17], 0, v[66:67]
	v_lshl_add_u64 v[74:75], v[64:65], 2, v[66:67]
	ds_read_b128 v[70:73], v114 offset:7616
	s_waitcnt vmcnt(7) lgkmcnt(0)
	v_pk_add_f32 v[68:69], v[72:73], v[158:159]
	v_pk_add_f32 v[66:67], v[70:71], v[156:157]
	global_store_dwordx4 v[74:75], v[66:69], off offset:256
.LBB0_2255:
	s_or_b64 exec, exec, s[2:3]
	s_or_b32 s2, s55, 32
	v_add_u32_e32 v102, s2, v183
	v_min_i32_e32 v66, 0x7fff, v102
	v_add_u32_e32 v68, 8, v102
	v_add_u32_e32 v70, 9, v102
	v_add_u32_e32 v72, 10, v102
	v_ashrrev_i32_e32 v66, 12, v66
	v_min_i32_e32 v68, 0x7fff, v68
	v_min_i32_e32 v70, 0x7fff, v70
	v_min_i32_e32 v72, 0x7fff, v72
	v_add_u32_e32 v66, 8, v66
	v_ashrrev_i32_e32 v68, 12, v68
	v_ashrrev_i32_e32 v70, 12, v70
	v_ashrrev_i32_e32 v72, 12, v72
	v_mul_hi_i32_i24_e32 v67, 0x3000, v66
	v_mul_i32_i24_e32 v66, 0x3000, v66
	v_add_u32_e32 v68, 8, v68
	v_add_u32_e32 v70, 8, v70
	v_add_u32_e32 v72, 8, v72
	v_lshl_add_u64 v[66:67], s[24:25], 0, v[66:67]
	v_mul_hi_i32_i24_e32 v69, 0x3000, v68
	v_mul_i32_i24_e32 v68, 0x3000, v68
	v_mul_hi_i32_i24_e32 v71, 0x3000, v70
	v_mul_i32_i24_e32 v70, 0x3000, v70
	v_mul_hi_i32_i24_e32 v73, 0x3000, v72
	v_mul_i32_i24_e32 v72, 0x3000, v72
	v_lshl_add_u64 v[66:67], v[66:67], 0, s[18:19]
	v_lshl_add_u64 v[68:69], s[24:25], 0, v[68:69]
	v_lshl_add_u64 v[70:71], s[24:25], 0, v[70:71]
	v_lshl_add_u64 v[72:73], s[24:25], 0, v[72:73]
	v_lshl_add_u64 v[74:75], v[66:67], 0, v[180:181]
	v_lshl_add_u64 v[68:69], v[68:69], 0, s[18:19]
	v_lshl_add_u64 v[70:71], v[70:71], 0, s[18:19]
	v_lshl_add_u64 v[72:73], v[72:73], 0, s[18:19]
	v_lshl_add_u64 v[76:77], v[68:69], 0, v[180:181]
	v_lshl_add_u64 v[78:79], v[70:71], 0, v[180:181]
	v_lshl_add_u64 v[80:81], v[72:73], 0, v[180:181]
	global_load_dword v103, v[74:75], off
	global_load_dword v104, v[74:75], off offset:128
	global_load_dword v105, v[76:77], off
	global_load_dword v106, v[76:77], off offset:128
	global_load_dword v107, v[78:79], off
	global_load_dword v108, v[78:79], off offset:128
	global_load_dword v109, v[80:81], off
	global_load_dword v110, v[80:81], off offset:128
	v_add_u32_e32 v74, 11, v102
	v_add_u32_e32 v82, 18, v102
	v_min_i32_e32 v74, 0x7fff, v74
	v_add_u32_e32 v76, 16, v102
	v_add_u32_e32 v78, 17, v102
	v_min_i32_e32 v82, 0x7fff, v82
	v_ashrrev_i32_e32 v74, 12, v74
	v_min_i32_e32 v76, 0x7fff, v76
	v_min_i32_e32 v78, 0x7fff, v78
	v_ashrrev_i32_e32 v82, 12, v82
	v_add_u32_e32 v74, 8, v74
	v_ashrrev_i32_e32 v76, 12, v76
	v_ashrrev_i32_e32 v78, 12, v78
	v_add_u32_e32 v82, 8, v82
	v_mul_hi_i32_i24_e32 v75, 0x3000, v74
	v_mul_i32_i24_e32 v74, 0x3000, v74
	v_add_u32_e32 v76, 8, v76
	v_add_u32_e32 v78, 8, v78
	v_mul_hi_i32_i24_e32 v83, 0x3000, v82
	v_mul_i32_i24_e32 v82, 0x3000, v82
	v_lshl_add_u64 v[74:75], s[24:25], 0, v[74:75]
	v_mul_hi_i32_i24_e32 v77, 0x3000, v76
	v_mul_i32_i24_e32 v76, 0x3000, v76
	v_mul_hi_i32_i24_e32 v79, 0x3000, v78
	v_mul_i32_i24_e32 v78, 0x3000, v78
	v_lshl_add_u64 v[82:83], s[24:25], 0, v[82:83]
	v_lshl_add_u64 v[74:75], v[74:75], 0, s[18:19]
	v_lshl_add_u64 v[76:77], s[24:25], 0, v[76:77]
	v_lshl_add_u64 v[78:79], s[24:25], 0, v[78:79]
	v_lshl_add_u64 v[82:83], v[82:83], 0, s[18:19]
	v_lshl_add_u64 v[80:81], v[74:75], 0, v[180:181]
	v_lshl_add_u64 v[76:77], v[76:77], 0, s[18:19]
	v_lshl_add_u64 v[78:79], v[78:79], 0, s[18:19]
	v_lshl_add_u64 v[88:89], v[82:83], 0, v[180:181]
	v_lshl_add_u64 v[84:85], v[76:77], 0, v[180:181]
	v_lshl_add_u64 v[86:87], v[78:79], 0, v[180:181]
	global_load_dword v111, v[80:81], off
	global_load_dword v112, v[80:81], off offset:128
	global_load_dword v113, v[84:85], off
	global_load_dword v122, v[84:85], off offset:128
	global_load_dword v123, v[86:87], off
	global_load_dword v124, v[86:87], off offset:128
	global_load_dword v125, v[88:89], off
	global_load_dword v126, v[88:89], off offset:128
	v_add_u32_e32 v80, 19, v102
	v_add_u32_e32 v88, 25, v102
	v_add_u32_e32 v90, 26, v102
	v_min_i32_e32 v80, 0x7fff, v80
	v_add_u32_e32 v86, 24, v102
	v_min_i32_e32 v88, 0x7fff, v88
	v_min_i32_e32 v90, 0x7fff, v90
	v_ashrrev_i32_e32 v80, 12, v80
	v_min_i32_e32 v86, 0x7fff, v86
	v_ashrrev_i32_e32 v88, 12, v88
	v_ashrrev_i32_e32 v90, 12, v90
	v_add_u32_e32 v80, 8, v80
	v_ashrrev_i32_e32 v86, 12, v86
	v_add_u32_e32 v88, 8, v88
	v_add_u32_e32 v90, 8, v90
	v_mul_hi_i32_i24_e32 v81, 0x3000, v80
	v_mul_i32_i24_e32 v80, 0x3000, v80
	v_add_u32_e32 v86, 8, v86
	v_mul_hi_i32_i24_e32 v89, 0x3000, v88
	v_mul_i32_i24_e32 v88, 0x3000, v88
	v_mul_hi_i32_i24_e32 v91, 0x3000, v90
	v_mul_i32_i24_e32 v90, 0x3000, v90
	v_lshl_add_u64 v[80:81], s[24:25], 0, v[80:81]
	v_mul_hi_i32_i24_e32 v87, 0x3000, v86
	v_mul_i32_i24_e32 v86, 0x3000, v86
	v_lshl_add_u64 v[88:89], s[24:25], 0, v[88:89]
	v_lshl_add_u64 v[90:91], s[24:25], 0, v[90:91]
	v_lshl_add_u64 v[84:85], v[80:81], 0, s[18:19]
	v_lshl_add_u64 v[86:87], s[24:25], 0, v[86:87]
	v_lshl_add_u64 v[88:89], v[88:89], 0, s[18:19]
	v_lshl_add_u64 v[90:91], v[90:91], 0, s[18:19]
	v_lshl_add_u64 v[80:81], v[84:85], 0, v[180:181]
	v_lshl_add_u64 v[86:87], v[86:87], 0, s[18:19]
	v_lshl_add_u64 v[94:95], v[88:89], 0, v[180:181]
	v_lshl_add_u64 v[100:101], v[90:91], 0, v[180:181]
	v_lshl_add_u64 v[92:93], v[86:87], 0, v[180:181]
	global_load_dword v127, v[80:81], off
	global_load_dword v160, v[80:81], off offset:128
	global_load_dword v161, v[92:93], off
	global_load_dword v164, v[92:93], off offset:128
	global_load_dword v165, v[94:95], off
	s_nop 0
	global_load_dword v94, v[94:95], off offset:128
	s_nop 0
	global_load_dword v95, v[100:101], off
	s_nop 0
	global_load_dword v100, v[100:101], off offset:128
	v_add_u32_e32 v80, 27, v102
	v_min_i32_e32 v80, 0x7fff, v80
	v_ashrrev_i32_e32 v80, 12, v80
	v_add_u32_e32 v80, 8, v80
	v_mul_hi_i32_i24_e32 v81, 0x3000, v80
	v_mul_i32_i24_e32 v80, 0x3000, v80
	v_lshl_add_u64 v[80:81], s[24:25], 0, v[80:81]
	v_lshl_add_u64 v[92:93], v[80:81], 0, s[18:19]
	v_lshl_add_u64 v[80:81], v[92:93], 0, v[180:181]
	global_load_dword v101, v[80:81], off
	s_nop 0
	global_load_dword v81, v[80:81], off offset:128
	s_waitcnt vmcnt(25)
	v_mul_f32_e32 v48, v48, v103
	s_waitcnt vmcnt(24)
	v_mul_f32_e32 v32, v32, v104
	ds_write2_b32 v162, v48, v32 offset1:32
	v_mul_f32_e32 v32, v49, v103
	v_mul_f32_e32 v33, v33, v104
	ds_write2_b32 v162, v32, v33 offset0:68 offset1:100
	v_mul_f32_e32 v32, v50, v103
	v_mul_f32_e32 v33, v34, v104
	ds_write2_b32 v162, v32, v33 offset0:136 offset1:168
	v_mul_f32_e32 v32, v51, v103
	v_mul_f32_e32 v33, v35, v104
	ds_write2_b32 v162, v32, v33 offset0:204 offset1:236
	s_waitcnt vmcnt(23)
	v_mul_f32_e32 v32, v52, v105
	s_waitcnt vmcnt(22)
	v_mul_f32_e32 v33, v36, v106
	ds_write2_b32 v115, v32, v33 offset0:32 offset1:64
	s_waitcnt vmcnt(21)
	v_mul_f32_e32 v32, v53, v107
	s_waitcnt vmcnt(20)
	v_mul_f32_e32 v33, v37, v108
	ds_write2_b32 v115, v32, v33 offset0:100 offset1:132
	s_waitcnt vmcnt(19)
	v_mul_f32_e32 v32, v54, v109
	s_waitcnt vmcnt(18)
	v_mul_f32_e32 v33, v38, v110
	ds_write2_b32 v115, v32, v33 offset0:168 offset1:200
	v_add_u32_e32 v80, s2, v163
	v_cmp_gt_i32_e32 vcc, s38, v80
	s_waitcnt vmcnt(17)
	v_mul_f32_e32 v32, v55, v111
	s_waitcnt vmcnt(16)
	v_mul_f32_e32 v33, v39, v112
	ds_write2_b32 v116, v32, v33 offset0:108 offset1:140
	s_waitcnt vmcnt(15)
	v_mul_f32_e32 v32, v56, v113
	s_waitcnt vmcnt(14)
	v_mul_f32_e32 v33, v40, v122
	ds_write2_b32 v117, v32, v33 offset0:64 offset1:96
	s_waitcnt vmcnt(13)
	v_mul_f32_e32 v32, v57, v123
	s_waitcnt vmcnt(12)
	v_mul_f32_e32 v33, v41, v124
	ds_write2_b32 v117, v32, v33 offset0:132 offset1:164
	s_waitcnt vmcnt(11)
	v_mul_f32_e32 v32, v58, v125
	s_waitcnt vmcnt(10)
	v_mul_f32_e32 v33, v42, v126
	ds_write2_b32 v117, v32, v33 offset0:200 offset1:232
	s_waitcnt vmcnt(9)
	v_mul_f32_e32 v32, v59, v127
	s_waitcnt vmcnt(8)
	v_mul_f32_e32 v33, v43, v160
	ds_write2_b32 v118, v32, v33 offset0:12 offset1:44
	s_waitcnt vmcnt(7)
	v_mul_f32_e32 v32, v60, v161
	s_waitcnt vmcnt(6)
	v_mul_f32_e32 v33, v44, v164
	ds_write2_b32 v119, v32, v33 offset0:96 offset1:128
	s_waitcnt vmcnt(5)
	v_mul_f32_e32 v32, v61, v165
	s_waitcnt vmcnt(4)
	v_mul_f32_e32 v33, v45, v94
	ds_write2_b32 v119, v32, v33 offset0:164 offset1:196
	s_waitcnt vmcnt(3)
	v_mul_f32_e32 v32, v62, v95
	s_waitcnt vmcnt(2)
	v_mul_f32_e32 v33, v46, v100
	ds_write2_b32 v120, v32, v33 offset0:104 offset1:136
	s_waitcnt vmcnt(1)
	v_mul_f32_e32 v32, v63, v101
	s_waitcnt vmcnt(0)
	v_mul_f32_e32 v33, v47, v81
	v_ashrrev_i32_e32 v81, 31, v80
	ds_write2_b32 v121, v32, v33 offset0:44 offset1:76
	v_add_u32_e32 v128, 0, v80
	v_ashrrev_i32_e32 v129, 31, v128
	v_lshlrev_b64 v[128:129], 12, v[128:129]
	v_lshl_add_u64 v[128:129], s[16:17], 0, v[128:129]
	v_lshl_add_u64 v[128:129], v[96:97], 2, v[128:129]
	global_load_dwordx4 v[128:131], v[128:129], off
	v_add_u32_e32 v132, 4, v80
	v_ashrrev_i32_e32 v133, 31, v132
	v_lshlrev_b64 v[132:133], 12, v[132:133]
	v_lshl_add_u64 v[132:133], s[16:17], 0, v[132:133]
	v_lshl_add_u64 v[132:133], v[96:97], 2, v[132:133]
	global_load_dwordx4 v[132:135], v[132:133], off
	v_add_u32_e32 v136, 8, v80
	v_ashrrev_i32_e32 v137, 31, v136
	v_lshlrev_b64 v[136:137], 12, v[136:137]
	v_lshl_add_u64 v[136:137], s[16:17], 0, v[136:137]
	v_lshl_add_u64 v[136:137], v[96:97], 2, v[136:137]
	global_load_dwordx4 v[136:139], v[136:137], off
	v_add_u32_e32 v140, 12, v80
	v_ashrrev_i32_e32 v141, 31, v140
	v_lshlrev_b64 v[140:141], 12, v[140:141]
	v_lshl_add_u64 v[140:141], s[16:17], 0, v[140:141]
	v_lshl_add_u64 v[140:141], v[96:97], 2, v[140:141]
	global_load_dwordx4 v[140:143], v[140:141], off
	v_add_u32_e32 v144, 16, v80
	v_ashrrev_i32_e32 v145, 31, v144
	v_lshlrev_b64 v[144:145], 12, v[144:145]
	v_lshl_add_u64 v[144:145], s[16:17], 0, v[144:145]
	v_lshl_add_u64 v[144:145], v[96:97], 2, v[144:145]
	global_load_dwordx4 v[144:147], v[144:145], off
	v_add_u32_e32 v148, 20, v80
	v_ashrrev_i32_e32 v149, 31, v148
	v_lshlrev_b64 v[148:149], 12, v[148:149]
	v_lshl_add_u64 v[148:149], s[16:17], 0, v[148:149]
	v_lshl_add_u64 v[148:149], v[96:97], 2, v[148:149]
	global_load_dwordx4 v[148:151], v[148:149], off
	v_add_u32_e32 v152, 24, v80
	v_ashrrev_i32_e32 v153, 31, v152
	v_lshlrev_b64 v[152:153], 12, v[152:153]
	v_lshl_add_u64 v[152:153], s[16:17], 0, v[152:153]
	v_lshl_add_u64 v[152:153], v[96:97], 2, v[152:153]
	global_load_dwordx4 v[152:155], v[152:153], off
	v_add_u32_e32 v156, 28, v80
	v_ashrrev_i32_e32 v157, 31, v156
	v_lshlrev_b64 v[156:157], 12, v[156:157]
	v_lshl_add_u64 v[156:157], s[16:17], 0, v[156:157]
	v_lshl_add_u64 v[156:157], v[96:97], 2, v[156:157]
	global_load_dwordx4 v[156:159], v[156:157], off
	s_and_saveexec_b64 s[2:3], vcc
	s_cbranch_execz .LBB0_2257
	v_lshlrev_b64 v[32:33], 12, v[80:81]
	v_lshl_add_u64 v[32:33], s[16:17], 0, v[32:33]
	v_lshl_add_u64 v[40:41], v[96:97], 2, v[32:33]
	ds_read_b128 v[36:39], v114
	s_waitcnt vmcnt(7) lgkmcnt(0)
	v_pk_add_f32 v[34:35], v[38:39], v[130:131]
	v_pk_add_f32 v[32:33], v[36:37], v[128:129]
	global_store_dwordx4 v[40:41], v[32:35], off
.LBB0_2257:
	s_or_b64 exec, exec, s[2:3]
	s_nop 0
	v_add_u32_e32 v32, 4, v80
	v_cmp_gt_i32_e64 s[2:3], s39, v80
	v_ashrrev_i32_e32 v33, 31, v32
	s_and_saveexec_b64 s[4:5], s[2:3]
	s_cbranch_execz .LBB0_2259
	v_lshlrev_b64 v[34:35], 12, v[32:33]
	v_lshl_add_u64 v[34:35], s[16:17], 0, v[34:35]
	v_lshl_add_u64 v[42:43], v[96:97], 2, v[34:35]
	ds_read_b128 v[38:41], v114 offset:1088
	s_waitcnt vmcnt(7) lgkmcnt(0)
	v_pk_add_f32 v[36:37], v[40:41], v[134:135]
	v_pk_add_f32 v[34:35], v[38:39], v[132:133]
	global_store_dwordx4 v[42:43], v[34:37], off
.LBB0_2259:
	s_or_b64 exec, exec, s[4:5]
	s_nop 0
	v_add_u32_e32 v34, 8, v80
	v_cmp_gt_i32_e64 s[4:5], s48, v80
	v_ashrrev_i32_e32 v35, 31, v34
	s_and_saveexec_b64 s[6:7], s[4:5]
	s_cbranch_execz .LBB0_2261
	v_lshlrev_b64 v[36:37], 12, v[34:35]
	v_lshl_add_u64 v[36:37], s[16:17], 0, v[36:37]
	v_lshl_add_u64 v[44:45], v[96:97], 2, v[36:37]
	ds_read_b128 v[40:43], v114 offset:2176
	s_waitcnt vmcnt(7) lgkmcnt(0)
	v_pk_add_f32 v[38:39], v[42:43], v[138:139]
	v_pk_add_f32 v[36:37], v[40:41], v[136:137]
	global_store_dwordx4 v[44:45], v[36:39], off
.LBB0_2261:
	s_or_b64 exec, exec, s[6:7]
	s_nop 0
	v_add_u32_e32 v36, 12, v80
	v_cmp_gt_i32_e64 s[6:7], s49, v80
	v_ashrrev_i32_e32 v37, 31, v36
	s_and_saveexec_b64 s[8:9], s[6:7]
	s_cbranch_execz .LBB0_2263
	v_lshlrev_b64 v[38:39], 12, v[36:37]
	v_lshl_add_u64 v[38:39], s[16:17], 0, v[38:39]
	v_lshl_add_u64 v[46:47], v[96:97], 2, v[38:39]
	ds_read_b128 v[42:45], v114 offset:3264
	s_waitcnt vmcnt(7) lgkmcnt(0)
	v_pk_add_f32 v[40:41], v[44:45], v[142:143]
	v_pk_add_f32 v[38:39], v[42:43], v[140:141]
	global_store_dwordx4 v[46:47], v[38:41], off
.LBB0_2263:
	s_or_b64 exec, exec, s[8:9]
	s_nop 0
	v_add_u32_e32 v38, 16, v80
	v_cmp_gt_i32_e64 s[8:9], s50, v80
	v_ashrrev_i32_e32 v39, 31, v38
	s_and_saveexec_b64 s[10:11], s[8:9]
	s_cbranch_execz .LBB0_2265
	v_lshlrev_b64 v[40:41], 12, v[38:39]
	v_lshl_add_u64 v[40:41], s[16:17], 0, v[40:41]
	v_lshl_add_u64 v[48:49], v[96:97], 2, v[40:41]
	ds_read_b128 v[44:47], v114 offset:4352
	s_waitcnt vmcnt(7) lgkmcnt(0)
	v_pk_add_f32 v[42:43], v[46:47], v[146:147]
	v_pk_add_f32 v[40:41], v[44:45], v[144:145]
	global_store_dwordx4 v[48:49], v[40:43], off
.LBB0_2265:
	s_or_b64 exec, exec, s[10:11]
	s_nop 0
	v_add_u32_e32 v40, 20, v80
	v_cmp_gt_i32_e64 s[10:11], s51, v80
	v_ashrrev_i32_e32 v41, 31, v40
	s_and_saveexec_b64 s[12:13], s[10:11]
	s_cbranch_execz .LBB0_2267
	v_lshlrev_b64 v[42:43], 12, v[40:41]
	v_lshl_add_u64 v[42:43], s[16:17], 0, v[42:43]
	v_lshl_add_u64 v[50:51], v[96:97], 2, v[42:43]
	ds_read_b128 v[46:49], v114 offset:5440
	s_waitcnt vmcnt(7) lgkmcnt(0)
	v_pk_add_f32 v[44:45], v[48:49], v[150:151]
	v_pk_add_f32 v[42:43], v[46:47], v[148:149]
	global_store_dwordx4 v[50:51], v[42:45], off
.LBB0_2267:
	s_or_b64 exec, exec, s[12:13]
	s_nop 0
	v_add_u32_e32 v42, 24, v80
	v_cmp_gt_i32_e64 s[12:13], s52, v80
	v_ashrrev_i32_e32 v43, 31, v42
	s_and_saveexec_b64 s[14:15], s[12:13]
	s_cbranch_execz .LBB0_2269
	v_lshlrev_b64 v[44:45], 12, v[42:43]
	v_lshl_add_u64 v[44:45], s[16:17], 0, v[44:45]
	v_lshl_add_u64 v[52:53], v[96:97], 2, v[44:45]
	ds_read_b128 v[48:51], v114 offset:6528
	s_waitcnt vmcnt(7) lgkmcnt(0)
	v_pk_add_f32 v[46:47], v[50:51], v[154:155]
	v_pk_add_f32 v[44:45], v[48:49], v[152:153]
	global_store_dwordx4 v[52:53], v[44:47], off
.LBB0_2269:
	s_or_b64 exec, exec, s[14:15]
	s_nop 0
	v_add_u32_e32 v44, 28, v80
	v_cmp_gt_i32_e64 s[14:15], s53, v80
	v_ashrrev_i32_e32 v45, 31, v44
	s_and_saveexec_b64 s[24:25], s[14:15]
	s_cbranch_execz .LBB0_2271
	v_lshlrev_b64 v[46:47], 12, v[44:45]
	v_lshl_add_u64 v[46:47], s[16:17], 0, v[46:47]
	v_lshl_add_u64 v[54:55], v[96:97], 2, v[46:47]
	ds_read_b128 v[50:53], v114 offset:7616
	s_waitcnt vmcnt(7) lgkmcnt(0)
	v_pk_add_f32 v[48:49], v[52:53], v[158:159]
	v_pk_add_f32 v[46:47], v[50:51], v[156:157]
	global_store_dwordx4 v[54:55], v[46:49], off
.LBB0_2271:
	s_or_b64 exec, exec, s[24:25]
	s_nop 0
	v_lshl_add_u64 v[46:47], v[66:67], 0, v[98:99]
	v_lshl_add_u64 v[48:49], v[68:69], 0, v[98:99]
	v_lshl_add_u64 v[50:51], v[70:71], 0, v[98:99]
	v_lshl_add_u64 v[52:53], v[72:73], 0, v[98:99]
	global_load_dword v54, v[46:47], off
	global_load_dword v55, v[46:47], off offset:128
	global_load_dword v56, v[48:49], off
	global_load_dword v57, v[48:49], off offset:128
	global_load_dword v58, v[50:51], off
	global_load_dword v59, v[50:51], off offset:128
	global_load_dword v60, v[52:53], off
	global_load_dword v61, v[52:53], off offset:128
	v_lshl_add_u64 v[46:47], v[74:75], 0, v[98:99]
	v_lshl_add_u64 v[48:49], v[76:77], 0, v[98:99]
	v_lshl_add_u64 v[50:51], v[78:79], 0, v[98:99]
	v_lshl_add_u64 v[52:53], v[82:83], 0, v[98:99]
	global_load_dword v62, v[46:47], off
	global_load_dword v63, v[46:47], off offset:128
	global_load_dword v66, v[48:49], off
	global_load_dword v67, v[48:49], off offset:128
	global_load_dword v68, v[50:51], off
	global_load_dword v69, v[50:51], off offset:128
	global_load_dword v70, v[52:53], off
	global_load_dword v71, v[52:53], off offset:128
	v_lshl_add_u64 v[46:47], v[84:85], 0, v[98:99]
	v_lshl_add_u64 v[48:49], v[86:87], 0, v[98:99]
	v_lshl_add_u64 v[50:51], v[88:89], 0, v[98:99]
	v_lshl_add_u64 v[52:53], v[90:91], 0, v[98:99]
	global_load_dword v72, v[46:47], off
	global_load_dword v73, v[46:47], off offset:128
	global_load_dword v74, v[48:49], off
	s_nop 0
	global_load_dword v48, v[48:49], off offset:128
	s_nop 0
	global_load_dword v49, v[50:51], off
	s_nop 0
	global_load_dword v50, v[50:51], off offset:128
	s_nop 0
	global_load_dword v51, v[52:53], off
	s_nop 0
	global_load_dword v52, v[52:53], off offset:128
	v_lshl_add_u64 v[46:47], v[92:93], 0, v[98:99]
	global_load_dword v53, v[46:47], off
	s_nop 0
	global_load_dword v46, v[46:47], off offset:128
	s_waitcnt vmcnt(25)
	v_mul_f32_e32 v16, v16, v54
	s_waitcnt vmcnt(24)
	v_mul_f32_e32 v0, v0, v55
	v_mul_f32_e32 v1, v1, v55
	v_mul_f32_e32 v17, v17, v54
	v_mul_f32_e32 v18, v18, v54
	v_mul_f32_e32 v2, v2, v55
	v_mul_f32_e32 v19, v19, v54
	v_mul_f32_e32 v3, v3, v55
	s_waitcnt vmcnt(23)
	v_mul_f32_e32 v20, v20, v56
	s_waitcnt vmcnt(22)
	v_mul_f32_e32 v4, v4, v57
	s_waitcnt vmcnt(21)
	v_mul_f32_e32 v21, v21, v58
	s_waitcnt vmcnt(20)
	v_mul_f32_e32 v5, v5, v59
	s_waitcnt vmcnt(19)
	v_mul_f32_e32 v22, v22, v60
	s_waitcnt vmcnt(18)
	v_mul_f32_e32 v6, v6, v61
	s_waitcnt vmcnt(17)
	v_mul_f32_e32 v23, v23, v62
	s_waitcnt vmcnt(16)
	v_mul_f32_e32 v7, v7, v63
	s_waitcnt vmcnt(15)
	v_mul_f32_e32 v24, v24, v66
	s_waitcnt vmcnt(14)
	v_mul_f32_e32 v8, v8, v67
	s_waitcnt vmcnt(13)
	v_mul_f32_e32 v25, v25, v68
	s_waitcnt vmcnt(12)
	v_mul_f32_e32 v9, v9, v69
	s_waitcnt vmcnt(11)
	v_mul_f32_e32 v26, v26, v70
	s_waitcnt vmcnt(10)
	v_mul_f32_e32 v10, v10, v71
	s_waitcnt vmcnt(9)
	v_mul_f32_e32 v27, v27, v72
	s_waitcnt vmcnt(8)
	v_mul_f32_e32 v11, v11, v73
	s_waitcnt vmcnt(7)
	v_mul_f32_e32 v28, v28, v74
	s_waitcnt vmcnt(6)
	v_mul_f32_e32 v12, v12, v48
	s_waitcnt vmcnt(5)
	v_mul_f32_e32 v29, v29, v49
	s_waitcnt vmcnt(4)
	v_mul_f32_e32 v13, v13, v50
	s_waitcnt vmcnt(3)
	v_mul_f32_e32 v30, v30, v51
	s_waitcnt vmcnt(2)
	v_mul_f32_e32 v14, v14, v52
	ds_write2_b32 v162, v16, v0 offset1:32
	ds_write2_b32 v162, v17, v1 offset0:68 offset1:100
	ds_write2_b32 v162, v18, v2 offset0:136 offset1:168
	ds_write2_b32 v162, v19, v3 offset0:204 offset1:236
	ds_write2_b32 v115, v20, v4 offset0:32 offset1:64
	ds_write2_b32 v115, v21, v5 offset0:100 offset1:132
	ds_write2_b32 v115, v22, v6 offset0:168 offset1:200
	ds_write2_b32 v116, v23, v7 offset0:108 offset1:140
	ds_write2_b32 v117, v24, v8 offset0:64 offset1:96
	ds_write2_b32 v117, v25, v9 offset0:132 offset1:164
	ds_write2_b32 v117, v26, v10 offset0:200 offset1:232
	ds_write2_b32 v118, v27, v11 offset0:12 offset1:44
	ds_write2_b32 v119, v28, v12 offset0:96 offset1:128
	ds_write2_b32 v119, v29, v13 offset0:164 offset1:196
	ds_write2_b32 v120, v30, v14 offset0:104 offset1:136
	s_waitcnt vmcnt(1)
	v_mul_f32_e32 v0, v31, v53
	s_waitcnt vmcnt(0)
	v_mul_f32_e32 v1, v15, v46
	ds_write2_b32 v121, v0, v1 offset0:44 offset1:76
	v_add_u32_e32 v128, 0, v80
	v_ashrrev_i32_e32 v129, 31, v128
	v_lshlrev_b64 v[128:129], 12, v[128:129]
	v_lshl_add_u64 v[128:129], s[16:17], 0, v[128:129]
	v_lshl_add_u64 v[128:129], v[64:65], 2, v[128:129]
	global_load_dwordx4 v[128:131], v[128:129], off offset:256
	v_add_u32_e32 v132, 4, v80
	v_ashrrev_i32_e32 v133, 31, v132
	v_lshlrev_b64 v[132:133], 12, v[132:133]
	v_lshl_add_u64 v[132:133], s[16:17], 0, v[132:133]
	v_lshl_add_u64 v[132:133], v[64:65], 2, v[132:133]
	global_load_dwordx4 v[132:135], v[132:133], off offset:256
	v_add_u32_e32 v136, 8, v80
	v_ashrrev_i32_e32 v137, 31, v136
	v_lshlrev_b64 v[136:137], 12, v[136:137]
	v_lshl_add_u64 v[136:137], s[16:17], 0, v[136:137]
	v_lshl_add_u64 v[136:137], v[64:65], 2, v[136:137]
	global_load_dwordx4 v[136:139], v[136:137], off offset:256
	v_add_u32_e32 v140, 12, v80
	v_ashrrev_i32_e32 v141, 31, v140
	v_lshlrev_b64 v[140:141], 12, v[140:141]
	v_lshl_add_u64 v[140:141], s[16:17], 0, v[140:141]
	v_lshl_add_u64 v[140:141], v[64:65], 2, v[140:141]
	global_load_dwordx4 v[140:143], v[140:141], off offset:256
	v_add_u32_e32 v144, 16, v80
	v_ashrrev_i32_e32 v145, 31, v144
	v_lshlrev_b64 v[144:145], 12, v[144:145]
	v_lshl_add_u64 v[144:145], s[16:17], 0, v[144:145]
	v_lshl_add_u64 v[144:145], v[64:65], 2, v[144:145]
	global_load_dwordx4 v[144:147], v[144:145], off offset:256
	v_add_u32_e32 v148, 20, v80
	v_ashrrev_i32_e32 v149, 31, v148
	v_lshlrev_b64 v[148:149], 12, v[148:149]
	v_lshl_add_u64 v[148:149], s[16:17], 0, v[148:149]
	v_lshl_add_u64 v[148:149], v[64:65], 2, v[148:149]
	global_load_dwordx4 v[148:151], v[148:149], off offset:256
	v_add_u32_e32 v152, 24, v80
	v_ashrrev_i32_e32 v153, 31, v152
	v_lshlrev_b64 v[152:153], 12, v[152:153]
	v_lshl_add_u64 v[152:153], s[16:17], 0, v[152:153]
	v_lshl_add_u64 v[152:153], v[64:65], 2, v[152:153]
	global_load_dwordx4 v[152:155], v[152:153], off offset:256
	v_add_u32_e32 v156, 28, v80
	v_ashrrev_i32_e32 v157, 31, v156
	v_lshlrev_b64 v[156:157], 12, v[156:157]
	v_lshl_add_u64 v[156:157], s[16:17], 0, v[156:157]
	v_lshl_add_u64 v[156:157], v[64:65], 2, v[156:157]
	global_load_dwordx4 v[156:159], v[156:157], off offset:256
	s_and_saveexec_b64 s[24:25], vcc
	s_cbranch_execz .LBB0_2279
	v_lshlrev_b64 v[0:1], 12, v[80:81]
	v_lshl_add_u64 v[0:1], s[16:17], 0, v[0:1]
	v_lshl_add_u64 v[8:9], v[64:65], 2, v[0:1]
	ds_read_b128 v[4:7], v114
	s_waitcnt vmcnt(7) lgkmcnt(0)
	v_pk_add_f32 v[2:3], v[6:7], v[130:131]
	v_pk_add_f32 v[0:1], v[4:5], v[128:129]
	global_store_dwordx4 v[8:9], v[0:3], off offset:256
	s_or_b64 exec, exec, s[24:25]
	s_and_saveexec_b64 s[24:25], s[2:3]
	s_cbranch_execnz .LBB0_2280

.LBB0_2274:
	v_lshlrev_b64 v[0:1], 12, v[34:35]
	v_lshl_add_u64 v[0:1], s[16:17], 0, v[0:1]
	v_lshl_add_u64 v[8:9], v[64:65], 2, v[0:1]
	ds_read_b128 v[4:7], v114 offset:2176
	s_waitcnt vmcnt(7) lgkmcnt(0)
	v_pk_add_f32 v[2:3], v[6:7], v[138:139]
	v_pk_add_f32 v[0:1], v[4:5], v[136:137]
	global_store_dwordx4 v[8:9], v[0:3], off offset:256
	s_or_b64 exec, exec, s[2:3]
	s_and_saveexec_b64 s[2:3], s[6:7]
	s_cbranch_execnz .LBB0_2282

.LBB0_2276:
	v_lshlrev_b64 v[0:1], 12, v[38:39]
	v_lshl_add_u64 v[0:1], s[16:17], 0, v[0:1]
	v_lshl_add_u64 v[8:9], v[64:65], 2, v[0:1]
	ds_read_b128 v[4:7], v114 offset:4352
	s_waitcnt vmcnt(7) lgkmcnt(0)
	v_pk_add_f32 v[2:3], v[6:7], v[146:147]
	v_pk_add_f32 v[0:1], v[4:5], v[144:145]
	global_store_dwordx4 v[8:9], v[0:3], off offset:256
	s_or_b64 exec, exec, s[2:3]
	s_and_saveexec_b64 s[2:3], s[10:11]
	s_cbranch_execnz .LBB0_2284

.LBB0_2278:
	v_lshlrev_b64 v[0:1], 12, v[42:43]
	v_lshl_add_u64 v[0:1], s[16:17], 0, v[0:1]
	v_lshl_add_u64 v[8:9], v[64:65], 2, v[0:1]
	ds_read_b128 v[4:7], v114 offset:6528
	s_waitcnt vmcnt(7) lgkmcnt(0)
	v_pk_add_f32 v[2:3], v[6:7], v[154:155]
	v_pk_add_f32 v[0:1], v[4:5], v[152:153]
	global_store_dwordx4 v[8:9], v[0:3], off offset:256
	s_or_b64 exec, exec, s[2:3]
	s_and_saveexec_b64 s[2:3], s[14:15]
	s_cbranch_execz .LBB0_2218
	s_branch .LBB0_2286

.LBB0_2280:
	v_lshlrev_b64 v[0:1], 12, v[32:33]
	v_lshl_add_u64 v[0:1], s[16:17], 0, v[0:1]
	v_lshl_add_u64 v[8:9], v[64:65], 2, v[0:1]
	ds_read_b128 v[4:7], v114 offset:1088
	s_waitcnt vmcnt(7) lgkmcnt(0)
	v_pk_add_f32 v[2:3], v[6:7], v[134:135]
	v_pk_add_f32 v[0:1], v[4:5], v[132:133]
	global_store_dwordx4 v[8:9], v[0:3], off offset:256
	s_or_b64 exec, exec, s[24:25]
	s_and_saveexec_b64 s[2:3], s[4:5]
	s_cbranch_execnz .LBB0_2274

.LBB0_2282:
	v_lshlrev_b64 v[0:1], 12, v[36:37]
	v_lshl_add_u64 v[0:1], s[16:17], 0, v[0:1]
	v_lshl_add_u64 v[8:9], v[64:65], 2, v[0:1]
	ds_read_b128 v[4:7], v114 offset:3264
	s_waitcnt vmcnt(7) lgkmcnt(0)
	v_pk_add_f32 v[2:3], v[6:7], v[142:143]
	v_pk_add_f32 v[0:1], v[4:5], v[140:141]
	global_store_dwordx4 v[8:9], v[0:3], off offset:256
	s_or_b64 exec, exec, s[2:3]
	s_and_saveexec_b64 s[2:3], s[8:9]
	s_cbranch_execnz .LBB0_2276

.LBB0_2284:
	v_lshlrev_b64 v[0:1], 12, v[40:41]
	v_lshl_add_u64 v[0:1], s[16:17], 0, v[0:1]
	v_lshl_add_u64 v[8:9], v[64:65], 2, v[0:1]
	ds_read_b128 v[4:7], v114 offset:5440
	s_waitcnt vmcnt(7) lgkmcnt(0)
	v_pk_add_f32 v[2:3], v[6:7], v[150:151]
	v_pk_add_f32 v[0:1], v[4:5], v[148:149]
	global_store_dwordx4 v[8:9], v[0:3], off offset:256
	s_or_b64 exec, exec, s[2:3]
	s_and_saveexec_b64 s[2:3], s[12:13]
	s_cbranch_execnz .LBB0_2278

.LBB0_2286:
	v_lshlrev_b64 v[0:1], 12, v[44:45]
	v_lshl_add_u64 v[0:1], s[16:17], 0, v[0:1]
	v_lshl_add_u64 v[8:9], v[64:65], 2, v[0:1]
	ds_read_b128 v[4:7], v114 offset:7616
	s_waitcnt vmcnt(7) lgkmcnt(0)
	v_pk_add_f32 v[2:3], v[6:7], v[158:159]
	v_pk_add_f32 v[0:1], v[4:5], v[156:157]
	global_store_dwordx4 v[8:9], v[0:3], off offset:256
	s_branch .LBB0_2218

.LBB0_2404:
	v_mbcnt_hi_u32_b32 v188, -1, v210
	s_load_dwordx2 s[2:3], s[0:1], 0x158
	s_load_dwordx2 s[4:5], s[0:1], 0x110
	s_ashr_i32 s7, s6, 31
	v_mov_b32_e32 v1, v188
	s_and_b32 s7, s7, s42
	s_add_i32 s82, s7, s6
	v_add_u32_e32 v0, s70, v1
	v_ashrrev_i32_e32 v189, 3, v0
	v_readfirstlane_b32 s8, v0
	v_lshlrev_b32_e32 v0, 3, v1
	v_and_b32_e32 v0, 56, v0
	s_cmpk_lt_i32 s82, 0x780
	s_cselect_b64 s[6:7], -1, 0
	s_cmpk_gt_i32 s82, 0x77f
	v_lshlrev_b32_e32 v160, 1, v0
	v_add_u32_e32 v190, 64, v189
	s_cbranch_scc1 .LBB0_2406
	s_mul_hi_i32 s9, s82, 0x88888889
	s_add_i32 s9, s9, s82
	s_lshr_b32 s10, s9, 31
	s_ashr_i32 s9, s9, 3
	s_add_i32 s9, s9, s10
	s_mul_i32 s10, s9, -15
	s_lshl_b32 s9, s9, 8
	v_add_u32_e32 v2, s9, v189
	v_min_i32_e32 v2, 0x7fff, v2
	v_ashrrev_i32_e32 v3, 31, v2
	v_lshlrev_b64 v[2:3], 11, v[2:3]
	s_add_i32 s10, s10, s82
	s_waitcnt lgkmcnt(0)
	v_lshl_add_u64 v[2:3], s[2:3], 0, v[2:3]
	v_mov_b32_e32 v161, 0
	s_lshl_b32 s10, s10, 8
	v_lshl_add_u64 v[2:3], v[2:3], 0, v[160:161]
	v_mbcnt_hi_u32_b32 v158, -1, v210
	s_and_b32 s90, s70, 0x40
	v_and_b32_e32 v159, 48, v158
	v_or_b32_e32 v159, s90, v159
	s_lshl_b32 s88, s70, 4
	s_lshl_b32 s92, s22, 4
	s_and_b32 s92, s92, 0x780
	s_mov_b32 s93, 0
	s_add_u32 m0, s88, 0
	v_lshl_add_u64 v[2:3], v[2:3], 0, s[92:93]
	v_xor_b32_e32 v2, v159, v2
	global_load_lds_dwordx4 v[2:3], off
	v_add_u32_e32 v2, s10, v189
	v_ashrrev_i32_e32 v3, 31, v2
	v_lshlrev_b64 v[2:3], 11, v[2:3]
	v_lshl_add_u64 v[2:3], s[4:5], 0, v[2:3]
	v_lshl_add_u64 v[2:3], v[2:3], 0, v[160:161]
	s_add_u32 m0, s88, 32768
	v_lshl_add_u64 v[2:3], v[2:3], 0, s[92:93]
	v_xor_b32_e32 v2, v159, v2
	global_load_lds_dwordx4 v[2:3], off
	v_add_u32_e32 v2, s9, v190
	v_min_i32_e32 v2, 0x7fff, v2
	v_ashrrev_i32_e32 v3, 31, v2
	v_lshlrev_b64 v[2:3], 11, v[2:3]
	v_lshl_add_u64 v[2:3], s[2:3], 0, v[2:3]
	v_lshl_add_u64 v[2:3], v[2:3], 0, v[160:161]
	s_add_u32 m0, s88, 8192
	v_lshl_add_u64 v[2:3], v[2:3], 0, s[92:93]
	v_xor_b32_e32 v2, v159, v2
	global_load_lds_dwordx4 v[2:3], off
	v_add_u32_e32 v2, s10, v190
	v_ashrrev_i32_e32 v3, 31, v2
	v_lshlrev_b64 v[2:3], 11, v[2:3]
	v_lshl_add_u64 v[2:3], s[4:5], 0, v[2:3]
	v_lshl_add_u64 v[2:3], v[2:3], 0, v[160:161]
	v_add_u32_e32 v4, 0x80, v189
	s_add_u32 m0, s88, 40960
	v_lshl_add_u64 v[2:3], v[2:3], 0, s[92:93]
	v_xor_b32_e32 v2, v159, v2
	global_load_lds_dwordx4 v[2:3], off
	v_add_u32_e32 v2, s9, v4
	v_min_i32_e32 v2, 0x7fff, v2
	v_ashrrev_i32_e32 v3, 31, v2
	v_lshlrev_b64 v[2:3], 11, v[2:3]
	v_lshl_add_u64 v[2:3], s[2:3], 0, v[2:3]
	v_lshl_add_u64 v[2:3], v[2:3], 0, v[160:161]
	s_add_u32 m0, s88, 16384
	v_lshl_add_u64 v[2:3], v[2:3], 0, s[92:93]
	v_xor_b32_e32 v2, v159, v2
	global_load_lds_dwordx4 v[2:3], off
	v_add_u32_e32 v2, s10, v4
	v_ashrrev_i32_e32 v3, 31, v2
	v_lshlrev_b64 v[2:3], 11, v[2:3]
	v_lshl_add_u64 v[2:3], s[4:5], 0, v[2:3]
	v_lshl_add_u64 v[2:3], v[2:3], 0, v[160:161]
	v_add_u32_e32 v4, 0xc0, v189
	s_add_u32 m0, s88, 49152
	v_lshl_add_u64 v[2:3], v[2:3], 0, s[92:93]
	v_xor_b32_e32 v2, v159, v2
	global_load_lds_dwordx4 v[2:3], off
	v_add_u32_e32 v2, s9, v4
	v_min_i32_e32 v2, 0x7fff, v2
	v_ashrrev_i32_e32 v3, 31, v2
	v_lshlrev_b64 v[2:3], 11, v[2:3]
	v_lshl_add_u64 v[2:3], s[2:3], 0, v[2:3]
	v_lshl_add_u64 v[2:3], v[2:3], 0, v[160:161]
	s_add_u32 m0, s88, 24576
	v_lshl_add_u64 v[2:3], v[2:3], 0, s[92:93]
	v_xor_b32_e32 v2, v159, v2
	global_load_lds_dwordx4 v[2:3], off
	v_add_u32_e32 v2, s10, v4
	v_ashrrev_i32_e32 v3, 31, v2
	v_lshlrev_b64 v[2:3], 11, v[2:3]
	v_lshl_add_u64 v[2:3], s[4:5], 0, v[2:3]
	v_lshl_add_u64 v[2:3], v[2:3], 0, v[160:161]
	s_add_u32 m0, s88, 57344
	v_lshl_add_u64 v[2:3], v[2:3], 0, s[92:93]
	v_xor_b32_e32 v2, v159, v2
	global_load_lds_dwordx4 v[2:3], off

.LBB0_2409:
	s_mul_hi_i32 s2, s82, 0x88888889
	s_add_i32 s2, s2, s82
	s_lshr_b32 s3, s2, 31
	s_ashr_i32 s5, s2, 3
	s_add_i32 s5, s5, s3
	s_lshl_b32 s85, s5, 8
	s_waitcnt lgkmcnt(0)
	v_add_u32_e32 v0, s85, v189
	v_min_i32_e32 v0, 0x7fff, v0
	v_ashrrev_i32_e32 v1, 31, v0
	v_lshlrev_b64 v[0:1], 11, v[0:1]
	s_mul_i32 s2, s5, 0xf00
	v_lshl_add_u64 v[172:173], v[168:169], 0, v[0:1]
	v_subrev_u32_e32 v0, s2, v197
	v_ashrrev_i32_e32 v1, 31, v0
	v_lshlrev_b64 v[0:1], 11, v[0:1]
	v_lshl_add_u64 v[180:181], v[170:171], 0, v[0:1]
	v_subrev_u32_e32 v0, s2, v198
	v_ashrrev_i32_e32 v1, 31, v0
	v_lshlrev_b64 v[0:1], 11, v[0:1]
	v_lshl_add_u64 v[182:183], v[170:171], 0, v[0:1]
	v_subrev_u32_e32 v0, s2, v199
	v_ashrrev_i32_e32 v1, 31, v0
	v_add_u32_e32 v2, s85, v190
	v_add_u32_e32 v4, s85, v163
	v_add_u32_e32 v6, s85, v192
	v_lshlrev_b64 v[0:1], 11, v[0:1]
	v_min_i32_e32 v2, 0x7fff, v2
	v_min_i32_e32 v4, 0x7fff, v4
	v_min_i32_e32 v6, 0x7fff, v6
	v_lshl_add_u64 v[184:185], v[170:171], 0, v[0:1]
	v_subrev_u32_e32 v0, s2, v200
	v_ashrrev_i32_e32 v3, 31, v2
	v_ashrrev_i32_e32 v5, 31, v4
	v_ashrrev_i32_e32 v7, 31, v6
	v_ashrrev_i32_e32 v1, 31, v0
	v_lshlrev_b64 v[2:3], 11, v[2:3]
	v_lshlrev_b64 v[4:5], 11, v[4:5]
	v_lshlrev_b64 v[6:7], 11, v[6:7]
	v_lshlrev_b64 v[0:1], 11, v[0:1]
	s_mov_b32 s4, s82
	v_lshl_add_u64 v[174:175], v[168:169], 0, v[2:3]
	v_lshl_add_u64 v[176:177], v[168:169], 0, v[4:5]
	v_lshl_add_u64 v[178:179], v[168:169], 0, v[6:7]
	v_lshl_add_u64 v[186:187], v[170:171], 0, v[0:1]
	s_mov_b64 s[2:3], 0
	s_mov_b32 s6, s21
	v_mov_b32_e32 v0, 0
	v_mov_b32_e32 v1, v161
	v_mov_b32_e32 v2, v161
	v_mov_b32_e32 v3, v161
	v_mov_b32_e32 v4, v161
	v_mov_b32_e32 v5, v161
	v_mov_b32_e32 v6, v161
	v_mov_b32_e32 v7, v161
	v_mov_b32_e32 v8, v161
	v_mov_b32_e32 v9, v161
	v_mov_b32_e32 v10, v161
	v_mov_b32_e32 v11, v161
	v_mov_b32_e32 v12, v161
	v_mov_b32_e32 v13, v161
	v_mov_b32_e32 v14, v161
	v_mov_b32_e32 v15, v161
	v_mov_b32_e32 v16, 0
	v_mov_b32_e32 v17, v161
	v_mov_b32_e32 v18, v161
	v_mov_b32_e32 v19, v161
	v_mov_b32_e32 v20, v161
	v_mov_b32_e32 v21, v161
	v_mov_b32_e32 v22, v161
	v_mov_b32_e32 v23, v161
	v_mov_b32_e32 v24, v161
	v_mov_b32_e32 v25, v161
	v_mov_b32_e32 v26, v161
	v_mov_b32_e32 v27, v161
	v_mov_b32_e32 v28, v161
	v_mov_b32_e32 v29, v161
	v_mov_b32_e32 v30, v161
	v_mov_b32_e32 v31, v161
	v_mov_b32_e32 v32, 0
	v_mov_b32_e32 v33, v161
	v_mov_b32_e32 v34, v161
	v_mov_b32_e32 v35, v161
	v_mov_b32_e32 v36, v161
	v_mov_b32_e32 v37, v161
	v_mov_b32_e32 v38, v161
	v_mov_b32_e32 v39, v161
	v_mov_b32_e32 v40, v161
	v_mov_b32_e32 v41, v161
	v_mov_b32_e32 v42, v161
	v_mov_b32_e32 v43, v161
	v_mov_b32_e32 v44, v161
	v_mov_b32_e32 v45, v161
	v_mov_b32_e32 v46, v161
	v_mov_b32_e32 v47, v161
	v_mov_b32_e32 v48, 0
	v_mov_b32_e32 v49, v161
	v_mov_b32_e32 v50, v161
	v_mov_b32_e32 v51, v161
	v_mov_b32_e32 v52, v161
	v_mov_b32_e32 v53, v161
	v_mov_b32_e32 v54, v161
	v_mov_b32_e32 v55, v161
	v_mov_b32_e32 v56, v161
	v_mov_b32_e32 v57, v161
	v_mov_b32_e32 v58, v161
	v_mov_b32_e32 v59, v161
	v_mov_b32_e32 v60, v161
	v_mov_b32_e32 v61, v161
	v_mov_b32_e32 v62, v161
	v_mov_b32_e32 v63, v161
	v_mov_b32_e32 v64, 0
	v_mov_b32_e32 v65, v161
	v_mov_b32_e32 v66, v161
	v_mov_b32_e32 v67, v161
	v_mov_b32_e32 v68, v161
	v_mov_b32_e32 v69, v161
	v_mov_b32_e32 v70, v161
	v_mov_b32_e32 v71, v161
	v_mov_b32_e32 v72, v161
	v_mov_b32_e32 v73, v161
	v_mov_b32_e32 v74, v161
	v_mov_b32_e32 v75, v161
	v_mov_b32_e32 v76, v161
	v_mov_b32_e32 v77, v161
	v_mov_b32_e32 v78, v161
	v_mov_b32_e32 v79, v161
	v_mov_b32_e32 v80, 0
	v_mov_b32_e32 v81, v161
	v_mov_b32_e32 v82, v161
	v_mov_b32_e32 v83, v161
	v_mov_b32_e32 v84, v161
	v_mov_b32_e32 v85, v161
	v_mov_b32_e32 v86, v161
	v_mov_b32_e32 v87, v161
	v_mov_b32_e32 v88, v161
	v_mov_b32_e32 v89, v161
	v_mov_b32_e32 v90, v161
	v_mov_b32_e32 v91, v161
	v_mov_b32_e32 v92, v161
	v_mov_b32_e32 v93, v161
	v_mov_b32_e32 v94, v161
	v_mov_b32_e32 v95, v161
	v_mov_b32_e32 v96, 0
	v_mov_b32_e32 v97, v161
	v_mov_b32_e32 v98, v161
	v_mov_b32_e32 v99, v161
	v_mov_b32_e32 v100, v161
	v_mov_b32_e32 v101, v161
	v_mov_b32_e32 v102, v161
	v_mov_b32_e32 v103, v161
	v_mov_b32_e32 v104, v161
	v_mov_b32_e32 v105, v161
	v_mov_b32_e32 v106, v161
	v_mov_b32_e32 v107, v161
	v_mov_b32_e32 v108, v161
	v_mov_b32_e32 v109, v161
	v_mov_b32_e32 v110, v161
	v_mov_b32_e32 v111, v161
	v_mov_b32_e32 v112, 0
	v_mov_b32_e32 v113, v161
	v_mov_b32_e32 v114, v161
	v_mov_b32_e32 v115, v161
	v_mov_b32_e32 v116, v161
	v_mov_b32_e32 v117, v161
	v_mov_b32_e32 v118, v161
	v_mov_b32_e32 v119, v161
	v_mov_b32_e32 v120, v161
	v_mov_b32_e32 v121, v161
	v_mov_b32_e32 v122, v161
	v_mov_b32_e32 v123, v161
	v_mov_b32_e32 v124, v161
	v_mov_b32_e32 v125, v161
	v_mov_b32_e32 v126, v161
	v_mov_b32_e32 v127, v161
	v_mbcnt_hi_u32_b32 v128, -1, v210
	s_and_b32 s90, s70, 0x40
	v_and_b32_e32 v159, 48, v128
	v_or_b32_e32 v159, s90, v159
	v_and_b32_e32 v129, 31, v128
	v_lshrrev_b32_e32 v130, 5, v128
	v_bfe_u32 v131, v128, 1, 3
	v_lshlrev_b32_e32 v132, 7, v129
	s_lshr_b32 s91, s70, 7
	s_lshl_b32 s91, s91, 13
	s_lshl_b32 s90, s90, 8
	s_add_u32 s90, s90, 0x8000
	s_lshl_b32 s88, s70, 4
	s_mov_b32 s89, 0x10000
	s_lshl_b32 s92, s22, 4
	s_and_b32 s92, s92, 0x780
	s_mov_b32 s93, 0
	v_xor_b32_e32 v133, v130, v131
	v_lshl_add_u32 v133, v133, 4, v132
	v_add_u32_e32 v228, s91, v133
	v_add_u32_e32 v232, s90, v133
	v_or_b32_e32 v133, 2, v130
	v_xor_b32_e32 v133, v133, v131
	v_lshl_add_u32 v133, v133, 4, v132
	v_add_u32_e32 v229, s91, v133
	v_add_u32_e32 v233, s90, v133
	v_or_b32_e32 v133, 4, v130
	v_xor_b32_e32 v133, v133, v131
	v_lshl_add_u32 v133, v133, 4, v132
	v_add_u32_e32 v230, s91, v133
	v_add_u32_e32 v234, s90, v133
	v_or_b32_e32 v133, 6, v130
	v_xor_b32_e32 v133, v133, v131
	v_lshl_add_u32 v133, v133, 4, v132
	v_add_u32_e32 v231, s91, v133
	v_add_u32_e32 v235, s90, v133
	s_waitcnt vmcnt(0)
	s_barrier
	ds_read_b128 v[202:205], v228
	ds_read_b128 v[212:215], v232
	ds_read_b128 v[206:209], v228 offset:4096
	ds_read_b128 v[216:219], v232 offset:4096
	ds_read_b128 v[220:223], v232 offset:8192
	ds_read_b128 v[224:227], v232 offset:12288
	s_add_u32 s94, s2, s92
	s_add_u32 s94, s94, 0x80
	s_and_b32 s94, s94, 0x780
	s_sub_u32 s94, s94, 0x80
	s_subb_u32 s95, 0, 0
	s_add_u32 s90, s88, s89
	s_add_u32 m0, s90, 0
	v_lshl_add_u64 v[152:153], v[172:173], 0, s[94:95]
	v_xor_b32_e32 v152, v159, v152
	global_load_lds_dwordx4 v[152:153], off
	s_add_u32 m0, s90, 32768
	v_lshl_add_u64 v[154:155], v[180:181], 0, s[94:95]
	v_xor_b32_e32 v154, v159, v154
	global_load_lds_dwordx4 v[154:155], off
	s_add_u32 m0, s90, 8192
	v_lshl_add_u64 v[156:157], v[174:175], 0, s[94:95]
	v_xor_b32_e32 v156, v159, v156
	global_load_lds_dwordx4 v[156:157], off
	s_add_u32 m0, s90, 40960
	v_lshl_add_u64 v[152:153], v[182:183], 0, s[94:95]
	v_xor_b32_e32 v152, v159, v152
	global_load_lds_dwordx4 v[152:153], off
	s_add_u32 m0, s90, 16384
	v_lshl_add_u64 v[154:155], v[176:177], 0, s[94:95]
	v_xor_b32_e32 v154, v159, v154
	global_load_lds_dwordx4 v[154:155], off
	s_add_u32 m0, s90, 49152
	v_lshl_add_u64 v[156:157], v[184:185], 0, s[94:95]
	v_xor_b32_e32 v156, v159, v156
	global_load_lds_dwordx4 v[156:157], off
	s_add_u32 m0, s90, 24576
	v_lshl_add_u64 v[152:153], v[178:179], 0, s[94:95]
	v_xor_b32_e32 v152, v159, v152
	global_load_lds_dwordx4 v[152:153], off
	s_add_u32 m0, s90, 57344
	v_lshl_add_u64 v[154:155], v[186:187], 0, s[94:95]
	v_xor_b32_e32 v154, v159, v154
	global_load_lds_dwordx4 v[154:155], off
	s_xor_b32 s89, s89, 0x10000
.Lgk4_loop:
	ds_read_b128 v[128:131], v229
	ds_read_b128 v[136:139], v233
	ds_read_b128 v[132:135], v229 offset:4096
	ds_read_b128 v[140:143], v233 offset:4096
	ds_read_b128 v[144:147], v233 offset:8192
	ds_read_b128 v[148:151], v233 offset:12288
	s_waitcnt lgkmcnt(6)
	v_mfma_f32_32x32x16_bf16 v[112:127], v[202:205], v[212:215], v[112:127]
	v_mfma_f32_32x32x16_bf16 v[48:63], v[206:209], v[212:215], v[48:63]
	v_mfma_f32_32x32x16_bf16 v[96:111], v[202:205], v[216:219], v[96:111]
	v_mfma_f32_32x32x16_bf16 v[32:47], v[206:209], v[216:219], v[32:47]
	v_mfma_f32_32x32x16_bf16 v[80:95], v[202:205], v[220:223], v[80:95]
	v_mfma_f32_32x32x16_bf16 v[16:31], v[206:209], v[220:223], v[16:31]
	v_mfma_f32_32x32x16_bf16 v[64:79], v[202:205], v[224:227], v[64:79]
	v_mfma_f32_32x32x16_bf16 v[0:15], v[206:209], v[224:227], v[0:15]
	ds_read_b128 v[202:205], v230
	ds_read_b128 v[212:215], v234
	ds_read_b128 v[206:209], v230 offset:4096
	ds_read_b128 v[216:219], v234 offset:4096
	ds_read_b128 v[220:223], v234 offset:8192
	ds_read_b128 v[224:227], v234 offset:12288
	s_waitcnt lgkmcnt(6)
	v_mfma_f32_32x32x16_bf16 v[112:127], v[128:131], v[136:139], v[112:127]
	v_mfma_f32_32x32x16_bf16 v[48:63], v[132:135], v[136:139], v[48:63]
	v_mfma_f32_32x32x16_bf16 v[96:111], v[128:131], v[140:143], v[96:111]
	v_mfma_f32_32x32x16_bf16 v[32:47], v[132:135], v[140:143], v[32:47]
	v_mfma_f32_32x32x16_bf16 v[80:95], v[128:131], v[144:147], v[80:95]
	v_mfma_f32_32x32x16_bf16 v[16:31], v[132:135], v[144:147], v[16:31]
	v_mfma_f32_32x32x16_bf16 v[64:79], v[128:131], v[148:151], v[64:79]
	v_mfma_f32_32x32x16_bf16 v[0:15], v[132:135], v[148:151], v[0:15]
	ds_read_b128 v[128:131], v231
	ds_read_b128 v[136:139], v235
	ds_read_b128 v[132:135], v231 offset:4096
	ds_read_b128 v[140:143], v235 offset:4096
	ds_read_b128 v[144:147], v235 offset:8192
	ds_read_b128 v[148:151], v235 offset:12288
	s_waitcnt lgkmcnt(6)
	v_mfma_f32_32x32x16_bf16 v[112:127], v[202:205], v[212:215], v[112:127]
	v_mfma_f32_32x32x16_bf16 v[48:63], v[206:209], v[212:215], v[48:63]
	v_mfma_f32_32x32x16_bf16 v[96:111], v[202:205], v[216:219], v[96:111]
	v_mfma_f32_32x32x16_bf16 v[32:47], v[206:209], v[216:219], v[32:47]
	v_mfma_f32_32x32x16_bf16 v[80:95], v[202:205], v[220:223], v[80:95]
	v_mfma_f32_32x32x16_bf16 v[16:31], v[206:209], v[220:223], v[16:31]
	v_mfma_f32_32x32x16_bf16 v[64:79], v[202:205], v[224:227], v[64:79]
	v_mfma_f32_32x32x16_bf16 v[0:15], v[206:209], v[224:227], v[0:15]
	s_waitcnt vmcnt(0) lgkmcnt(0)
	s_barrier
	v_xor_b32_e32 v228, 0x10000, v228
	v_xor_b32_e32 v232, 0x10000, v232
	ds_read_b128 v[202:205], v228
	ds_read_b128 v[212:215], v232
	ds_read_b128 v[206:209], v228 offset:4096
	ds_read_b128 v[216:219], v232 offset:4096
	ds_read_b128 v[220:223], v232 offset:8192
	ds_read_b128 v[224:227], v232 offset:12288
	s_cmpk_eq_i32 s2, 0x700
	s_cbranch_scc1 .Lgk4_nodma
	s_add_u32 s94, s2, s92
	s_add_u32 s94, s94, 0x100
	s_and_b32 s94, s94, 0x780
	s_sub_u32 s94, s94, 0x80
	s_subb_u32 s95, 0, 0
	s_add_u32 s90, s88, s89
	v_mfma_f32_32x32x16_bf16 v[112:127], v[128:131], v[136:139], v[112:127]
	v_xor_b32_e32 v229, 0x10000, v229
	v_xor_b32_e32 v233, 0x10000, v233
	s_add_u32 m0, s90, 0
	v_lshl_add_u64 v[152:153], v[172:173], 0, s[94:95]
	v_xor_b32_e32 v152, v159, v152
	global_load_lds_dwordx4 v[152:153], off
	v_mfma_f32_32x32x16_bf16 v[48:63], v[132:135], v[136:139], v[48:63]
	v_xor_b32_e32 v230, 0x10000, v230
	v_xor_b32_e32 v234, 0x10000, v234
	s_add_u32 m0, s90, 32768
	v_lshl_add_u64 v[154:155], v[180:181], 0, s[94:95]
	v_xor_b32_e32 v154, v159, v154
	global_load_lds_dwordx4 v[154:155], off
	v_mfma_f32_32x32x16_bf16 v[96:111], v[128:131], v[140:143], v[96:111]
	v_xor_b32_e32 v231, 0x10000, v231
	v_xor_b32_e32 v235, 0x10000, v235
	s_add_u32 m0, s90, 8192
	v_lshl_add_u64 v[156:157], v[174:175], 0, s[94:95]
	v_xor_b32_e32 v156, v159, v156
	global_load_lds_dwordx4 v[156:157], off
	v_mfma_f32_32x32x16_bf16 v[32:47], v[132:135], v[140:143], v[32:47]
	s_add_u32 m0, s90, 40960
	v_lshl_add_u64 v[152:153], v[182:183], 0, s[94:95]
	v_xor_b32_e32 v152, v159, v152
	global_load_lds_dwordx4 v[152:153], off
	v_mfma_f32_32x32x16_bf16 v[80:95], v[128:131], v[144:147], v[80:95]
	s_add_u32 m0, s90, 16384
	v_lshl_add_u64 v[154:155], v[176:177], 0, s[94:95]
	v_xor_b32_e32 v154, v159, v154
	global_load_lds_dwordx4 v[154:155], off
	v_mfma_f32_32x32x16_bf16 v[16:31], v[132:135], v[144:147], v[16:31]
	s_add_u32 m0, s90, 49152
	v_lshl_add_u64 v[156:157], v[184:185], 0, s[94:95]
	v_xor_b32_e32 v156, v159, v156
	global_load_lds_dwordx4 v[156:157], off
	v_mfma_f32_32x32x16_bf16 v[64:79], v[128:131], v[148:151], v[64:79]
	s_add_u32 m0, s90, 24576
	v_lshl_add_u64 v[152:153], v[178:179], 0, s[94:95]
	v_xor_b32_e32 v152, v159, v152
	global_load_lds_dwordx4 v[152:153], off
	v_mfma_f32_32x32x16_bf16 v[0:15], v[132:135], v[148:151], v[0:15]
	s_add_u32 m0, s90, 57344
	v_lshl_add_u64 v[154:155], v[186:187], 0, s[94:95]
	v_xor_b32_e32 v154, v159, v154
	global_load_lds_dwordx4 v[154:155], off
	s_branch .Lgk4_join
.Lgk4_nodma:
	v_mfma_f32_32x32x16_bf16 v[112:127], v[128:131], v[136:139], v[112:127]
	v_xor_b32_e32 v229, 0x10000, v229
	v_xor_b32_e32 v233, 0x10000, v233
	v_mfma_f32_32x32x16_bf16 v[48:63], v[132:135], v[136:139], v[48:63]
	v_xor_b32_e32 v230, 0x10000, v230
	v_xor_b32_e32 v234, 0x10000, v234
	v_mfma_f32_32x32x16_bf16 v[96:111], v[128:131], v[140:143], v[96:111]
	v_xor_b32_e32 v231, 0x10000, v231
	v_xor_b32_e32 v235, 0x10000, v235
	v_mfma_f32_32x32x16_bf16 v[32:47], v[132:135], v[140:143], v[32:47]
	v_mfma_f32_32x32x16_bf16 v[80:95], v[128:131], v[144:147], v[80:95]
	v_mfma_f32_32x32x16_bf16 v[16:31], v[132:135], v[144:147], v[16:31]
	v_mfma_f32_32x32x16_bf16 v[64:79], v[128:131], v[148:151], v[64:79]
	v_mfma_f32_32x32x16_bf16 v[0:15], v[132:135], v[148:151], v[0:15]
.Lgk4_join:
	s_xor_b32 s89, s89, 0x10000
	s_add_i32 s6, s6, 1
	s_add_u32 s2, s2, 0x80
	s_addc_u32 s3, s3, 0
	s_cmpk_eq_i32 s2, 0x780
	s_cbranch_scc0 .Lgk4_loop
	s_add_i32 s82, s4, s42
	s_cmpk_gt_i32 s82, 0x77f
	s_cselect_b64 s[34:35], -1, 0
	s_and_b64 vcc, exec, s[34:35]
	s_cbranch_vccnz .LBB0_2413
	s_mul_hi_i32 s2, s82, 0x88888889
	s_add_i32 s2, s2, s82
	s_lshr_b32 s3, s2, 31
	s_ashr_i32 s2, s2, 3
	s_add_i32 s2, s2, s3
	s_mul_i32 s3, s2, -15
	s_lshl_b32 s2, s2, 8
	v_add_u32_e32 v129, s2, v190
	s_add_i32 s3, s3, s82
	v_min_i32_e32 v132, 0x7fff, v129
	v_add_u32_e32 v129, s2, v163
	s_lshl_b32 s3, s3, 8
	v_add_u32_e32 v128, s2, v189
	v_min_i32_e32 v136, 0x7fff, v129
	v_add_u32_e32 v129, s2, v192
	v_min_i32_e32 v128, 0x7fff, v128
	v_add_u32_e32 v130, s3, v189
	v_add_u32_e32 v134, s3, v190
	v_add_u32_e32 v138, s3, v163
	v_min_i32_e32 v140, 0x7fff, v129
	v_add_u32_e32 v142, s3, v192
	v_ashrrev_i32_e32 v143, 31, v142
	v_ashrrev_i32_e32 v141, 31, v140
	v_ashrrev_i32_e32 v139, 31, v138
	v_ashrrev_i32_e32 v137, 31, v136
	v_ashrrev_i32_e32 v135, 31, v134
	v_ashrrev_i32_e32 v133, 31, v132
	v_ashrrev_i32_e32 v131, 31, v130
	v_ashrrev_i32_e32 v129, 31, v128
	v_lshlrev_b64 v[142:143], 11, v[142:143]
	v_lshlrev_b64 v[140:141], 11, v[140:141]
	v_lshlrev_b64 v[138:139], 11, v[138:139]
	v_lshlrev_b64 v[136:137], 11, v[136:137]
	v_lshlrev_b64 v[134:135], 11, v[134:135]
	v_lshlrev_b64 v[132:133], 11, v[132:133]
	v_lshlrev_b64 v[130:131], 11, v[130:131]
	v_lshlrev_b64 v[128:129], 11, v[128:129]
	v_lshl_add_u64 v[156:157], v[164:165], 0, v[142:143]
	v_lshl_add_u64 v[152:153], v[166:167], 0, v[140:141]
	v_lshl_add_u64 v[148:149], v[164:165], 0, v[138:139]
	v_lshl_add_u64 v[144:145], v[166:167], 0, v[136:137]
	v_lshl_add_u64 v[140:141], v[164:165], 0, v[134:135]
	v_lshl_add_u64 v[136:137], v[166:167], 0, v[132:133]
	v_lshl_add_u64 v[132:133], v[164:165], 0, v[130:131]
	v_lshl_add_u64 v[128:129], v[166:167], 0, v[128:129]
	s_add_u32 m0, s88, 0
	v_lshl_add_u64 v[128:129], v[128:129], 0, s[92:93]
	v_xor_b32_e32 v128, v159, v128
	global_load_lds_dwordx4 v[128:129], off
	s_add_u32 m0, s88, 32768
	v_lshl_add_u64 v[132:133], v[132:133], 0, s[92:93]
	v_xor_b32_e32 v132, v159, v132
	global_load_lds_dwordx4 v[132:133], off
	s_add_u32 m0, s88, 8192
	v_lshl_add_u64 v[136:137], v[136:137], 0, s[92:93]
	v_xor_b32_e32 v136, v159, v136
	global_load_lds_dwordx4 v[136:137], off
	s_add_u32 m0, s88, 40960
	v_lshl_add_u64 v[140:141], v[140:141], 0, s[92:93]
	v_xor_b32_e32 v140, v159, v140
	global_load_lds_dwordx4 v[140:141], off
	s_add_u32 m0, s88, 16384
	v_lshl_add_u64 v[144:145], v[144:145], 0, s[92:93]
	v_xor_b32_e32 v144, v159, v144
	global_load_lds_dwordx4 v[144:145], off
	s_add_u32 m0, s88, 49152
	v_lshl_add_u64 v[148:149], v[148:149], 0, s[92:93]
	v_xor_b32_e32 v148, v159, v148
	global_load_lds_dwordx4 v[148:149], off
	s_add_u32 m0, s88, 24576
	v_lshl_add_u64 v[152:153], v[152:153], 0, s[92:93]
	v_xor_b32_e32 v152, v159, v152
	global_load_lds_dwordx4 v[152:153], off
	s_add_u32 m0, s88, 57344
	v_lshl_add_u64 v[156:157], v[156:157], 0, s[92:93]
	v_xor_b32_e32 v156, v159, v156
	global_load_lds_dwordx4 v[156:157], off
.LBB0_2413:
	ds_read_b128 v[128:131], v229
	ds_read_b128 v[136:139], v233
	ds_read_b128 v[132:135], v229 offset:4096
	ds_read_b128 v[140:143], v233 offset:4096
	ds_read_b128 v[144:147], v233 offset:8192
	ds_read_b128 v[148:151], v233 offset:12288
	s_waitcnt lgkmcnt(6)
	v_mfma_f32_32x32x16_bf16 v[112:127], v[202:205], v[212:215], v[112:127]
	v_mfma_f32_32x32x16_bf16 v[48:63], v[206:209], v[212:215], v[48:63]
	v_mfma_f32_32x32x16_bf16 v[96:111], v[202:205], v[216:219], v[96:111]
	v_mfma_f32_32x32x16_bf16 v[32:47], v[206:209], v[216:219], v[32:47]
	v_mfma_f32_32x32x16_bf16 v[80:95], v[202:205], v[220:223], v[80:95]
	v_mfma_f32_32x32x16_bf16 v[16:31], v[206:209], v[220:223], v[16:31]
	v_mfma_f32_32x32x16_bf16 v[64:79], v[202:205], v[224:227], v[64:79]
	v_mfma_f32_32x32x16_bf16 v[0:15], v[206:209], v[224:227], v[0:15]
	ds_read_b128 v[202:205], v230
	ds_read_b128 v[212:215], v234
	ds_read_b128 v[206:209], v230 offset:4096
	ds_read_b128 v[216:219], v234 offset:4096
	ds_read_b128 v[220:223], v234 offset:8192
	ds_read_b128 v[224:227], v234 offset:12288
	s_waitcnt lgkmcnt(6)
	v_mfma_f32_32x32x16_bf16 v[112:127], v[128:131], v[136:139], v[112:127]
	v_mfma_f32_32x32x16_bf16 v[48:63], v[132:135], v[136:139], v[48:63]
	v_mfma_f32_32x32x16_bf16 v[96:111], v[128:131], v[140:143], v[96:111]
	v_mfma_f32_32x32x16_bf16 v[32:47], v[132:135], v[140:143], v[32:47]
	v_mfma_f32_32x32x16_bf16 v[80:95], v[128:131], v[144:147], v[80:95]
	v_mfma_f32_32x32x16_bf16 v[16:31], v[132:135], v[144:147], v[16:31]
	v_mfma_f32_32x32x16_bf16 v[64:79], v[128:131], v[148:151], v[64:79]
	v_mfma_f32_32x32x16_bf16 v[0:15], v[132:135], v[148:151], v[0:15]
	ds_read_b128 v[128:131], v231
	ds_read_b128 v[136:139], v235
	ds_read_b128 v[132:135], v231 offset:4096
	ds_read_b128 v[140:143], v235 offset:4096
	ds_read_b128 v[144:147], v235 offset:8192
	ds_read_b128 v[148:151], v235 offset:12288
	s_waitcnt lgkmcnt(6)
	v_mfma_f32_32x32x16_bf16 v[112:127], v[202:205], v[212:215], v[112:127]
	v_mfma_f32_32x32x16_bf16 v[48:63], v[206:209], v[212:215], v[48:63]
	v_mfma_f32_32x32x16_bf16 v[96:111], v[202:205], v[216:219], v[96:111]
	v_mfma_f32_32x32x16_bf16 v[32:47], v[206:209], v[216:219], v[32:47]
	v_mfma_f32_32x32x16_bf16 v[80:95], v[202:205], v[220:223], v[80:95]
	v_mfma_f32_32x32x16_bf16 v[16:31], v[206:209], v[220:223], v[16:31]
	v_mfma_f32_32x32x16_bf16 v[64:79], v[202:205], v[224:227], v[64:79]
	v_mfma_f32_32x32x16_bf16 v[0:15], v[206:209], v[224:227], v[0:15]
	s_waitcnt lgkmcnt(0)
	s_barrier
	v_xor_b32_e32 v228, 0x10000, v228
	v_xor_b32_e32 v232, 0x10000, v232
	v_mfma_f32_32x32x16_bf16 v[112:127], v[128:131], v[136:139], v[112:127]
	v_xor_b32_e32 v229, 0x10000, v229
	v_xor_b32_e32 v233, 0x10000, v233
	v_mfma_f32_32x32x16_bf16 v[48:63], v[132:135], v[136:139], v[48:63]
	v_xor_b32_e32 v230, 0x10000, v230
	v_xor_b32_e32 v234, 0x10000, v234
	v_mfma_f32_32x32x16_bf16 v[96:111], v[128:131], v[140:143], v[96:111]
	v_xor_b32_e32 v231, 0x10000, v231
	v_xor_b32_e32 v235, 0x10000, v235
	v_mfma_f32_32x32x16_bf16 v[32:47], v[132:135], v[140:143], v[32:47]
	v_mfma_f32_32x32x16_bf16 v[80:95], v[128:131], v[144:147], v[80:95]
	v_mfma_f32_32x32x16_bf16 v[16:31], v[132:135], v[144:147], v[16:31]
	v_mfma_f32_32x32x16_bf16 v[64:79], v[128:131], v[148:151], v[64:79]
	v_mfma_f32_32x32x16_bf16 v[0:15], v[132:135], v[148:151], v[0:15]
	s_mul_i32 s2, s5, -15
	s_add_i32 s2, s2, s4
	s_lshl_b32 s2, s2, 8
	s_or_b32 s20, s2, s73
	s_add_i32 s85, s85, s72
	s_ashr_i32 s54, s20, 6
	s_cmp_gt_i32 s54, 15
	s_cselect_b64 s[4:5], -1, 0
	s_cmp_gt_u32 s54, 39
	s_cselect_b64 s[48:49], -1, 0
	s_cmp_gt_u32 s54, 55
	s_cselect_b64 s[38:39], -1, 0
	s_add_i32 s12, s54, -16
	s_lshr_b32 s83, s12, 2
	s_mov_b64 s[2:3], -1
	s_and_b64 vcc, exec, s[4:5]
	v_mov_b32_e32 v180, v191
	s_nop 0
	v_ashrrev_i32_e32 v203, 3, v180
	v_and_b32_e32 v204, -4, v203
	v_add_u32_e32 v181, s85, v204
	v_and_b32_e32 v176, 31, v180
	v_min_i32_e32 v172, 0x7fff, v181
	s_cbranch_vccz .LBB0_2427
	s_and_b64 vcc, exec, s[48:49]
	s_cbranch_vccz .LBB0_2420
	v_mul_f32_e32 v160, 0xbfb8aa3b, v112
	v_exp_f32_e32 v173, v160
	s_nop 0
	v_mul_f32_e32 v160, 0xbfb8aa3b, v96
	v_exp_f32_e32 v160, v160
	s_and_b64 vcc, exec, s[38:39]
	v_add_f32_e32 v173, 1.0, v173
	s_cbranch_vccz .LBB0_2417
	v_div_scale_f32 v174, s[2:3], v173, v173, 1.0
	v_rcp_f32_e32 v175, v174
	v_add_f32_e32 v177, 1.0, v160
	v_fma_f32 v178, -v174, v175, 1.0
	v_fmac_f32_e32 v175, v178, v175
	v_div_scale_f32 v178, vcc, 1.0, v173, 1.0
	v_mul_f32_e32 v179, v178, v175
	v_fma_f32 v182, -v174, v179, v178
	v_fmac_f32_e32 v179, v182, v175
	v_fma_f32 v174, -v174, v179, v178
	v_div_scale_f32 v178, s[2:3], v177, v177, 1.0
	v_rcp_f32_e32 v182, v178
	v_div_fmas_f32 v174, v174, v175, v179
	v_div_fixup_f32 v174, v174, v173, 1.0
	s_mov_b64 s[2:3], 0
	v_fma_f32 v175, -v178, v182, 1.0
	v_fmac_f32_e32 v182, v175, v182
	v_div_scale_f32 v175, vcc, 1.0, v177, 1.0
	v_mul_f32_e32 v179, v175, v182
	v_fma_f32 v183, -v178, v179, v175
	v_fmac_f32_e32 v179, v183, v182
	v_fma_f32 v175, -v178, v179, v175
	v_div_fmas_f32 v175, v175, v182, v179
	v_div_fixup_f32 v175, v175, v177, 1.0

.LBB0_4473:
	v_mbcnt_hi_u32_b32 v211, -1, v210
	s_load_dwordx2 s[2:3], s[0:1], 0x138
	s_load_dwordx2 s[4:5], s[0:1], 0x158
	s_ashr_i32 s7, s6, 31
	v_mov_b32_e32 v1, v211
	s_and_b32 s7, s7, s42
	s_waitcnt lgkmcnt(0)
	s_add_i32 s54, s7, s6
	v_add_u32_e32 v0, s70, v1
	v_ashrrev_i32_e32 v212, 3, v0
	v_readfirstlane_b32 s8, v0
	v_lshlrev_b32_e32 v0, 3, v1
	v_and_b32_e32 v0, 56, v0
	s_cmpk_lt_i32 s54, 0x200
	s_cselect_b64 s[6:7], -1, 0
	s_cmpk_gt_i32 s54, 0x1ff
	v_lshlrev_b32_e32 v168, 1, v0
	v_add_u32_e32 v213, 64, v212
	s_cbranch_scc1 .LBB0_4475
	s_ashr_i32 s9, s54, 31
	s_lshr_b32 s9, s9, 30
	s_add_i32 s9, s54, s9
	s_ashr_i32 s9, s9, 2
	s_lshl_b32 s10, s9, 8
	v_add_u32_e32 v2, s10, v212
	v_min_i32_e32 v2, 0x7fff, v2
	v_ashrrev_i32_e32 v3, 31, v2
	v_lshlrev_b64 v[2:3], 11, v[2:3]
	s_lshl_b32 s9, s9, 10
	s_lshl_b32 s11, s54, 8
	v_lshl_add_u64 v[2:3], s[4:5], 0, v[2:3]
	v_mov_b32_e32 v169, 0
	s_sub_i32 s9, s11, s9
	v_lshl_add_u64 v[2:3], v[2:3], 0, v[168:169]
	v_mbcnt_hi_u32_b32 v158, -1, v210
	s_and_b32 s90, s70, 0x40
	v_and_b32_e32 v159, 48, v158
	v_or_b32_e32 v159, s90, v159
	s_lshl_b32 s88, s70, 4
	s_lshl_b32 s92, s22, 4
	s_and_b32 s92, s92, 0x780
	s_mov_b32 s93, 0
	s_add_u32 m0, s88, 0
	v_lshl_add_u64 v[2:3], v[2:3], 0, s[92:93]
	v_xor_b32_e32 v2, v159, v2
	global_load_lds_dwordx4 v[2:3], off
	v_add_u32_e32 v2, s9, v212
	v_ashrrev_i32_e32 v3, 31, v2
	v_lshlrev_b64 v[2:3], 11, v[2:3]
	v_lshl_add_u64 v[2:3], s[2:3], 0, v[2:3]
	v_lshl_add_u64 v[2:3], v[2:3], 0, v[168:169]
	s_add_u32 m0, s88, 32768
	v_lshl_add_u64 v[2:3], v[2:3], 0, s[92:93]
	v_xor_b32_e32 v2, v159, v2
	global_load_lds_dwordx4 v[2:3], off
	v_add_u32_e32 v2, s10, v213
	v_min_i32_e32 v2, 0x7fff, v2
	v_ashrrev_i32_e32 v3, 31, v2
	v_lshlrev_b64 v[2:3], 11, v[2:3]
	v_lshl_add_u64 v[2:3], s[4:5], 0, v[2:3]
	v_lshl_add_u64 v[2:3], v[2:3], 0, v[168:169]
	s_add_u32 m0, s88, 8192
	v_lshl_add_u64 v[2:3], v[2:3], 0, s[92:93]
	v_xor_b32_e32 v2, v159, v2
	global_load_lds_dwordx4 v[2:3], off
	v_add_u32_e32 v2, s9, v213
	v_ashrrev_i32_e32 v3, 31, v2
	v_lshlrev_b64 v[2:3], 11, v[2:3]
	v_lshl_add_u64 v[2:3], s[2:3], 0, v[2:3]
	v_lshl_add_u64 v[2:3], v[2:3], 0, v[168:169]
	v_add_u32_e32 v4, 0x80, v212
	s_add_u32 m0, s88, 40960
	v_lshl_add_u64 v[2:3], v[2:3], 0, s[92:93]
	v_xor_b32_e32 v2, v159, v2
	global_load_lds_dwordx4 v[2:3], off
	v_add_u32_e32 v2, s10, v4
	v_min_i32_e32 v2, 0x7fff, v2
	v_ashrrev_i32_e32 v3, 31, v2
	v_lshlrev_b64 v[2:3], 11, v[2:3]
	v_lshl_add_u64 v[2:3], s[4:5], 0, v[2:3]
	v_lshl_add_u64 v[2:3], v[2:3], 0, v[168:169]
	s_add_u32 m0, s88, 16384
	v_lshl_add_u64 v[2:3], v[2:3], 0, s[92:93]
	v_xor_b32_e32 v2, v159, v2
	global_load_lds_dwordx4 v[2:3], off
	v_add_u32_e32 v2, s9, v4
	v_ashrrev_i32_e32 v3, 31, v2
	v_lshlrev_b64 v[2:3], 11, v[2:3]
	v_lshl_add_u64 v[2:3], s[2:3], 0, v[2:3]
	v_lshl_add_u64 v[2:3], v[2:3], 0, v[168:169]
	v_add_u32_e32 v4, 0xc0, v212
	s_add_u32 m0, s88, 49152
	v_lshl_add_u64 v[2:3], v[2:3], 0, s[92:93]
	v_xor_b32_e32 v2, v159, v2
	global_load_lds_dwordx4 v[2:3], off
	v_add_u32_e32 v2, s10, v4
	v_min_i32_e32 v2, 0x7fff, v2
	v_ashrrev_i32_e32 v3, 31, v2
	v_lshlrev_b64 v[2:3], 11, v[2:3]
	v_lshl_add_u64 v[2:3], s[4:5], 0, v[2:3]
	v_lshl_add_u64 v[2:3], v[2:3], 0, v[168:169]
	s_add_u32 m0, s88, 24576
	v_lshl_add_u64 v[2:3], v[2:3], 0, s[92:93]
	v_xor_b32_e32 v2, v159, v2
	global_load_lds_dwordx4 v[2:3], off
	v_add_u32_e32 v2, s9, v4
	v_ashrrev_i32_e32 v3, 31, v2
	v_lshlrev_b64 v[2:3], 11, v[2:3]
	v_lshl_add_u64 v[2:3], s[2:3], 0, v[2:3]
	v_lshl_add_u64 v[2:3], v[2:3], 0, v[168:169]
	s_add_u32 m0, s88, 57344
	v_lshl_add_u64 v[2:3], v[2:3], 0, s[92:93]
	v_xor_b32_e32 v2, v159, v2
	global_load_lds_dwordx4 v[2:3], off

.LBB0_4478:
	s_ashr_i32 s2, s54, 31
	s_lshr_b32 s2, s2, 30
	s_add_i32 s2, s54, s2
	s_ashr_i32 s2, s2, 2
	s_lshl_b32 s4, s2, 8
	v_add_u32_e32 v0, s4, v212
	v_min_i32_e32 v0, 0x7fff, v0
	v_ashrrev_i32_e32 v1, 31, v0
	s_lshl_b32 s6, s2, 10
	v_lshlrev_b64 v[0:1], 11, v[0:1]
	v_lshl_add_u64 v[160:161], v[176:177], 0, v[0:1]
	v_subrev_u32_e32 v0, s6, v220
	v_ashrrev_i32_e32 v1, 31, v0
	v_lshlrev_b64 v[0:1], 11, v[0:1]
	v_lshl_add_u64 v[180:181], v[178:179], 0, v[0:1]
	v_subrev_u32_e32 v0, s6, v221
	v_ashrrev_i32_e32 v1, 31, v0
	v_lshlrev_b64 v[0:1], 11, v[0:1]
	v_lshl_add_u64 v[182:183], v[178:179], 0, v[0:1]
	v_subrev_u32_e32 v0, s6, v222
	v_ashrrev_i32_e32 v1, 31, v0
	v_add_u32_e32 v2, s4, v213
	v_add_u32_e32 v4, s4, v171
	v_add_u32_e32 v6, s4, v215
	v_lshlrev_b64 v[0:1], 11, v[0:1]
	v_min_i32_e32 v2, 0x7fff, v2
	v_min_i32_e32 v4, 0x7fff, v4
	v_min_i32_e32 v6, 0x7fff, v6
	v_lshl_add_u64 v[184:185], v[178:179], 0, v[0:1]
	v_subrev_u32_e32 v0, s6, v223
	v_ashrrev_i32_e32 v3, 31, v2
	v_ashrrev_i32_e32 v5, 31, v4
	v_ashrrev_i32_e32 v7, 31, v6
	v_ashrrev_i32_e32 v1, 31, v0
	v_lshlrev_b64 v[2:3], 11, v[2:3]
	v_lshlrev_b64 v[4:5], 11, v[4:5]
	v_lshlrev_b64 v[6:7], 11, v[6:7]
	v_lshlrev_b64 v[0:1], 11, v[0:1]
	s_mov_b32 s5, s54
	v_lshl_add_u64 v[162:163], v[176:177], 0, v[2:3]
	v_lshl_add_u64 v[164:165], v[176:177], 0, v[4:5]
	v_lshl_add_u64 v[166:167], v[176:177], 0, v[6:7]
	v_lshl_add_u64 v[186:187], v[178:179], 0, v[0:1]
	s_mov_b64 s[2:3], 0
	s_mov_b32 s7, 0
	v_mov_b32_e32 v0, 0
	v_mov_b32_e32 v1, v169
	v_mov_b32_e32 v2, v169
	v_mov_b32_e32 v3, v169
	v_mov_b32_e32 v4, v169
	v_mov_b32_e32 v5, v169
	v_mov_b32_e32 v6, v169
	v_mov_b32_e32 v7, v169
	v_mov_b32_e32 v8, v169
	v_mov_b32_e32 v9, v169
	v_mov_b32_e32 v10, v169
	v_mov_b32_e32 v11, v169
	v_mov_b32_e32 v12, v169
	v_mov_b32_e32 v13, v169
	v_mov_b32_e32 v14, v169
	v_mov_b32_e32 v15, v169
	v_mov_b32_e32 v16, 0
	v_mov_b32_e32 v17, v169
	v_mov_b32_e32 v18, v169
	v_mov_b32_e32 v19, v169
	v_mov_b32_e32 v20, v169
	v_mov_b32_e32 v21, v169
	v_mov_b32_e32 v22, v169
	v_mov_b32_e32 v23, v169
	v_mov_b32_e32 v24, v169
	v_mov_b32_e32 v25, v169
	v_mov_b32_e32 v26, v169
	v_mov_b32_e32 v27, v169
	v_mov_b32_e32 v28, v169
	v_mov_b32_e32 v29, v169
	v_mov_b32_e32 v30, v169
	v_mov_b32_e32 v31, v169
	v_mov_b32_e32 v32, 0
	v_mov_b32_e32 v33, v169
	v_mov_b32_e32 v34, v169
	v_mov_b32_e32 v35, v169
	v_mov_b32_e32 v36, v169
	v_mov_b32_e32 v37, v169
	v_mov_b32_e32 v38, v169
	v_mov_b32_e32 v39, v169
	v_mov_b32_e32 v40, v169
	v_mov_b32_e32 v41, v169
	v_mov_b32_e32 v42, v169
	v_mov_b32_e32 v43, v169
	v_mov_b32_e32 v44, v169
	v_mov_b32_e32 v45, v169
	v_mov_b32_e32 v46, v169
	v_mov_b32_e32 v47, v169
	v_mov_b32_e32 v48, 0
	v_mov_b32_e32 v49, v169
	v_mov_b32_e32 v50, v169
	v_mov_b32_e32 v51, v169
	v_mov_b32_e32 v52, v169
	v_mov_b32_e32 v53, v169
	v_mov_b32_e32 v54, v169
	v_mov_b32_e32 v55, v169
	v_mov_b32_e32 v56, v169
	v_mov_b32_e32 v57, v169
	v_mov_b32_e32 v58, v169
	v_mov_b32_e32 v59, v169
	v_mov_b32_e32 v60, v169
	v_mov_b32_e32 v61, v169
	v_mov_b32_e32 v62, v169
	v_mov_b32_e32 v63, v169
	v_mov_b32_e32 v64, 0
	v_mov_b32_e32 v65, v169
	v_mov_b32_e32 v66, v169
	v_mov_b32_e32 v67, v169
	v_mov_b32_e32 v68, v169
	v_mov_b32_e32 v69, v169
	v_mov_b32_e32 v70, v169
	v_mov_b32_e32 v71, v169
	v_mov_b32_e32 v72, v169
	v_mov_b32_e32 v73, v169
	v_mov_b32_e32 v74, v169
	v_mov_b32_e32 v75, v169
	v_mov_b32_e32 v76, v169
	v_mov_b32_e32 v77, v169
	v_mov_b32_e32 v78, v169
	v_mov_b32_e32 v79, v169
	v_mov_b32_e32 v80, 0
	v_mov_b32_e32 v81, v169
	v_mov_b32_e32 v82, v169
	v_mov_b32_e32 v83, v169
	v_mov_b32_e32 v84, v169
	v_mov_b32_e32 v85, v169
	v_mov_b32_e32 v86, v169
	v_mov_b32_e32 v87, v169
	v_mov_b32_e32 v88, v169
	v_mov_b32_e32 v89, v169
	v_mov_b32_e32 v90, v169
	v_mov_b32_e32 v91, v169
	v_mov_b32_e32 v92, v169
	v_mov_b32_e32 v93, v169
	v_mov_b32_e32 v94, v169
	v_mov_b32_e32 v95, v169
	s_waitcnt vmcnt(7)
	v_mov_b32_e32 v96, 0
	v_mov_b32_e32 v97, v169
	v_mov_b32_e32 v98, v169
	v_mov_b32_e32 v99, v169
	s_waitcnt vmcnt(6)
	v_mov_b32_e32 v100, v169
	v_mov_b32_e32 v101, v169
	v_mov_b32_e32 v102, v169
	v_mov_b32_e32 v103, v169
	s_waitcnt vmcnt(5)
	v_mov_b32_e32 v104, v169
	v_mov_b32_e32 v105, v169
	v_mov_b32_e32 v106, v169
	v_mov_b32_e32 v107, v169
	s_waitcnt vmcnt(4)
	v_mov_b32_e32 v108, v169
	v_mov_b32_e32 v109, v169
	v_mov_b32_e32 v110, v169
	v_mov_b32_e32 v111, v169
	s_waitcnt vmcnt(3)
	v_mov_b32_e32 v112, 0
	v_mov_b32_e32 v113, v169
	v_mov_b32_e32 v114, v169
	v_mov_b32_e32 v115, v169
	s_waitcnt vmcnt(2)
	v_mov_b32_e32 v116, v169
	v_mov_b32_e32 v117, v169
	v_mov_b32_e32 v118, v169
	v_mov_b32_e32 v119, v169
	s_waitcnt vmcnt(1)
	v_mov_b32_e32 v120, v169
	v_mov_b32_e32 v121, v169
	v_mov_b32_e32 v122, v169
	v_mov_b32_e32 v123, v169
	s_waitcnt vmcnt(0)
	v_mov_b32_e32 v124, v169
	v_mov_b32_e32 v125, v169
	v_mov_b32_e32 v126, v169
	v_mov_b32_e32 v127, v169
	v_mbcnt_hi_u32_b32 v128, -1, v210
	s_and_b32 s90, s70, 0x40
	v_and_b32_e32 v159, 48, v128
	v_or_b32_e32 v159, s90, v159
	v_and_b32_e32 v129, 31, v128
	v_lshrrev_b32_e32 v130, 5, v128
	v_bfe_u32 v131, v128, 1, 3
	v_lshlrev_b32_e32 v132, 7, v129
	s_lshr_b32 s91, s70, 7
	s_lshl_b32 s91, s91, 13
	s_lshl_b32 s90, s90, 8
	s_add_u32 s90, s90, 0x8000
	s_lshl_b32 s88, s70, 4
	s_mov_b32 s89, 0x10000
	s_lshl_b32 s92, s22, 4
	s_and_b32 s92, s92, 0x780
	s_mov_b32 s93, 0
	v_xor_b32_e32 v133, v130, v131
	v_lshl_add_u32 v133, v133, 4, v132
	v_add_u32_e32 v230, s91, v133
	v_add_u32_e32 v234, s90, v133
	v_or_b32_e32 v133, 2, v130
	v_xor_b32_e32 v133, v133, v131
	v_lshl_add_u32 v133, v133, 4, v132
	v_add_u32_e32 v231, s91, v133
	v_add_u32_e32 v235, s90, v133
	v_or_b32_e32 v133, 4, v130
	v_xor_b32_e32 v133, v133, v131
	v_lshl_add_u32 v133, v133, 4, v132
	v_add_u32_e32 v232, s91, v133
	v_add_u32_e32 v236, s90, v133
	v_or_b32_e32 v133, 6, v130
	v_xor_b32_e32 v133, v133, v131
	v_lshl_add_u32 v133, v133, 4, v132
	v_add_u32_e32 v233, s91, v133
	v_add_u32_e32 v237, s90, v133
	s_waitcnt vmcnt(0)
	s_barrier
	ds_read_b128 v[188:191], v230
	ds_read_b128 v[196:199], v234
	ds_read_b128 v[192:195], v230 offset:4096
	ds_read_b128 v[200:203], v234 offset:4096
	ds_read_b128 v[204:207], v234 offset:8192
	ds_read_b128 v[226:229], v234 offset:12288
	s_add_u32 s94, s2, s92
	s_add_u32 s94, s94, 0x80
	s_and_b32 s94, s94, 0x780
	s_sub_u32 s94, s94, 0x80
	s_subb_u32 s95, 0, 0
	s_add_u32 s90, s88, s89
	s_add_u32 m0, s90, 0
	v_lshl_add_u64 v[152:153], v[160:161], 0, s[94:95]
	v_xor_b32_e32 v152, v159, v152
	global_load_lds_dwordx4 v[152:153], off
	s_add_u32 m0, s90, 32768
	v_lshl_add_u64 v[154:155], v[180:181], 0, s[94:95]
	v_xor_b32_e32 v154, v159, v154
	global_load_lds_dwordx4 v[154:155], off
	s_add_u32 m0, s90, 8192
	v_lshl_add_u64 v[156:157], v[162:163], 0, s[94:95]
	v_xor_b32_e32 v156, v159, v156
	global_load_lds_dwordx4 v[156:157], off
	s_add_u32 m0, s90, 40960
	v_lshl_add_u64 v[152:153], v[182:183], 0, s[94:95]
	v_xor_b32_e32 v152, v159, v152
	global_load_lds_dwordx4 v[152:153], off
	s_add_u32 m0, s90, 16384
	v_lshl_add_u64 v[154:155], v[164:165], 0, s[94:95]
	v_xor_b32_e32 v154, v159, v154
	global_load_lds_dwordx4 v[154:155], off
	s_add_u32 m0, s90, 49152
	v_lshl_add_u64 v[156:157], v[184:185], 0, s[94:95]
	v_xor_b32_e32 v156, v159, v156
	global_load_lds_dwordx4 v[156:157], off
	s_add_u32 m0, s90, 24576
	v_lshl_add_u64 v[152:153], v[166:167], 0, s[94:95]
	v_xor_b32_e32 v152, v159, v152
	global_load_lds_dwordx4 v[152:153], off
	s_add_u32 m0, s90, 57344
	v_lshl_add_u64 v[154:155], v[186:187], 0, s[94:95]
	v_xor_b32_e32 v154, v159, v154
	global_load_lds_dwordx4 v[154:155], off
	s_xor_b32 s89, s89, 0x10000

.LBB0_4482:
	ds_read_b128 v[128:131], v231
	ds_read_b128 v[136:139], v235
	ds_read_b128 v[132:135], v231 offset:4096
	ds_read_b128 v[140:143], v235 offset:4096
	ds_read_b128 v[144:147], v235 offset:8192
	ds_read_b128 v[148:151], v235 offset:12288
	s_waitcnt lgkmcnt(6)
	v_mfma_f32_32x32x16_bf16 v[112:127], v[188:191], v[196:199], v[112:127]
	v_mfma_f32_32x32x16_bf16 v[48:63], v[192:195], v[196:199], v[48:63]
	v_mfma_f32_32x32x16_bf16 v[96:111], v[188:191], v[200:203], v[96:111]
	v_mfma_f32_32x32x16_bf16 v[32:47], v[192:195], v[200:203], v[32:47]
	v_mfma_f32_32x32x16_bf16 v[80:95], v[188:191], v[204:207], v[80:95]
	v_mfma_f32_32x32x16_bf16 v[16:31], v[192:195], v[204:207], v[16:31]
	v_mfma_f32_32x32x16_bf16 v[64:79], v[188:191], v[226:229], v[64:79]
	v_mfma_f32_32x32x16_bf16 v[0:15], v[192:195], v[226:229], v[0:15]
	ds_read_b128 v[188:191], v232
	ds_read_b128 v[196:199], v236
	ds_read_b128 v[192:195], v232 offset:4096
	ds_read_b128 v[200:203], v236 offset:4096
	ds_read_b128 v[204:207], v236 offset:8192
	ds_read_b128 v[226:229], v236 offset:12288
	s_waitcnt lgkmcnt(6)
	v_mfma_f32_32x32x16_bf16 v[112:127], v[128:131], v[136:139], v[112:127]
	v_mfma_f32_32x32x16_bf16 v[48:63], v[132:135], v[136:139], v[48:63]
	v_mfma_f32_32x32x16_bf16 v[96:111], v[128:131], v[140:143], v[96:111]
	v_mfma_f32_32x32x16_bf16 v[32:47], v[132:135], v[140:143], v[32:47]
	v_mfma_f32_32x32x16_bf16 v[80:95], v[128:131], v[144:147], v[80:95]
	v_mfma_f32_32x32x16_bf16 v[16:31], v[132:135], v[144:147], v[16:31]
	v_mfma_f32_32x32x16_bf16 v[64:79], v[128:131], v[148:151], v[64:79]
	v_mfma_f32_32x32x16_bf16 v[0:15], v[132:135], v[148:151], v[0:15]
	ds_read_b128 v[128:131], v233
	ds_read_b128 v[136:139], v237
	ds_read_b128 v[132:135], v233 offset:4096
	ds_read_b128 v[140:143], v237 offset:4096
	ds_read_b128 v[144:147], v237 offset:8192
	ds_read_b128 v[148:151], v237 offset:12288
	s_waitcnt lgkmcnt(6)
	v_mfma_f32_32x32x16_bf16 v[112:127], v[188:191], v[196:199], v[112:127]
	v_mfma_f32_32x32x16_bf16 v[48:63], v[192:195], v[196:199], v[48:63]
	v_mfma_f32_32x32x16_bf16 v[96:111], v[188:191], v[200:203], v[96:111]
	v_mfma_f32_32x32x16_bf16 v[32:47], v[192:195], v[200:203], v[32:47]
	v_mfma_f32_32x32x16_bf16 v[80:95], v[188:191], v[204:207], v[80:95]
	v_mfma_f32_32x32x16_bf16 v[16:31], v[192:195], v[204:207], v[16:31]
	v_mfma_f32_32x32x16_bf16 v[64:79], v[188:191], v[226:229], v[64:79]
	v_mfma_f32_32x32x16_bf16 v[0:15], v[192:195], v[226:229], v[0:15]
	s_waitcnt lgkmcnt(0)
	s_barrier
	v_xor_b32_e32 v230, 0x10000, v230
	v_xor_b32_e32 v234, 0x10000, v234
	v_mfma_f32_32x32x16_bf16 v[112:127], v[128:131], v[136:139], v[112:127]
	v_xor_b32_e32 v231, 0x10000, v231
	v_xor_b32_e32 v235, 0x10000, v235
	v_mfma_f32_32x32x16_bf16 v[48:63], v[132:135], v[136:139], v[48:63]
	v_xor_b32_e32 v232, 0x10000, v232
	v_xor_b32_e32 v236, 0x10000, v236
	v_mfma_f32_32x32x16_bf16 v[96:111], v[128:131], v[140:143], v[96:111]
	v_xor_b32_e32 v233, 0x10000, v233
	v_xor_b32_e32 v237, 0x10000, v237
	v_mfma_f32_32x32x16_bf16 v[32:47], v[132:135], v[140:143], v[32:47]
	v_mfma_f32_32x32x16_bf16 v[80:95], v[128:131], v[144:147], v[80:95]
	v_mfma_f32_32x32x16_bf16 v[16:31], v[132:135], v[144:147], v[16:31]
	v_mfma_f32_32x32x16_bf16 v[64:79], v[128:131], v[148:151], v[64:79]
	v_mfma_f32_32x32x16_bf16 v[0:15], v[132:135], v[148:151], v[0:15]
	s_lshl_b32 s2, s5, 8
	s_sub_i32 s2, s2, s6
	v_mov_b32_e32 v168, v214
	s_add_i32 s55, s4, s30
	s_or_b32 s26, s2, s31
	s_ashr_i32 s27, s26, 31
	s_load_dwordx2 s[24:25], s[0:1], 0x140
	v_ashrrev_i32_e32 v180, 3, v168
	v_and_b32_e32 v183, -4, v180
	v_add_u32_e32 v225, s55, v183
	v_add_u32_e32 v190, 8, v225
	v_min_i32_e32 v190, 0x7fff, v190
	v_ashrrev_i32_e32 v190, 12, v190
	v_add_u32_e32 v190, 16, v190
	v_mul_hi_i32_i24_e32 v191, 0x3000, v190
	v_mul_i32_i24_e32 v190, 0x3000, v190
	v_min_i32_e32 v184, 0x7fff, v225
	v_ashrrev_i32_e32 v184, 12, v184
	v_and_b32_e32 v182, 31, v168
	v_add_u32_e32 v184, 16, v184
	v_or_b32_e32 v180, s26, v182
	v_mul_hi_i32_i24_e32 v185, 0x3000, v184
	v_mul_i32_i24_e32 v184, 0x3000, v184
	v_ashrrev_i32_e32 v181, 31, v180
	s_waitcnt lgkmcnt(0)
	v_lshl_add_u64 v[184:185], s[24:25], 0, v[184:185]
	v_lshl_add_u64 v[184:185], v[184:185], 0, s[18:19]
	v_lshlrev_b64 v[180:181], 2, v[180:181]
	v_lshl_add_u64 v[196:197], v[184:185], 0, v[180:181]
	v_lshl_add_u64 v[186:187], s[24:25], 0, v[190:191]
	v_add_u32_e32 v188, 9, v225
	v_add_u32_e32 v190, 10, v225
	v_min_i32_e32 v188, 0x7fff, v188
	v_min_i32_e32 v190, 0x7fff, v190
	v_ashrrev_i32_e32 v188, 12, v188
	v_ashrrev_i32_e32 v190, 12, v190
	v_add_u32_e32 v188, 16, v188
	v_add_u32_e32 v190, 16, v190
	v_mul_hi_i32_i24_e32 v189, 0x3000, v188
	v_mul_i32_i24_e32 v188, 0x3000, v188
	v_mul_hi_i32_i24_e32 v191, 0x3000, v190
	v_mul_i32_i24_e32 v190, 0x3000, v190
	v_lshl_add_u64 v[188:189], s[24:25], 0, v[188:189]
	v_lshl_add_u64 v[190:191], s[24:25], 0, v[190:191]
	v_lshl_add_u64 v[186:187], v[186:187], 0, s[18:19]
	v_lshl_add_u64 v[188:189], v[188:189], 0, s[18:19]
	v_lshl_add_u64 v[190:191], v[190:191], 0, s[18:19]
	v_lshl_add_u64 v[206:207], v[186:187], 0, v[180:181]
	v_add_u32_e32 v208, 18, v225
	v_min_i32_e32 v208, 0x7fff, v208
	v_ashrrev_i32_e32 v208, 12, v208
	v_add_u32_e32 v208, 16, v208
	v_mul_hi_i32_i24_e32 v209, 0x3000, v208
	v_mul_i32_i24_e32 v208, 0x3000, v208
	v_lshl_add_u64 v[208:209], s[24:25], 0, v[208:209]
	v_lshl_add_u64 v[202:203], v[188:189], 0, v[180:181]
	v_lshl_add_u64 v[204:205], v[190:191], 0, v[180:181]
	global_load_dword v232, v[196:197], off
	global_load_dword v233, v[196:197], off offset:128
	global_load_dword v242, v[206:207], off
	global_load_dword v243, v[206:207], off offset:128
	global_load_dword v244, v[202:203], off
	global_load_dword v245, v[202:203], off offset:128
	global_load_dword v246, v[204:205], off
	global_load_dword v247, v[204:205], off offset:128
	v_add_u32_e32 v196, 17, v225
	v_min_i32_e32 v196, 0x7fff, v196
	v_ashrrev_i32_e32 v196, 12, v196
	v_add_u32_e32 v196, 16, v196
	v_mul_hi_i32_i24_e32 v197, 0x3000, v196
	v_mul_i32_i24_e32 v196, 0x3000, v196
	v_lshl_add_u64 v[196:197], s[24:25], 0, v[196:197]
	v_lshl_add_u64 v[196:197], v[196:197], 0, s[18:19]
	v_lshl_add_u64 v[206:207], v[196:197], 0, v[180:181]
	s_waitcnt vmcnt(7)
	s_nop 5
	v_mul_f32_e32 v112, v112, v232
	v_add_u32_e32 v192, 11, v225
	v_add_u32_e32 v194, 16, v225
	v_min_i32_e32 v192, 0x7fff, v192
	v_min_i32_e32 v194, 0x7fff, v194
	v_ashrrev_i32_e32 v192, 12, v192
	v_ashrrev_i32_e32 v194, 12, v194
	v_add_u32_e32 v192, 16, v192
	v_add_u32_e32 v194, 16, v194
	v_mul_hi_i32_i24_e32 v193, 0x3000, v192
	v_mul_i32_i24_e32 v192, 0x3000, v192
	v_mul_hi_i32_i24_e32 v195, 0x3000, v194
	v_mul_i32_i24_e32 v194, 0x3000, v194
	v_lshl_add_u64 v[192:193], s[24:25], 0, v[192:193]
	v_lshl_add_u64 v[194:195], s[24:25], 0, v[194:195]
	v_lshl_add_u64 v[192:193], v[192:193], 0, s[18:19]
	v_lshl_add_u64 v[194:195], v[194:195], 0, s[18:19]
	v_lshl_add_u64 v[202:203], v[192:193], 0, v[180:181]
	v_lshl_add_u64 v[204:205], v[194:195], 0, v[180:181]
	s_waitcnt vmcnt(6)
	s_nop 5
	v_mul_f32_e32 v96, v96, v233
	v_mul_f32_e32 v97, v97, v233
	v_lshl_add_u64 v[198:199], v[208:209], 0, s[18:19]
	v_lshl_add_u64 v[200:201], v[198:199], 0, v[180:181]
	global_load_dword v234, v[202:203], off
	global_load_dword v235, v[202:203], off offset:128
	global_load_dword v236, v[204:205], off
	global_load_dword v237, v[204:205], off offset:128
	global_load_dword v238, v[206:207], off
	global_load_dword v239, v[206:207], off offset:128
	global_load_dword v240, v[200:201], off
	global_load_dword v241, v[200:201], off offset:128
	v_add_u32_e32 v200, 19, v225
	v_add_u32_e32 v204, 25, v225
	v_add_u32_e32 v206, 26, v225
	v_min_i32_e32 v200, 0x7fff, v200
	v_add_u32_e32 v202, 24, v225
	v_min_i32_e32 v204, 0x7fff, v204
	v_min_i32_e32 v206, 0x7fff, v206
	v_ashrrev_i32_e32 v200, 12, v200
	v_min_i32_e32 v202, 0x7fff, v202
	v_ashrrev_i32_e32 v204, 12, v204
	v_ashrrev_i32_e32 v206, 12, v206
	v_add_u32_e32 v200, 16, v200
	v_ashrrev_i32_e32 v202, 12, v202
	v_add_u32_e32 v204, 16, v204
	v_add_u32_e32 v206, 16, v206
	v_mul_hi_i32_i24_e32 v201, 0x3000, v200
	v_mul_i32_i24_e32 v200, 0x3000, v200
	v_add_u32_e32 v202, 16, v202
	v_mul_hi_i32_i24_e32 v205, 0x3000, v204
	v_mul_i32_i24_e32 v204, 0x3000, v204
	v_mul_hi_i32_i24_e32 v207, 0x3000, v206
	v_mul_i32_i24_e32 v206, 0x3000, v206
	v_lshl_add_u64 v[200:201], s[24:25], 0, v[200:201]
	v_mul_hi_i32_i24_e32 v203, 0x3000, v202
	v_mul_i32_i24_e32 v202, 0x3000, v202
	v_lshl_add_u64 v[204:205], s[24:25], 0, v[204:205]
	v_lshl_add_u64 v[206:207], s[24:25], 0, v[206:207]
	v_lshl_add_u64 v[200:201], v[200:201], 0, s[18:19]
	v_lshl_add_u64 v[202:203], s[24:25], 0, v[202:203]
	v_lshl_add_u64 v[204:205], v[204:205], 0, s[18:19]
	v_lshl_add_u64 v[206:207], v[206:207], 0, s[18:19]
	v_lshl_add_u64 v[208:209], v[200:201], 0, v[180:181]
	v_lshl_add_u64 v[202:203], v[202:203], 0, s[18:19]
	v_lshl_add_u64 v[228:229], v[204:205], 0, v[180:181]
	v_lshl_add_u64 v[230:231], v[206:207], 0, v[180:181]
	v_lshl_add_u64 v[226:227], v[202:203], 0, v[180:181]
	global_load_dword v248, v[208:209], off
	global_load_dword v249, v[208:209], off offset:128
	global_load_dword v250, v[226:227], off
	global_load_dword v251, v[226:227], off offset:128
	global_load_dword v252, v[228:229], off
	s_nop 0
	global_load_dword v228, v[228:229], off offset:128
	s_nop 0
	global_load_dword v229, v[230:231], off
	s_nop 0
	global_load_dword v230, v[230:231], off offset:128
	v_add_u32_e32 v208, 27, v225
	v_min_i32_e32 v208, 0x7fff, v208
	v_ashrrev_i32_e32 v208, 12, v208
	v_add_u32_e32 v208, 16, v208
	v_mul_hi_i32_i24_e32 v209, 0x3000, v208
	v_mul_i32_i24_e32 v208, 0x3000, v208
	v_lshl_add_u64 v[208:209], s[24:25], 0, v[208:209]
	v_lshl_add_u64 v[208:209], v[208:209], 0, s[18:19]
	v_lshl_add_u64 v[226:227], v[208:209], 0, v[180:181]
	global_load_dword v225, v[226:227], off
	s_nop 0
	global_load_dword v226, v[226:227], off offset:128
	v_mad_u64_u32 v[160:161], s[2:3], v183, s36, v[182:183]
	v_lshl_add_u32 v162, v160, 2, s34
	ds_write2_b32 v162, v112, v96 offset1:32
	v_mul_f32_e32 v96, v113, v232
	ds_write2_b32 v162, v96, v97 offset0:68 offset1:100
	v_mul_f32_e32 v96, v114, v232
	v_mul_f32_e32 v97, v98, v233
	ds_write2_b32 v162, v96, v97 offset0:136 offset1:168
	v_mul_f32_e32 v96, v115, v232
	v_mul_f32_e32 v97, v99, v233
	ds_write2_b32 v162, v96, v97 offset0:204 offset1:236
	s_waitcnt vmcnt(23)
	v_mul_f32_e32 v96, v116, v242
	s_waitcnt vmcnt(22)
	v_mul_f32_e32 v97, v100, v243
	v_add_u32_e32 v115, 0x800, v162
	ds_write2_b32 v115, v96, v97 offset0:32 offset1:64
	s_waitcnt vmcnt(21)
	v_mul_f32_e32 v96, v117, v244
	s_waitcnt vmcnt(20)
	v_mul_f32_e32 v97, v101, v245
	ds_write2_b32 v115, v96, v97 offset0:100 offset1:132
	s_waitcnt vmcnt(19)
	v_mul_f32_e32 v96, v118, v246
	s_waitcnt vmcnt(18)
	v_mul_f32_e32 v97, v102, v247
	ds_write2_b32 v115, v96, v97 offset0:168 offset1:200
	v_add_u32_e32 v116, 0xa00, v162
	v_add_u32_e32 v117, 0x1000, v162
	s_waitcnt vmcnt(17)
	v_mul_f32_e32 v96, v119, v234
	s_waitcnt vmcnt(16)
	v_mul_f32_e32 v97, v103, v235
	ds_write2_b32 v116, v96, v97 offset0:108 offset1:140
	s_waitcnt vmcnt(15)
	v_mul_f32_e32 v96, v120, v236
	s_waitcnt vmcnt(14)
	v_mul_f32_e32 v97, v104, v237
	ds_write2_b32 v117, v96, v97 offset0:64 offset1:96
	s_waitcnt vmcnt(13)
	v_mul_f32_e32 v96, v121, v238
	s_waitcnt vmcnt(12)
	v_mul_f32_e32 v97, v105, v239
	ds_write2_b32 v117, v96, v97 offset0:132 offset1:164
	s_waitcnt vmcnt(11)
	v_mul_f32_e32 v96, v122, v240
	s_waitcnt vmcnt(10)
	v_mul_f32_e32 v97, v106, v241
	ds_write2_b32 v117, v96, v97 offset0:200 offset1:232
	v_add_u32_e32 v118, 0x1400, v162
	v_add_u32_e32 v119, 0x1800, v162
	v_ashrrev_i32_e32 v163, 4, v168
	v_and_b32_e32 v160, 15, v168
	v_add_u32_e32 v120, 0x1a00, v162
	v_mul_lo_u32 v164, v163, s37
	v_lshl_add_u32 v165, v160, 4, s34
	v_lshlrev_b32_e32 v168, 2, v160
	v_add_u32_e32 v160, s55, v163
	v_add_u32_e32 v121, 0x1c00, v162
	v_cmp_gt_i32_e32 vcc, s38, v160
	v_ashrrev_i32_e32 v161, 31, v160
	v_add_u32_e32 v114, v165, v164
	s_waitcnt vmcnt(9)
	v_mul_f32_e32 v96, v123, v248
	s_waitcnt vmcnt(8)
	v_mul_f32_e32 v97, v107, v249
	ds_write2_b32 v118, v96, v97 offset0:12 offset1:44
	s_waitcnt vmcnt(7)
	v_mul_f32_e32 v96, v124, v250
	s_waitcnt vmcnt(6)
	v_mul_f32_e32 v97, v108, v251
	ds_write2_b32 v119, v96, v97 offset0:96 offset1:128
	s_waitcnt vmcnt(5)
	v_mul_f32_e32 v96, v125, v252
	s_waitcnt vmcnt(4)
	v_mul_f32_e32 v97, v109, v228
	ds_write2_b32 v119, v96, v97 offset0:164 offset1:196
	s_waitcnt vmcnt(3)
	v_mul_f32_e32 v96, v126, v229
	s_waitcnt vmcnt(2)
	v_mul_f32_e32 v97, v110, v230
	ds_write2_b32 v120, v96, v97 offset0:104 offset1:136
	s_waitcnt vmcnt(1)
	v_mul_f32_e32 v96, v127, v225
	s_waitcnt vmcnt(0)
	v_mul_f32_e32 v97, v111, v226
	ds_write2_b32 v121, v96, v97 offset0:44 offset1:76
	v_or_b32_e32 v96, s26, v168
	v_mov_b32_e32 v97, s27
	v_add_u32_e32 v128, 0, v160
	v_ashrrev_i32_e32 v129, 31, v128
	v_lshlrev_b64 v[128:129], 12, v[128:129]
	v_lshl_add_u64 v[128:129], s[16:17], 0, v[128:129]
	v_lshl_add_u64 v[128:129], v[96:97], 2, v[128:129]
	global_load_dwordx4 v[128:131], v[128:129], off
	v_add_u32_e32 v132, 4, v160
	v_ashrrev_i32_e32 v133, 31, v132
	v_lshlrev_b64 v[132:133], 12, v[132:133]
	v_lshl_add_u64 v[132:133], s[16:17], 0, v[132:133]
	v_lshl_add_u64 v[132:133], v[96:97], 2, v[132:133]
	global_load_dwordx4 v[132:135], v[132:133], off
	v_add_u32_e32 v136, 8, v160
	v_ashrrev_i32_e32 v137, 31, v136
	v_lshlrev_b64 v[136:137], 12, v[136:137]
	v_lshl_add_u64 v[136:137], s[16:17], 0, v[136:137]
	v_lshl_add_u64 v[136:137], v[96:97], 2, v[136:137]
	global_load_dwordx4 v[136:139], v[136:137], off
	v_add_u32_e32 v140, 12, v160
	v_ashrrev_i32_e32 v141, 31, v140
	v_lshlrev_b64 v[140:141], 12, v[140:141]
	v_lshl_add_u64 v[140:141], s[16:17], 0, v[140:141]
	v_lshl_add_u64 v[140:141], v[96:97], 2, v[140:141]
	global_load_dwordx4 v[140:143], v[140:141], off
	v_add_u32_e32 v144, 16, v160
	v_ashrrev_i32_e32 v145, 31, v144
	v_lshlrev_b64 v[144:145], 12, v[144:145]
	v_lshl_add_u64 v[144:145], s[16:17], 0, v[144:145]
	v_lshl_add_u64 v[144:145], v[96:97], 2, v[144:145]
	global_load_dwordx4 v[144:147], v[144:145], off
	v_add_u32_e32 v148, 20, v160
	v_ashrrev_i32_e32 v149, 31, v148
	v_lshlrev_b64 v[148:149], 12, v[148:149]
	v_lshl_add_u64 v[148:149], s[16:17], 0, v[148:149]
	v_lshl_add_u64 v[148:149], v[96:97], 2, v[148:149]
	global_load_dwordx4 v[148:151], v[148:149], off
	v_add_u32_e32 v152, 24, v160
	v_ashrrev_i32_e32 v153, 31, v152
	v_lshlrev_b64 v[152:153], 12, v[152:153]
	v_lshl_add_u64 v[152:153], s[16:17], 0, v[152:153]
	v_lshl_add_u64 v[152:153], v[96:97], 2, v[152:153]
	global_load_dwordx4 v[152:155], v[152:153], off
	v_add_u32_e32 v156, 28, v160
	v_ashrrev_i32_e32 v157, 31, v156
	v_lshlrev_b64 v[156:157], 12, v[156:157]
	v_lshl_add_u64 v[156:157], s[16:17], 0, v[156:157]
	v_lshl_add_u64 v[156:157], v[96:97], 2, v[156:157]
	global_load_dwordx4 v[156:159], v[156:157], off
	s_and_saveexec_b64 s[2:3], vcc
	s_cbranch_execz .LBB0_4484
	v_lshlrev_b64 v[98:99], 12, v[160:161]
	v_lshl_add_u64 v[98:99], s[16:17], 0, v[98:99]
	v_lshl_add_u64 v[106:107], v[96:97], 2, v[98:99]
	ds_read_b128 v[102:105], v114
	s_waitcnt vmcnt(7) lgkmcnt(0)
	v_pk_add_f32 v[100:101], v[104:105], v[130:131]
	v_pk_add_f32 v[98:99], v[102:103], v[128:129]
	global_store_dwordx4 v[106:107], v[98:101], off

.LBB0_4514:
	s_or_b64 exec, exec, s[2:3]
	s_or_b32 s2, s55, 32
	v_add_u32_e32 v102, s2, v183
	v_min_i32_e32 v66, 0x7fff, v102
	v_add_u32_e32 v68, 8, v102
	v_add_u32_e32 v70, 9, v102
	v_add_u32_e32 v72, 10, v102
	v_ashrrev_i32_e32 v66, 12, v66
	v_min_i32_e32 v68, 0x7fff, v68
	v_min_i32_e32 v70, 0x7fff, v70
	v_min_i32_e32 v72, 0x7fff, v72
	v_add_u32_e32 v66, 16, v66
	v_ashrrev_i32_e32 v68, 12, v68
	v_ashrrev_i32_e32 v70, 12, v70
	v_ashrrev_i32_e32 v72, 12, v72
	v_mul_hi_i32_i24_e32 v67, 0x3000, v66
	v_mul_i32_i24_e32 v66, 0x3000, v66
	v_add_u32_e32 v68, 16, v68
	v_add_u32_e32 v70, 16, v70
	v_add_u32_e32 v72, 16, v72
	v_lshl_add_u64 v[66:67], s[24:25], 0, v[66:67]
	v_mul_hi_i32_i24_e32 v69, 0x3000, v68
	v_mul_i32_i24_e32 v68, 0x3000, v68
	v_mul_hi_i32_i24_e32 v71, 0x3000, v70
	v_mul_i32_i24_e32 v70, 0x3000, v70
	v_mul_hi_i32_i24_e32 v73, 0x3000, v72
	v_mul_i32_i24_e32 v72, 0x3000, v72
	v_lshl_add_u64 v[66:67], v[66:67], 0, s[18:19]
	v_lshl_add_u64 v[68:69], s[24:25], 0, v[68:69]
	v_lshl_add_u64 v[70:71], s[24:25], 0, v[70:71]
	v_lshl_add_u64 v[72:73], s[24:25], 0, v[72:73]
	v_lshl_add_u64 v[74:75], v[66:67], 0, v[180:181]
	v_lshl_add_u64 v[68:69], v[68:69], 0, s[18:19]
	v_lshl_add_u64 v[70:71], v[70:71], 0, s[18:19]
	v_lshl_add_u64 v[72:73], v[72:73], 0, s[18:19]
	v_lshl_add_u64 v[76:77], v[68:69], 0, v[180:181]
	v_lshl_add_u64 v[78:79], v[70:71], 0, v[180:181]
	v_lshl_add_u64 v[80:81], v[72:73], 0, v[180:181]
	global_load_dword v103, v[74:75], off
	global_load_dword v104, v[74:75], off offset:128
	global_load_dword v105, v[76:77], off
	global_load_dword v106, v[76:77], off offset:128
	global_load_dword v107, v[78:79], off
	global_load_dword v108, v[78:79], off offset:128
	global_load_dword v109, v[80:81], off
	global_load_dword v110, v[80:81], off offset:128
	v_add_u32_e32 v74, 11, v102
	v_add_u32_e32 v82, 18, v102
	v_min_i32_e32 v74, 0x7fff, v74
	v_add_u32_e32 v76, 16, v102
	v_add_u32_e32 v78, 17, v102
	v_min_i32_e32 v82, 0x7fff, v82
	v_ashrrev_i32_e32 v74, 12, v74
	v_min_i32_e32 v76, 0x7fff, v76
	v_min_i32_e32 v78, 0x7fff, v78
	v_ashrrev_i32_e32 v82, 12, v82
	v_add_u32_e32 v74, 16, v74
	v_ashrrev_i32_e32 v76, 12, v76
	v_ashrrev_i32_e32 v78, 12, v78
	v_add_u32_e32 v82, 16, v82
	v_mul_hi_i32_i24_e32 v75, 0x3000, v74
	v_mul_i32_i24_e32 v74, 0x3000, v74
	v_add_u32_e32 v76, 16, v76
	v_add_u32_e32 v78, 16, v78
	v_mul_hi_i32_i24_e32 v83, 0x3000, v82
	v_mul_i32_i24_e32 v82, 0x3000, v82
	v_lshl_add_u64 v[74:75], s[24:25], 0, v[74:75]
	v_mul_hi_i32_i24_e32 v77, 0x3000, v76
	v_mul_i32_i24_e32 v76, 0x3000, v76
	v_mul_hi_i32_i24_e32 v79, 0x3000, v78
	v_mul_i32_i24_e32 v78, 0x3000, v78
	v_lshl_add_u64 v[82:83], s[24:25], 0, v[82:83]
	v_lshl_add_u64 v[74:75], v[74:75], 0, s[18:19]
	v_lshl_add_u64 v[76:77], s[24:25], 0, v[76:77]
	v_lshl_add_u64 v[78:79], s[24:25], 0, v[78:79]
	v_lshl_add_u64 v[82:83], v[82:83], 0, s[18:19]
	v_lshl_add_u64 v[80:81], v[74:75], 0, v[180:181]
	v_lshl_add_u64 v[76:77], v[76:77], 0, s[18:19]
	v_lshl_add_u64 v[78:79], v[78:79], 0, s[18:19]
	v_lshl_add_u64 v[88:89], v[82:83], 0, v[180:181]
	v_lshl_add_u64 v[84:85], v[76:77], 0, v[180:181]
	v_lshl_add_u64 v[86:87], v[78:79], 0, v[180:181]
	global_load_dword v111, v[80:81], off
	global_load_dword v112, v[80:81], off offset:128
	global_load_dword v113, v[84:85], off
	global_load_dword v122, v[84:85], off offset:128
	global_load_dword v123, v[86:87], off
	global_load_dword v124, v[86:87], off offset:128
	global_load_dword v125, v[88:89], off
	global_load_dword v126, v[88:89], off offset:128
	v_add_u32_e32 v80, 19, v102
	v_add_u32_e32 v88, 25, v102
	v_add_u32_e32 v90, 26, v102
	v_min_i32_e32 v80, 0x7fff, v80
	v_add_u32_e32 v86, 24, v102
	v_min_i32_e32 v88, 0x7fff, v88
	v_min_i32_e32 v90, 0x7fff, v90
	v_ashrrev_i32_e32 v80, 12, v80
	v_min_i32_e32 v86, 0x7fff, v86
	v_ashrrev_i32_e32 v88, 12, v88
	v_ashrrev_i32_e32 v90, 12, v90
	v_add_u32_e32 v80, 16, v80
	v_ashrrev_i32_e32 v86, 12, v86
	v_add_u32_e32 v88, 16, v88
	v_add_u32_e32 v90, 16, v90
	v_mul_hi_i32_i24_e32 v81, 0x3000, v80
	v_mul_i32_i24_e32 v80, 0x3000, v80
	v_add_u32_e32 v86, 16, v86
	v_mul_hi_i32_i24_e32 v89, 0x3000, v88
	v_mul_i32_i24_e32 v88, 0x3000, v88
	v_mul_hi_i32_i24_e32 v91, 0x3000, v90
	v_mul_i32_i24_e32 v90, 0x3000, v90
	v_lshl_add_u64 v[80:81], s[24:25], 0, v[80:81]
	v_mul_hi_i32_i24_e32 v87, 0x3000, v86
	v_mul_i32_i24_e32 v86, 0x3000, v86
	v_lshl_add_u64 v[88:89], s[24:25], 0, v[88:89]
	v_lshl_add_u64 v[90:91], s[24:25], 0, v[90:91]
	v_lshl_add_u64 v[84:85], v[80:81], 0, s[18:19]
	v_lshl_add_u64 v[86:87], s[24:25], 0, v[86:87]
	v_lshl_add_u64 v[88:89], v[88:89], 0, s[18:19]
	v_lshl_add_u64 v[90:91], v[90:91], 0, s[18:19]
	v_lshl_add_u64 v[80:81], v[84:85], 0, v[180:181]
	v_lshl_add_u64 v[86:87], v[86:87], 0, s[18:19]
	v_lshl_add_u64 v[94:95], v[88:89], 0, v[180:181]
	v_lshl_add_u64 v[100:101], v[90:91], 0, v[180:181]
	v_lshl_add_u64 v[92:93], v[86:87], 0, v[180:181]
	global_load_dword v127, v[80:81], off
	global_load_dword v160, v[80:81], off offset:128
	global_load_dword v161, v[92:93], off
	global_load_dword v164, v[92:93], off offset:128
	global_load_dword v165, v[94:95], off
	s_nop 0
	global_load_dword v94, v[94:95], off offset:128
	s_nop 0
	global_load_dword v95, v[100:101], off
	s_nop 0
	global_load_dword v100, v[100:101], off offset:128
	v_add_u32_e32 v80, 27, v102
	v_min_i32_e32 v80, 0x7fff, v80
	v_ashrrev_i32_e32 v80, 12, v80
	v_add_u32_e32 v80, 16, v80
	v_mul_hi_i32_i24_e32 v81, 0x3000, v80
	v_mul_i32_i24_e32 v80, 0x3000, v80
	v_lshl_add_u64 v[80:81], s[24:25], 0, v[80:81]
	v_lshl_add_u64 v[92:93], v[80:81], 0, s[18:19]
	v_lshl_add_u64 v[80:81], v[92:93], 0, v[180:181]
	global_load_dword v101, v[80:81], off
	s_nop 0
	global_load_dword v81, v[80:81], off offset:128
	s_waitcnt vmcnt(25)
	v_mul_f32_e32 v48, v48, v103
	s_waitcnt vmcnt(24)
	v_mul_f32_e32 v32, v32, v104
	ds_write2_b32 v162, v48, v32 offset1:32
	v_mul_f32_e32 v32, v49, v103
	v_mul_f32_e32 v33, v33, v104
	ds_write2_b32 v162, v32, v33 offset0:68 offset1:100
	v_mul_f32_e32 v32, v50, v103
	v_mul_f32_e32 v33, v34, v104
	ds_write2_b32 v162, v32, v33 offset0:136 offset1:168
	v_mul_f32_e32 v32, v51, v103
	v_mul_f32_e32 v33, v35, v104
	ds_write2_b32 v162, v32, v33 offset0:204 offset1:236
	s_waitcnt vmcnt(23)
	v_mul_f32_e32 v32, v52, v105
	s_waitcnt vmcnt(22)
	v_mul_f32_e32 v33, v36, v106
	ds_write2_b32 v115, v32, v33 offset0:32 offset1:64
	s_waitcnt vmcnt(21)
	v_mul_f32_e32 v32, v53, v107
	s_waitcnt vmcnt(20)
	v_mul_f32_e32 v33, v37, v108
	ds_write2_b32 v115, v32, v33 offset0:100 offset1:132
	s_waitcnt vmcnt(19)
	v_mul_f32_e32 v32, v54, v109
	s_waitcnt vmcnt(18)
	v_mul_f32_e32 v33, v38, v110
	ds_write2_b32 v115, v32, v33 offset0:168 offset1:200
	v_add_u32_e32 v80, s2, v163
	v_cmp_gt_i32_e32 vcc, s38, v80
	s_waitcnt vmcnt(17)
	v_mul_f32_e32 v32, v55, v111
	s_waitcnt vmcnt(16)
	v_mul_f32_e32 v33, v39, v112
	ds_write2_b32 v116, v32, v33 offset0:108 offset1:140
	s_waitcnt vmcnt(15)
	v_mul_f32_e32 v32, v56, v113
	s_waitcnt vmcnt(14)
	v_mul_f32_e32 v33, v40, v122
	ds_write2_b32 v117, v32, v33 offset0:64 offset1:96
	s_waitcnt vmcnt(13)
	v_mul_f32_e32 v32, v57, v123
	s_waitcnt vmcnt(12)
	v_mul_f32_e32 v33, v41, v124
	ds_write2_b32 v117, v32, v33 offset0:132 offset1:164
	s_waitcnt vmcnt(11)
	v_mul_f32_e32 v32, v58, v125
	s_waitcnt vmcnt(10)
	v_mul_f32_e32 v33, v42, v126
	ds_write2_b32 v117, v32, v33 offset0:200 offset1:232
	s_waitcnt vmcnt(9)
	v_mul_f32_e32 v32, v59, v127
	s_waitcnt vmcnt(8)
	v_mul_f32_e32 v33, v43, v160
	ds_write2_b32 v118, v32, v33 offset0:12 offset1:44
	s_waitcnt vmcnt(7)
	v_mul_f32_e32 v32, v60, v161
	s_waitcnt vmcnt(6)
	v_mul_f32_e32 v33, v44, v164
	ds_write2_b32 v119, v32, v33 offset0:96 offset1:128
	s_waitcnt vmcnt(5)
	v_mul_f32_e32 v32, v61, v165
	s_waitcnt vmcnt(4)
	v_mul_f32_e32 v33, v45, v94
	ds_write2_b32 v119, v32, v33 offset0:164 offset1:196
	s_waitcnt vmcnt(3)
	v_mul_f32_e32 v32, v62, v95
	s_waitcnt vmcnt(2)
	v_mul_f32_e32 v33, v46, v100
	ds_write2_b32 v120, v32, v33 offset0:104 offset1:136
	s_waitcnt vmcnt(1)
	v_mul_f32_e32 v32, v63, v101
	s_waitcnt vmcnt(0)
	v_mul_f32_e32 v33, v47, v81
	v_ashrrev_i32_e32 v81, 31, v80
	ds_write2_b32 v121, v32, v33 offset0:44 offset1:76
	v_add_u32_e32 v128, 0, v80
	v_ashrrev_i32_e32 v129, 31, v128
	v_lshlrev_b64 v[128:129], 12, v[128:129]
	v_lshl_add_u64 v[128:129], s[16:17], 0, v[128:129]
	v_lshl_add_u64 v[128:129], v[96:97], 2, v[128:129]
	global_load_dwordx4 v[128:131], v[128:129], off
	v_add_u32_e32 v132, 4, v80
	v_ashrrev_i32_e32 v133, 31, v132
	v_lshlrev_b64 v[132:133], 12, v[132:133]
	v_lshl_add_u64 v[132:133], s[16:17], 0, v[132:133]
	v_lshl_add_u64 v[132:133], v[96:97], 2, v[132:133]
	global_load_dwordx4 v[132:135], v[132:133], off
	v_add_u32_e32 v136, 8, v80
	v_ashrrev_i32_e32 v137, 31, v136
	v_lshlrev_b64 v[136:137], 12, v[136:137]
	v_lshl_add_u64 v[136:137], s[16:17], 0, v[136:137]
	v_lshl_add_u64 v[136:137], v[96:97], 2, v[136:137]
	global_load_dwordx4 v[136:139], v[136:137], off
	v_add_u32_e32 v140, 12, v80
	v_ashrrev_i32_e32 v141, 31, v140
	v_lshlrev_b64 v[140:141], 12, v[140:141]
	v_lshl_add_u64 v[140:141], s[16:17], 0, v[140:141]
	v_lshl_add_u64 v[140:141], v[96:97], 2, v[140:141]
	global_load_dwordx4 v[140:143], v[140:141], off
	v_add_u32_e32 v144, 16, v80
	v_ashrrev_i32_e32 v145, 31, v144
	v_lshlrev_b64 v[144:145], 12, v[144:145]
	v_lshl_add_u64 v[144:145], s[16:17], 0, v[144:145]
	v_lshl_add_u64 v[144:145], v[96:97], 2, v[144:145]
	global_load_dwordx4 v[144:147], v[144:145], off
	v_add_u32_e32 v148, 20, v80
	v_ashrrev_i32_e32 v149, 31, v148
	v_lshlrev_b64 v[148:149], 12, v[148:149]
	v_lshl_add_u64 v[148:149], s[16:17], 0, v[148:149]
	v_lshl_add_u64 v[148:149], v[96:97], 2, v[148:149]
	global_load_dwordx4 v[148:151], v[148:149], off
	v_add_u32_e32 v152, 24, v80
	v_ashrrev_i32_e32 v153, 31, v152
	v_lshlrev_b64 v[152:153], 12, v[152:153]
	v_lshl_add_u64 v[152:153], s[16:17], 0, v[152:153]
	v_lshl_add_u64 v[152:153], v[96:97], 2, v[152:153]
	global_load_dwordx4 v[152:155], v[152:153], off
	v_add_u32_e32 v156, 28, v80
	v_ashrrev_i32_e32 v157, 31, v156
	v_lshlrev_b64 v[156:157], 12, v[156:157]
	v_lshl_add_u64 v[156:157], s[16:17], 0, v[156:157]
	v_lshl_add_u64 v[156:157], v[96:97], 2, v[156:157]
	global_load_dwordx4 v[156:159], v[156:157], off
	s_and_saveexec_b64 s[2:3], vcc
	s_cbranch_execz .LBB0_4516
	v_lshlrev_b64 v[32:33], 12, v[80:81]
	v_lshl_add_u64 v[32:33], s[16:17], 0, v[32:33]
	v_lshl_add_u64 v[40:41], v[96:97], 2, v[32:33]
	ds_read_b128 v[36:39], v114
	s_waitcnt vmcnt(7) lgkmcnt(0)
	v_pk_add_f32 v[34:35], v[38:39], v[130:131]
	v_pk_add_f32 v[32:33], v[36:37], v[128:129]
	global_store_dwordx4 v[40:41], v[32:35], off

.LBB0_4663:
	v_mbcnt_hi_u32_b32 v188, -1, v210
	s_load_dwordx2 s[2:3], s[0:1], 0x158
	s_load_dwordx2 s[4:5], s[0:1], 0xc8
	s_ashr_i32 s7, s6, 31
	v_mov_b32_e32 v1, v188
	s_and_b32 s7, s7, s42
	s_add_i32 s68, s7, s6
	v_add_u32_e32 v0, s70, v1
	v_ashrrev_i32_e32 v189, 3, v0
	v_readfirstlane_b32 s8, v0
	v_lshlrev_b32_e32 v0, 3, v1
	v_and_b32_e32 v0, 56, v0
	s_cmpk_lt_i32 s68, 0x300
	s_cselect_b64 s[6:7], -1, 0
	s_cmpk_gt_i32 s68, 0x2ff
	v_lshlrev_b32_e32 v160, 1, v0
	v_add_u32_e32 v190, 64, v189
	s_cbranch_scc1 .LBB0_4665
	s_mul_hi_i32 s9, s68, 0x2aaaaaab
	s_lshr_b32 s10, s9, 31
	s_add_i32 s9, s9, s10
	s_mul_i32 s10, s9, -6
	s_lshl_b32 s9, s9, 8
	v_add_u32_e32 v2, s9, v189
	v_min_i32_e32 v2, 0x7fff, v2
	v_ashrrev_i32_e32 v3, 31, v2
	v_lshlrev_b64 v[2:3], 11, v[2:3]
	s_add_i32 s10, s10, s68
	s_waitcnt lgkmcnt(0)
	v_lshl_add_u64 v[2:3], s[2:3], 0, v[2:3]
	v_mov_b32_e32 v161, 0
	s_lshl_b32 s10, s10, 8
	v_lshl_add_u64 v[2:3], v[2:3], 0, v[160:161]
	v_mbcnt_hi_u32_b32 v158, -1, v210
	s_and_b32 s90, s70, 0x40
	v_and_b32_e32 v159, 48, v158
	v_or_b32_e32 v159, s90, v159
	s_lshl_b32 s88, s70, 4
	s_lshl_b32 s92, s22, 4
	s_and_b32 s92, s92, 0x780
	s_mov_b32 s93, 0
	s_add_u32 m0, s88, 0
	v_lshl_add_u64 v[2:3], v[2:3], 0, s[92:93]
	v_xor_b32_e32 v2, v159, v2
	global_load_lds_dwordx4 v[2:3], off
	v_add_u32_e32 v2, s10, v189
	v_ashrrev_i32_e32 v3, 31, v2
	v_lshlrev_b64 v[2:3], 11, v[2:3]
	v_lshl_add_u64 v[2:3], s[4:5], 0, v[2:3]
	v_lshl_add_u64 v[2:3], v[2:3], 0, v[160:161]
	s_add_u32 m0, s88, 32768
	v_lshl_add_u64 v[2:3], v[2:3], 0, s[92:93]
	v_xor_b32_e32 v2, v159, v2
	global_load_lds_dwordx4 v[2:3], off
	v_add_u32_e32 v2, s9, v190
	v_min_i32_e32 v2, 0x7fff, v2
	v_ashrrev_i32_e32 v3, 31, v2
	v_lshlrev_b64 v[2:3], 11, v[2:3]
	v_lshl_add_u64 v[2:3], s[2:3], 0, v[2:3]
	v_lshl_add_u64 v[2:3], v[2:3], 0, v[160:161]
	s_add_u32 m0, s88, 8192
	v_lshl_add_u64 v[2:3], v[2:3], 0, s[92:93]
	v_xor_b32_e32 v2, v159, v2
	global_load_lds_dwordx4 v[2:3], off
	v_add_u32_e32 v2, s10, v190
	v_ashrrev_i32_e32 v3, 31, v2
	v_lshlrev_b64 v[2:3], 11, v[2:3]
	v_lshl_add_u64 v[2:3], s[4:5], 0, v[2:3]
	v_lshl_add_u64 v[2:3], v[2:3], 0, v[160:161]
	v_add_u32_e32 v4, 0x80, v189
	s_add_u32 m0, s88, 40960
	v_lshl_add_u64 v[2:3], v[2:3], 0, s[92:93]
	v_xor_b32_e32 v2, v159, v2
	global_load_lds_dwordx4 v[2:3], off
	v_add_u32_e32 v2, s9, v4
	v_min_i32_e32 v2, 0x7fff, v2
	v_ashrrev_i32_e32 v3, 31, v2
	v_lshlrev_b64 v[2:3], 11, v[2:3]
	v_lshl_add_u64 v[2:3], s[2:3], 0, v[2:3]
	v_lshl_add_u64 v[2:3], v[2:3], 0, v[160:161]
	s_add_u32 m0, s88, 16384
	v_lshl_add_u64 v[2:3], v[2:3], 0, s[92:93]
	v_xor_b32_e32 v2, v159, v2
	global_load_lds_dwordx4 v[2:3], off
	v_add_u32_e32 v2, s10, v4
	v_ashrrev_i32_e32 v3, 31, v2
	v_lshlrev_b64 v[2:3], 11, v[2:3]
	v_lshl_add_u64 v[2:3], s[4:5], 0, v[2:3]
	v_lshl_add_u64 v[2:3], v[2:3], 0, v[160:161]
	v_add_u32_e32 v4, 0xc0, v189
	s_add_u32 m0, s88, 49152
	v_lshl_add_u64 v[2:3], v[2:3], 0, s[92:93]
	v_xor_b32_e32 v2, v159, v2
	global_load_lds_dwordx4 v[2:3], off
	v_add_u32_e32 v2, s9, v4
	v_min_i32_e32 v2, 0x7fff, v2
	v_ashrrev_i32_e32 v3, 31, v2
	v_lshlrev_b64 v[2:3], 11, v[2:3]
	v_lshl_add_u64 v[2:3], s[2:3], 0, v[2:3]
	v_lshl_add_u64 v[2:3], v[2:3], 0, v[160:161]
	s_add_u32 m0, s88, 24576
	v_lshl_add_u64 v[2:3], v[2:3], 0, s[92:93]
	v_xor_b32_e32 v2, v159, v2
	global_load_lds_dwordx4 v[2:3], off
	v_add_u32_e32 v2, s10, v4
	v_ashrrev_i32_e32 v3, 31, v2
	v_lshlrev_b64 v[2:3], 11, v[2:3]
	v_lshl_add_u64 v[2:3], s[4:5], 0, v[2:3]
	v_lshl_add_u64 v[2:3], v[2:3], 0, v[160:161]
	s_add_u32 m0, s88, 57344
	v_lshl_add_u64 v[2:3], v[2:3], 0, s[92:93]
	v_xor_b32_e32 v2, v159, v2
	global_load_lds_dwordx4 v[2:3], off

.LBB0_4668:
	s_mul_hi_i32 s5, s68, 0x2aaaaaab
	s_lshr_b32 s2, s5, 31
	s_add_i32 s5, s5, s2
	s_lshl_b32 s69, s5, 8
	s_waitcnt lgkmcnt(0)
	v_add_u32_e32 v0, s69, v189
	v_min_i32_e32 v0, 0x7fff, v0
	v_ashrrev_i32_e32 v1, 31, v0
	v_lshlrev_b64 v[0:1], 11, v[0:1]
	s_mul_i32 s2, s5, 0x600
	v_lshl_add_u64 v[172:173], v[168:169], 0, v[0:1]
	v_subrev_u32_e32 v0, s2, v200
	v_ashrrev_i32_e32 v1, 31, v0
	v_lshlrev_b64 v[0:1], 11, v[0:1]
	v_lshl_add_u64 v[180:181], v[170:171], 0, v[0:1]
	v_subrev_u32_e32 v0, s2, v201
	v_ashrrev_i32_e32 v1, 31, v0
	v_lshlrev_b64 v[0:1], 11, v[0:1]
	v_lshl_add_u64 v[182:183], v[170:171], 0, v[0:1]
	v_subrev_u32_e32 v0, s2, v202
	v_ashrrev_i32_e32 v1, 31, v0
	v_add_u32_e32 v2, s69, v190
	v_add_u32_e32 v4, s69, v163
	v_add_u32_e32 v6, s69, v192
	v_lshlrev_b64 v[0:1], 11, v[0:1]
	v_min_i32_e32 v2, 0x7fff, v2
	v_min_i32_e32 v4, 0x7fff, v4
	v_min_i32_e32 v6, 0x7fff, v6
	v_lshl_add_u64 v[184:185], v[170:171], 0, v[0:1]
	v_subrev_u32_e32 v0, s2, v203
	v_ashrrev_i32_e32 v3, 31, v2
	v_ashrrev_i32_e32 v5, 31, v4
	v_ashrrev_i32_e32 v7, 31, v6
	v_ashrrev_i32_e32 v1, 31, v0
	v_lshlrev_b64 v[2:3], 11, v[2:3]
	v_lshlrev_b64 v[4:5], 11, v[4:5]
	v_lshlrev_b64 v[6:7], 11, v[6:7]
	v_lshlrev_b64 v[0:1], 11, v[0:1]
	s_mov_b32 s4, s68
	v_lshl_add_u64 v[174:175], v[168:169], 0, v[2:3]
	v_lshl_add_u64 v[176:177], v[168:169], 0, v[4:5]
	v_lshl_add_u64 v[178:179], v[168:169], 0, v[6:7]
	v_lshl_add_u64 v[186:187], v[170:171], 0, v[0:1]
	s_mov_b64 s[2:3], 0
	s_mov_b32 s6, s25
	v_mov_b32_e32 v0, v161
	v_mov_b32_e32 v1, v161
	v_mov_b32_e32 v2, v161
	v_mov_b32_e32 v3, v161
	v_mov_b32_e32 v4, v161
	v_mov_b32_e32 v5, v161
	v_mov_b32_e32 v6, v161
	v_mov_b32_e32 v7, v161
	v_mov_b32_e32 v8, v161
	v_mov_b32_e32 v9, v161
	v_mov_b32_e32 v10, v161
	v_mov_b32_e32 v11, v161
	v_mov_b32_e32 v12, v161
	v_mov_b32_e32 v13, v161
	v_mov_b32_e32 v14, v161
	v_mov_b32_e32 v15, v161
	v_mov_b32_e32 v16, v161
	v_mov_b32_e32 v17, v161
	v_mov_b32_e32 v18, v161
	v_mov_b32_e32 v19, v161
	v_mov_b32_e32 v20, v161
	v_mov_b32_e32 v21, v161
	v_mov_b32_e32 v22, v161
	v_mov_b32_e32 v23, v161
	v_mov_b32_e32 v24, v161
	v_mov_b32_e32 v25, v161
	v_mov_b32_e32 v26, v161
	v_mov_b32_e32 v27, v161
	v_mov_b32_e32 v28, v161
	v_mov_b32_e32 v29, v161
	v_mov_b32_e32 v30, v161
	v_mov_b32_e32 v31, v161
	v_mov_b32_e32 v32, v161
	v_mov_b32_e32 v33, v161
	v_mov_b32_e32 v34, v161
	v_mov_b32_e32 v35, v161
	v_mov_b32_e32 v36, v161
	v_mov_b32_e32 v37, v161
	v_mov_b32_e32 v38, v161
	v_mov_b32_e32 v39, v161
	v_mov_b32_e32 v40, v161
	v_mov_b32_e32 v41, v161
	v_mov_b32_e32 v42, v161
	v_mov_b32_e32 v43, v161
	v_mov_b32_e32 v44, v161
	v_mov_b32_e32 v45, v161
	v_mov_b32_e32 v46, v161
	v_mov_b32_e32 v47, v161
	v_mov_b32_e32 v48, v161
	v_mov_b32_e32 v49, v161
	v_mov_b32_e32 v50, v161
	v_mov_b32_e32 v51, v161
	v_mov_b32_e32 v52, v161
	v_mov_b32_e32 v53, v161
	v_mov_b32_e32 v54, v161
	v_mov_b32_e32 v55, v161
	v_mov_b32_e32 v56, v161
	v_mov_b32_e32 v57, v161
	v_mov_b32_e32 v58, v161
	v_mov_b32_e32 v59, v161
	v_mov_b32_e32 v60, v161
	v_mov_b32_e32 v61, v161
	v_mov_b32_e32 v62, v161
	v_mov_b32_e32 v63, v161
	v_mov_b32_e32 v64, v161
	v_mov_b32_e32 v65, v161
	v_mov_b32_e32 v66, v161
	v_mov_b32_e32 v67, v161
	v_mov_b32_e32 v68, v161
	v_mov_b32_e32 v69, v161
	v_mov_b32_e32 v70, v161
	v_mov_b32_e32 v71, v161
	v_mov_b32_e32 v72, v161
	v_mov_b32_e32 v73, v161
	v_mov_b32_e32 v74, v161
	v_mov_b32_e32 v75, v161
	v_mov_b32_e32 v76, v161
	v_mov_b32_e32 v77, v161
	v_mov_b32_e32 v78, v161
	v_mov_b32_e32 v79, v161
	v_mov_b32_e32 v80, v161
	v_mov_b32_e32 v81, v161
	v_mov_b32_e32 v82, v161
	v_mov_b32_e32 v83, v161
	v_mov_b32_e32 v84, v161
	v_mov_b32_e32 v85, v161
	v_mov_b32_e32 v86, v161
	v_mov_b32_e32 v87, v161
	v_mov_b32_e32 v88, v161
	v_mov_b32_e32 v89, v161
	v_mov_b32_e32 v90, v161
	v_mov_b32_e32 v91, v161
	v_mov_b32_e32 v92, v161
	v_mov_b32_e32 v93, v161
	v_mov_b32_e32 v94, v161
	v_mov_b32_e32 v95, v161
	s_waitcnt vmcnt(7)
	v_mov_b32_e32 v96, v161
	v_mov_b32_e32 v97, v161
	v_mov_b32_e32 v98, v161
	v_mov_b32_e32 v99, v161
	s_waitcnt vmcnt(6)
	v_mov_b32_e32 v100, v161
	v_mov_b32_e32 v101, v161
	v_mov_b32_e32 v102, v161
	v_mov_b32_e32 v103, v161
	s_waitcnt vmcnt(5)
	v_mov_b32_e32 v104, v161
	v_mov_b32_e32 v105, v161
	v_mov_b32_e32 v106, v161
	v_mov_b32_e32 v107, v161
	s_waitcnt vmcnt(4)
	v_mov_b32_e32 v108, v161
	v_mov_b32_e32 v109, v161
	v_mov_b32_e32 v110, v161
	v_mov_b32_e32 v111, v161
	s_waitcnt vmcnt(3)
	v_mov_b32_e32 v112, v161
	v_mov_b32_e32 v113, v161
	v_mov_b32_e32 v114, v161
	v_mov_b32_e32 v115, v161
	s_waitcnt vmcnt(2)
	v_mov_b32_e32 v116, v161
	v_mov_b32_e32 v117, v161
	v_mov_b32_e32 v118, v161
	v_mov_b32_e32 v119, v161
	s_waitcnt vmcnt(1)
	v_mov_b32_e32 v120, v161
	v_mov_b32_e32 v121, v161
	v_mov_b32_e32 v122, v161
	v_mov_b32_e32 v123, v161
	s_waitcnt vmcnt(0)
	v_mov_b32_e32 v124, v161
	v_mov_b32_e32 v125, v161
	v_mov_b32_e32 v126, v161
	v_mov_b32_e32 v127, v161
	v_mbcnt_hi_u32_b32 v128, -1, v210
	s_and_b32 s90, s70, 0x40
	v_and_b32_e32 v159, 48, v128
	v_or_b32_e32 v159, s90, v159
	v_and_b32_e32 v129, 31, v128
	v_lshrrev_b32_e32 v130, 5, v128
	v_bfe_u32 v131, v128, 1, 3
	v_lshlrev_b32_e32 v132, 7, v129
	s_lshr_b32 s91, s70, 7
	s_lshl_b32 s91, s91, 13
	s_lshl_b32 s90, s90, 8
	s_add_u32 s90, s90, 0x8000
	s_lshl_b32 s88, s70, 4
	s_mov_b32 s89, 0x10000
	s_lshl_b32 s92, s22, 4
	s_and_b32 s92, s92, 0x780
	s_mov_b32 s93, 0
	v_xor_b32_e32 v133, v130, v131
	v_lshl_add_u32 v133, v133, 4, v132
	v_add_u32_e32 v232, s91, v133
	v_add_u32_e32 v236, s90, v133
	v_or_b32_e32 v133, 2, v130
	v_xor_b32_e32 v133, v133, v131
	v_lshl_add_u32 v133, v133, 4, v132
	v_add_u32_e32 v233, s91, v133
	v_add_u32_e32 v237, s90, v133
	v_or_b32_e32 v133, 4, v130
	v_xor_b32_e32 v133, v133, v131
	v_lshl_add_u32 v133, v133, 4, v132
	v_add_u32_e32 v234, s91, v133
	v_add_u32_e32 v238, s90, v133
	v_or_b32_e32 v133, 6, v130
	v_xor_b32_e32 v133, v133, v131
	v_lshl_add_u32 v133, v133, 4, v132
	v_add_u32_e32 v235, s91, v133
	v_add_u32_e32 v239, s90, v133
	s_waitcnt vmcnt(0)
	s_barrier
	ds_read_b128 v[206:209], v232
	ds_read_b128 v[216:219], v236
	ds_read_b128 v[212:215], v232 offset:4096
	ds_read_b128 v[220:223], v236 offset:4096
	ds_read_b128 v[224:227], v236 offset:8192
	ds_read_b128 v[228:231], v236 offset:12288
	s_add_u32 s94, s2, s92
	s_add_u32 s94, s94, 0x80
	s_and_b32 s94, s94, 0x780
	s_sub_u32 s94, s94, 0x80
	s_subb_u32 s95, 0, 0
	s_add_u32 s90, s88, s89
	s_add_u32 m0, s90, 0
	v_lshl_add_u64 v[152:153], v[172:173], 0, s[94:95]
	v_xor_b32_e32 v152, v159, v152
	global_load_lds_dwordx4 v[152:153], off
	s_add_u32 m0, s90, 32768
	v_lshl_add_u64 v[154:155], v[180:181], 0, s[94:95]
	v_xor_b32_e32 v154, v159, v154
	global_load_lds_dwordx4 v[154:155], off
	s_add_u32 m0, s90, 8192
	v_lshl_add_u64 v[156:157], v[174:175], 0, s[94:95]
	v_xor_b32_e32 v156, v159, v156
	global_load_lds_dwordx4 v[156:157], off
	s_add_u32 m0, s90, 40960
	v_lshl_add_u64 v[152:153], v[182:183], 0, s[94:95]
	v_xor_b32_e32 v152, v159, v152
	global_load_lds_dwordx4 v[152:153], off
	s_add_u32 m0, s90, 16384
	v_lshl_add_u64 v[154:155], v[176:177], 0, s[94:95]
	v_xor_b32_e32 v154, v159, v154
	global_load_lds_dwordx4 v[154:155], off
	s_add_u32 m0, s90, 49152
	v_lshl_add_u64 v[156:157], v[184:185], 0, s[94:95]
	v_xor_b32_e32 v156, v159, v156
	global_load_lds_dwordx4 v[156:157], off
	s_add_u32 m0, s90, 24576
	v_lshl_add_u64 v[152:153], v[178:179], 0, s[94:95]
	v_xor_b32_e32 v152, v159, v152
	global_load_lds_dwordx4 v[152:153], off
	s_add_u32 m0, s90, 57344
	v_lshl_add_u64 v[154:155], v[186:187], 0, s[94:95]
	v_xor_b32_e32 v154, v159, v154
	global_load_lds_dwordx4 v[154:155], off
	s_xor_b32 s89, s89, 0x10000

.LBB0_5635:
	v_mbcnt_hi_u32_b32 v211, -1, v210
	s_load_dwordx2 s[2:3], s[0:1], 0xf8
	s_load_dwordx2 s[4:5], s[0:1], 0x158
	s_ashr_i32 s7, s6, 31
	v_mov_b32_e32 v1, v211
	s_and_b32 s7, s7, s42
	s_add_i32 s54, s7, s6
	v_add_u32_e32 v0, s70, v1
	v_ashrrev_i32_e32 v212, 3, v0
	v_readfirstlane_b32 s8, v0
	v_lshlrev_b32_e32 v0, 3, v1
	v_and_b32_e32 v0, 56, v0
	s_cmpk_lt_i32 s54, 0x200
	s_cselect_b64 s[6:7], -1, 0
	s_cmpk_gt_i32 s54, 0x1ff
	v_lshlrev_b32_e32 v168, 1, v0
	v_add_u32_e32 v213, 64, v212
	s_cbranch_scc1 .LBB0_5637
	s_ashr_i32 s9, s54, 31
	s_lshr_b32 s9, s9, 30
	s_add_i32 s9, s54, s9
	s_ashr_i32 s9, s9, 2
	s_lshl_b32 s10, s9, 8
	v_add_u32_e32 v2, s10, v212
	v_min_i32_e32 v2, 0x7fff, v2
	v_ashrrev_i32_e32 v3, 31, v2
	v_lshlrev_b64 v[2:3], 11, v[2:3]
	s_lshl_b32 s9, s9, 10
	s_lshl_b32 s11, s54, 8
	s_waitcnt lgkmcnt(0)
	v_lshl_add_u64 v[2:3], s[4:5], 0, v[2:3]
	v_mov_b32_e32 v169, 0
	s_sub_i32 s9, s11, s9
	v_lshl_add_u64 v[2:3], v[2:3], 0, v[168:169]
	v_mbcnt_hi_u32_b32 v158, -1, v210
	s_and_b32 s90, s70, 0x40
	v_and_b32_e32 v159, 48, v158
	v_or_b32_e32 v159, s90, v159
	s_lshl_b32 s88, s70, 4
	s_lshl_b32 s92, s22, 4
	s_and_b32 s92, s92, 0x780
	s_mov_b32 s93, 0
	s_add_u32 m0, s88, 0
	v_lshl_add_u64 v[2:3], v[2:3], 0, s[92:93]
	v_xor_b32_e32 v2, v159, v2
	global_load_lds_dwordx4 v[2:3], off
	v_add_u32_e32 v2, s9, v212
	v_ashrrev_i32_e32 v3, 31, v2
	v_lshlrev_b64 v[2:3], 11, v[2:3]
	v_lshl_add_u64 v[2:3], s[2:3], 0, v[2:3]
	v_lshl_add_u64 v[2:3], v[2:3], 0, v[168:169]
	s_add_u32 m0, s88, 32768
	v_lshl_add_u64 v[2:3], v[2:3], 0, s[92:93]
	v_xor_b32_e32 v2, v159, v2
	global_load_lds_dwordx4 v[2:3], off
	v_add_u32_e32 v2, s10, v213
	v_min_i32_e32 v2, 0x7fff, v2
	v_ashrrev_i32_e32 v3, 31, v2
	v_lshlrev_b64 v[2:3], 11, v[2:3]
	v_lshl_add_u64 v[2:3], s[4:5], 0, v[2:3]
	v_lshl_add_u64 v[2:3], v[2:3], 0, v[168:169]
	s_add_u32 m0, s88, 8192
	v_lshl_add_u64 v[2:3], v[2:3], 0, s[92:93]
	v_xor_b32_e32 v2, v159, v2
	global_load_lds_dwordx4 v[2:3], off
	v_add_u32_e32 v2, s9, v213
	v_ashrrev_i32_e32 v3, 31, v2
	v_lshlrev_b64 v[2:3], 11, v[2:3]
	v_lshl_add_u64 v[2:3], s[2:3], 0, v[2:3]
	v_lshl_add_u64 v[2:3], v[2:3], 0, v[168:169]
	v_add_u32_e32 v4, 0x80, v212
	s_add_u32 m0, s88, 40960
	v_lshl_add_u64 v[2:3], v[2:3], 0, s[92:93]
	v_xor_b32_e32 v2, v159, v2
	global_load_lds_dwordx4 v[2:3], off
	v_add_u32_e32 v2, s10, v4
	v_min_i32_e32 v2, 0x7fff, v2
	v_ashrrev_i32_e32 v3, 31, v2
	v_lshlrev_b64 v[2:3], 11, v[2:3]
	v_lshl_add_u64 v[2:3], s[4:5], 0, v[2:3]
	v_lshl_add_u64 v[2:3], v[2:3], 0, v[168:169]
	s_add_u32 m0, s88, 16384
	v_lshl_add_u64 v[2:3], v[2:3], 0, s[92:93]
	v_xor_b32_e32 v2, v159, v2
	global_load_lds_dwordx4 v[2:3], off
	v_add_u32_e32 v2, s9, v4
	v_ashrrev_i32_e32 v3, 31, v2
	v_lshlrev_b64 v[2:3], 11, v[2:3]
	v_lshl_add_u64 v[2:3], s[2:3], 0, v[2:3]
	v_lshl_add_u64 v[2:3], v[2:3], 0, v[168:169]
	v_add_u32_e32 v4, 0xc0, v212
	s_add_u32 m0, s88, 49152
	v_lshl_add_u64 v[2:3], v[2:3], 0, s[92:93]
	v_xor_b32_e32 v2, v159, v2
	global_load_lds_dwordx4 v[2:3], off
	v_add_u32_e32 v2, s10, v4
	v_min_i32_e32 v2, 0x7fff, v2
	v_ashrrev_i32_e32 v3, 31, v2
	v_lshlrev_b64 v[2:3], 11, v[2:3]
	v_lshl_add_u64 v[2:3], s[4:5], 0, v[2:3]
	v_lshl_add_u64 v[2:3], v[2:3], 0, v[168:169]
	s_add_u32 m0, s88, 24576
	v_lshl_add_u64 v[2:3], v[2:3], 0, s[92:93]
	v_xor_b32_e32 v2, v159, v2
	global_load_lds_dwordx4 v[2:3], off
	v_add_u32_e32 v2, s9, v4
	v_ashrrev_i32_e32 v3, 31, v2
	v_lshlrev_b64 v[2:3], 11, v[2:3]
	v_lshl_add_u64 v[2:3], s[2:3], 0, v[2:3]
	v_lshl_add_u64 v[2:3], v[2:3], 0, v[168:169]
	s_add_u32 m0, s88, 57344
	v_lshl_add_u64 v[2:3], v[2:3], 0, s[92:93]
	v_xor_b32_e32 v2, v159, v2
	global_load_lds_dwordx4 v[2:3], off

.LBB0_5644:
	ds_read_b128 v[128:131], v231
	ds_read_b128 v[136:139], v235
	ds_read_b128 v[132:135], v231 offset:4096
	ds_read_b128 v[140:143], v235 offset:4096
	ds_read_b128 v[144:147], v235 offset:8192
	ds_read_b128 v[148:151], v235 offset:12288
	s_waitcnt lgkmcnt(6)
	v_mfma_f32_32x32x16_bf16 v[112:127], v[188:191], v[196:199], v[112:127]
	v_mfma_f32_32x32x16_bf16 v[48:63], v[192:195], v[196:199], v[48:63]
	v_mfma_f32_32x32x16_bf16 v[96:111], v[188:191], v[200:203], v[96:111]
	v_mfma_f32_32x32x16_bf16 v[32:47], v[192:195], v[200:203], v[32:47]
	v_mfma_f32_32x32x16_bf16 v[80:95], v[188:191], v[204:207], v[80:95]
	v_mfma_f32_32x32x16_bf16 v[16:31], v[192:195], v[204:207], v[16:31]
	v_mfma_f32_32x32x16_bf16 v[64:79], v[188:191], v[226:229], v[64:79]
	v_mfma_f32_32x32x16_bf16 v[0:15], v[192:195], v[226:229], v[0:15]
	ds_read_b128 v[188:191], v232
	ds_read_b128 v[196:199], v236
	ds_read_b128 v[192:195], v232 offset:4096
	ds_read_b128 v[200:203], v236 offset:4096
	ds_read_b128 v[204:207], v236 offset:8192
	ds_read_b128 v[226:229], v236 offset:12288
	s_waitcnt lgkmcnt(6)
	v_mfma_f32_32x32x16_bf16 v[112:127], v[128:131], v[136:139], v[112:127]
	v_mfma_f32_32x32x16_bf16 v[48:63], v[132:135], v[136:139], v[48:63]
	v_mfma_f32_32x32x16_bf16 v[96:111], v[128:131], v[140:143], v[96:111]
	v_mfma_f32_32x32x16_bf16 v[32:47], v[132:135], v[140:143], v[32:47]
	v_mfma_f32_32x32x16_bf16 v[80:95], v[128:131], v[144:147], v[80:95]
	v_mfma_f32_32x32x16_bf16 v[16:31], v[132:135], v[144:147], v[16:31]
	v_mfma_f32_32x32x16_bf16 v[64:79], v[128:131], v[148:151], v[64:79]
	v_mfma_f32_32x32x16_bf16 v[0:15], v[132:135], v[148:151], v[0:15]
	ds_read_b128 v[128:131], v233
	ds_read_b128 v[136:139], v237
	ds_read_b128 v[132:135], v233 offset:4096
	ds_read_b128 v[140:143], v237 offset:4096
	ds_read_b128 v[144:147], v237 offset:8192
	ds_read_b128 v[148:151], v237 offset:12288
	s_waitcnt lgkmcnt(6)
	v_mfma_f32_32x32x16_bf16 v[112:127], v[188:191], v[196:199], v[112:127]
	v_mfma_f32_32x32x16_bf16 v[48:63], v[192:195], v[196:199], v[48:63]
	v_mfma_f32_32x32x16_bf16 v[96:111], v[188:191], v[200:203], v[96:111]
	v_mfma_f32_32x32x16_bf16 v[32:47], v[192:195], v[200:203], v[32:47]
	v_mfma_f32_32x32x16_bf16 v[80:95], v[188:191], v[204:207], v[80:95]
	v_mfma_f32_32x32x16_bf16 v[16:31], v[192:195], v[204:207], v[16:31]
	v_mfma_f32_32x32x16_bf16 v[64:79], v[188:191], v[226:229], v[64:79]
	v_mfma_f32_32x32x16_bf16 v[0:15], v[192:195], v[226:229], v[0:15]
	s_waitcnt lgkmcnt(0)
	s_barrier
	v_xor_b32_e32 v230, 0x10000, v230
	v_xor_b32_e32 v234, 0x10000, v234
	v_mfma_f32_32x32x16_bf16 v[112:127], v[128:131], v[136:139], v[112:127]
	v_xor_b32_e32 v231, 0x10000, v231
	v_xor_b32_e32 v235, 0x10000, v235
	v_mfma_f32_32x32x16_bf16 v[48:63], v[132:135], v[136:139], v[48:63]
	v_xor_b32_e32 v232, 0x10000, v232
	v_xor_b32_e32 v236, 0x10000, v236
	v_mfma_f32_32x32x16_bf16 v[96:111], v[128:131], v[140:143], v[96:111]
	v_xor_b32_e32 v233, 0x10000, v233
	v_xor_b32_e32 v237, 0x10000, v237
	v_mfma_f32_32x32x16_bf16 v[32:47], v[132:135], v[140:143], v[32:47]
	v_mfma_f32_32x32x16_bf16 v[80:95], v[128:131], v[144:147], v[80:95]
	v_mfma_f32_32x32x16_bf16 v[16:31], v[132:135], v[144:147], v[16:31]
	v_mfma_f32_32x32x16_bf16 v[64:79], v[128:131], v[148:151], v[64:79]
	v_mfma_f32_32x32x16_bf16 v[0:15], v[132:135], v[148:151], v[0:15]
	s_lshl_b32 s2, s5, 8
	s_sub_i32 s2, s2, s6
	v_mov_b32_e32 v168, v214
	s_add_i32 s55, s4, s30
	s_or_b32 s26, s2, s31
	s_ashr_i32 s27, s26, 31
	s_load_dwordx2 s[24:25], s[0:1], 0x140
	v_ashrrev_i32_e32 v180, 3, v168
	v_and_b32_e32 v183, -4, v180
	v_add_u32_e32 v225, s55, v183
	v_add_u32_e32 v190, 8, v225
	v_min_i32_e32 v190, 0x7fff, v190
	v_ashrrev_i32_e32 v190, 12, v190
	v_add_u32_e32 v190, 24, v190
	v_mul_hi_i32_i24_e32 v191, 0x3000, v190
	v_mul_i32_i24_e32 v190, 0x3000, v190
	v_min_i32_e32 v184, 0x7fff, v225
	v_ashrrev_i32_e32 v184, 12, v184
	v_and_b32_e32 v182, 31, v168
	v_add_u32_e32 v184, 24, v184
	v_or_b32_e32 v180, s26, v182
	v_mul_hi_i32_i24_e32 v185, 0x3000, v184
	v_mul_i32_i24_e32 v184, 0x3000, v184
	v_ashrrev_i32_e32 v181, 31, v180
	s_waitcnt lgkmcnt(0)
	v_lshl_add_u64 v[184:185], s[24:25], 0, v[184:185]
	v_lshl_add_u64 v[184:185], v[184:185], 0, s[18:19]
	v_lshlrev_b64 v[180:181], 2, v[180:181]
	v_lshl_add_u64 v[196:197], v[184:185], 0, v[180:181]
	v_lshl_add_u64 v[186:187], s[24:25], 0, v[190:191]
	v_add_u32_e32 v188, 9, v225
	v_add_u32_e32 v190, 10, v225
	v_min_i32_e32 v188, 0x7fff, v188
	v_min_i32_e32 v190, 0x7fff, v190
	v_ashrrev_i32_e32 v188, 12, v188
	v_ashrrev_i32_e32 v190, 12, v190
	v_add_u32_e32 v188, 24, v188
	v_add_u32_e32 v190, 24, v190
	v_mul_hi_i32_i24_e32 v189, 0x3000, v188
	v_mul_i32_i24_e32 v188, 0x3000, v188
	v_mul_hi_i32_i24_e32 v191, 0x3000, v190
	v_mul_i32_i24_e32 v190, 0x3000, v190
	v_lshl_add_u64 v[188:189], s[24:25], 0, v[188:189]
	v_lshl_add_u64 v[190:191], s[24:25], 0, v[190:191]
	v_lshl_add_u64 v[186:187], v[186:187], 0, s[18:19]
	v_lshl_add_u64 v[188:189], v[188:189], 0, s[18:19]
	v_lshl_add_u64 v[190:191], v[190:191], 0, s[18:19]
	v_lshl_add_u64 v[206:207], v[186:187], 0, v[180:181]
	v_add_u32_e32 v208, 18, v225
	v_min_i32_e32 v208, 0x7fff, v208
	v_ashrrev_i32_e32 v208, 12, v208
	v_add_u32_e32 v208, 24, v208
	v_mul_hi_i32_i24_e32 v209, 0x3000, v208
	v_mul_i32_i24_e32 v208, 0x3000, v208
	v_lshl_add_u64 v[208:209], s[24:25], 0, v[208:209]
	v_lshl_add_u64 v[202:203], v[188:189], 0, v[180:181]
	v_lshl_add_u64 v[204:205], v[190:191], 0, v[180:181]
	global_load_dword v232, v[196:197], off
	global_load_dword v233, v[196:197], off offset:128
	global_load_dword v242, v[206:207], off
	global_load_dword v243, v[206:207], off offset:128
	global_load_dword v244, v[202:203], off
	global_load_dword v245, v[202:203], off offset:128
	global_load_dword v246, v[204:205], off
	global_load_dword v247, v[204:205], off offset:128
	v_add_u32_e32 v196, 17, v225
	v_min_i32_e32 v196, 0x7fff, v196
	v_ashrrev_i32_e32 v196, 12, v196
	v_add_u32_e32 v196, 24, v196
	v_mul_hi_i32_i24_e32 v197, 0x3000, v196
	v_mul_i32_i24_e32 v196, 0x3000, v196
	v_lshl_add_u64 v[196:197], s[24:25], 0, v[196:197]
	v_lshl_add_u64 v[196:197], v[196:197], 0, s[18:19]
	v_lshl_add_u64 v[206:207], v[196:197], 0, v[180:181]
	s_waitcnt vmcnt(7)
	s_nop 5
	v_mul_f32_e32 v112, v112, v232
	v_add_u32_e32 v192, 11, v225
	v_add_u32_e32 v194, 16, v225
	v_min_i32_e32 v192, 0x7fff, v192
	v_min_i32_e32 v194, 0x7fff, v194
	v_ashrrev_i32_e32 v192, 12, v192
	v_ashrrev_i32_e32 v194, 12, v194
	v_add_u32_e32 v192, 24, v192
	v_add_u32_e32 v194, 24, v194
	v_mul_hi_i32_i24_e32 v193, 0x3000, v192
	v_mul_i32_i24_e32 v192, 0x3000, v192
	v_mul_hi_i32_i24_e32 v195, 0x3000, v194
	v_mul_i32_i24_e32 v194, 0x3000, v194
	v_lshl_add_u64 v[192:193], s[24:25], 0, v[192:193]
	v_lshl_add_u64 v[194:195], s[24:25], 0, v[194:195]
	v_lshl_add_u64 v[192:193], v[192:193], 0, s[18:19]
	v_lshl_add_u64 v[194:195], v[194:195], 0, s[18:19]
	v_lshl_add_u64 v[202:203], v[192:193], 0, v[180:181]
	v_lshl_add_u64 v[204:205], v[194:195], 0, v[180:181]
	s_waitcnt vmcnt(6)
	s_nop 5
	v_mul_f32_e32 v96, v96, v233
	v_mul_f32_e32 v97, v97, v233
	v_lshl_add_u64 v[198:199], v[208:209], 0, s[18:19]
	v_lshl_add_u64 v[200:201], v[198:199], 0, v[180:181]
	global_load_dword v234, v[202:203], off
	global_load_dword v235, v[202:203], off offset:128
	global_load_dword v236, v[204:205], off
	global_load_dword v237, v[204:205], off offset:128
	global_load_dword v238, v[206:207], off
	global_load_dword v239, v[206:207], off offset:128
	global_load_dword v240, v[200:201], off
	global_load_dword v241, v[200:201], off offset:128
	v_add_u32_e32 v200, 19, v225
	v_add_u32_e32 v204, 25, v225
	v_add_u32_e32 v206, 26, v225
	v_min_i32_e32 v200, 0x7fff, v200
	v_add_u32_e32 v202, 24, v225
	v_min_i32_e32 v204, 0x7fff, v204
	v_min_i32_e32 v206, 0x7fff, v206
	v_ashrrev_i32_e32 v200, 12, v200
	v_min_i32_e32 v202, 0x7fff, v202
	v_ashrrev_i32_e32 v204, 12, v204
	v_ashrrev_i32_e32 v206, 12, v206
	v_add_u32_e32 v200, 24, v200
	v_ashrrev_i32_e32 v202, 12, v202
	v_add_u32_e32 v204, 24, v204
	v_add_u32_e32 v206, 24, v206
	v_mul_hi_i32_i24_e32 v201, 0x3000, v200
	v_mul_i32_i24_e32 v200, 0x3000, v200
	v_add_u32_e32 v202, 24, v202
	v_mul_hi_i32_i24_e32 v205, 0x3000, v204
	v_mul_i32_i24_e32 v204, 0x3000, v204
	v_mul_hi_i32_i24_e32 v207, 0x3000, v206
	v_mul_i32_i24_e32 v206, 0x3000, v206
	v_lshl_add_u64 v[200:201], s[24:25], 0, v[200:201]
	v_mul_hi_i32_i24_e32 v203, 0x3000, v202
	v_mul_i32_i24_e32 v202, 0x3000, v202
	v_lshl_add_u64 v[204:205], s[24:25], 0, v[204:205]
	v_lshl_add_u64 v[206:207], s[24:25], 0, v[206:207]
	v_lshl_add_u64 v[200:201], v[200:201], 0, s[18:19]
	v_lshl_add_u64 v[202:203], s[24:25], 0, v[202:203]
	v_lshl_add_u64 v[204:205], v[204:205], 0, s[18:19]
	v_lshl_add_u64 v[206:207], v[206:207], 0, s[18:19]
	v_lshl_add_u64 v[208:209], v[200:201], 0, v[180:181]
	v_lshl_add_u64 v[202:203], v[202:203], 0, s[18:19]
	v_lshl_add_u64 v[228:229], v[204:205], 0, v[180:181]
	v_lshl_add_u64 v[230:231], v[206:207], 0, v[180:181]
	v_lshl_add_u64 v[226:227], v[202:203], 0, v[180:181]
	global_load_dword v248, v[208:209], off
	global_load_dword v249, v[208:209], off offset:128
	global_load_dword v250, v[226:227], off
	global_load_dword v251, v[226:227], off offset:128
	global_load_dword v252, v[228:229], off
	s_nop 0
	global_load_dword v228, v[228:229], off offset:128
	s_nop 0
	global_load_dword v229, v[230:231], off
	s_nop 0
	global_load_dword v230, v[230:231], off offset:128
	v_add_u32_e32 v208, 27, v225
	v_min_i32_e32 v208, 0x7fff, v208
	v_ashrrev_i32_e32 v208, 12, v208
	v_add_u32_e32 v208, 24, v208
	v_mul_hi_i32_i24_e32 v209, 0x3000, v208
	v_mul_i32_i24_e32 v208, 0x3000, v208
	v_lshl_add_u64 v[208:209], s[24:25], 0, v[208:209]
	v_lshl_add_u64 v[208:209], v[208:209], 0, s[18:19]
	v_lshl_add_u64 v[226:227], v[208:209], 0, v[180:181]
	global_load_dword v225, v[226:227], off
	s_nop 0
	global_load_dword v226, v[226:227], off offset:128
	v_mad_u64_u32 v[160:161], s[2:3], v183, s36, v[182:183]
	v_lshl_add_u32 v162, v160, 2, s34
	ds_write2_b32 v162, v112, v96 offset1:32
	v_mul_f32_e32 v96, v113, v232
	ds_write2_b32 v162, v96, v97 offset0:68 offset1:100
	v_mul_f32_e32 v96, v114, v232
	v_mul_f32_e32 v97, v98, v233
	ds_write2_b32 v162, v96, v97 offset0:136 offset1:168
	v_mul_f32_e32 v96, v115, v232
	v_mul_f32_e32 v97, v99, v233
	ds_write2_b32 v162, v96, v97 offset0:204 offset1:236
	s_waitcnt vmcnt(23)
	v_mul_f32_e32 v96, v116, v242
	s_waitcnt vmcnt(22)
	v_mul_f32_e32 v97, v100, v243
	v_add_u32_e32 v115, 0x800, v162
	ds_write2_b32 v115, v96, v97 offset0:32 offset1:64
	s_waitcnt vmcnt(21)
	v_mul_f32_e32 v96, v117, v244
	s_waitcnt vmcnt(20)
	v_mul_f32_e32 v97, v101, v245
	ds_write2_b32 v115, v96, v97 offset0:100 offset1:132
	s_waitcnt vmcnt(19)
	v_mul_f32_e32 v96, v118, v246
	s_waitcnt vmcnt(18)
	v_mul_f32_e32 v97, v102, v247
	ds_write2_b32 v115, v96, v97 offset0:168 offset1:200
	v_add_u32_e32 v116, 0xa00, v162
	v_add_u32_e32 v117, 0x1000, v162
	s_waitcnt vmcnt(17)
	v_mul_f32_e32 v96, v119, v234
	s_waitcnt vmcnt(16)
	v_mul_f32_e32 v97, v103, v235
	ds_write2_b32 v116, v96, v97 offset0:108 offset1:140
	s_waitcnt vmcnt(15)
	v_mul_f32_e32 v96, v120, v236
	s_waitcnt vmcnt(14)
	v_mul_f32_e32 v97, v104, v237
	ds_write2_b32 v117, v96, v97 offset0:64 offset1:96
	s_waitcnt vmcnt(13)
	v_mul_f32_e32 v96, v121, v238
	s_waitcnt vmcnt(12)
	v_mul_f32_e32 v97, v105, v239
	ds_write2_b32 v117, v96, v97 offset0:132 offset1:164
	s_waitcnt vmcnt(11)
	v_mul_f32_e32 v96, v122, v240
	s_waitcnt vmcnt(10)
	v_mul_f32_e32 v97, v106, v241
	ds_write2_b32 v117, v96, v97 offset0:200 offset1:232
	v_add_u32_e32 v118, 0x1400, v162
	v_add_u32_e32 v119, 0x1800, v162
	v_ashrrev_i32_e32 v163, 4, v168
	v_and_b32_e32 v160, 15, v168
	v_add_u32_e32 v120, 0x1a00, v162
	v_mul_lo_u32 v164, v163, s37
	v_lshl_add_u32 v165, v160, 4, s34
	v_lshlrev_b32_e32 v168, 2, v160
	v_add_u32_e32 v160, s55, v163
	v_add_u32_e32 v121, 0x1c00, v162
	v_cmp_gt_i32_e32 vcc, s38, v160
	v_ashrrev_i32_e32 v161, 31, v160
	v_add_u32_e32 v114, v165, v164
	s_waitcnt vmcnt(9)
	v_mul_f32_e32 v96, v123, v248
	s_waitcnt vmcnt(8)
	v_mul_f32_e32 v97, v107, v249
	ds_write2_b32 v118, v96, v97 offset0:12 offset1:44
	s_waitcnt vmcnt(7)
	v_mul_f32_e32 v96, v124, v250
	s_waitcnt vmcnt(6)
	v_mul_f32_e32 v97, v108, v251
	ds_write2_b32 v119, v96, v97 offset0:96 offset1:128
	s_waitcnt vmcnt(5)
	v_mul_f32_e32 v96, v125, v252
	s_waitcnt vmcnt(4)
	v_mul_f32_e32 v97, v109, v228
	ds_write2_b32 v119, v96, v97 offset0:164 offset1:196
	s_waitcnt vmcnt(3)
	v_mul_f32_e32 v96, v126, v229
	s_waitcnt vmcnt(2)
	v_mul_f32_e32 v97, v110, v230
	ds_write2_b32 v120, v96, v97 offset0:104 offset1:136
	s_waitcnt vmcnt(1)
	v_mul_f32_e32 v96, v127, v225
	s_waitcnt vmcnt(0)
	v_mul_f32_e32 v97, v111, v226
	ds_write2_b32 v121, v96, v97 offset0:44 offset1:76
	v_or_b32_e32 v96, s26, v168
	v_mov_b32_e32 v97, s27
	v_add_u32_e32 v128, 0, v160
	v_ashrrev_i32_e32 v129, 31, v128
	v_lshlrev_b64 v[128:129], 12, v[128:129]
	v_lshl_add_u64 v[128:129], s[16:17], 0, v[128:129]
	v_lshl_add_u64 v[128:129], v[96:97], 2, v[128:129]
	global_load_dwordx4 v[128:131], v[128:129], off
	v_add_u32_e32 v132, 4, v160
	v_ashrrev_i32_e32 v133, 31, v132
	v_lshlrev_b64 v[132:133], 12, v[132:133]
	v_lshl_add_u64 v[132:133], s[16:17], 0, v[132:133]
	v_lshl_add_u64 v[132:133], v[96:97], 2, v[132:133]
	global_load_dwordx4 v[132:135], v[132:133], off
	v_add_u32_e32 v136, 8, v160
	v_ashrrev_i32_e32 v137, 31, v136
	v_lshlrev_b64 v[136:137], 12, v[136:137]
	v_lshl_add_u64 v[136:137], s[16:17], 0, v[136:137]
	v_lshl_add_u64 v[136:137], v[96:97], 2, v[136:137]
	global_load_dwordx4 v[136:139], v[136:137], off
	v_add_u32_e32 v140, 12, v160
	v_ashrrev_i32_e32 v141, 31, v140
	v_lshlrev_b64 v[140:141], 12, v[140:141]
	v_lshl_add_u64 v[140:141], s[16:17], 0, v[140:141]
	v_lshl_add_u64 v[140:141], v[96:97], 2, v[140:141]
	global_load_dwordx4 v[140:143], v[140:141], off
	v_add_u32_e32 v144, 16, v160
	v_ashrrev_i32_e32 v145, 31, v144
	v_lshlrev_b64 v[144:145], 12, v[144:145]
	v_lshl_add_u64 v[144:145], s[16:17], 0, v[144:145]
	v_lshl_add_u64 v[144:145], v[96:97], 2, v[144:145]
	global_load_dwordx4 v[144:147], v[144:145], off
	v_add_u32_e32 v148, 20, v160
	v_ashrrev_i32_e32 v149, 31, v148
	v_lshlrev_b64 v[148:149], 12, v[148:149]
	v_lshl_add_u64 v[148:149], s[16:17], 0, v[148:149]
	v_lshl_add_u64 v[148:149], v[96:97], 2, v[148:149]
	global_load_dwordx4 v[148:151], v[148:149], off
	v_add_u32_e32 v152, 24, v160
	v_ashrrev_i32_e32 v153, 31, v152
	v_lshlrev_b64 v[152:153], 12, v[152:153]
	v_lshl_add_u64 v[152:153], s[16:17], 0, v[152:153]
	v_lshl_add_u64 v[152:153], v[96:97], 2, v[152:153]
	global_load_dwordx4 v[152:155], v[152:153], off
	v_add_u32_e32 v156, 28, v160
	v_ashrrev_i32_e32 v157, 31, v156
	v_lshlrev_b64 v[156:157], 12, v[156:157]
	v_lshl_add_u64 v[156:157], s[16:17], 0, v[156:157]
	v_lshl_add_u64 v[156:157], v[96:97], 2, v[156:157]
	global_load_dwordx4 v[156:159], v[156:157], off
	s_and_saveexec_b64 s[2:3], vcc
	s_cbranch_execz .LBB0_5646
	v_lshlrev_b64 v[98:99], 12, v[160:161]
	v_lshl_add_u64 v[98:99], s[16:17], 0, v[98:99]
	v_lshl_add_u64 v[106:107], v[96:97], 2, v[98:99]
	ds_read_b128 v[102:105], v114
	s_waitcnt vmcnt(7) lgkmcnt(0)
	v_pk_add_f32 v[100:101], v[104:105], v[130:131]
	v_pk_add_f32 v[98:99], v[102:103], v[128:129]
	global_store_dwordx4 v[106:107], v[98:101], off

.LBB0_5676:
	s_or_b64 exec, exec, s[2:3]
	s_or_b32 s2, s55, 32
	v_add_u32_e32 v102, s2, v183
	v_min_i32_e32 v66, 0x7fff, v102
	v_add_u32_e32 v68, 8, v102
	v_add_u32_e32 v70, 9, v102
	v_add_u32_e32 v72, 10, v102
	v_ashrrev_i32_e32 v66, 12, v66
	v_min_i32_e32 v68, 0x7fff, v68
	v_min_i32_e32 v70, 0x7fff, v70
	v_min_i32_e32 v72, 0x7fff, v72
	v_add_u32_e32 v66, 24, v66
	v_ashrrev_i32_e32 v68, 12, v68
	v_ashrrev_i32_e32 v70, 12, v70
	v_ashrrev_i32_e32 v72, 12, v72
	v_mul_hi_i32_i24_e32 v67, 0x3000, v66
	v_mul_i32_i24_e32 v66, 0x3000, v66
	v_add_u32_e32 v68, 24, v68
	v_add_u32_e32 v70, 24, v70
	v_add_u32_e32 v72, 24, v72
	v_lshl_add_u64 v[66:67], s[24:25], 0, v[66:67]
	v_mul_hi_i32_i24_e32 v69, 0x3000, v68
	v_mul_i32_i24_e32 v68, 0x3000, v68
	v_mul_hi_i32_i24_e32 v71, 0x3000, v70
	v_mul_i32_i24_e32 v70, 0x3000, v70
	v_mul_hi_i32_i24_e32 v73, 0x3000, v72
	v_mul_i32_i24_e32 v72, 0x3000, v72
	v_lshl_add_u64 v[66:67], v[66:67], 0, s[18:19]
	v_lshl_add_u64 v[68:69], s[24:25], 0, v[68:69]
	v_lshl_add_u64 v[70:71], s[24:25], 0, v[70:71]
	v_lshl_add_u64 v[72:73], s[24:25], 0, v[72:73]
	v_lshl_add_u64 v[74:75], v[66:67], 0, v[180:181]
	v_lshl_add_u64 v[68:69], v[68:69], 0, s[18:19]
	v_lshl_add_u64 v[70:71], v[70:71], 0, s[18:19]
	v_lshl_add_u64 v[72:73], v[72:73], 0, s[18:19]
	v_lshl_add_u64 v[76:77], v[68:69], 0, v[180:181]
	v_lshl_add_u64 v[78:79], v[70:71], 0, v[180:181]
	v_lshl_add_u64 v[80:81], v[72:73], 0, v[180:181]
	global_load_dword v103, v[74:75], off
	global_load_dword v104, v[74:75], off offset:128
	global_load_dword v105, v[76:77], off
	global_load_dword v106, v[76:77], off offset:128
	global_load_dword v107, v[78:79], off
	global_load_dword v108, v[78:79], off offset:128
	global_load_dword v109, v[80:81], off
	global_load_dword v110, v[80:81], off offset:128
	v_add_u32_e32 v74, 11, v102
	v_add_u32_e32 v82, 18, v102
	v_min_i32_e32 v74, 0x7fff, v74
	v_add_u32_e32 v76, 16, v102
	v_add_u32_e32 v78, 17, v102
	v_min_i32_e32 v82, 0x7fff, v82
	v_ashrrev_i32_e32 v74, 12, v74
	v_min_i32_e32 v76, 0x7fff, v76
	v_min_i32_e32 v78, 0x7fff, v78
	v_ashrrev_i32_e32 v82, 12, v82
	v_add_u32_e32 v74, 24, v74
	v_ashrrev_i32_e32 v76, 12, v76
	v_ashrrev_i32_e32 v78, 12, v78
	v_add_u32_e32 v82, 24, v82
	v_mul_hi_i32_i24_e32 v75, 0x3000, v74
	v_mul_i32_i24_e32 v74, 0x3000, v74
	v_add_u32_e32 v76, 24, v76
	v_add_u32_e32 v78, 24, v78
	v_mul_hi_i32_i24_e32 v83, 0x3000, v82
	v_mul_i32_i24_e32 v82, 0x3000, v82
	v_lshl_add_u64 v[74:75], s[24:25], 0, v[74:75]
	v_mul_hi_i32_i24_e32 v77, 0x3000, v76
	v_mul_i32_i24_e32 v76, 0x3000, v76
	v_mul_hi_i32_i24_e32 v79, 0x3000, v78
	v_mul_i32_i24_e32 v78, 0x3000, v78
	v_lshl_add_u64 v[82:83], s[24:25], 0, v[82:83]
	v_lshl_add_u64 v[74:75], v[74:75], 0, s[18:19]
	v_lshl_add_u64 v[76:77], s[24:25], 0, v[76:77]
	v_lshl_add_u64 v[78:79], s[24:25], 0, v[78:79]
	v_lshl_add_u64 v[82:83], v[82:83], 0, s[18:19]
	v_lshl_add_u64 v[80:81], v[74:75], 0, v[180:181]
	v_lshl_add_u64 v[76:77], v[76:77], 0, s[18:19]
	v_lshl_add_u64 v[78:79], v[78:79], 0, s[18:19]
	v_lshl_add_u64 v[88:89], v[82:83], 0, v[180:181]
	v_lshl_add_u64 v[84:85], v[76:77], 0, v[180:181]
	v_lshl_add_u64 v[86:87], v[78:79], 0, v[180:181]
	global_load_dword v111, v[80:81], off
	global_load_dword v112, v[80:81], off offset:128
	global_load_dword v113, v[84:85], off
	global_load_dword v122, v[84:85], off offset:128
	global_load_dword v123, v[86:87], off
	global_load_dword v124, v[86:87], off offset:128
	global_load_dword v125, v[88:89], off
	global_load_dword v126, v[88:89], off offset:128
	v_add_u32_e32 v80, 19, v102
	v_add_u32_e32 v88, 25, v102
	v_add_u32_e32 v90, 26, v102
	v_min_i32_e32 v80, 0x7fff, v80
	v_add_u32_e32 v86, 24, v102
	v_min_i32_e32 v88, 0x7fff, v88
	v_min_i32_e32 v90, 0x7fff, v90
	v_ashrrev_i32_e32 v80, 12, v80
	v_min_i32_e32 v86, 0x7fff, v86
	v_ashrrev_i32_e32 v88, 12, v88
	v_ashrrev_i32_e32 v90, 12, v90
	v_add_u32_e32 v80, 24, v80
	v_ashrrev_i32_e32 v86, 12, v86
	v_add_u32_e32 v88, 24, v88
	v_add_u32_e32 v90, 24, v90
	v_mul_hi_i32_i24_e32 v81, 0x3000, v80
	v_mul_i32_i24_e32 v80, 0x3000, v80
	v_add_u32_e32 v86, 24, v86
	v_mul_hi_i32_i24_e32 v89, 0x3000, v88
	v_mul_i32_i24_e32 v88, 0x3000, v88
	v_mul_hi_i32_i24_e32 v91, 0x3000, v90
	v_mul_i32_i24_e32 v90, 0x3000, v90
	v_lshl_add_u64 v[80:81], s[24:25], 0, v[80:81]
	v_mul_hi_i32_i24_e32 v87, 0x3000, v86
	v_mul_i32_i24_e32 v86, 0x3000, v86
	v_lshl_add_u64 v[88:89], s[24:25], 0, v[88:89]
	v_lshl_add_u64 v[90:91], s[24:25], 0, v[90:91]
	v_lshl_add_u64 v[84:85], v[80:81], 0, s[18:19]
	v_lshl_add_u64 v[86:87], s[24:25], 0, v[86:87]
	v_lshl_add_u64 v[88:89], v[88:89], 0, s[18:19]
	v_lshl_add_u64 v[90:91], v[90:91], 0, s[18:19]
	v_lshl_add_u64 v[80:81], v[84:85], 0, v[180:181]
	v_lshl_add_u64 v[86:87], v[86:87], 0, s[18:19]
	v_lshl_add_u64 v[94:95], v[88:89], 0, v[180:181]
	v_lshl_add_u64 v[100:101], v[90:91], 0, v[180:181]
	v_lshl_add_u64 v[92:93], v[86:87], 0, v[180:181]
	global_load_dword v127, v[80:81], off
	global_load_dword v160, v[80:81], off offset:128
	global_load_dword v161, v[92:93], off
	global_load_dword v164, v[92:93], off offset:128
	global_load_dword v165, v[94:95], off
	s_nop 0
	global_load_dword v94, v[94:95], off offset:128
	s_nop 0
	global_load_dword v95, v[100:101], off
	s_nop 0
	global_load_dword v100, v[100:101], off offset:128
	v_add_u32_e32 v80, 27, v102
	v_min_i32_e32 v80, 0x7fff, v80
	v_ashrrev_i32_e32 v80, 12, v80
	v_add_u32_e32 v80, 24, v80
	v_mul_hi_i32_i24_e32 v81, 0x3000, v80
	v_mul_i32_i24_e32 v80, 0x3000, v80
	v_lshl_add_u64 v[80:81], s[24:25], 0, v[80:81]
	v_lshl_add_u64 v[92:93], v[80:81], 0, s[18:19]
	v_lshl_add_u64 v[80:81], v[92:93], 0, v[180:181]
	global_load_dword v101, v[80:81], off
	s_nop 0
	global_load_dword v81, v[80:81], off offset:128
	s_waitcnt vmcnt(25)
	v_mul_f32_e32 v48, v48, v103
	s_waitcnt vmcnt(24)
	v_mul_f32_e32 v32, v32, v104
	ds_write2_b32 v162, v48, v32 offset1:32
	v_mul_f32_e32 v32, v49, v103
	v_mul_f32_e32 v33, v33, v104
	ds_write2_b32 v162, v32, v33 offset0:68 offset1:100
	v_mul_f32_e32 v32, v50, v103
	v_mul_f32_e32 v33, v34, v104
	ds_write2_b32 v162, v32, v33 offset0:136 offset1:168
	v_mul_f32_e32 v32, v51, v103
	v_mul_f32_e32 v33, v35, v104
	ds_write2_b32 v162, v32, v33 offset0:204 offset1:236
	s_waitcnt vmcnt(23)
	v_mul_f32_e32 v32, v52, v105
	s_waitcnt vmcnt(22)
	v_mul_f32_e32 v33, v36, v106
	ds_write2_b32 v115, v32, v33 offset0:32 offset1:64
	s_waitcnt vmcnt(21)
	v_mul_f32_e32 v32, v53, v107
	s_waitcnt vmcnt(20)
	v_mul_f32_e32 v33, v37, v108
	ds_write2_b32 v115, v32, v33 offset0:100 offset1:132
	s_waitcnt vmcnt(19)
	v_mul_f32_e32 v32, v54, v109
	s_waitcnt vmcnt(18)
	v_mul_f32_e32 v33, v38, v110
	ds_write2_b32 v115, v32, v33 offset0:168 offset1:200
	v_add_u32_e32 v80, s2, v163
	v_cmp_gt_i32_e32 vcc, s38, v80
	s_waitcnt vmcnt(17)
	v_mul_f32_e32 v32, v55, v111
	s_waitcnt vmcnt(16)
	v_mul_f32_e32 v33, v39, v112
	ds_write2_b32 v116, v32, v33 offset0:108 offset1:140
	s_waitcnt vmcnt(15)
	v_mul_f32_e32 v32, v56, v113
	s_waitcnt vmcnt(14)
	v_mul_f32_e32 v33, v40, v122
	ds_write2_b32 v117, v32, v33 offset0:64 offset1:96
	s_waitcnt vmcnt(13)
	v_mul_f32_e32 v32, v57, v123
	s_waitcnt vmcnt(12)
	v_mul_f32_e32 v33, v41, v124
	ds_write2_b32 v117, v32, v33 offset0:132 offset1:164
	s_waitcnt vmcnt(11)
	v_mul_f32_e32 v32, v58, v125
	s_waitcnt vmcnt(10)
	v_mul_f32_e32 v33, v42, v126
	ds_write2_b32 v117, v32, v33 offset0:200 offset1:232
	s_waitcnt vmcnt(9)
	v_mul_f32_e32 v32, v59, v127
	s_waitcnt vmcnt(8)
	v_mul_f32_e32 v33, v43, v160
	ds_write2_b32 v118, v32, v33 offset0:12 offset1:44
	s_waitcnt vmcnt(7)
	v_mul_f32_e32 v32, v60, v161
	s_waitcnt vmcnt(6)
	v_mul_f32_e32 v33, v44, v164
	ds_write2_b32 v119, v32, v33 offset0:96 offset1:128
	s_waitcnt vmcnt(5)
	v_mul_f32_e32 v32, v61, v165
	s_waitcnt vmcnt(4)
	v_mul_f32_e32 v33, v45, v94
	ds_write2_b32 v119, v32, v33 offset0:164 offset1:196
	s_waitcnt vmcnt(3)
	v_mul_f32_e32 v32, v62, v95
	s_waitcnt vmcnt(2)
	v_mul_f32_e32 v33, v46, v100
	ds_write2_b32 v120, v32, v33 offset0:104 offset1:136
	s_waitcnt vmcnt(1)
	v_mul_f32_e32 v32, v63, v101
	s_waitcnt vmcnt(0)
	v_mul_f32_e32 v33, v47, v81
	v_ashrrev_i32_e32 v81, 31, v80
	ds_write2_b32 v121, v32, v33 offset0:44 offset1:76
	v_add_u32_e32 v128, 0, v80
	v_ashrrev_i32_e32 v129, 31, v128
	v_lshlrev_b64 v[128:129], 12, v[128:129]
	v_lshl_add_u64 v[128:129], s[16:17], 0, v[128:129]
	v_lshl_add_u64 v[128:129], v[96:97], 2, v[128:129]
	global_load_dwordx4 v[128:131], v[128:129], off
	v_add_u32_e32 v132, 4, v80
	v_ashrrev_i32_e32 v133, 31, v132
	v_lshlrev_b64 v[132:133], 12, v[132:133]
	v_lshl_add_u64 v[132:133], s[16:17], 0, v[132:133]
	v_lshl_add_u64 v[132:133], v[96:97], 2, v[132:133]
	global_load_dwordx4 v[132:135], v[132:133], off
	v_add_u32_e32 v136, 8, v80
	v_ashrrev_i32_e32 v137, 31, v136
	v_lshlrev_b64 v[136:137], 12, v[136:137]
	v_lshl_add_u64 v[136:137], s[16:17], 0, v[136:137]
	v_lshl_add_u64 v[136:137], v[96:97], 2, v[136:137]
	global_load_dwordx4 v[136:139], v[136:137], off
	v_add_u32_e32 v140, 12, v80
	v_ashrrev_i32_e32 v141, 31, v140
	v_lshlrev_b64 v[140:141], 12, v[140:141]
	v_lshl_add_u64 v[140:141], s[16:17], 0, v[140:141]
	v_lshl_add_u64 v[140:141], v[96:97], 2, v[140:141]
	global_load_dwordx4 v[140:143], v[140:141], off
	v_add_u32_e32 v144, 16, v80
	v_ashrrev_i32_e32 v145, 31, v144
	v_lshlrev_b64 v[144:145], 12, v[144:145]
	v_lshl_add_u64 v[144:145], s[16:17], 0, v[144:145]
	v_lshl_add_u64 v[144:145], v[96:97], 2, v[144:145]
	global_load_dwordx4 v[144:147], v[144:145], off
	v_add_u32_e32 v148, 20, v80
	v_ashrrev_i32_e32 v149, 31, v148
	v_lshlrev_b64 v[148:149], 12, v[148:149]
	v_lshl_add_u64 v[148:149], s[16:17], 0, v[148:149]
	v_lshl_add_u64 v[148:149], v[96:97], 2, v[148:149]
	global_load_dwordx4 v[148:151], v[148:149], off
	v_add_u32_e32 v152, 24, v80
	v_ashrrev_i32_e32 v153, 31, v152
	v_lshlrev_b64 v[152:153], 12, v[152:153]
	v_lshl_add_u64 v[152:153], s[16:17], 0, v[152:153]
	v_lshl_add_u64 v[152:153], v[96:97], 2, v[152:153]
	global_load_dwordx4 v[152:155], v[152:153], off
	v_add_u32_e32 v156, 28, v80
	v_ashrrev_i32_e32 v157, 31, v156
	v_lshlrev_b64 v[156:157], 12, v[156:157]
	v_lshl_add_u64 v[156:157], s[16:17], 0, v[156:157]
	v_lshl_add_u64 v[156:157], v[96:97], 2, v[156:157]
	global_load_dwordx4 v[156:159], v[156:157], off
	s_and_saveexec_b64 s[2:3], vcc
	s_cbranch_execz .LBB0_5678
	v_lshlrev_b64 v[32:33], 12, v[80:81]
	v_lshl_add_u64 v[32:33], s[16:17], 0, v[32:33]
	v_lshl_add_u64 v[40:41], v[96:97], 2, v[32:33]
	ds_read_b128 v[36:39], v114
	s_waitcnt vmcnt(7) lgkmcnt(0)
	v_pk_add_f32 v[34:35], v[38:39], v[130:131]
	v_pk_add_f32 v[32:33], v[36:37], v[128:129]
	global_store_dwordx4 v[40:41], v[32:35], off
